# mixer_deserialize_v3
# speedup vs baseline: 1.0376x; 1.0264x over previous
; __device__ __forceinline__ float bperm_f(int src_lane, float v) { return __builtin_bit_cast(float, __builtin_amdgcn_ds_bpermute(src_lane << 2, __builtin_bit_cast(int, v))); }
;     __device__ __forceinline__ void operator()(Acc& acc, const Unit& u, int wr, int wc, int fr, int fq) const {
;         const int b = u.pm / UPU, j = u.pm % UPU;
;         const int tbase = 252 * j + 126 * wr - 2 + fr;
;         const int ch0 = 128 * u.pn + 32 * wc + 8 * fq;
;         float chain = 0.f;
;         { const int ln = (fq << 4) | fr; f32x4 pq[8];
; #pragma unroll
;           for (int q = 0; q < 8; ++q) { const int t = tbase + 16 * q; const bool ok = (t >= 0) && (t < SEQ); pq[q] = *(const f32x4*)(ssq + (size_t)(b * SEQ + (ok ? t : 0)) * 16 + 4 * fq); }
; #pragma unroll
;           for (int q = 0; q < 8; ++q) {
;             const int t = tbase + 16 * q; const bool ok = (t >= 0) && (t < SEQ);
;             float sq = (pq[q][0] + pq[q][1]) + (pq[q][2] + pq[q][3]); sq += bperm_f(ln ^ 16, sq); sq += bperm_f(ln ^ 32, sq);
;             const float rs = rsqrtf(sq * (1.0f / DM) + EPS);
; #pragma unroll
;             for (int bj = 0; bj < 2; ++bj)
; #pragma unroll
;                 for (int n = 0; n < 2; ++n)
; #pragma unroll
;                     for (int i = 0; i < 4; ++i) { const float v = acc[q >> 2][bj][q & 3][n][i]; acc[q >> 2][bj][q & 3][n][i] = ok ? v * rs : 0.f; }
.LBB0_43:
	s_mul_hi_i32 s21, s20, 0x3e0f83e1
	s_lshr_b32 s27, s21, 31
	s_ashr_i32 s21, s21, 3
	s_add_i32 s21, s21, s27
	s_mul_i32 s27, s21, 33
	s_sub_i32 s20, s20, s27
	s_mulk_i32 s20, 0xfc
	v_add_u32_e32 v198, s20, v194
	v_add_u32_e32 v223, 16, v198
	v_cmp_gt_u32_e64 s[56:57], s97, v198
	v_cmp_gt_u32_e64 s[52:53], s97, v223
	s_lshl_b32 s20, s21, 13
	v_cndmask_b32_e64 v132, 0, v198, s[56:57]
	v_cndmask_b32_e64 v136, 0, v223, s[52:53]
	v_add_u32_e32 v132, s20, v132
	v_add_u32_e32 v136, s20, v136
	v_ashrrev_i32_e32 v133, 31, v132
	v_ashrrev_i32_e32 v137, 31, v136
	v_lshlrev_b64 v[132:133], 6, v[132:133]
	v_lshlrev_b64 v[136:137], 6, v[136:137]
	v_lshl_add_u64 v[132:133], v[146:147], 0, v[132:133]
	v_lshl_add_u64 v[136:137], v[146:147], 0, v[136:137]
	flat_load_dwordx4 v[132:135], v[132:133]
	v_add_u32_e32 v227, 32, v198
	flat_load_dwordx4 v[136:139], v[136:137]
	v_add_u32_e32 v226, 48, v198
	v_cmp_gt_u32_e64 s[54:55], s97, v227
	v_add_u32_e32 v225, 64, v198
	v_cmp_gt_u32_e64 s[50:51], s97, v226
	v_cndmask_b32_e64 v152, 0, v227, s[54:55]
	v_cmp_gt_u32_e64 s[48:49], s97, v225
	v_cndmask_b32_e64 v153, 0, v226, s[50:51]
	v_add_u32_e32 v152, s20, v152
	v_cndmask_b32_e64 v155, 0, v225, s[48:49]
	v_add_u32_e32 v154, s20, v153
	v_ashrrev_i32_e32 v153, 31, v152
	v_add_u32_e32 v156, s20, v155
	v_ashrrev_i32_e32 v155, 31, v154
	v_lshlrev_b64 v[152:153], 6, v[152:153]
	v_lshlrev_b64 v[154:155], 6, v[154:155]
	v_add_u32_e32 v224, 0x50, v198
	v_cmp_gt_u32_e64 s[46:47], s97, v224
	s_mov_b32 s44, 0x358637bd
	v_add_u32_e32 v222, 0x60, v198
	v_add_u32_e32 v199, 0x70, v198
	v_cndmask_b32_e64 v157, 0, v224, s[46:47]
	v_mov_b64_e32 v[188:189], s[44:45]
	v_cmp_gt_u32_e64 s[44:45], s97, v222
	v_cmp_gt_u32_e32 vcc, s97, v199
	v_add_u32_e32 v158, s20, v157
	v_ashrrev_i32_e32 v157, 31, v156
	v_cndmask_b32_e64 v159, 0, v222, s[44:45]
	v_cndmask_b32_e32 v161, 0, v199, vcc
	v_lshlrev_b64 v[156:157], 6, v[156:157]
	s_mov_b32 s90, 0x3a800000
	v_add_u32_e32 v160, s20, v159
	v_add_u32_e32 v162, s20, v161
	v_ashrrev_i32_e32 v159, 31, v158
	v_ashrrev_i32_e32 v161, 31, v160
	v_ashrrev_i32_e32 v163, 31, v162
	v_lshlrev_b64 v[158:159], 6, v[158:159]
	v_lshlrev_b64 v[160:161], 6, v[160:161]
	v_lshlrev_b64 v[162:163], 6, v[162:163]
	s_waitcnt vmcnt(0) lgkmcnt(0)
	v_mov_b32_e32 v174, v133
	v_mov_b32_e32 v175, v134
	v_mov_b32_e32 v133, v135
	v_mov_b32_e32 v134, v137
	v_mov_b32_e32 v135, v138
	v_mov_b32_e32 v137, v139
	v_pk_add_f32 v[132:133], v[174:175], v[132:133]
	v_pk_add_f32 v[134:135], v[134:135], v[136:137]
	v_mov_b32_e32 v137, v132
	v_mov_b32_e32 v136, v134
	v_mov_b32_e32 v132, v135
	v_pk_add_f32 v[132:133], v[136:137], v[132:133]
	v_lshl_add_u64 v[136:137], v[146:147], 0, v[152:153]
	v_lshl_add_u64 v[138:139], v[146:147], 0, v[154:155]
	flat_load_dwordx4 v[190:193], v[136:137]
	flat_load_dwordx4 v[228:231], v[138:139]
	ds_bpermute_b32 v135, v195, v133
	ds_bpermute_b32 v134, v195, v132
	v_lshl_add_u64 v[136:137], v[146:147], 0, v[156:157]
	v_lshl_add_u64 v[138:139], v[146:147], 0, v[158:159]
	v_lshl_add_u64 v[152:153], v[146:147], 0, v[160:161]
	v_lshl_add_u64 v[154:155], v[146:147], 0, v[162:163]
	s_waitcnt lgkmcnt(0)
	v_pk_add_f32 v[132:133], v[132:133], v[134:135]
	ds_bpermute_b32 v135, v196, v133
	ds_bpermute_b32 v134, v196, v132
	s_waitcnt lgkmcnt(0)
	v_pk_add_f32 v[132:133], v[132:133], v[134:135]
	s_nop 0
	v_pk_fma_f32 v[156:157], v[132:133], s[90:91], v[188:189] op_sel_hi:[1,0,0]
	s_nop 0
	v_mul_f32_e32 v132, 0x4b800000, v157
	v_cmp_gt_f32_e64 s[58:59], s29, v157
	s_nop 1
	v_cndmask_b32_e64 v132, v157, v132, s[58:59]
	v_rsq_f32_e32 v157, v132
	flat_load_dwordx4 v[232:235], v[136:137]
	flat_load_dwordx4 v[236:239], v[138:139]
	s_nop 0
	flat_load_dwordx4 v[136:139], v[152:153]
	flat_load_dwordx4 v[132:135], v[154:155]
	v_mul_f32_e32 v152, 0x45800000, v157
	v_cndmask_b32_e64 v153, v157, v152, s[58:59]
	v_mul_f32_e32 v152, v126, v153
	v_mul_f32_e32 v108, v108, v153
	v_mul_f32_e32 v157, v122, v153
	v_cndmask_b32_e64 v122, 0, v152, s[56:57]
	v_cndmask_b32_e64 v152, 0, v108, s[56:57]
	v_mul_f32_e32 v108, v109, v153
	v_mul_f32_e32 v109, 0x4b800000, v156
	v_cmp_gt_f32_e64 s[58:59], s29, v156
	v_mul_f32_e32 v128, v128, v153
	v_mul_f32_e32 v130, v130, v153
	v_cndmask_b32_e64 v109, v156, v109, s[58:59]
	v_rsq_f32_e32 v109, v109
	v_mul_f32_e32 v124, v124, v153
	v_cndmask_b32_e64 v182, 0, v128, s[56:57]
	v_cndmask_b32_e64 v128, 0, v108, s[56:57]
	v_mul_f32_e32 v108, v110, v153
	v_cndmask_b32_e64 v160, 0, v130, s[56:57]
	v_cndmask_b32_e64 v130, 0, v124, s[56:57]
	v_cndmask_b32_e64 v124, 0, v108, s[56:57]
	v_mul_f32_e32 v108, v111, v153
	v_cndmask_b32_e64 v110, 0, v108, s[56:57]
	v_mul_f32_e32 v108, 0x45800000, v109
	v_cndmask_b32_e64 v108, v109, v108, s[58:59]
	v_mul_f32_e32 v109, v116, v108
	v_cndmask_b32_e64 v187, 0, v109, s[52:53]
	v_mul_f32_e32 v109, v117, v108
	v_cndmask_b32_e64 v181, 0, v109, s[52:53]
	v_mul_f32_e32 v109, v118, v108
	v_cndmask_b32_e64 v175, 0, v109, s[52:53]
	v_mul_f32_e32 v109, v119, v108
	v_cndmask_b32_e64 v162, 0, v157, s[56:57]
	v_cndmask_b32_e64 v157, 0, v109, s[52:53]
	v_mul_f32_e32 v109, v112, v108
	v_cndmask_b32_e64 v119, 0, v109, s[52:53]
	v_mul_f32_e32 v109, v113, v108
	v_mul_f32_e32 v104, v104, v108
	v_cndmask_b32_e64 v117, 0, v109, s[52:53]
	v_mul_f32_e32 v109, v114, v108
	v_cndmask_b32_e64 v186, 0, v104, s[52:53]
	v_mul_f32_e32 v104, v105, v108
	v_cndmask_b32_e64 v113, 0, v109, s[52:53]
	v_mul_f32_e32 v109, v115, v108
	v_cndmask_b32_e64 v180, 0, v104, s[52:53]
	v_mul_f32_e32 v106, v106, v108
	v_cndmask_b32_e64 v174, 0, v106, s[52:53]
	v_mul_f32_e32 v106, v107, v108
	v_cndmask_b32_e64 v156, 0, v106, s[52:53]
	v_mul_f32_e32 v92, v92, v108
	v_cndmask_b32_e64 v118, 0, v92, s[52:53]
	v_mul_f32_e32 v92, v93, v108
	v_mul_f32_e32 v121, v121, v153
	s_waitcnt vmcnt(0)
; __device__ __forceinline__ float bperm_f(int src_lane, float v) { return __builtin_bit_cast(float, __builtin_amdgcn_ds_bpermute(src_lane << 2, __builtin_bit_cast(int, v))); }
;     __device__ __forceinline__ void operator()(Acc& acc, const Unit& u, int wr, int wc, int fr, int fq) const {
;     ...
;           for (int q = 0; q < 8; ++q) {
;             const int t = tbase + 16 * q; const bool ok = (t >= 0) && (t < SEQ);
;             float sq = (pq[q][0] + pq[q][1]) + (pq[q][2] + pq[q][3]); sq += bperm_f(ln ^ 16, sq); sq += bperm_f(ln ^ 32, sq);
;             const float rs = rsqrtf(sq * (1.0f / DM) + EPS);
; #pragma unroll
;             for (int bj = 0; bj < 2; ++bj)
; #pragma unroll
;                 for (int n = 0; n < 2; ++n)
; #pragma unroll
;                     for (int i = 0; i < 4; ++i) { const float v = acc[q >> 2][bj][q & 3][n][i]; acc[q >> 2][bj][q & 3][n][i] = ok ? v * rs : 0.f; }
	v_mov_b32_e32 v104, v191
	v_mov_b32_e32 v105, v192
	v_mov_b32_e32 v191, v193
	v_mov_b32_e32 v114, v229
	v_mov_b32_e32 v115, v230
	v_mov_b32_e32 v229, v231
	v_pk_add_f32 v[104:105], v[104:105], v[190:191]
	v_pk_add_f32 v[114:115], v[114:115], v[228:229]
	v_mov_b32_e32 v191, v104
	v_mov_b32_e32 v190, v114
	v_mov_b32_e32 v104, v115
	v_pk_add_f32 v[104:105], v[190:191], v[104:105]
	ds_bpermute_b32 v115, v195, v105
	ds_bpermute_b32 v114, v195, v104
	v_cndmask_b32_e64 v116, 0, v92, s[52:53]
	v_mul_f32_e32 v129, v129, v153
	v_mul_f32_e32 v131, v131, v153
	v_mul_f32_e32 v125, v125, v153
	s_waitcnt lgkmcnt(0)
	v_pk_add_f32 v[104:105], v[104:105], v[114:115]
	ds_bpermute_b32 v107, v196, v105
	ds_bpermute_b32 v106, v196, v104
	v_mul_f32_e32 v127, v127, v153
	v_mul_f32_e32 v155, v120, v153
	v_cndmask_b32_e64 v178, 0, v121, s[56:57]
	v_mul_f32_e32 v121, v123, v153
	s_waitcnt lgkmcnt(0)
	v_pk_add_f32 v[92:93], v[104:105], v[106:107]
	v_cndmask_b32_e64 v176, 0, v129, s[56:57]
	v_pk_fma_f32 v[92:93], v[92:93], s[90:91], v[188:189] op_sel_hi:[1,0,0]
	v_cndmask_b32_e64 v154, 0, v131, s[56:57]
	v_cndmask_b32_e64 v126, 0, v125, s[56:57]
	v_cndmask_b32_e64 v120, 0, v127, s[56:57]
	v_cndmask_b32_e64 v184, 0, v155, s[56:57]
	v_cndmask_b32_e64 v158, 0, v121, s[56:57]
	v_mul_f32_e32 v104, 0x4b800000, v93
	v_cmp_gt_f32_e64 s[56:57], s29, v93
	v_mul_f32_e32 v94, v94, v108
	v_cndmask_b32_e64 v112, 0, v94, s[52:53]
	v_cndmask_b32_e64 v93, v93, v104, s[56:57]
	v_rsq_f32_e32 v93, v93
	v_mul_f32_e32 v94, v95, v108
	v_cndmask_b32_e64 v108, 0, v94, s[52:53]
	v_cndmask_b32_e64 v109, 0, v109, s[52:53]
	v_mul_f32_e32 v94, 0x45800000, v93
	v_cndmask_b32_e64 v111, v93, v94, s[56:57]
	v_mul_f32_e32 v76, v76, v111
	v_mul_f32_e32 v93, v100, v111
	v_cndmask_b32_e64 v100, 0, v76, s[54:55]
	v_mul_f32_e32 v76, v77, v111
	v_mul_f32_e32 v77, 0x4b800000, v92
	v_cmp_gt_f32_e64 s[52:53], s29, v92
	v_cndmask_b32_e64 v115, 0, v93, s[54:55]
	v_mul_f32_e32 v93, v101, v111
	v_cndmask_b32_e64 v77, v92, v77, s[52:53]
	v_cndmask_b32_e64 v107, 0, v93, s[54:55]
	v_mul_f32_e32 v93, v102, v111
	v_rsq_f32_e32 v77, v77
	v_cndmask_b32_e64 v105, 0, v93, s[54:55]
	v_mul_f32_e32 v93, v103, v111
	v_cndmask_b32_e64 v103, 0, v93, s[54:55]
	v_mul_f32_e32 v93, v96, v111
	v_cndmask_b32_e64 v96, 0, v76, s[54:55]
	v_mul_f32_e32 v76, v78, v111
	v_cndmask_b32_e64 v94, 0, v76, s[54:55]
	v_mul_f32_e32 v76, v79, v111
	v_cndmask_b32_e64 v92, 0, v76, s[54:55]
	v_mul_f32_e32 v76, 0x45800000, v77
	v_cndmask_b32_e64 v101, 0, v93, s[54:55]
	v_mul_f32_e32 v93, v97, v111
	v_mul_f32_e32 v88, v88, v111
	v_cndmask_b32_e64 v76, v77, v76, s[52:53]
	v_cndmask_b32_e64 v97, 0, v93, s[54:55]
	v_mul_f32_e32 v93, v98, v111
	v_cndmask_b32_e64 v114, 0, v88, s[54:55]
	v_mul_f32_e32 v88, v89, v111
	v_mul_f32_e32 v77, v84, v76
	v_cndmask_b32_e64 v95, 0, v93, s[54:55]
	v_mul_f32_e32 v93, v99, v111
	v_cndmask_b32_e64 v106, 0, v88, s[54:55]
	v_mul_f32_e32 v88, v90, v111
	v_cndmask_b32_e64 v99, 0, v77, s[50:51]
	v_mul_f32_e32 v77, v85, v76
	v_cndmask_b32_e64 v104, 0, v88, s[54:55]
	v_mul_f32_e32 v88, v91, v111
	v_cndmask_b32_e64 v91, 0, v77, s[50:51]
	v_mul_f32_e32 v77, v86, v76
	v_cndmask_b32_e64 v89, 0, v77, s[50:51]
	v_mul_f32_e32 v77, v87, v76
	v_cndmask_b32_e64 v87, 0, v77, s[50:51]
	v_mul_f32_e32 v77, v80, v76
	v_cndmask_b32_e64 v85, 0, v77, s[50:51]
	v_mul_f32_e32 v77, v81, v76
	v_mul_f32_e32 v72, v72, v76
	v_cndmask_b32_e64 v81, 0, v77, s[50:51]
	v_mul_f32_e32 v77, v82, v76
	v_cndmask_b32_e64 v98, 0, v72, s[50:51]
	v_mul_f32_e32 v72, v73, v76
	v_cndmask_b32_e64 v79, 0, v77, s[50:51]
	v_mul_f32_e32 v77, v83, v76
	v_cndmask_b32_e64 v90, 0, v72, s[50:51]
	v_mov_b32_e32 v72, v233
	v_mov_b32_e32 v73, v234
	v_mov_b32_e32 v233, v235
	v_mov_b32_e32 v82, v237
	v_mov_b32_e32 v83, v238
	v_mov_b32_e32 v237, v239
	v_pk_add_f32 v[72:73], v[72:73], v[232:233]
	v_pk_add_f32 v[82:83], v[82:83], v[236:237]
	v_mov_b32_e32 v191, v72
	v_mov_b32_e32 v190, v82
	v_mov_b32_e32 v72, v83
	v_pk_add_f32 v[72:73], v[190:191], v[72:73]
	ds_bpermute_b32 v83, v195, v73
	ds_bpermute_b32 v82, v195, v72
	v_mul_f32_e32 v74, v74, v76
	v_cndmask_b32_e64 v102, 0, v88, s[54:55]
	v_cndmask_b32_e64 v88, 0, v74, s[50:51]
	v_mul_f32_e32 v74, v75, v76
	s_waitcnt lgkmcnt(0)
	v_pk_add_f32 v[72:73], v[72:73], v[82:83]
	v_cndmask_b32_e64 v86, 0, v74, s[50:51]
	ds_bpermute_b32 v75, v196, v73
	ds_bpermute_b32 v74, v196, v72
	v_mul_f32_e32 v68, v68, v76
	v_cndmask_b32_e64 v84, 0, v68, s[50:51]
	v_mul_f32_e32 v68, v69, v76
	v_cndmask_b32_e64 v80, 0, v68, s[50:51]
	s_waitcnt lgkmcnt(0)
; __device__ __forceinline__ float bperm_f(int src_lane, float v) { return __builtin_bit_cast(float, __builtin_amdgcn_ds_bpermute(src_lane << 2, __builtin_bit_cast(int, v))); }
;     __device__ __forceinline__ void operator()(Acc& acc, const Unit& u, int wr, int wc, int fr, int fq) const {
;     ...
;           for (int q = 0; q < 8; ++q) {
;             const int t = tbase + 16 * q; const bool ok = (t >= 0) && (t < SEQ);
;             float sq = (pq[q][0] + pq[q][1]) + (pq[q][2] + pq[q][3]); sq += bperm_f(ln ^ 16, sq); sq += bperm_f(ln ^ 32, sq);
;             const float rs = rsqrtf(sq * (1.0f / DM) + EPS);
; #pragma unroll
;             for (int bj = 0; bj < 2; ++bj)
; #pragma unroll
;                 for (int n = 0; n < 2; ++n)
; #pragma unroll
;                     for (int i = 0; i < 4; ++i) { const float v = acc[q >> 2][bj][q & 3][n][i]; acc[q >> 2][bj][q & 3][n][i] = ok ? v * rs : 0.f; }
	v_pk_add_f32 v[68:69], v[72:73], v[74:75]
	v_mul_f32_e32 v70, v70, v76
	v_pk_fma_f32 v[82:83], v[68:69], s[90:91], v[188:189] op_sel_hi:[1,0,0]
	v_mul_f32_e32 v69, v71, v76
	v_mul_f32_e32 v68, 0x4b800000, v83
	v_cmp_gt_f32_e64 s[52:53], s29, v83
	v_cndmask_b32_e64 v76, 0, v69, s[50:51]
	v_cndmask_b32_e64 v77, 0, v77, s[50:51]
	v_cndmask_b32_e64 v68, v83, v68, s[52:53]
	v_rsq_f32_e32 v68, v68
	v_cndmask_b32_e64 v78, 0, v70, s[50:51]
	v_cmp_gt_f32_e64 s[50:51], s29, v82
	v_cndmask_b32_e64 v93, 0, v93, s[54:55]
	v_mul_f32_e32 v69, 0x45800000, v68
	v_cndmask_b32_e64 v83, v68, v69, s[52:53]
	v_mul_f32_e32 v44, v44, v83
	v_cndmask_b32_e64 v68, 0, v44, s[48:49]
	v_mul_f32_e32 v44, v45, v83
	v_mul_f32_e32 v45, 0x4b800000, v82
	v_mul_f32_e32 v64, v64, v83
	v_cndmask_b32_e64 v45, v82, v45, s[50:51]
	v_cndmask_b32_e64 v191, 0, v64, s[48:49]
	v_mul_f32_e32 v64, v65, v83
	v_mul_f32_e32 v60, v60, v83
	v_rsq_f32_e32 v45, v45
	v_cndmask_b32_e64 v75, 0, v64, s[48:49]
	v_mul_f32_e32 v64, v66, v83
	v_cndmask_b32_e64 v69, 0, v60, s[48:49]
	v_mul_f32_e32 v60, v61, v83
	v_cndmask_b32_e64 v73, 0, v64, s[48:49]
	v_mul_f32_e32 v64, v67, v83
	v_cndmask_b32_e64 v67, 0, v60, s[48:49]
	v_mul_f32_e32 v60, v62, v83
	v_cndmask_b32_e64 v66, 0, v44, s[48:49]
	v_mul_f32_e32 v44, v46, v83
	v_cndmask_b32_e64 v71, 0, v64, s[48:49]
	v_cndmask_b32_e64 v65, 0, v60, s[48:49]
	v_mul_f32_e32 v60, v63, v83
	v_cndmask_b32_e64 v64, 0, v44, s[48:49]
	v_mul_f32_e32 v44, v47, v83
	v_cndmask_b32_e64 v61, 0, v60, s[48:49]
	v_cndmask_b32_e64 v60, 0, v44, s[48:49]
	v_mul_f32_e32 v44, 0x45800000, v45
	v_mul_f32_e32 v56, v56, v83
	v_cndmask_b32_e64 v44, v45, v44, s[50:51]
	v_cndmask_b32_e64 v190, 0, v56, s[48:49]
	v_mul_f32_e32 v56, v57, v83
	v_mul_f32_e32 v45, v52, v44
	v_cndmask_b32_e64 v74, 0, v56, s[48:49]
	v_mul_f32_e32 v56, v58, v83
	v_cndmask_b32_e64 v193, 0, v45, s[46:47]
	v_mul_f32_e32 v45, v53, v44
	v_cndmask_b32_e64 v72, 0, v56, s[48:49]
	v_mul_f32_e32 v56, v59, v83
	v_cndmask_b32_e64 v59, 0, v45, s[46:47]
	v_mul_f32_e32 v45, v54, v44
	v_cndmask_b32_e64 v57, 0, v45, s[46:47]
	v_mul_f32_e32 v45, v55, v44
	v_cndmask_b32_e64 v55, 0, v45, s[46:47]
	v_mul_f32_e32 v45, v48, v44
	v_cndmask_b32_e64 v53, 0, v45, s[46:47]
	v_mul_f32_e32 v45, v49, v44
	v_mul_f32_e32 v40, v40, v44
	v_cndmask_b32_e64 v49, 0, v45, s[46:47]
	v_mul_f32_e32 v45, v50, v44
	v_cndmask_b32_e64 v192, 0, v40, s[46:47]
	v_mul_f32_e32 v40, v41, v44
	v_cndmask_b32_e64 v47, 0, v45, s[46:47]
	v_mul_f32_e32 v45, v51, v44
	v_cndmask_b32_e64 v58, 0, v40, s[46:47]
	v_mov_b32_e32 v40, v137
	v_mov_b32_e32 v41, v138
	v_mov_b32_e32 v137, v139
	v_mov_b32_e32 v50, v133
	v_mov_b32_e32 v51, v134
	v_mov_b32_e32 v133, v135
	v_pk_add_f32 v[40:41], v[40:41], v[136:137]
	v_pk_add_f32 v[50:51], v[50:51], v[132:133]
	v_mov_b32_e32 v63, v40
	v_mov_b32_e32 v62, v50
	v_mov_b32_e32 v40, v51
	v_pk_add_f32 v[40:41], v[62:63], v[40:41]
	ds_bpermute_b32 v51, v195, v41
	ds_bpermute_b32 v50, v195, v40
	v_mul_f32_e32 v42, v42, v44
	v_cndmask_b32_e64 v70, 0, v56, s[48:49]
	v_cndmask_b32_e64 v56, 0, v42, s[46:47]
	v_mul_f32_e32 v42, v43, v44
	s_waitcnt lgkmcnt(0)
	v_pk_add_f32 v[40:41], v[40:41], v[50:51]
	v_cndmask_b32_e64 v54, 0, v42, s[46:47]
	ds_bpermute_b32 v43, v196, v41
	ds_bpermute_b32 v42, v196, v40
	v_mul_f32_e32 v28, v28, v44
	v_cndmask_b32_e64 v52, 0, v28, s[46:47]
	v_mul_f32_e32 v28, v29, v44
	v_cndmask_b32_e64 v48, 0, v28, s[46:47]
	s_waitcnt lgkmcnt(0)
	v_pk_add_f32 v[28:29], v[40:41], v[42:43]
	v_mul_f32_e32 v30, v30, v44
	v_pk_fma_f32 v[28:29], v[28:29], s[90:91], v[188:189] op_sel_hi:[1,0,0]
	v_cndmask_b32_e64 v46, 0, v30, s[46:47]
	v_mul_f32_e32 v40, 0x4b800000, v29
	v_cmp_gt_f32_e64 s[48:49], s29, v29
	v_mul_f32_e32 v30, v31, v44
	v_cndmask_b32_e64 v44, 0, v30, s[46:47]
	v_cndmask_b32_e64 v29, v29, v40, s[48:49]
	v_rsq_f32_e32 v29, v29
	v_cndmask_b32_e64 v45, 0, v45, s[46:47]
	v_cmp_gt_f32_e64 s[46:47], s29, v28
	v_mul_f32_e32 v30, 0x45800000, v29
	v_cndmask_b32_e64 v40, v29, v30, s[48:49]
	v_mul_f32_e32 v12, v12, v40
	v_mul_f32_e32 v29, v36, v40
	v_cndmask_b32_e64 v36, 0, v12, s[44:45]
	v_mul_f32_e32 v12, v13, v40
	v_mul_f32_e32 v13, 0x4b800000, v28
	v_cndmask_b32_e64 v133, 0, v29, s[44:45]
	v_mul_f32_e32 v29, v37, v40
	v_cndmask_b32_e64 v13, v28, v13, s[46:47]
	v_cndmask_b32_e64 v63, 0, v29, s[44:45]
	v_mul_f32_e32 v29, v38, v40
	v_rsq_f32_e32 v13, v13
	v_cndmask_b32_e64 v43, 0, v29, s[44:45]
	v_mul_f32_e32 v29, v39, v40
	v_cndmask_b32_e64 v39, 0, v29, s[44:45]
	v_mul_f32_e32 v29, v32, v40
	v_cndmask_b32_e64 v32, 0, v12, s[44:45]
	v_mul_f32_e32 v12, v14, v40
	v_cndmask_b32_e64 v30, 0, v12, s[44:45]
	v_mul_f32_e32 v12, v15, v40
	v_cndmask_b32_e64 v28, 0, v12, s[44:45]
	v_mul_f32_e32 v12, 0x45800000, v13
	v_cndmask_b32_e64 v12, v13, v12, s[46:47]
	v_mul_f32_e32 v13, v20, v12
	v_cndmask_b32_e32 v135, 0, v13, vcc
	v_mul_f32_e32 v13, v21, v12
	v_cndmask_b32_e32 v83, 0, v13, vcc
	v_mul_f32_e32 v13, v22, v12
	v_cndmask_b32_e64 v37, 0, v29, s[44:45]
	v_mul_f32_e32 v29, v33, v40
	v_mul_f32_e32 v24, v24, v40
	v_cndmask_b32_e32 v51, 0, v13, vcc
	v_mul_f32_e32 v13, v23, v12
	v_cndmask_b32_e64 v33, 0, v29, s[44:45]
	v_mul_f32_e32 v29, v34, v40
	v_cndmask_b32_e64 v132, 0, v24, s[44:45]
	v_mul_f32_e32 v24, v25, v40
	v_cndmask_b32_e32 v41, 0, v13, vcc
	v_mul_f32_e32 v13, v16, v12
	v_mul_f32_e32 v8, v8, v12
	v_mul_f32_e32 v4, v4, v12
	v_cndmask_b32_e64 v31, 0, v29, s[44:45]
	v_mul_f32_e32 v29, v35, v40
	v_cndmask_b32_e64 v62, 0, v24, s[44:45]
	v_mul_f32_e32 v24, v26, v40
	v_cndmask_b32_e32 v35, 0, v13, vcc
	v_mul_f32_e32 v13, v17, v12
	v_cndmask_b32_e32 v134, 0, v8, vcc
	v_mul_f32_e32 v8, v9, v12
	v_cndmask_b32_e32 v34, 0, v4, vcc
	v_mul_f32_e32 v4, v5, v12
; __device__ __forceinline__ float sigmoidf_(float x) { return __builtin_amdgcn_rcpf(1.0f + __expf(-x)); }
; template <int N> __device__ __forceinline__ float dpp_ror(float v) { return __builtin_bit_cast(float, __builtin_amdgcn_update_dpp(0, __builtin_bit_cast(int, v), 0x120 + N, 0xf, 0xf, false)); }
;     __device__ __forceinline__ void operator()(Acc& acc, const Unit& u, int wr, int wc, int fr, int fq) const {
;     ...
;         for (int n = 0; n < 2; ++n) {
; #pragma unroll
;             for (int i = 0; i < 4; ++i) {
;                 const int cg_ = ch0 + 4 * n + i, cv_ = DFF + cg_;
;                 const float g0 = cw[cg_], g1 = cw[NUP + cg_], g2 = cw[2 * NUP + cg_], gb = cb[cg_];
;                 const float v0 = cw[cv_], v1 = cw[NUP + cv_], v2 = cw[2 * NUP + cv_], vb = cb[cv_];
;                 float pg1 = 0.f, pg2 = 0.f, pv1 = 0.f, pv2 = 0.f;
; #pragma unroll
;                 for (int q = 0; q < 8; ++q) {
;                     float cgv = acc[q >> 2][0][q & 3][n][i], cvv = acc[q >> 2][1][q & 3][n][i];
;                     asm volatile("" : "+v"(cgv), "+v"(cvv) : "v"(chain));
;                     const float tg1 = dpp_ror<1>(cgv), tg2 = dpp_ror<2>(cgv), tv1 = dpp_ror<1>(cvv), tv2 = dpp_ror<2>(cvv);
;                     const float sg1 = fr >= 1 ? tg1 : pg1, sg2 = fr >= 2 ? tg2 : pg2, sv1 = fr >= 1 ? tv1 : pv1, sv2 = fr >= 2 ? tv2 : pv2;
;                     const float gg = gb + g0 * sg2 + g1 * sg1 + g2 * cgv;
;                     const float vv = vb + v0 * sv2 + v1 * sv1 + v2 * cvv;
;                     chain = gg * sigmoidf_(gg) * vv; acc[q >> 2][0][q & 3][n][i] = chain;
;                     pg1 = tg1; pg2 = tg2; pv1 = tv1; pv2 = tv2;
;                 }
	v_cndmask_b32_e64 v42, 0, v24, s[44:45]
	v_mul_f32_e32 v24, v27, v40
	v_cndmask_b32_e32 v27, 0, v13, vcc
	v_mul_f32_e32 v13, v18, v12
	v_cndmask_b32_e32 v82, 0, v8, vcc
	v_mul_f32_e32 v8, v10, v12
	v_cndmask_b32_e32 v26, 0, v4, vcc
	v_mul_f32_e32 v4, v6, v12
	v_cndmask_b32_e32 v15, 0, v13, vcc
	v_mul_f32_e32 v13, v19, v12
	v_cndmask_b32_e32 v50, 0, v8, vcc
	v_mul_f32_e32 v8, v11, v12
	v_cndmask_b32_e32 v14, 0, v4, vcc
	v_mul_f32_e32 v4, v7, v12
	v_cndmask_b32_e64 v29, 0, v29, s[44:45]
	v_cndmask_b32_e64 v38, 0, v24, s[44:45]
	v_cndmask_b32_e32 v13, 0, v13, vcc
	v_cndmask_b32_e32 v40, 0, v8, vcc
	v_cndmask_b32_e32 v12, 0, v4, vcc
	v_lshl_or_b32 v4, s34, 7, v2
	v_ashrrev_i32_e32 v5, 31, v4
	v_lshlrev_b64 v[16:17], 2, v[4:5]
	v_lshl_add_u64 v[6:7], s[36:37], 0, v[16:17]
	s_movk_i32 s21, 0x5000
	v_add_co_u32_e32 v8, vcc, s21, v6
	s_mov_b32 s21, 0xb000
	s_nop 0
	v_addc_co_u32_e32 v9, vcc, 0, v7, vcc
	v_add_co_u32_e32 v10, vcc, s21, v6
	v_lshl_add_u64 v[16:17], s[60:61], 0, v[16:17]
	s_nop 0
	v_addc_co_u32_e32 v11, vcc, 0, v7, vcc
	global_load_dword v139, v[6:7], off
	global_load_dword v137, v[8:9], off offset:2048
	global_load_dword v136, v[10:11], off
	global_load_dword v189, v[16:17], off
	v_add_co_u32_e32 v18, vcc, s97, v6
	s_mov_b32 s21, 0xd000
	s_nop 0
	v_addc_co_u32_e32 v19, vcc, 0, v7, vcc
	v_add_co_u32_e32 v22, vcc, s80, v6
	global_load_dword v138, v[18:19], off offset:3072
	s_nop 0
	v_addc_co_u32_e32 v23, vcc, 0, v7, vcc
	v_add_co_u32_e32 v20, vcc, s97, v16
	s_nop 0
	s_nop 0
	v_addc_co_u32_e32 v21, vcc, 0, v17, vcc
	v_add_co_u32_e32 v24, vcc, s21, v6
	global_load_dword v188, v[20:21], off offset:3072
	s_nop 0
	v_addc_co_u32_e32 v25, vcc, 0, v7, vcc
	global_load_dword v229, v[22:23], off offset:1024
	global_load_dword v228, v[24:25], off offset:3072
	s_nop 0
	s_nop 0
	s_nop 0
	v_mov_b32_dpp v111, v182 row_ror:1 row_mask:0xf bank_mask:0xf
	v_mov_b32_dpp v121, v182 row_ror:2 row_mask:0xf bank_mask:0xf
	v_cndmask_b32_e64 v183, v111, 0, s[38:39]
	v_cndmask_b32_e64 v155, 0, v121, s[40:41]
	v_mov_b32_dpp v123, v184 row_ror:1 row_mask:0xf bank_mask:0xf
	v_mov_b32_dpp v125, v184 row_ror:2 row_mask:0xf bank_mask:0xf
	v_cndmask_b32_e64 v185, v123, 0, s[38:39]
	v_cndmask_b32_e64 v159, 0, v125, s[40:41]
	s_nop 0
	s_nop 0
	s_nop 0
	s_nop 0
	s_waitcnt vmcnt(5)
	v_pk_mul_f32 v[182:183], v[136:137], v[182:183]
	s_waitcnt vmcnt(4)
	v_fma_f32 v155, v139, v155, v189
	v_add_f32_e32 v155, v183, v155
	v_add_f32_e32 v155, v182, v155
	v_mul_f32_e32 v161, 0xbfb8aa3b, v155
	v_exp_f32_e32 v161, v161
	v_mov_b32_e32 v183, v136
	v_add_f32_e32 v136, 1.0, v161
	v_rcp_f32_e32 v161, v136
	s_waitcnt vmcnt(2)
	v_fma_f32 v159, v138, v159, v188
	v_mul_f32_e32 v155, v155, v161
	s_waitcnt vmcnt(1)
	v_mov_b32_e32 v136, v229
	s_waitcnt vmcnt(0)
	v_pk_mul_f32 v[184:185], v[228:229], v[184:185]
	v_mov_b32_e32 v182, v228
	v_add_f32_e32 v159, v185, v159
	v_add_f32_e32 v159, v184, v159
	v_mul_f32_e32 v184, v159, v155
	s_nop 0
	s_nop 0
	v_mov_b32_dpp v129, v187 row_ror:2 row_mask:0xf bank_mask:0xf
	v_mov_b32_dpp v153, v186 row_ror:2 row_mask:0xf bank_mask:0xf
	v_mov_b32_dpp v127, v187 row_ror:1 row_mask:0xf bank_mask:0xf
	v_mov_b32_dpp v131, v186 row_ror:1 row_mask:0xf bank_mask:0xf
	v_cndmask_b32_e64 v231, v121, v129, s[40:41]
	v_cndmask_b32_e64 v230, v125, v153, s[40:41]
	v_cndmask_b32_e64 v229, v127, v111, s[38:39]
	v_cndmask_b32_e64 v228, v131, v123, s[38:39]
	v_pk_fma_f32 v[230:231], v[138:139], v[230:231], v[188:189]
	s_nop 0
	v_pk_fma_f32 v[228:229], v[136:137], v[228:229], v[230:231]
	s_nop 0
	v_pk_fma_f32 v[186:187], v[182:183], v[186:187], v[228:229]
	s_nop 0
	v_mul_f32_e32 v111, 0xbfb8aa3b, v187
	v_exp_f32_e32 v111, v111
	s_nop 0
	v_add_f32_e32 v111, 1.0, v111
	v_rcp_f32_e32 v111, v111
	s_nop 0
	v_mul_f32_e32 v111, v187, v111
	v_mul_f32_e32 v185, v186, v111
	s_nop 1
	v_mov_b32_dpp v123, v115 row_ror:2 row_mask:0xf bank_mask:0xf
	v_mov_b32_dpp v155, v114 row_ror:2 row_mask:0xf bank_mask:0xf
	v_mov_b32_dpp v121, v115 row_ror:1 row_mask:0xf bank_mask:0xf
	v_mov_b32_dpp v125, v114 row_ror:1 row_mask:0xf bank_mask:0xf
	v_cndmask_b32_e64 v229, v129, v123, s[40:41]
	v_cndmask_b32_e64 v228, v153, v155, s[40:41]
	v_cndmask_b32_e64 v187, v121, v127, s[38:39]
	v_cndmask_b32_e64 v186, v125, v131, s[38:39]
	v_pk_fma_f32 v[228:229], v[138:139], v[228:229], v[188:189]
	s_nop 0
	v_pk_fma_f32 v[186:187], v[136:137], v[186:187], v[228:229]
	s_nop 0
	v_pk_fma_f32 v[114:115], v[182:183], v[114:115], v[186:187]
	s_nop 0
	v_mul_f32_e32 v111, 0xbfb8aa3b, v115
	v_exp_f32_e32 v111, v111
	s_nop 0
	v_add_f32_e32 v111, 1.0, v111
	v_rcp_f32_e32 v111, v111
	s_nop 0
	v_mul_f32_e32 v111, v115, v111
	v_mul_f32_e32 v186, v114, v111
	s_nop 1
	v_mov_b32_dpp v129, v99 row_ror:2 row_mask:0xf bank_mask:0xf
	v_mov_b32_dpp v153, v98 row_ror:2 row_mask:0xf bank_mask:0xf
	v_mov_b32_dpp v127, v99 row_ror:1 row_mask:0xf bank_mask:0xf
	v_mov_b32_dpp v131, v98 row_ror:1 row_mask:0xf bank_mask:0xf
	v_cndmask_b32_e64 v229, v123, v129, s[40:41]
	v_cndmask_b32_e64 v228, v155, v153, s[40:41]
	v_cndmask_b32_e64 v115, v127, v121, s[38:39]
	v_cndmask_b32_e64 v114, v131, v125, s[38:39]
	v_pk_fma_f32 v[228:229], v[138:139], v[228:229], v[188:189]
	s_nop 0
	v_pk_fma_f32 v[114:115], v[136:137], v[114:115], v[228:229]
	s_nop 0
	v_pk_fma_f32 v[98:99], v[182:183], v[98:99], v[114:115]
	s_nop 0
	v_mul_f32_e32 v111, 0xbfb8aa3b, v99
	v_exp_f32_e32 v111, v111
	s_nop 0
	v_add_f32_e32 v111, 1.0, v111
	v_rcp_f32_e32 v111, v111
	s_nop 0
	v_mul_f32_e32 v99, v99, v111
	v_mul_f32_e32 v187, v98, v99
	s_nop 1
	v_mov_b32_dpp v123, v191 row_ror:2 row_mask:0xf bank_mask:0xf
	v_mov_b32_dpp v155, v190 row_ror:2 row_mask:0xf bank_mask:0xf
; __device__ __forceinline__ float sigmoidf_(float x) { return __builtin_amdgcn_rcpf(1.0f + __expf(-x)); }
; template <int N> __device__ __forceinline__ float dpp_ror(float v) { return __builtin_bit_cast(float, __builtin_amdgcn_update_dpp(0, __builtin_bit_cast(int, v), 0x120 + N, 0xf, 0xf, false)); }
;     __device__ __forceinline__ void operator()(Acc& acc, const Unit& u, int wr, int wc, int fr, int fq) const {
;     ...
;             for (int i = 0; i < 4; ++i) {
;                 const int cg_ = ch0 + 4 * n + i, cv_ = DFF + cg_;
;                 const float g0 = cw[cg_], g1 = cw[NUP + cg_], g2 = cw[2 * NUP + cg_], gb = cb[cg_];
;                 const float v0 = cw[cv_], v1 = cw[NUP + cv_], v2 = cw[2 * NUP + cv_], vb = cb[cv_];
;                 float pg1 = 0.f, pg2 = 0.f, pv1 = 0.f, pv2 = 0.f;
; #pragma unroll
;                 for (int q = 0; q < 8; ++q) {
;                     float cgv = acc[q >> 2][0][q & 3][n][i], cvv = acc[q >> 2][1][q & 3][n][i];
;                     asm volatile("" : "+v"(cgv), "+v"(cvv) : "v"(chain));
;                     const float tg1 = dpp_ror<1>(cgv), tg2 = dpp_ror<2>(cgv), tv1 = dpp_ror<1>(cvv), tv2 = dpp_ror<2>(cvv);
;                     const float sg1 = fr >= 1 ? tg1 : pg1, sg2 = fr >= 2 ? tg2 : pg2, sv1 = fr >= 1 ? tv1 : pv1, sv2 = fr >= 2 ? tv2 : pv2;
;                     const float gg = gb + g0 * sg2 + g1 * sg1 + g2 * cgv;
;                     const float vv = vb + v0 * sv2 + v1 * sv1 + v2 * cvv;
;                     chain = gg * sigmoidf_(gg) * vv; acc[q >> 2][0][q & 3][n][i] = chain;
;                     pg1 = tg1; pg2 = tg2; pv1 = tv1; pv2 = tv2;
;                 }
	v_mov_b32_dpp v121, v191 row_ror:1 row_mask:0xf bank_mask:0xf
	v_mov_b32_dpp v125, v190 row_ror:1 row_mask:0xf bank_mask:0xf
	v_cndmask_b32_e64 v115, v129, v123, s[40:41]
	v_cndmask_b32_e64 v114, v153, v155, s[40:41]
	v_cndmask_b32_e64 v99, v121, v127, s[38:39]
	v_cndmask_b32_e64 v98, v125, v131, s[38:39]
	v_pk_fma_f32 v[114:115], v[138:139], v[114:115], v[188:189]
	s_nop 0
	v_pk_fma_f32 v[98:99], v[136:137], v[98:99], v[114:115]
	s_nop 0
	v_pk_fma_f32 v[98:99], v[182:183], v[190:191], v[98:99]
	s_nop 0
	v_mul_f32_e32 v111, 0xbfb8aa3b, v99
	v_exp_f32_e32 v111, v111
	s_nop 0
	v_add_f32_e32 v111, 1.0, v111
	v_rcp_f32_e32 v111, v111
	s_nop 0
	v_mul_f32_e32 v99, v99, v111
	v_mul_f32_e32 v190, v98, v99
	s_nop 1
	v_mov_b32_dpp v129, v193 row_ror:2 row_mask:0xf bank_mask:0xf
	v_mov_b32_dpp v153, v192 row_ror:2 row_mask:0xf bank_mask:0xf
	v_mov_b32_dpp v127, v193 row_ror:1 row_mask:0xf bank_mask:0xf
	v_mov_b32_dpp v131, v192 row_ror:1 row_mask:0xf bank_mask:0xf
	v_cndmask_b32_e64 v115, v123, v129, s[40:41]
	v_cndmask_b32_e64 v114, v155, v153, s[40:41]
	v_cndmask_b32_e64 v99, v127, v121, s[38:39]
	v_cndmask_b32_e64 v98, v131, v125, s[38:39]
	v_pk_fma_f32 v[114:115], v[138:139], v[114:115], v[188:189]
	s_nop 0
	v_pk_fma_f32 v[98:99], v[136:137], v[98:99], v[114:115]
	s_nop 0
	v_pk_fma_f32 v[98:99], v[182:183], v[192:193], v[98:99]
	s_nop 0
	v_mul_f32_e32 v111, 0xbfb8aa3b, v99
	v_exp_f32_e32 v111, v111
	s_nop 0
	v_add_f32_e32 v111, 1.0, v111
	v_rcp_f32_e32 v111, v111
	s_nop 0
	v_mul_f32_e32 v99, v99, v111
	v_mul_f32_e32 v191, v98, v99
	s_nop 1
	v_mov_b32_dpp v123, v133 row_ror:2 row_mask:0xf bank_mask:0xf
	v_mov_b32_dpp v155, v132 row_ror:2 row_mask:0xf bank_mask:0xf
	v_mov_b32_dpp v121, v133 row_ror:1 row_mask:0xf bank_mask:0xf
	v_mov_b32_dpp v125, v132 row_ror:1 row_mask:0xf bank_mask:0xf
	v_cndmask_b32_e64 v115, v129, v123, s[40:41]
	v_cndmask_b32_e64 v114, v153, v155, s[40:41]
	v_cndmask_b32_e64 v99, v121, v127, s[38:39]
	v_cndmask_b32_e64 v98, v125, v131, s[38:39]
	v_pk_fma_f32 v[114:115], v[138:139], v[114:115], v[188:189]
	s_nop 0
	v_pk_fma_f32 v[98:99], v[136:137], v[98:99], v[114:115]
	s_nop 0
	v_pk_fma_f32 v[98:99], v[182:183], v[132:133], v[98:99]
	s_nop 0
	v_mul_f32_e32 v111, 0xbfb8aa3b, v99
	v_exp_f32_e32 v111, v111
	s_nop 0
	v_add_f32_e32 v111, 1.0, v111
	v_rcp_f32_e32 v111, v111
	s_nop 0
	v_mul_f32_e32 v99, v99, v111
	v_mul_f32_e32 v192, v98, v99
	s_nop 1
	v_mov_b32_dpp v114, v135 row_ror:1 row_mask:0xf bank_mask:0xf
	v_mov_b32_dpp v115, v135 row_ror:2 row_mask:0xf bank_mask:0xf
	v_mov_b32_dpp v129, v134 row_ror:2 row_mask:0xf bank_mask:0xf
	v_mov_b32_dpp v127, v134 row_ror:1 row_mask:0xf bank_mask:0xf
	v_cndmask_b32_e64 v99, v114, v121, s[38:39]
	v_cndmask_b32_e64 v115, v123, v115, s[40:41]
	v_cndmask_b32_e64 v114, v155, v129, s[40:41]
	v_cndmask_b32_e64 v98, v127, v125, s[38:39]
	v_pk_fma_f32 v[114:115], v[138:139], v[114:115], v[188:189]
	s_nop 0
	v_pk_fma_f32 v[98:99], v[136:137], v[98:99], v[114:115]
	s_nop 0
	v_pk_fma_f32 v[98:99], v[182:183], v[134:135], v[98:99]
	s_nop 0
	v_mul_f32_e32 v111, 0xbfb8aa3b, v99
	v_exp_f32_e32 v111, v111
	s_nop 0
	v_add_f32_e32 v111, 1.0, v111
	v_rcp_f32_e32 v111, v111
	s_nop 0
	v_mul_f32_e32 v99, v99, v111
	v_mul_f32_e32 v136, v98, v99
	global_load_dword v115, v[6:7], off offset:4
	global_load_dword v99, v[8:9], off offset:2052
	global_load_dword v98, v[10:11], off offset:4
	global_load_dword v133, v[16:17], off offset:4
	global_load_dword v132, v[20:21], off offset:3076
	global_load_dword v114, v[18:19], off offset:3076
	global_load_dword v139, v[22:23], off offset:1028
	global_load_dword v138, v[24:25], off offset:3076
	s_nop 0
	s_nop 0
	s_nop 0
	s_nop 0
	v_mov_b32_dpp v111, v176 row_ror:1 row_mask:0xf bank_mask:0xf
	v_mov_b32_dpp v121, v176 row_ror:2 row_mask:0xf bank_mask:0xf
	v_cndmask_b32_e64 v177, v111, 0, s[38:39]
	v_cndmask_b32_e64 v134, 0, v121, s[40:41]
	v_mov_b32_dpp v123, v178 row_ror:1 row_mask:0xf bank_mask:0xf
	v_cndmask_b32_e64 v179, v123, 0, s[38:39]
	v_mov_b32_dpp v125, v178 row_ror:2 row_mask:0xf bank_mask:0xf
	v_cndmask_b32_e64 v137, 0, v125, s[40:41]
	s_nop 0
	s_nop 0
	s_nop 0
	s_nop 0
	s_waitcnt vmcnt(4)
	v_fma_f32 v155, v115, v134, v133
	v_pk_mul_f32 v[134:135], v[98:99], v[176:177]
	s_waitcnt vmcnt(2)
	v_fma_f32 v137, v114, v137, v132
	v_add_f32_e32 v135, v135, v155
	v_add_f32_e32 v155, v134, v135
	v_mul_f32_e32 v134, 0xbfb8aa3b, v155
	v_exp_f32_e32 v159, v134
	v_mov_b32_e32 v135, v98
	s_waitcnt vmcnt(0)
; __device__ __forceinline__ float sigmoidf_(float x) { return __builtin_amdgcn_rcpf(1.0f + __expf(-x)); }
; template <int N> __device__ __forceinline__ float dpp_ror(float v) { return __builtin_bit_cast(float, __builtin_amdgcn_update_dpp(0, __builtin_bit_cast(int, v), 0x120 + N, 0xf, 0xf, false)); }
;     __device__ __forceinline__ void operator()(Acc& acc, const Unit& u, int wr, int wc, int fr, int fq) const {
;     ...
;                 for (int q = 0; q < 8; ++q) {
;                     float cgv = acc[q >> 2][0][q & 3][n][i], cvv = acc[q >> 2][1][q & 3][n][i];
;                     asm volatile("" : "+v"(cgv), "+v"(cvv) : "v"(chain));
;                     const float tg1 = dpp_ror<1>(cgv), tg2 = dpp_ror<2>(cgv), tv1 = dpp_ror<1>(cvv), tv2 = dpp_ror<2>(cvv);
;                     const float sg1 = fr >= 1 ? tg1 : pg1, sg2 = fr >= 2 ? tg2 : pg2, sv1 = fr >= 1 ? tv1 : pv1, sv2 = fr >= 2 ? tv2 : pv2;
;                     const float gg = gb + g0 * sg2 + g1 * sg1 + g2 * cgv;
;                     const float vv = vb + v0 * sv2 + v1 * sv1 + v2 * cvv;
;                     chain = gg * sigmoidf_(gg) * vv; acc[q >> 2][0][q & 3][n][i] = chain;
;                     pg1 = tg1; pg2 = tg2; pv1 = tv1; pv2 = tv2;
;                 }
	v_pk_mul_f32 v[176:177], v[138:139], v[178:179]
	v_mov_b32_e32 v134, v138
	v_add_f32_e32 v98, 1.0, v159
	v_rcp_f32_e32 v138, v98
	v_add_f32_e32 v137, v177, v137
	v_add_f32_e32 v137, v176, v137
	v_mov_b32_e32 v98, v139
	v_mul_f32_e32 v138, v155, v138
	v_mul_f32_e32 v137, v137, v138
	s_nop 0
	s_nop 0
	v_mov_b32_dpp v129, v181 row_ror:2 row_mask:0xf bank_mask:0xf
	v_mov_b32_dpp v153, v180 row_ror:2 row_mask:0xf bank_mask:0xf
	v_mov_b32_dpp v127, v181 row_ror:1 row_mask:0xf bank_mask:0xf
	v_mov_b32_dpp v131, v180 row_ror:1 row_mask:0xf bank_mask:0xf
	v_cndmask_b32_e64 v177, v121, v129, s[40:41]
	v_cndmask_b32_e64 v176, v125, v153, s[40:41]
	v_cndmask_b32_e64 v139, v127, v111, s[38:39]
	v_cndmask_b32_e64 v138, v131, v123, s[38:39]
	v_pk_fma_f32 v[176:177], v[114:115], v[176:177], v[132:133]
	s_nop 0
	v_pk_fma_f32 v[138:139], v[98:99], v[138:139], v[176:177]
	s_nop 0
	v_pk_fma_f32 v[138:139], v[134:135], v[180:181], v[138:139]
	s_nop 0
	v_mul_f32_e32 v111, 0xbfb8aa3b, v139
	v_exp_f32_e32 v111, v111
	s_nop 0
	v_add_f32_e32 v111, 1.0, v111
	v_rcp_f32_e32 v111, v111
	s_nop 0
	v_mul_f32_e32 v111, v139, v111
	v_mul_f32_e32 v138, v138, v111
	s_nop 0
	s_nop 0
	v_mov_b32_dpp v123, v107 row_ror:2 row_mask:0xf bank_mask:0xf
	v_mov_b32_dpp v155, v106 row_ror:2 row_mask:0xf bank_mask:0xf
	v_mov_b32_dpp v121, v107 row_ror:1 row_mask:0xf bank_mask:0xf
	v_mov_b32_dpp v125, v106 row_ror:1 row_mask:0xf bank_mask:0xf
	v_cndmask_b32_e64 v179, v129, v123, s[40:41]
	v_cndmask_b32_e64 v178, v153, v155, s[40:41]
	v_cndmask_b32_e64 v177, v121, v127, s[38:39]
	v_cndmask_b32_e64 v176, v125, v131, s[38:39]
	v_pk_fma_f32 v[178:179], v[114:115], v[178:179], v[132:133]
	s_nop 0
	v_pk_fma_f32 v[176:177], v[98:99], v[176:177], v[178:179]
	s_nop 0
	v_pk_fma_f32 v[106:107], v[134:135], v[106:107], v[176:177]
	s_nop 0
	v_mul_f32_e32 v111, 0xbfb8aa3b, v107
	v_exp_f32_e32 v111, v111
	s_nop 0
	v_add_f32_e32 v111, 1.0, v111
	v_rcp_f32_e32 v111, v111
	s_nop 0
	v_mul_f32_e32 v107, v107, v111
	v_mul_f32_e32 v106, v106, v107
	s_nop 0
	s_nop 0
	v_mov_b32_dpp v129, v91 row_ror:2 row_mask:0xf bank_mask:0xf
	v_mov_b32_dpp v139, v90 row_ror:2 row_mask:0xf bank_mask:0xf
	v_mov_b32_dpp v127, v91 row_ror:1 row_mask:0xf bank_mask:0xf
	v_mov_b32_dpp v131, v90 row_ror:1 row_mask:0xf bank_mask:0xf
	v_cndmask_b32_e64 v179, v123, v129, s[40:41]
	v_cndmask_b32_e64 v178, v155, v139, s[40:41]
	v_cndmask_b32_e64 v177, v127, v121, s[38:39]
	v_cndmask_b32_e64 v176, v131, v125, s[38:39]
	v_pk_fma_f32 v[178:179], v[114:115], v[178:179], v[132:133]
	s_nop 0
	v_pk_fma_f32 v[176:177], v[98:99], v[176:177], v[178:179]
	s_nop 0
	v_pk_fma_f32 v[90:91], v[134:135], v[90:91], v[176:177]
	s_nop 0
	v_mul_f32_e32 v107, 0xbfb8aa3b, v91
	v_exp_f32_e32 v107, v107
	s_nop 0
	v_add_f32_e32 v107, 1.0, v107
	v_rcp_f32_e32 v107, v107
	s_nop 0
	v_mul_f32_e32 v91, v91, v107
	v_mul_f32_e32 v90, v90, v91
	s_nop 1
	v_mov_b32_dpp v121, v75 row_ror:2 row_mask:0xf bank_mask:0xf
	v_mov_b32_dpp v125, v74 row_ror:2 row_mask:0xf bank_mask:0xf
	v_mov_b32_dpp v111, v75 row_ror:1 row_mask:0xf bank_mask:0xf
	v_mov_b32_dpp v123, v74 row_ror:1 row_mask:0xf bank_mask:0xf
	v_cndmask_b32_e64 v179, v129, v121, s[40:41]
	v_cndmask_b32_e64 v178, v139, v125, s[40:41]
	v_cndmask_b32_e64 v177, v111, v127, s[38:39]
	v_cndmask_b32_e64 v176, v123, v131, s[38:39]
	v_pk_fma_f32 v[178:179], v[114:115], v[178:179], v[132:133]
	s_nop 0
	v_pk_fma_f32 v[176:177], v[98:99], v[176:177], v[178:179]
	s_nop 0
	v_pk_fma_f32 v[74:75], v[134:135], v[74:75], v[176:177]
	s_nop 0
	v_mul_f32_e32 v91, 0xbfb8aa3b, v75
	v_exp_f32_e32 v91, v91
	s_nop 0
	v_add_f32_e32 v91, 1.0, v91
	v_rcp_f32_e32 v91, v91
	s_nop 0
	v_mul_f32_e32 v75, v75, v91
	v_mul_f32_e32 v91, v74, v75
	s_nop 1
	v_mov_b32_dpp v129, v59 row_ror:2 row_mask:0xf bank_mask:0xf
	v_mov_b32_dpp v139, v58 row_ror:2 row_mask:0xf bank_mask:0xf
	v_mov_b32_dpp v127, v59 row_ror:1 row_mask:0xf bank_mask:0xf
	v_mov_b32_dpp v131, v58 row_ror:1 row_mask:0xf bank_mask:0xf
	v_cndmask_b32_e64 v177, v121, v129, s[40:41]
	v_cndmask_b32_e64 v176, v125, v139, s[40:41]
	v_cndmask_b32_e64 v75, v127, v111, s[38:39]
	v_cndmask_b32_e64 v74, v131, v123, s[38:39]
	v_pk_fma_f32 v[176:177], v[114:115], v[176:177], v[132:133]
	s_nop 0
	v_pk_fma_f32 v[74:75], v[98:99], v[74:75], v[176:177]
	s_nop 0
	v_pk_fma_f32 v[58:59], v[134:135], v[58:59], v[74:75]
	s_nop 0
	v_mul_f32_e32 v74, 0xbfb8aa3b, v59
	v_exp_f32_e32 v74, v74
	s_nop 0
	v_add_f32_e32 v74, 1.0, v74
	v_rcp_f32_e32 v74, v74
	s_nop 0
	v_mul_f32_e32 v59, v59, v74
	v_mul_f32_e32 v107, v58, v59
	s_nop 1
	v_mov_b32_dpp v121, v63 row_ror:2 row_mask:0xf bank_mask:0xf
	v_mov_b32_dpp v125, v62 row_ror:2 row_mask:0xf bank_mask:0xf
	v_mov_b32_dpp v111, v63 row_ror:1 row_mask:0xf bank_mask:0xf
	v_mov_b32_dpp v123, v62 row_ror:1 row_mask:0xf bank_mask:0xf
	v_cndmask_b32_e64 v75, v129, v121, s[40:41]
	v_cndmask_b32_e64 v74, v139, v125, s[40:41]
	v_cndmask_b32_e64 v59, v111, v127, s[38:39]
	v_cndmask_b32_e64 v58, v123, v131, s[38:39]
	v_pk_fma_f32 v[74:75], v[114:115], v[74:75], v[132:133]
	s_nop 0
	v_pk_fma_f32 v[58:59], v[98:99], v[58:59], v[74:75]
	s_nop 0
	v_pk_fma_f32 v[58:59], v[134:135], v[62:63], v[58:59]
	s_nop 0
	v_mul_f32_e32 v62, 0xbfb8aa3b, v59
	v_exp_f32_e32 v62, v62
	s_nop 0
	v_add_f32_e32 v62, 1.0, v62
	v_rcp_f32_e32 v62, v62
	s_nop 0
	v_mul_f32_e32 v59, v59, v62
	v_mul_f32_e32 v139, v58, v59
	s_nop 1
	v_mov_b32_dpp v63, v83 row_ror:1 row_mask:0xf bank_mask:0xf
	v_mov_b32_dpp v74, v83 row_ror:2 row_mask:0xf bank_mask:0xf
	v_mov_b32_dpp v127, v82 row_ror:2 row_mask:0xf bank_mask:0xf
	v_mov_b32_dpp v75, v82 row_ror:1 row_mask:0xf bank_mask:0xf
	v_cndmask_b32_e64 v59, v63, v111, s[38:39]
; __device__ __forceinline__ float sigmoidf_(float x) { return __builtin_amdgcn_rcpf(1.0f + __expf(-x)); }
; template <int N> __device__ __forceinline__ float dpp_ror(float v) { return __builtin_bit_cast(float, __builtin_amdgcn_update_dpp(0, __builtin_bit_cast(int, v), 0x120 + N, 0xf, 0xf, false)); }
;     __device__ __forceinline__ void operator()(Acc& acc, const Unit& u, int wr, int wc, int fr, int fq) const {
;     ...
;             for (int i = 0; i < 4; ++i) {
;                 const int cg_ = ch0 + 4 * n + i, cv_ = DFF + cg_;
;                 const float g0 = cw[cg_], g1 = cw[NUP + cg_], g2 = cw[2 * NUP + cg_], gb = cb[cg_];
;                 const float v0 = cw[cv_], v1 = cw[NUP + cv_], v2 = cw[2 * NUP + cv_], vb = cb[cv_];
;                 float pg1 = 0.f, pg2 = 0.f, pv1 = 0.f, pv2 = 0.f;
; #pragma unroll
;                 for (int q = 0; q < 8; ++q) {
;                     float cgv = acc[q >> 2][0][q & 3][n][i], cvv = acc[q >> 2][1][q & 3][n][i];
;                     asm volatile("" : "+v"(cgv), "+v"(cvv) : "v"(chain));
;                     const float tg1 = dpp_ror<1>(cgv), tg2 = dpp_ror<2>(cgv), tv1 = dpp_ror<1>(cvv), tv2 = dpp_ror<2>(cvv);
;                     const float sg1 = fr >= 1 ? tg1 : pg1, sg2 = fr >= 2 ? tg2 : pg2, sv1 = fr >= 1 ? tv1 : pv1, sv2 = fr >= 2 ? tv2 : pv2;
;                     const float gg = gb + g0 * sg2 + g1 * sg1 + g2 * cgv;
;                     const float vv = vb + v0 * sv2 + v1 * sv1 + v2 * cvv;
;                     chain = gg * sigmoidf_(gg) * vv; acc[q >> 2][0][q & 3][n][i] = chain;
;                     pg1 = tg1; pg2 = tg2; pv1 = tv1; pv2 = tv2;
;                 }
	v_cndmask_b32_e64 v63, v121, v74, s[40:41]
	v_cndmask_b32_e64 v62, v125, v127, s[40:41]
	v_cndmask_b32_e64 v58, v75, v123, s[38:39]
	v_pk_fma_f32 v[62:63], v[114:115], v[62:63], v[132:133]
	s_nop 0
	v_pk_fma_f32 v[58:59], v[98:99], v[58:59], v[62:63]
	s_nop 0
	v_pk_fma_f32 v[58:59], v[134:135], v[82:83], v[58:59]
	s_nop 0
	v_mul_f32_e32 v62, 0xbfb8aa3b, v59
	v_exp_f32_e32 v62, v62
	s_nop 0
	v_add_f32_e32 v62, 1.0, v62
	v_rcp_f32_e32 v62, v62
	s_nop 0
	v_mul_f32_e32 v59, v59, v62
	v_mul_f32_e32 v98, v58, v59
	global_load_dword v63, v[6:7], off offset:8
	global_load_dword v59, v[8:9], off offset:2056
	global_load_dword v58, v[10:11], off offset:8
	global_load_dword v75, v[16:17], off offset:8
	global_load_dword v74, v[20:21], off offset:3080
	global_load_dword v62, v[18:19], off offset:3080
	global_load_dword v115, v[22:23], off offset:1032
	global_load_dword v114, v[24:25], off offset:3080
	s_nop 0
	s_nop 0
	s_nop 0
	s_nop 0
	v_mov_b32_dpp v111, v160 row_ror:1 row_mask:0xf bank_mask:0xf
	v_mov_b32_dpp v121, v160 row_ror:2 row_mask:0xf bank_mask:0xf
	v_cndmask_b32_e64 v161, v111, 0, s[38:39]
	v_cndmask_b32_e64 v82, 0, v121, s[40:41]
	v_mov_b32_dpp v123, v162 row_ror:1 row_mask:0xf bank_mask:0xf
	v_cndmask_b32_e64 v163, v123, 0, s[38:39]
	v_mov_b32_dpp v125, v162 row_ror:2 row_mask:0xf bank_mask:0xf
	v_cndmask_b32_e64 v99, 0, v125, s[40:41]
	s_nop 0
	s_nop 0
	s_nop 0
	s_nop 0
	s_waitcnt vmcnt(4)
	v_fma_f32 v132, v63, v82, v75
	v_pk_mul_f32 v[82:83], v[58:59], v[160:161]
	s_waitcnt vmcnt(2)
	v_fma_f32 v99, v62, v99, v74
	v_add_f32_e32 v83, v83, v132
	v_add_f32_e32 v135, v82, v83
	v_mul_f32_e32 v82, 0xbfb8aa3b, v135
	v_exp_f32_e32 v153, v82
	v_mov_b32_e32 v83, v58
	s_waitcnt vmcnt(0)
	v_pk_mul_f32 v[132:133], v[114:115], v[162:163]
	v_mov_b32_e32 v82, v114
	v_add_f32_e32 v58, 1.0, v153
	v_rcp_f32_e32 v114, v58
	v_add_f32_e32 v99, v133, v99
	v_add_f32_e32 v99, v132, v99
	v_mov_b32_e32 v58, v115
	v_mul_f32_e32 v114, v135, v114
	v_mul_f32_e32 v99, v99, v114
	s_nop 0
	s_nop 0
	v_mov_b32_dpp v129, v175 row_ror:2 row_mask:0xf bank_mask:0xf
	v_mov_b32_dpp v134, v174 row_ror:2 row_mask:0xf bank_mask:0xf
	v_mov_b32_dpp v127, v175 row_ror:1 row_mask:0xf bank_mask:0xf
	v_mov_b32_dpp v131, v174 row_ror:1 row_mask:0xf bank_mask:0xf
	v_cndmask_b32_e64 v133, v121, v129, s[40:41]
	v_cndmask_b32_e64 v132, v125, v134, s[40:41]
	v_cndmask_b32_e64 v115, v127, v111, s[38:39]
	v_cndmask_b32_e64 v114, v131, v123, s[38:39]
	v_pk_fma_f32 v[132:133], v[62:63], v[132:133], v[74:75]
	s_nop 0
	v_pk_fma_f32 v[114:115], v[58:59], v[114:115], v[132:133]
	s_nop 0
	v_pk_fma_f32 v[114:115], v[82:83], v[174:175], v[114:115]
	s_nop 0
	v_mul_f32_e32 v111, 0xbfb8aa3b, v115
	v_exp_f32_e32 v111, v111
	s_nop 0
	v_add_f32_e32 v111, 1.0, v111
	v_rcp_f32_e32 v111, v111
	s_nop 0
	v_mul_f32_e32 v111, v115, v111
	v_mul_f32_e32 v114, v114, v111
	s_nop 0
	s_nop 0
	v_mov_b32_dpp v123, v105 row_ror:2 row_mask:0xf bank_mask:0xf
	v_mov_b32_dpp v153, v104 row_ror:2 row_mask:0xf bank_mask:0xf
	v_mov_b32_dpp v121, v105 row_ror:1 row_mask:0xf bank_mask:0xf
	v_mov_b32_dpp v125, v104 row_ror:1 row_mask:0xf bank_mask:0xf
	v_cndmask_b32_e64 v135, v129, v123, s[40:41]
	v_cndmask_b32_e64 v134, v134, v153, s[40:41]
	v_cndmask_b32_e64 v133, v121, v127, s[38:39]
	v_cndmask_b32_e64 v132, v125, v131, s[38:39]
	v_pk_fma_f32 v[134:135], v[62:63], v[134:135], v[74:75]
	s_nop 0
	v_pk_fma_f32 v[132:133], v[58:59], v[132:133], v[134:135]
	s_nop 0
	v_pk_fma_f32 v[104:105], v[82:83], v[104:105], v[132:133]
	s_nop 0
	v_mul_f32_e32 v111, 0xbfb8aa3b, v105
	v_exp_f32_e32 v111, v111
	s_nop 0
	v_add_f32_e32 v111, 1.0, v111
	v_rcp_f32_e32 v111, v111
	s_nop 0
	v_mul_f32_e32 v105, v105, v111
	v_mul_f32_e32 v104, v104, v105
	s_nop 0
	s_nop 0
	v_mov_b32_dpp v127, v89 row_ror:2 row_mask:0xf bank_mask:0xf
	v_mov_b32_dpp v131, v88 row_ror:2 row_mask:0xf bank_mask:0xf
	v_mov_b32_dpp v115, v89 row_ror:1 row_mask:0xf bank_mask:0xf
	v_mov_b32_dpp v129, v88 row_ror:1 row_mask:0xf bank_mask:0xf
	v_cndmask_b32_e64 v135, v123, v127, s[40:41]
	v_cndmask_b32_e64 v134, v153, v131, s[40:41]
	v_cndmask_b32_e64 v133, v115, v121, s[38:39]
	v_cndmask_b32_e64 v132, v129, v125, s[38:39]
	v_pk_fma_f32 v[134:135], v[62:63], v[134:135], v[74:75]
	s_nop 0
	v_pk_fma_f32 v[132:133], v[58:59], v[132:133], v[134:135]
	s_nop 0
	v_pk_fma_f32 v[88:89], v[82:83], v[88:89], v[132:133]
	s_nop 0
	v_mul_f32_e32 v105, 0xbfb8aa3b, v89
	v_exp_f32_e32 v105, v105
	s_nop 0
	v_add_f32_e32 v105, 1.0, v105
	v_rcp_f32_e32 v105, v105
	s_nop 0
	v_mul_f32_e32 v89, v89, v105
	v_mul_f32_e32 v88, v88, v89
	s_nop 0
	s_nop 0
	v_mov_b32_dpp v121, v73 row_ror:2 row_mask:0xf bank_mask:0xf
	v_mov_b32_dpp v125, v72 row_ror:2 row_mask:0xf bank_mask:0xf
	v_mov_b32_dpp v111, v73 row_ror:1 row_mask:0xf bank_mask:0xf
	v_mov_b32_dpp v123, v72 row_ror:1 row_mask:0xf bank_mask:0xf
	v_cndmask_b32_e64 v135, v127, v121, s[40:41]
	v_cndmask_b32_e64 v134, v131, v125, s[40:41]
	v_cndmask_b32_e64 v133, v111, v115, s[38:39]
	v_cndmask_b32_e64 v132, v123, v129, s[38:39]
	v_pk_fma_f32 v[134:135], v[62:63], v[134:135], v[74:75]
	s_nop 0
	v_pk_fma_f32 v[132:133], v[58:59], v[132:133], v[134:135]
	s_nop 0
	v_pk_fma_f32 v[72:73], v[82:83], v[72:73], v[132:133]
	s_nop 0
	v_mul_f32_e32 v89, 0xbfb8aa3b, v73
	v_exp_f32_e32 v89, v89
	s_nop 0
	v_add_f32_e32 v89, 1.0, v89
	v_rcp_f32_e32 v89, v89
	s_nop 0
	v_mul_f32_e32 v73, v73, v89
	v_mul_f32_e32 v72, v72, v73
	s_nop 1
	v_mov_b32_dpp v115, v57 row_ror:2 row_mask:0xf bank_mask:0xf
	v_mov_b32_dpp v129, v56 row_ror:2 row_mask:0xf bank_mask:0xf
	v_mov_b32_dpp v105, v57 row_ror:1 row_mask:0xf bank_mask:0xf
	v_mov_b32_dpp v127, v56 row_ror:1 row_mask:0xf bank_mask:0xf
; __device__ __forceinline__ float sigmoidf_(float x) { return __builtin_amdgcn_rcpf(1.0f + __expf(-x)); }
; template <int N> __device__ __forceinline__ float dpp_ror(float v) { return __builtin_bit_cast(float, __builtin_amdgcn_update_dpp(0, __builtin_bit_cast(int, v), 0x120 + N, 0xf, 0xf, false)); }
;     __device__ __forceinline__ void operator()(Acc& acc, const Unit& u, int wr, int wc, int fr, int fq) const {
;     ...
;         for (int n = 0; n < 2; ++n) {
; #pragma unroll
;             for (int i = 0; i < 4; ++i) {
;                 const int cg_ = ch0 + 4 * n + i, cv_ = DFF + cg_;
;                 const float g0 = cw[cg_], g1 = cw[NUP + cg_], g2 = cw[2 * NUP + cg_], gb = cb[cg_];
;                 const float v0 = cw[cv_], v1 = cw[NUP + cv_], v2 = cw[2 * NUP + cv_], vb = cb[cv_];
;                 float pg1 = 0.f, pg2 = 0.f, pv1 = 0.f, pv2 = 0.f;
; #pragma unroll
;                 for (int q = 0; q < 8; ++q) {
;                     float cgv = acc[q >> 2][0][q & 3][n][i], cvv = acc[q >> 2][1][q & 3][n][i];
;                     asm volatile("" : "+v"(cgv), "+v"(cvv) : "v"(chain));
;                     const float tg1 = dpp_ror<1>(cgv), tg2 = dpp_ror<2>(cgv), tv1 = dpp_ror<1>(cvv), tv2 = dpp_ror<2>(cvv);
;                     const float sg1 = fr >= 1 ? tg1 : pg1, sg2 = fr >= 2 ? tg2 : pg2, sv1 = fr >= 1 ? tv1 : pv1, sv2 = fr >= 2 ? tv2 : pv2;
;                     const float gg = gb + g0 * sg2 + g1 * sg1 + g2 * cgv;
;                     const float vv = vb + v0 * sv2 + v1 * sv1 + v2 * cvv;
;                     chain = gg * sigmoidf_(gg) * vv; acc[q >> 2][0][q & 3][n][i] = chain;
;                     pg1 = tg1; pg2 = tg2; pv1 = tv1; pv2 = tv2;
;                 }
	v_cndmask_b32_e64 v135, v121, v115, s[40:41]
	v_cndmask_b32_e64 v134, v125, v129, s[40:41]
	v_cndmask_b32_e64 v133, v105, v111, s[38:39]
	v_cndmask_b32_e64 v132, v127, v123, s[38:39]
	v_pk_fma_f32 v[134:135], v[62:63], v[134:135], v[74:75]
	s_nop 0
	v_pk_fma_f32 v[132:133], v[58:59], v[132:133], v[134:135]
	s_nop 0
	v_pk_fma_f32 v[56:57], v[82:83], v[56:57], v[132:133]
	s_nop 0
	v_mul_f32_e32 v73, 0xbfb8aa3b, v57
	v_exp_f32_e32 v73, v73
	s_nop 0
	v_add_f32_e32 v73, 1.0, v73
	v_rcp_f32_e32 v73, v73
	s_nop 0
	v_mul_f32_e32 v57, v57, v73
	v_mul_f32_e32 v73, v56, v57
	s_nop 1
	v_mov_b32_dpp v121, v43 row_ror:2 row_mask:0xf bank_mask:0xf
	v_mov_b32_dpp v125, v42 row_ror:2 row_mask:0xf bank_mask:0xf
	v_mov_b32_dpp v111, v43 row_ror:1 row_mask:0xf bank_mask:0xf
	v_mov_b32_dpp v123, v42 row_ror:1 row_mask:0xf bank_mask:0xf
	v_cndmask_b32_e64 v133, v115, v121, s[40:41]
	v_cndmask_b32_e64 v132, v129, v125, s[40:41]
	v_cndmask_b32_e64 v57, v111, v105, s[38:39]
	v_cndmask_b32_e64 v56, v123, v127, s[38:39]
	v_pk_fma_f32 v[132:133], v[62:63], v[132:133], v[74:75]
	s_nop 0
	v_pk_fma_f32 v[56:57], v[58:59], v[56:57], v[132:133]
	s_nop 0
	v_pk_fma_f32 v[42:43], v[82:83], v[42:43], v[56:57]
	s_nop 0
	v_mul_f32_e32 v56, 0xbfb8aa3b, v43
	v_exp_f32_e32 v56, v56
	s_nop 0
	v_add_f32_e32 v56, 1.0, v56
	v_rcp_f32_e32 v56, v56
	s_nop 0
	v_mul_f32_e32 v43, v43, v56
	v_mul_f32_e32 v89, v42, v43
	s_nop 1
	v_mov_b32_dpp v57, v51 row_ror:1 row_mask:0xf bank_mask:0xf
	v_mov_b32_dpp v105, v51 row_ror:2 row_mask:0xf bank_mask:0xf
	v_mov_b32_dpp v127, v50 row_ror:2 row_mask:0xf bank_mask:0xf
	v_mov_b32_dpp v115, v50 row_ror:1 row_mask:0xf bank_mask:0xf
	v_cndmask_b32_e64 v43, v57, v111, s[38:39]
	v_cndmask_b32_e64 v57, v121, v105, s[40:41]
	v_cndmask_b32_e64 v56, v125, v127, s[40:41]
	v_cndmask_b32_e64 v42, v115, v123, s[38:39]
	v_pk_fma_f32 v[56:57], v[62:63], v[56:57], v[74:75]
	s_nop 0
	v_pk_fma_f32 v[42:43], v[58:59], v[42:43], v[56:57]
	s_nop 0
	v_pk_fma_f32 v[42:43], v[82:83], v[50:51], v[42:43]
	s_nop 0
	v_mul_f32_e32 v50, 0xbfb8aa3b, v43
	v_exp_f32_e32 v50, v50
	s_nop 0
	v_add_f32_e32 v50, 1.0, v50
	v_rcp_f32_e32 v50, v50
	s_nop 0
	v_mul_f32_e32 v43, v43, v50
	v_mul_f32_e32 v62, v42, v43
	global_load_dword v51, v[6:7], off offset:12
	global_load_dword v43, v[8:9], off offset:2060
	global_load_dword v42, v[10:11], off offset:12
	global_load_dword v57, v[16:17], off offset:12
	global_load_dword v56, v[20:21], off offset:3084
	global_load_dword v50, v[18:19], off offset:3084
	global_load_dword v75, v[22:23], off offset:1036
	global_load_dword v74, v[24:25], off offset:3084
	s_nop 0
	s_nop 0
	s_nop 0
	s_nop 0
	v_mov_b32_dpp v105, v154 row_ror:1 row_mask:0xf bank_mask:0xf
	v_mov_b32_dpp v111, v154 row_ror:2 row_mask:0xf bank_mask:0xf
	v_cndmask_b32_e64 v155, v105, 0, s[38:39]
	v_cndmask_b32_e64 v58, 0, v111, s[40:41]
	v_mov_b32_dpp v115, v158 row_ror:1 row_mask:0xf bank_mask:0xf
	v_cndmask_b32_e64 v159, v115, 0, s[38:39]
	v_mov_b32_dpp v121, v158 row_ror:2 row_mask:0xf bank_mask:0xf
	v_cndmask_b32_e64 v63, 0, v121, s[40:41]
	s_nop 0
	s_nop 0
	s_nop 0
	s_nop 0
	s_waitcnt vmcnt(4)
	v_fma_f32 v82, v51, v58, v57
	v_pk_mul_f32 v[58:59], v[42:43], v[154:155]
	s_waitcnt vmcnt(2)
	v_fma_f32 v63, v50, v63, v56
	v_add_f32_e32 v59, v59, v82
	v_add_f32_e32 v131, v58, v59
	v_mul_f32_e32 v58, 0xbfb8aa3b, v131
	v_exp_f32_e32 v132, v58
	v_mov_b32_e32 v59, v42
	s_waitcnt vmcnt(0)
	v_pk_mul_f32 v[82:83], v[74:75], v[158:159]
	v_mov_b32_e32 v58, v74
	v_add_f32_e32 v42, 1.0, v132
	v_rcp_f32_e32 v74, v42
	v_add_f32_e32 v63, v83, v63
	v_add_f32_e32 v63, v82, v63
	v_mov_b32_e32 v42, v75
	v_mul_f32_e32 v74, v131, v74
	v_mul_f32_e32 v63, v63, v74
	s_nop 1
	v_mov_b32_dpp v125, v157 row_ror:2 row_mask:0xf bank_mask:0xf
	v_mov_b32_dpp v129, v156 row_ror:2 row_mask:0xf bank_mask:0xf
	v_mov_b32_dpp v123, v157 row_ror:1 row_mask:0xf bank_mask:0xf
	v_mov_b32_dpp v127, v156 row_ror:1 row_mask:0xf bank_mask:0xf
	v_cndmask_b32_e64 v83, v111, v125, s[40:41]
	v_cndmask_b32_e64 v82, v121, v129, s[40:41]
	v_cndmask_b32_e64 v75, v123, v105, s[38:39]
	v_cndmask_b32_e64 v74, v127, v115, s[38:39]
	v_pk_fma_f32 v[82:83], v[50:51], v[82:83], v[56:57]
	s_nop 0
	v_pk_fma_f32 v[74:75], v[42:43], v[74:75], v[82:83]
	s_nop 0
	v_pk_fma_f32 v[74:75], v[58:59], v[156:157], v[74:75]
	s_nop 0
	v_mul_f32_e32 v82, 0xbfb8aa3b, v75
	v_exp_f32_e32 v82, v82
	s_nop 0
	v_add_f32_e32 v82, 1.0, v82
	v_rcp_f32_e32 v82, v82
	s_nop 0
	v_mul_f32_e32 v75, v75, v82
	v_mul_f32_e32 v74, v74, v75
	s_nop 1
	v_mov_b32_dpp v111, v103 row_ror:2 row_mask:0xf bank_mask:0xf
	v_mov_b32_dpp v121, v102 row_ror:2 row_mask:0xf bank_mask:0xf
	v_mov_b32_dpp v105, v103 row_ror:1 row_mask:0xf bank_mask:0xf
	v_mov_b32_dpp v115, v102 row_ror:1 row_mask:0xf bank_mask:0xf
	v_cndmask_b32_e64 v133, v125, v111, s[40:41]
	v_cndmask_b32_e64 v132, v129, v121, s[40:41]
	v_cndmask_b32_e64 v83, v105, v123, s[38:39]
	v_cndmask_b32_e64 v82, v115, v127, s[38:39]
	v_pk_fma_f32 v[132:133], v[50:51], v[132:133], v[56:57]
	s_nop 0
	v_pk_fma_f32 v[82:83], v[42:43], v[82:83], v[132:133]
	s_nop 0
	v_pk_fma_f32 v[82:83], v[58:59], v[102:103], v[82:83]
	s_nop 0
	v_mul_f32_e32 v75, 0xbfb8aa3b, v83
	v_exp_f32_e32 v75, v75
	s_nop 0
	v_add_f32_e32 v75, 1.0, v75
	v_rcp_f32_e32 v75, v75
	s_nop 0
	v_mul_f32_e32 v75, v83, v75
	v_mul_f32_e32 v75, v82, v75
	s_nop 1
	v_mov_b32_dpp v125, v87 row_ror:2 row_mask:0xf bank_mask:0xf
	v_mov_b32_dpp v129, v86 row_ror:2 row_mask:0xf bank_mask:0xf
	v_mov_b32_dpp v123, v87 row_ror:1 row_mask:0xf bank_mask:0xf
	v_mov_b32_dpp v127, v86 row_ror:1 row_mask:0xf bank_mask:0xf
	v_cndmask_b32_e64 v103, v111, v125, s[40:41]
	v_cndmask_b32_e64 v102, v121, v129, s[40:41]
; __device__ __forceinline__ float sigmoidf_(float x) { return __builtin_amdgcn_rcpf(1.0f + __expf(-x)); }
; template <int N> __device__ __forceinline__ float dpp_ror(float v) { return __builtin_bit_cast(float, __builtin_amdgcn_update_dpp(0, __builtin_bit_cast(int, v), 0x120 + N, 0xf, 0xf, false)); }
;     __device__ __forceinline__ void operator()(Acc& acc, const Unit& u, int wr, int wc, int fr, int fq) const {
;     ...
;         for (int n = 0; n < 2; ++n) {
; #pragma unroll
;             for (int i = 0; i < 4; ++i) {
;                 const int cg_ = ch0 + 4 * n + i, cv_ = DFF + cg_;
;                 const float g0 = cw[cg_], g1 = cw[NUP + cg_], g2 = cw[2 * NUP + cg_], gb = cb[cg_];
;                 const float v0 = cw[cv_], v1 = cw[NUP + cv_], v2 = cw[2 * NUP + cv_], vb = cb[cv_];
;                 float pg1 = 0.f, pg2 = 0.f, pv1 = 0.f, pv2 = 0.f;
; #pragma unroll
;                 for (int q = 0; q < 8; ++q) {
;                     float cgv = acc[q >> 2][0][q & 3][n][i], cvv = acc[q >> 2][1][q & 3][n][i];
;                     asm volatile("" : "+v"(cgv), "+v"(cvv) : "v"(chain));
;                     const float tg1 = dpp_ror<1>(cgv), tg2 = dpp_ror<2>(cgv), tv1 = dpp_ror<1>(cvv), tv2 = dpp_ror<2>(cvv);
;                     const float sg1 = fr >= 1 ? tg1 : pg1, sg2 = fr >= 2 ? tg2 : pg2, sv1 = fr >= 1 ? tv1 : pv1, sv2 = fr >= 2 ? tv2 : pv2;
;                     const float gg = gb + g0 * sg2 + g1 * sg1 + g2 * cgv;
;                     const float vv = vb + v0 * sv2 + v1 * sv1 + v2 * cvv;
;                     chain = gg * sigmoidf_(gg) * vv; acc[q >> 2][0][q & 3][n][i] = chain;
;                     pg1 = tg1; pg2 = tg2; pv1 = tv1; pv2 = tv2;
;                 }
	v_cndmask_b32_e64 v83, v123, v105, s[38:39]
	v_cndmask_b32_e64 v82, v127, v115, s[38:39]
	v_pk_fma_f32 v[102:103], v[50:51], v[102:103], v[56:57]
	s_nop 0
	v_pk_fma_f32 v[82:83], v[42:43], v[82:83], v[102:103]
	s_nop 0
	v_pk_fma_f32 v[82:83], v[58:59], v[86:87], v[82:83]
	s_nop 0
	v_mul_f32_e32 v86, 0xbfb8aa3b, v83
	v_exp_f32_e32 v86, v86
	s_nop 0
	v_add_f32_e32 v86, 1.0, v86
	v_rcp_f32_e32 v86, v86
	s_nop 0
	v_mul_f32_e32 v83, v83, v86
	v_mul_f32_e32 v82, v82, v83
	s_nop 1
	v_mov_b32_dpp v111, v71 row_ror:2 row_mask:0xf bank_mask:0xf
	v_mov_b32_dpp v121, v70 row_ror:2 row_mask:0xf bank_mask:0xf
	v_mov_b32_dpp v105, v71 row_ror:1 row_mask:0xf bank_mask:0xf
	v_mov_b32_dpp v115, v70 row_ror:1 row_mask:0xf bank_mask:0xf
	v_cndmask_b32_e64 v103, v125, v111, s[40:41]
	v_cndmask_b32_e64 v102, v129, v121, s[40:41]
	v_cndmask_b32_e64 v87, v105, v123, s[38:39]
	v_cndmask_b32_e64 v86, v115, v127, s[38:39]
	v_pk_fma_f32 v[102:103], v[50:51], v[102:103], v[56:57]
	s_nop 0
	v_pk_fma_f32 v[86:87], v[42:43], v[86:87], v[102:103]
	s_nop 0
	v_pk_fma_f32 v[70:71], v[58:59], v[70:71], v[86:87]
	s_nop 0
	v_mul_f32_e32 v83, 0xbfb8aa3b, v71
	v_exp_f32_e32 v83, v83
	s_nop 0
	v_add_f32_e32 v83, 1.0, v83
	v_rcp_f32_e32 v83, v83
	s_nop 0
	v_mul_f32_e32 v71, v71, v83
	v_mul_f32_e32 v70, v70, v71
	s_nop 0
	s_nop 0
	v_mov_b32_dpp v125, v55 row_ror:2 row_mask:0xf bank_mask:0xf
	v_mov_b32_dpp v129, v54 row_ror:2 row_mask:0xf bank_mask:0xf
	v_mov_b32_dpp v123, v55 row_ror:1 row_mask:0xf bank_mask:0xf
	v_mov_b32_dpp v127, v54 row_ror:1 row_mask:0xf bank_mask:0xf
	v_cndmask_b32_e64 v103, v111, v125, s[40:41]
	v_cndmask_b32_e64 v102, v121, v129, s[40:41]
	v_cndmask_b32_e64 v87, v123, v105, s[38:39]
	v_cndmask_b32_e64 v86, v127, v115, s[38:39]
	v_pk_fma_f32 v[102:103], v[50:51], v[102:103], v[56:57]
	s_nop 0
	v_pk_fma_f32 v[86:87], v[42:43], v[86:87], v[102:103]
	s_nop 0
	v_pk_fma_f32 v[54:55], v[58:59], v[54:55], v[86:87]
	s_nop 0
	v_mul_f32_e32 v71, 0xbfb8aa3b, v55
	v_exp_f32_e32 v71, v71
	s_nop 0
	v_add_f32_e32 v71, 1.0, v71
	v_rcp_f32_e32 v71, v71
	s_nop 0
	v_mul_f32_e32 v55, v55, v71
	v_mul_f32_e32 v55, v54, v55
	s_nop 1
	v_mov_b32_dpp v105, v39 row_ror:2 row_mask:0xf bank_mask:0xf
	v_mov_b32_dpp v115, v38 row_ror:2 row_mask:0xf bank_mask:0xf
	v_mov_b32_dpp v83, v39 row_ror:1 row_mask:0xf bank_mask:0xf
	v_mov_b32_dpp v111, v38 row_ror:1 row_mask:0xf bank_mask:0xf
	v_cndmask_b32_e64 v103, v125, v105, s[40:41]
	v_cndmask_b32_e64 v102, v129, v115, s[40:41]
	v_cndmask_b32_e64 v87, v83, v123, s[38:39]
	v_cndmask_b32_e64 v86, v111, v127, s[38:39]
	v_pk_fma_f32 v[102:103], v[50:51], v[102:103], v[56:57]
	s_nop 0
	v_pk_fma_f32 v[86:87], v[42:43], v[86:87], v[102:103]
	s_nop 0
	v_pk_fma_f32 v[38:39], v[58:59], v[38:39], v[86:87]
	s_nop 0
	v_mul_f32_e32 v54, 0xbfb8aa3b, v39
	v_exp_f32_e32 v54, v54
	s_nop 0
	s_nop 0
	v_add_f32_e32 v54, 1.0, v54
	v_rcp_f32_e32 v54, v54
	s_nop 0
	v_mul_f32_e32 v39, v39, v54
	v_mul_f32_e32 v71, v38, v39
	s_nop 1
	v_mov_b32_dpp v86, v41 row_ror:1 row_mask:0xf bank_mask:0xf
	v_mov_b32_dpp v87, v41 row_ror:2 row_mask:0xf bank_mask:0xf
	v_mov_b32_dpp v103, v40 row_ror:2 row_mask:0xf bank_mask:0xf
	v_mov_b32_dpp v102, v40 row_ror:1 row_mask:0xf bank_mask:0xf
	v_cndmask_b32_e64 v39, v86, v83, s[38:39]
	v_cndmask_b32_e64 v87, v105, v87, s[40:41]
	v_cndmask_b32_e64 v86, v115, v103, s[40:41]
	v_cndmask_b32_e64 v38, v102, v111, s[38:39]
	v_pk_fma_f32 v[50:51], v[50:51], v[86:87], v[56:57]
	s_nop 0
	v_pk_fma_f32 v[38:39], v[42:43], v[38:39], v[50:51]
	s_nop 0
	v_pk_fma_f32 v[38:39], v[58:59], v[40:41], v[38:39]
	s_nop 0
	v_mul_f32_e32 v40, 0xbfb8aa3b, v39
	v_exp_f32_e32 v40, v40
	s_nop 0
	v_add_f32_e32 v40, 1.0, v40
	v_rcp_f32_e32 v40, v40
	s_nop 0
	v_mul_f32_e32 v39, v39, v40
	v_mul_f32_e32 v54, v38, v39
	global_load_dword v41, v[6:7], off offset:16
	global_load_dword v39, v[8:9], off offset:2064
	global_load_dword v38, v[10:11], off offset:16
	global_load_dword v43, v[16:17], off offset:16
	global_load_dword v42, v[20:21], off offset:3088
	global_load_dword v40, v[18:19], off offset:3088
	global_load_dword v57, v[22:23], off offset:1040
	global_load_dword v56, v[24:25], off offset:3088
	s_nop 0
	s_nop 0
	s_nop 0
	s_nop 0
	v_mov_b32_dpp v83, v130 row_ror:1 row_mask:0xf bank_mask:0xf
	v_mov_b32_dpp v86, v130 row_ror:2 row_mask:0xf bank_mask:0xf
	v_cndmask_b32_e64 v131, v83, 0, s[38:39]
	v_cndmask_b32_e64 v50, 0, v86, s[40:41]
	v_mov_b32_dpp v87, v152 row_ror:1 row_mask:0xf bank_mask:0xf
	v_mov_b32_dpp v102, v152 row_ror:2 row_mask:0xf bank_mask:0xf
	v_cndmask_b32_e64 v153, v87, 0, s[38:39]
	v_cndmask_b32_e64 v58, 0, v102, s[40:41]
	s_nop 0
	s_nop 0
	s_nop 0
	s_nop 0
	s_waitcnt vmcnt(4)
	v_fma_f32 v59, v41, v50, v43
	v_pk_mul_f32 v[50:51], v[38:39], v[130:131]
	s_waitcnt vmcnt(2)
	v_fma_f32 v121, v40, v58, v42
	v_add_f32_e32 v51, v51, v59
	v_add_f32_e32 v123, v50, v51
	v_mul_f32_e32 v50, 0xbfb8aa3b, v123
	v_exp_f32_e32 v125, v50
	v_mov_b32_e32 v51, v38
	s_waitcnt vmcnt(0)
; __device__ __forceinline__ float sigmoidf_(float x) { return __builtin_amdgcn_rcpf(1.0f + __expf(-x)); }
; template <int N> __device__ __forceinline__ float dpp_ror(float v) { return __builtin_bit_cast(float, __builtin_amdgcn_update_dpp(0, __builtin_bit_cast(int, v), 0x120 + N, 0xf, 0xf, false)); }
;     __device__ __forceinline__ void operator()(Acc& acc, const Unit& u, int wr, int wc, int fr, int fq) const {
;     ...
;         for (int n = 0; n < 2; ++n) {
; #pragma unroll
;             for (int i = 0; i < 4; ++i) {
;                 const int cg_ = ch0 + 4 * n + i, cv_ = DFF + cg_;
;                 const float g0 = cw[cg_], g1 = cw[NUP + cg_], g2 = cw[2 * NUP + cg_], gb = cb[cg_];
;                 const float v0 = cw[cv_], v1 = cw[NUP + cv_], v2 = cw[2 * NUP + cv_], vb = cb[cv_];
;                 float pg1 = 0.f, pg2 = 0.f, pv1 = 0.f, pv2 = 0.f;
; #pragma unroll
;                 for (int q = 0; q < 8; ++q) {
;                     float cgv = acc[q >> 2][0][q & 3][n][i], cvv = acc[q >> 2][1][q & 3][n][i];
;                     asm volatile("" : "+v"(cgv), "+v"(cvv) : "v"(chain));
;                     const float tg1 = dpp_ror<1>(cgv), tg2 = dpp_ror<2>(cgv), tv1 = dpp_ror<1>(cvv), tv2 = dpp_ror<2>(cvv);
;                     const float sg1 = fr >= 1 ? tg1 : pg1, sg2 = fr >= 2 ? tg2 : pg2, sv1 = fr >= 1 ? tv1 : pv1, sv2 = fr >= 2 ? tv2 : pv2;
;                     const float gg = gb + g0 * sg2 + g1 * sg1 + g2 * cgv;
;                     const float vv = vb + v0 * sv2 + v1 * sv1 + v2 * cvv;
;                     chain = gg * sigmoidf_(gg) * vv; acc[q >> 2][0][q & 3][n][i] = chain;
;                     pg1 = tg1; pg2 = tg2; pv1 = tv1; pv2 = tv2;
;                 }
	v_pk_mul_f32 v[58:59], v[56:57], v[152:153]
	v_mov_b32_e32 v50, v56
	v_add_f32_e32 v38, 1.0, v125
	v_rcp_f32_e32 v56, v38
	v_mov_b32_e32 v38, v57
	v_add_f32_e32 v57, v59, v121
	v_add_f32_e32 v57, v58, v57
	v_mul_f32_e32 v56, v123, v56
	v_mul_f32_e32 v56, v57, v56
	s_nop 1
	v_mov_b32_dpp v105, v119 row_ror:2 row_mask:0xf bank_mask:0xf
	v_mov_b32_dpp v111, v118 row_ror:1 row_mask:0xf bank_mask:0xf
	v_mov_b32_dpp v115, v118 row_ror:2 row_mask:0xf bank_mask:0xf
	v_mov_b32_dpp v103, v119 row_ror:1 row_mask:0xf bank_mask:0xf
	v_cndmask_b32_e64 v58, v111, v87, s[38:39]
	v_cndmask_b32_e64 v87, v86, v105, s[40:41]
	v_cndmask_b32_e64 v86, v102, v115, s[40:41]
	v_cndmask_b32_e64 v59, v103, v83, s[38:39]
	v_pk_fma_f32 v[86:87], v[40:41], v[86:87], v[42:43]
	s_nop 0
	v_pk_fma_f32 v[58:59], v[38:39], v[58:59], v[86:87]
	s_nop 0
	v_pk_fma_f32 v[58:59], v[50:51], v[118:119], v[58:59]
	s_nop 0
	v_mul_f32_e32 v57, 0xbfb8aa3b, v59
	v_exp_f32_e32 v57, v57
	s_nop 0
	v_add_f32_e32 v57, 1.0, v57
	v_rcp_f32_e32 v57, v57
	s_nop 0
	v_mul_f32_e32 v57, v59, v57
	v_mul_f32_e32 v57, v58, v57
	s_nop 1
	v_mov_b32_dpp v102, v101 row_ror:2 row_mask:0xf bank_mask:0xf
	v_mov_b32_dpp v119, v100 row_ror:2 row_mask:0xf bank_mask:0xf
	v_mov_b32_dpp v83, v101 row_ror:1 row_mask:0xf bank_mask:0xf
	v_mov_b32_dpp v118, v100 row_ror:1 row_mask:0xf bank_mask:0xf
	v_cndmask_b32_e64 v87, v105, v102, s[40:41]
	v_cndmask_b32_e64 v86, v115, v119, s[40:41]
	v_cndmask_b32_e64 v59, v83, v103, s[38:39]
	v_cndmask_b32_e64 v58, v118, v111, s[38:39]
	v_pk_fma_f32 v[86:87], v[40:41], v[86:87], v[42:43]
	s_nop 0
	v_pk_fma_f32 v[58:59], v[38:39], v[58:59], v[86:87]
	s_nop 0
	v_pk_fma_f32 v[58:59], v[50:51], v[100:101], v[58:59]
	s_nop 0
	v_mul_f32_e32 v86, 0xbfb8aa3b, v59
	v_exp_f32_e32 v86, v86
	s_nop 0
	v_add_f32_e32 v86, 1.0, v86
	v_rcp_f32_e32 v86, v86
	s_nop 0
	v_mul_f32_e32 v59, v59, v86
	v_mul_f32_e32 v58, v58, v59
	s_nop 1
	v_mov_b32_dpp v105, v85 row_ror:2 row_mask:0xf bank_mask:0xf
	v_mov_b32_dpp v115, v84 row_ror:2 row_mask:0xf bank_mask:0xf
	v_mov_b32_dpp v103, v85 row_ror:1 row_mask:0xf bank_mask:0xf
	v_mov_b32_dpp v111, v84 row_ror:1 row_mask:0xf bank_mask:0xf
	v_cndmask_b32_e64 v101, v102, v105, s[40:41]
	v_cndmask_b32_e64 v100, v119, v115, s[40:41]
	v_cndmask_b32_e64 v87, v103, v83, s[38:39]
	v_cndmask_b32_e64 v86, v111, v118, s[38:39]
	v_pk_fma_f32 v[100:101], v[40:41], v[100:101], v[42:43]
	s_nop 0
	v_pk_fma_f32 v[86:87], v[38:39], v[86:87], v[100:101]
	s_nop 0
	v_pk_fma_f32 v[84:85], v[50:51], v[84:85], v[86:87]
	s_nop 0
	v_mul_f32_e32 v59, 0xbfb8aa3b, v85
	v_exp_f32_e32 v59, v59
	s_nop 0
	v_add_f32_e32 v59, 1.0, v59
	v_rcp_f32_e32 v59, v59
	s_nop 0
	v_mul_f32_e32 v59, v85, v59
	v_mul_f32_e32 v59, v84, v59
	s_nop 1
	v_mov_b32_dpp v100, v69 row_ror:2 row_mask:0xf bank_mask:0xf
	v_mov_b32_dpp v102, v68 row_ror:2 row_mask:0xf bank_mask:0xf
	v_mov_b32_dpp v83, v69 row_ror:1 row_mask:0xf bank_mask:0xf
	v_mov_b32_dpp v101, v68 row_ror:1 row_mask:0xf bank_mask:0xf
	v_cndmask_b32_e64 v87, v105, v100, s[40:41]
	v_cndmask_b32_e64 v86, v115, v102, s[40:41]
	v_cndmask_b32_e64 v85, v83, v103, s[38:39]
	v_cndmask_b32_e64 v84, v101, v111, s[38:39]
	v_pk_fma_f32 v[86:87], v[40:41], v[86:87], v[42:43]
	s_nop 0
	v_pk_fma_f32 v[84:85], v[38:39], v[84:85], v[86:87]
	s_nop 0
	v_pk_fma_f32 v[68:69], v[50:51], v[68:69], v[84:85]
	s_nop 0
	v_mul_f32_e32 v84, 0xbfb8aa3b, v69
	v_exp_f32_e32 v84, v84
	s_nop 0
	v_add_f32_e32 v84, 1.0, v84
	v_rcp_f32_e32 v84, v84
	s_nop 0
	v_mul_f32_e32 v69, v69, v84
	v_mul_f32_e32 v68, v68, v69
	s_nop 1
	v_mov_b32_dpp v105, v53 row_ror:2 row_mask:0xf bank_mask:0xf
	v_mov_b32_dpp v115, v52 row_ror:2 row_mask:0xf bank_mask:0xf
	v_mov_b32_dpp v103, v53 row_ror:1 row_mask:0xf bank_mask:0xf
	v_mov_b32_dpp v111, v52 row_ror:1 row_mask:0xf bank_mask:0xf
	v_cndmask_b32_e64 v87, v100, v105, s[40:41]
	v_cndmask_b32_e64 v86, v102, v115, s[40:41]
	v_cndmask_b32_e64 v85, v103, v83, s[38:39]
	v_cndmask_b32_e64 v84, v111, v101, s[38:39]
	v_pk_fma_f32 v[86:87], v[40:41], v[86:87], v[42:43]
	s_nop 0
	v_pk_fma_f32 v[84:85], v[38:39], v[84:85], v[86:87]
	s_nop 0
	v_pk_fma_f32 v[52:53], v[50:51], v[52:53], v[84:85]
	s_nop 0
	v_mul_f32_e32 v69, 0xbfb8aa3b, v53
	v_exp_f32_e32 v69, v69
	s_nop 0
	v_add_f32_e32 v69, 1.0, v69
	v_rcp_f32_e32 v69, v69
	s_nop 0
	v_mul_f32_e32 v53, v53, v69
	v_mul_f32_e32 v52, v52, v53
	s_nop 0
	s_nop 0
	v_mov_b32_dpp v100, v37 row_ror:2 row_mask:0xf bank_mask:0xf
	v_mov_b32_dpp v102, v36 row_ror:2 row_mask:0xf bank_mask:0xf
	v_mov_b32_dpp v83, v37 row_ror:1 row_mask:0xf bank_mask:0xf
	v_mov_b32_dpp v101, v36 row_ror:1 row_mask:0xf bank_mask:0xf
	v_cndmask_b32_e64 v87, v105, v100, s[40:41]
	v_cndmask_b32_e64 v86, v115, v102, s[40:41]
	v_cndmask_b32_e64 v85, v83, v103, s[38:39]
	v_cndmask_b32_e64 v84, v101, v111, s[38:39]
	v_pk_fma_f32 v[86:87], v[40:41], v[86:87], v[42:43]
	s_nop 0
	v_pk_fma_f32 v[84:85], v[38:39], v[84:85], v[86:87]
	s_nop 0
	v_pk_fma_f32 v[36:37], v[50:51], v[36:37], v[84:85]
	s_nop 0
	v_mul_f32_e32 v53, 0xbfb8aa3b, v37
	v_exp_f32_e32 v53, v53
	s_nop 0
	v_add_f32_e32 v53, 1.0, v53
	v_rcp_f32_e32 v53, v53
	s_nop 0
	v_mul_f32_e32 v37, v37, v53
	v_mul_f32_e32 v53, v36, v37
	s_nop 1
	v_mov_b32_dpp v84, v35 row_ror:2 row_mask:0xf bank_mask:0xf
	v_mov_b32_dpp v85, v34 row_ror:1 row_mask:0xf bank_mask:0xf
	v_mov_b32_dpp v86, v34 row_ror:2 row_mask:0xf bank_mask:0xf
	v_mov_b32_dpp v69, v35 row_ror:1 row_mask:0xf bank_mask:0xf
	v_cndmask_b32_e64 v36, v85, v101, s[38:39]
	v_cndmask_b32_e64 v85, v100, v84, s[40:41]
	v_cndmask_b32_e64 v84, v102, v86, s[40:41]
	v_cndmask_b32_e64 v37, v69, v83, s[38:39]
	v_pk_fma_f32 v[40:41], v[40:41], v[84:85], v[42:43]
	s_nop 0
	v_pk_fma_f32 v[36:37], v[38:39], v[36:37], v[40:41]
	s_nop 0
	v_pk_fma_f32 v[34:35], v[50:51], v[34:35], v[36:37]
	s_nop 0
	v_mul_f32_e32 v36, 0xbfb8aa3b, v35
	v_exp_f32_e32 v36, v36
	s_nop 0
	v_add_f32_e32 v36, 1.0, v36
	v_rcp_f32_e32 v36, v36
	s_nop 0
	v_mul_f32_e32 v35, v35, v36
	v_mul_f32_e32 v42, v34, v35
	global_load_dword v37, v[6:7], off offset:20
	global_load_dword v35, v[8:9], off offset:2068
	global_load_dword v34, v[10:11], off offset:20
	global_load_dword v39, v[16:17], off offset:20
	global_load_dword v38, v[20:21], off offset:3092
	global_load_dword v36, v[18:19], off offset:3092
	global_load_dword v51, v[22:23], off offset:1044
	global_load_dword v50, v[24:25], off offset:3092
	s_nop 0
	s_nop 0
	s_nop 0
	s_nop 0
	v_mov_b32_dpp v69, v126 row_ror:1 row_mask:0xf bank_mask:0xf
	v_mov_b32_dpp v83, v126 row_ror:2 row_mask:0xf bank_mask:0xf
	v_cndmask_b32_e64 v127, v69, 0, s[38:39]
	v_cndmask_b32_e64 v40, 0, v83, s[40:41]
	v_mov_b32_dpp v86, v128 row_ror:1 row_mask:0xf bank_mask:0xf
	v_cndmask_b32_e64 v129, v86, 0, s[38:39]
	v_mov_b32_dpp v87, v128 row_ror:2 row_mask:0xf bank_mask:0xf
	v_cndmask_b32_e64 v43, 0, v87, s[40:41]
	s_nop 0
	s_nop 0
	s_nop 0
	s_nop 0
	s_nop 0
	s_waitcnt vmcnt(4)
; __device__ __forceinline__ float sigmoidf_(float x) { return __builtin_amdgcn_rcpf(1.0f + __expf(-x)); }
; template <int N> __device__ __forceinline__ float dpp_ror(float v) { return __builtin_bit_cast(float, __builtin_amdgcn_update_dpp(0, __builtin_bit_cast(int, v), 0x120 + N, 0xf, 0xf, false)); }
;     __device__ __forceinline__ void operator()(Acc& acc, const Unit& u, int wr, int wc, int fr, int fq) const {
;     ...
;         for (int n = 0; n < 2; ++n) {
; #pragma unroll
;             for (int i = 0; i < 4; ++i) {
;                 const int cg_ = ch0 + 4 * n + i, cv_ = DFF + cg_;
;                 const float g0 = cw[cg_], g1 = cw[NUP + cg_], g2 = cw[2 * NUP + cg_], gb = cb[cg_];
;                 const float v0 = cw[cv_], v1 = cw[NUP + cv_], v2 = cw[2 * NUP + cv_], vb = cb[cv_];
;                 float pg1 = 0.f, pg2 = 0.f, pv1 = 0.f, pv2 = 0.f;
; #pragma unroll
;                 for (int q = 0; q < 8; ++q) {
;                     float cgv = acc[q >> 2][0][q & 3][n][i], cvv = acc[q >> 2][1][q & 3][n][i];
;                     asm volatile("" : "+v"(cgv), "+v"(cvv) : "v"(chain));
;                     const float tg1 = dpp_ror<1>(cgv), tg2 = dpp_ror<2>(cgv), tv1 = dpp_ror<1>(cvv), tv2 = dpp_ror<2>(cvv);
;                     const float sg1 = fr >= 1 ? tg1 : pg1, sg2 = fr >= 2 ? tg2 : pg2, sv1 = fr >= 1 ? tv1 : pv1, sv2 = fr >= 2 ? tv2 : pv2;
;                     const float gg = gb + g0 * sg2 + g1 * sg1 + g2 * cgv;
;                     const float vv = vb + v0 * sv2 + v1 * sv1 + v2 * cvv;
;                     chain = gg * sigmoidf_(gg) * vv; acc[q >> 2][0][q & 3][n][i] = chain;
;                     pg1 = tg1; pg2 = tg2; pv1 = tv1; pv2 = tv2;
;                 }
	v_fma_f32 v84, v37, v40, v39
	v_pk_mul_f32 v[40:41], v[34:35], v[126:127]
	s_waitcnt vmcnt(2)
	v_fma_f32 v43, v36, v43, v38
	v_add_f32_e32 v41, v41, v84
	v_add_f32_e32 v105, v40, v41
	v_mul_f32_e32 v40, 0xbfb8aa3b, v105
	v_exp_f32_e32 v111, v40
	v_mov_b32_e32 v41, v34
	s_waitcnt vmcnt(0)
	v_pk_mul_f32 v[84:85], v[50:51], v[128:129]
	v_mov_b32_e32 v40, v50
	v_add_f32_e32 v34, 1.0, v111
	v_rcp_f32_e32 v50, v34
	v_add_f32_e32 v43, v85, v43
	v_add_f32_e32 v43, v84, v43
	v_mov_b32_e32 v34, v51
	v_mul_f32_e32 v50, v105, v50
	v_mul_f32_e32 v43, v43, v50
	s_nop 0
	s_nop 0
	v_mov_b32_dpp v101, v117 row_ror:2 row_mask:0xf bank_mask:0xf
	v_mov_b32_dpp v103, v116 row_ror:2 row_mask:0xf bank_mask:0xf
	v_mov_b32_dpp v100, v117 row_ror:1 row_mask:0xf bank_mask:0xf
	v_mov_b32_dpp v102, v116 row_ror:1 row_mask:0xf bank_mask:0xf
	v_cndmask_b32_e64 v85, v83, v101, s[40:41]
	v_cndmask_b32_e64 v84, v87, v103, s[40:41]
	v_cndmask_b32_e64 v51, v100, v69, s[38:39]
	v_cndmask_b32_e64 v50, v102, v86, s[38:39]
	v_pk_fma_f32 v[84:85], v[36:37], v[84:85], v[38:39]
	s_nop 0
	v_pk_fma_f32 v[50:51], v[34:35], v[50:51], v[84:85]
	s_nop 0
	v_pk_fma_f32 v[50:51], v[40:41], v[116:117], v[50:51]
	s_nop 0
	v_mul_f32_e32 v69, 0xbfb8aa3b, v51
	v_exp_f32_e32 v69, v69
	s_nop 0
	v_add_f32_e32 v69, 1.0, v69
	v_rcp_f32_e32 v69, v69
	s_nop 0
	v_mul_f32_e32 v51, v51, v69
	v_mul_f32_e32 v50, v50, v51
	s_nop 1
	v_mov_b32_dpp v105, v97 row_ror:2 row_mask:0xf bank_mask:0xf
	v_mov_b32_dpp v115, v96 row_ror:2 row_mask:0xf bank_mask:0xf
	v_mov_b32_dpp v83, v97 row_ror:1 row_mask:0xf bank_mask:0xf
	v_mov_b32_dpp v111, v96 row_ror:1 row_mask:0xf bank_mask:0xf
	v_cndmask_b32_e64 v87, v101, v105, s[40:41]
	v_cndmask_b32_e64 v86, v103, v115, s[40:41]
	v_cndmask_b32_e64 v85, v83, v100, s[38:39]
	v_cndmask_b32_e64 v84, v111, v102, s[38:39]
	v_pk_fma_f32 v[86:87], v[36:37], v[86:87], v[38:39]
	s_nop 0
	v_pk_fma_f32 v[84:85], v[34:35], v[84:85], v[86:87]
	s_nop 0
	v_pk_fma_f32 v[84:85], v[40:41], v[96:97], v[84:85]
	s_nop 0
	v_mul_f32_e32 v51, 0xbfb8aa3b, v85
	v_exp_f32_e32 v51, v51
	s_nop 0
	s_nop 0
	v_add_f32_e32 v51, 1.0, v51
	v_rcp_f32_e32 v51, v51
	s_nop 0
	v_mul_f32_e32 v51, v85, v51
	v_mul_f32_e32 v51, v84, v51
	s_nop 1
	v_mov_b32_dpp v97, v81 row_ror:2 row_mask:0xf bank_mask:0xf
	v_mov_b32_dpp v101, v80 row_ror:2 row_mask:0xf bank_mask:0xf
	v_mov_b32_dpp v96, v81 row_ror:1 row_mask:0xf bank_mask:0xf
	v_mov_b32_dpp v100, v80 row_ror:1 row_mask:0xf bank_mask:0xf
	v_cndmask_b32_e64 v87, v105, v97, s[40:41]
	v_cndmask_b32_e64 v86, v115, v101, s[40:41]
	v_cndmask_b32_e64 v85, v96, v83, s[38:39]
	v_cndmask_b32_e64 v84, v100, v111, s[38:39]
	v_pk_fma_f32 v[86:87], v[36:37], v[86:87], v[38:39]
	s_nop 0
	v_pk_fma_f32 v[84:85], v[34:35], v[84:85], v[86:87]
	s_nop 0
	v_pk_fma_f32 v[80:81], v[40:41], v[80:81], v[84:85]
	s_nop 0
	v_mul_f32_e32 v69, 0xbfb8aa3b, v81
	v_exp_f32_e32 v69, v69
	s_nop 0
	v_add_f32_e32 v69, 1.0, v69
	v_rcp_f32_e32 v69, v69
	s_nop 0
	v_mul_f32_e32 v69, v81, v69
	v_mul_f32_e32 v69, v80, v69
	s_nop 1
	v_mov_b32_dpp v86, v67 row_ror:2 row_mask:0xf bank_mask:0xf
	v_mov_b32_dpp v102, v66 row_ror:2 row_mask:0xf bank_mask:0xf
	v_mov_b32_dpp v83, v67 row_ror:1 row_mask:0xf bank_mask:0xf
	v_mov_b32_dpp v87, v66 row_ror:1 row_mask:0xf bank_mask:0xf
	v_cndmask_b32_e64 v85, v97, v86, s[40:41]
	v_cndmask_b32_e64 v84, v101, v102, s[40:41]
	v_cndmask_b32_e64 v81, v83, v96, s[38:39]
	v_cndmask_b32_e64 v80, v87, v100, s[38:39]
	v_pk_fma_f32 v[84:85], v[36:37], v[84:85], v[38:39]
	s_nop 0
	v_pk_fma_f32 v[80:81], v[34:35], v[80:81], v[84:85]
	s_nop 0
	v_pk_fma_f32 v[66:67], v[40:41], v[66:67], v[80:81]
	s_nop 0
	v_mul_f32_e32 v80, 0xbfb8aa3b, v67
	v_exp_f32_e32 v80, v80
	s_nop 0
	v_add_f32_e32 v80, 1.0, v80
	v_rcp_f32_e32 v80, v80
	s_nop 0
	v_mul_f32_e32 v67, v67, v80
	v_mul_f32_e32 v66, v66, v67
	s_nop 1
	v_mov_b32_dpp v97, v49 row_ror:2 row_mask:0xf bank_mask:0xf
	v_mov_b32_dpp v101, v48 row_ror:2 row_mask:0xf bank_mask:0xf
	v_mov_b32_dpp v96, v49 row_ror:1 row_mask:0xf bank_mask:0xf
	v_mov_b32_dpp v100, v48 row_ror:1 row_mask:0xf bank_mask:0xf
	v_cndmask_b32_e64 v85, v86, v97, s[40:41]
	v_cndmask_b32_e64 v84, v102, v101, s[40:41]
	v_cndmask_b32_e64 v81, v96, v83, s[38:39]
	v_cndmask_b32_e64 v80, v100, v87, s[38:39]
	v_pk_fma_f32 v[84:85], v[36:37], v[84:85], v[38:39]
	s_nop 0
	v_pk_fma_f32 v[80:81], v[34:35], v[80:81], v[84:85]
	s_nop 0
	v_pk_fma_f32 v[48:49], v[40:41], v[48:49], v[80:81]
	s_nop 0
	v_mul_f32_e32 v67, 0xbfb8aa3b, v49
	v_exp_f32_e32 v67, v67
	s_nop 0
	v_add_f32_e32 v67, 1.0, v67
	v_rcp_f32_e32 v67, v67
	s_nop 0
	v_mul_f32_e32 v49, v49, v67
	v_mul_f32_e32 v48, v48, v49
	s_nop 0
	s_nop 0
	v_mov_b32_dpp v86, v33 row_ror:2 row_mask:0xf bank_mask:0xf
	v_mov_b32_dpp v102, v32 row_ror:2 row_mask:0xf bank_mask:0xf
	v_mov_b32_dpp v83, v33 row_ror:1 row_mask:0xf bank_mask:0xf
	v_mov_b32_dpp v87, v32 row_ror:1 row_mask:0xf bank_mask:0xf
	v_cndmask_b32_e64 v85, v97, v86, s[40:41]
	v_cndmask_b32_e64 v84, v101, v102, s[40:41]
	v_cndmask_b32_e64 v81, v83, v96, s[38:39]
	v_cndmask_b32_e64 v80, v87, v100, s[38:39]
	v_pk_fma_f32 v[84:85], v[36:37], v[84:85], v[38:39]
	s_nop 0
	v_pk_fma_f32 v[80:81], v[34:35], v[80:81], v[84:85]
	s_nop 0
	v_pk_fma_f32 v[32:33], v[40:41], v[32:33], v[80:81]
	s_nop 0
	v_mul_f32_e32 v49, 0xbfb8aa3b, v33
	v_exp_f32_e32 v49, v49
	s_nop 0
	v_add_f32_e32 v49, 1.0, v49
	v_rcp_f32_e32 v49, v49
	s_nop 0
	v_mul_f32_e32 v33, v33, v49
	v_mul_f32_e32 v49, v32, v33
	s_nop 1
	v_mov_b32_dpp v80, v27 row_ror:2 row_mask:0xf bank_mask:0xf
	v_mov_b32_dpp v81, v26 row_ror:1 row_mask:0xf bank_mask:0xf
	v_mov_b32_dpp v84, v26 row_ror:2 row_mask:0xf bank_mask:0xf
; __device__ __forceinline__ float sigmoidf_(float x) { return __builtin_amdgcn_rcpf(1.0f + __expf(-x)); }
; template <int N> __device__ __forceinline__ float dpp_ror(float v) { return __builtin_bit_cast(float, __builtin_amdgcn_update_dpp(0, __builtin_bit_cast(int, v), 0x120 + N, 0xf, 0xf, false)); }
;     __device__ __forceinline__ void operator()(Acc& acc, const Unit& u, int wr, int wc, int fr, int fq) const {
;     ...
;         for (int n = 0; n < 2; ++n) {
; #pragma unroll
;             for (int i = 0; i < 4; ++i) {
;                 const int cg_ = ch0 + 4 * n + i, cv_ = DFF + cg_;
;                 const float g0 = cw[cg_], g1 = cw[NUP + cg_], g2 = cw[2 * NUP + cg_], gb = cb[cg_];
;                 const float v0 = cw[cv_], v1 = cw[NUP + cv_], v2 = cw[2 * NUP + cv_], vb = cb[cv_];
;                 float pg1 = 0.f, pg2 = 0.f, pv1 = 0.f, pv2 = 0.f;
; #pragma unroll
;                 for (int q = 0; q < 8; ++q) {
;                     float cgv = acc[q >> 2][0][q & 3][n][i], cvv = acc[q >> 2][1][q & 3][n][i];
;                     asm volatile("" : "+v"(cgv), "+v"(cvv) : "v"(chain));
;                     const float tg1 = dpp_ror<1>(cgv), tg2 = dpp_ror<2>(cgv), tv1 = dpp_ror<1>(cvv), tv2 = dpp_ror<2>(cvv);
;                     const float sg1 = fr >= 1 ? tg1 : pg1, sg2 = fr >= 2 ? tg2 : pg2, sv1 = fr >= 1 ? tv1 : pv1, sv2 = fr >= 2 ? tv2 : pv2;
;                     const float gg = gb + g0 * sg2 + g1 * sg1 + g2 * cgv;
;                     const float vv = vb + v0 * sv2 + v1 * sv1 + v2 * cvv;
;                     chain = gg * sigmoidf_(gg) * vv; acc[q >> 2][0][q & 3][n][i] = chain;
;                     pg1 = tg1; pg2 = tg2; pv1 = tv1; pv2 = tv2;
;                 }
	v_mov_b32_dpp v67, v27 row_ror:1 row_mask:0xf bank_mask:0xf
	v_cndmask_b32_e64 v32, v81, v87, s[38:39]
	v_cndmask_b32_e64 v81, v86, v80, s[40:41]
	v_cndmask_b32_e64 v80, v102, v84, s[40:41]
	v_cndmask_b32_e64 v33, v67, v83, s[38:39]
	v_pk_fma_f32 v[36:37], v[36:37], v[80:81], v[38:39]
	s_nop 0
	v_pk_fma_f32 v[32:33], v[34:35], v[32:33], v[36:37]
	s_nop 0
	v_pk_fma_f32 v[26:27], v[40:41], v[26:27], v[32:33]
	s_nop 0
	v_mul_f32_e32 v32, 0xbfb8aa3b, v27
	v_exp_f32_e32 v32, v32
	s_nop 0
	v_add_f32_e32 v32, 1.0, v32
	v_rcp_f32_e32 v32, v32
	s_nop 0
	v_mul_f32_e32 v27, v27, v32
	v_mul_f32_e32 v38, v26, v27
	global_load_dword v33, v[6:7], off offset:24
	global_load_dword v27, v[8:9], off offset:2072
	global_load_dword v26, v[10:11], off offset:24
	global_load_dword v35, v[16:17], off offset:24
	global_load_dword v34, v[20:21], off offset:3096
	global_load_dword v32, v[18:19], off offset:3096
	global_load_dword v41, v[22:23], off offset:1048
	global_load_dword v40, v[24:25], off offset:3096
	s_nop 0
	s_nop 0
	s_nop 0
	s_nop 0
	v_mov_b32_dpp v67, v122 row_ror:1 row_mask:0xf bank_mask:0xf
	v_mov_b32_dpp v83, v122 row_ror:2 row_mask:0xf bank_mask:0xf
	v_cndmask_b32_e64 v123, v67, 0, s[38:39]
	v_cndmask_b32_e64 v36, 0, v83, s[40:41]
	v_mov_b32_dpp v84, v124 row_ror:1 row_mask:0xf bank_mask:0xf
	v_cndmask_b32_e64 v125, v84, 0, s[38:39]
	v_mov_b32_dpp v85, v124 row_ror:2 row_mask:0xf bank_mask:0xf
	v_cndmask_b32_e64 v39, 0, v85, s[40:41]
	s_nop 0
	s_nop 0
	s_nop 0
	s_nop 0
	s_nop 0
	s_waitcnt vmcnt(4)
	v_fma_f32 v80, v33, v36, v35
	v_pk_mul_f32 v[36:37], v[26:27], v[122:123]
	s_waitcnt vmcnt(2)
	v_fma_f32 v39, v32, v39, v34
	v_add_f32_e32 v37, v37, v80
	v_add_f32_e32 v100, v36, v37
	v_mul_f32_e32 v36, 0xbfb8aa3b, v100
	v_exp_f32_e32 v101, v36
	v_mov_b32_e32 v37, v26
	s_waitcnt vmcnt(0)
	v_pk_mul_f32 v[80:81], v[40:41], v[124:125]
	v_mov_b32_e32 v36, v40
	v_add_f32_e32 v26, 1.0, v101
	v_rcp_f32_e32 v40, v26
	v_add_f32_e32 v39, v81, v39
	v_add_f32_e32 v39, v80, v39
	v_mov_b32_e32 v26, v41
	v_mul_f32_e32 v40, v100, v40
	v_mul_f32_e32 v39, v39, v40
	s_nop 0
	s_nop 0
	v_mov_b32_dpp v87, v113 row_ror:2 row_mask:0xf bank_mask:0xf
	v_mov_b32_dpp v97, v112 row_ror:2 row_mask:0xf bank_mask:0xf
	v_mov_b32_dpp v86, v113 row_ror:1 row_mask:0xf bank_mask:0xf
	v_mov_b32_dpp v96, v112 row_ror:1 row_mask:0xf bank_mask:0xf
	v_cndmask_b32_e64 v81, v83, v87, s[40:41]
	v_cndmask_b32_e64 v80, v85, v97, s[40:41]
	v_cndmask_b32_e64 v41, v86, v67, s[38:39]
	v_cndmask_b32_e64 v40, v96, v84, s[38:39]
	v_pk_fma_f32 v[80:81], v[32:33], v[80:81], v[34:35]
	s_nop 0
	v_pk_fma_f32 v[40:41], v[26:27], v[40:41], v[80:81]
	s_nop 0
	v_pk_fma_f32 v[40:41], v[36:37], v[112:113], v[40:41]
	s_nop 0
	v_mul_f32_e32 v67, 0xbfb8aa3b, v41
	v_exp_f32_e32 v67, v67
	s_nop 0
	v_add_f32_e32 v67, 1.0, v67
	v_rcp_f32_e32 v67, v67
	s_nop 0
	v_mul_f32_e32 v41, v41, v67
	v_mul_f32_e32 v40, v40, v41
	s_nop 1
	v_mov_b32_dpp v100, v95 row_ror:2 row_mask:0xf bank_mask:0xf
	v_mov_b32_dpp v102, v94 row_ror:2 row_mask:0xf bank_mask:0xf
	v_mov_b32_dpp v83, v95 row_ror:1 row_mask:0xf bank_mask:0xf
	v_mov_b32_dpp v101, v94 row_ror:1 row_mask:0xf bank_mask:0xf
	v_cndmask_b32_e64 v85, v87, v100, s[40:41]
	v_cndmask_b32_e64 v84, v97, v102, s[40:41]
	v_cndmask_b32_e64 v81, v83, v86, s[38:39]
	v_cndmask_b32_e64 v80, v101, v96, s[38:39]
	v_pk_fma_f32 v[84:85], v[32:33], v[84:85], v[34:35]
	s_nop 0
	v_pk_fma_f32 v[80:81], v[26:27], v[80:81], v[84:85]
	s_nop 0
	v_pk_fma_f32 v[80:81], v[36:37], v[94:95], v[80:81]
	s_nop 0
	v_mul_f32_e32 v41, 0xbfb8aa3b, v81
	v_exp_f32_e32 v41, v41
	s_nop 0
	s_nop 0
	v_add_f32_e32 v41, 1.0, v41
	v_rcp_f32_e32 v41, v41
	s_nop 0
	v_mul_f32_e32 v41, v81, v41
	v_mul_f32_e32 v41, v80, v41
	s_nop 1
	v_mov_b32_dpp v87, v79 row_ror:2 row_mask:0xf bank_mask:0xf
	v_mov_b32_dpp v95, v78 row_ror:2 row_mask:0xf bank_mask:0xf
	v_mov_b32_dpp v86, v79 row_ror:1 row_mask:0xf bank_mask:0xf
	v_mov_b32_dpp v94, v78 row_ror:1 row_mask:0xf bank_mask:0xf
	v_cndmask_b32_e64 v85, v100, v87, s[40:41]
	v_cndmask_b32_e64 v84, v102, v95, s[40:41]
	v_cndmask_b32_e64 v81, v86, v83, s[38:39]
	v_cndmask_b32_e64 v80, v94, v101, s[38:39]
	v_pk_fma_f32 v[84:85], v[32:33], v[84:85], v[34:35]
	s_nop 0
	v_pk_fma_f32 v[80:81], v[26:27], v[80:81], v[84:85]
	s_nop 0
	v_pk_fma_f32 v[78:79], v[36:37], v[78:79], v[80:81]
	s_nop 0
	v_mul_f32_e32 v67, 0xbfb8aa3b, v79
	v_exp_f32_e32 v67, v67
	s_nop 0
	v_add_f32_e32 v67, 1.0, v67
	v_rcp_f32_e32 v67, v67
	s_nop 0
	v_mul_f32_e32 v67, v79, v67
	v_mul_f32_e32 v67, v78, v67
	s_nop 1
	v_mov_b32_dpp v84, v65 row_ror:2 row_mask:0xf bank_mask:0xf
	v_mov_b32_dpp v96, v64 row_ror:2 row_mask:0xf bank_mask:0xf
	v_mov_b32_dpp v83, v65 row_ror:1 row_mask:0xf bank_mask:0xf
	v_mov_b32_dpp v85, v64 row_ror:1 row_mask:0xf bank_mask:0xf
	v_cndmask_b32_e64 v81, v87, v84, s[40:41]
	v_cndmask_b32_e64 v80, v95, v96, s[40:41]
	v_cndmask_b32_e64 v79, v83, v86, s[38:39]
	v_cndmask_b32_e64 v78, v85, v94, s[38:39]
	v_pk_fma_f32 v[80:81], v[32:33], v[80:81], v[34:35]
	s_nop 0
	v_pk_fma_f32 v[78:79], v[26:27], v[78:79], v[80:81]
	s_nop 0
	v_pk_fma_f32 v[64:65], v[36:37], v[64:65], v[78:79]
	s_nop 0
	v_mul_f32_e32 v78, 0xbfb8aa3b, v65
	v_exp_f32_e32 v78, v78
	s_nop 0
	v_add_f32_e32 v78, 1.0, v78
	v_rcp_f32_e32 v78, v78
	s_nop 0
	v_mul_f32_e32 v65, v65, v78
	v_mul_f32_e32 v64, v64, v65
	s_nop 1
	v_mov_b32_dpp v87, v47 row_ror:2 row_mask:0xf bank_mask:0xf
	v_mov_b32_dpp v95, v46 row_ror:2 row_mask:0xf bank_mask:0xf
	v_mov_b32_dpp v86, v47 row_ror:1 row_mask:0xf bank_mask:0xf
	v_mov_b32_dpp v94, v46 row_ror:1 row_mask:0xf bank_mask:0xf
	v_cndmask_b32_e64 v81, v84, v87, s[40:41]
	v_cndmask_b32_e64 v80, v96, v95, s[40:41]
; __device__ __forceinline__ float sigmoidf_(float x) { return __builtin_amdgcn_rcpf(1.0f + __expf(-x)); }
; template <int N> __device__ __forceinline__ float dpp_ror(float v) { return __builtin_bit_cast(float, __builtin_amdgcn_update_dpp(0, __builtin_bit_cast(int, v), 0x120 + N, 0xf, 0xf, false)); }
;     __device__ __forceinline__ void operator()(Acc& acc, const Unit& u, int wr, int wc, int fr, int fq) const {
;     ...
;             for (int i = 0; i < 4; ++i) {
;                 const int cg_ = ch0 + 4 * n + i, cv_ = DFF + cg_;
;                 const float g0 = cw[cg_], g1 = cw[NUP + cg_], g2 = cw[2 * NUP + cg_], gb = cb[cg_];
;                 const float v0 = cw[cv_], v1 = cw[NUP + cv_], v2 = cw[2 * NUP + cv_], vb = cb[cv_];
;                 float pg1 = 0.f, pg2 = 0.f, pv1 = 0.f, pv2 = 0.f;
; #pragma unroll
;                 for (int q = 0; q < 8; ++q) {
;                     float cgv = acc[q >> 2][0][q & 3][n][i], cvv = acc[q >> 2][1][q & 3][n][i];
;                     asm volatile("" : "+v"(cgv), "+v"(cvv) : "v"(chain));
;                     const float tg1 = dpp_ror<1>(cgv), tg2 = dpp_ror<2>(cgv), tv1 = dpp_ror<1>(cvv), tv2 = dpp_ror<2>(cvv);
;                     const float sg1 = fr >= 1 ? tg1 : pg1, sg2 = fr >= 2 ? tg2 : pg2, sv1 = fr >= 1 ? tv1 : pv1, sv2 = fr >= 2 ? tv2 : pv2;
;                     const float gg = gb + g0 * sg2 + g1 * sg1 + g2 * cgv;
;                     const float vv = vb + v0 * sv2 + v1 * sv1 + v2 * cvv;
;                     chain = gg * sigmoidf_(gg) * vv; acc[q >> 2][0][q & 3][n][i] = chain;
;                     pg1 = tg1; pg2 = tg2; pv1 = tv1; pv2 = tv2;
;                 }
	v_cndmask_b32_e64 v79, v86, v83, s[38:39]
	v_cndmask_b32_e64 v78, v94, v85, s[38:39]
	v_pk_fma_f32 v[80:81], v[32:33], v[80:81], v[34:35]
	s_nop 0
	v_pk_fma_f32 v[78:79], v[26:27], v[78:79], v[80:81]
	s_nop 0
	v_pk_fma_f32 v[46:47], v[36:37], v[46:47], v[78:79]
	s_nop 0
	v_mul_f32_e32 v65, 0xbfb8aa3b, v47
	v_exp_f32_e32 v65, v65
	s_nop 0
	v_add_f32_e32 v65, 1.0, v65
	v_rcp_f32_e32 v65, v65
	s_nop 0
	v_mul_f32_e32 v47, v47, v65
	v_mul_f32_e32 v46, v46, v47
	s_nop 0
	s_nop 0
	v_mov_b32_dpp v84, v31 row_ror:2 row_mask:0xf bank_mask:0xf
	v_mov_b32_dpp v96, v30 row_ror:2 row_mask:0xf bank_mask:0xf
	v_mov_b32_dpp v83, v31 row_ror:1 row_mask:0xf bank_mask:0xf
	v_mov_b32_dpp v85, v30 row_ror:1 row_mask:0xf bank_mask:0xf
	v_cndmask_b32_e64 v81, v87, v84, s[40:41]
	v_cndmask_b32_e64 v80, v95, v96, s[40:41]
	v_cndmask_b32_e64 v79, v83, v86, s[38:39]
	v_cndmask_b32_e64 v78, v85, v94, s[38:39]
	v_pk_fma_f32 v[80:81], v[32:33], v[80:81], v[34:35]
	s_nop 0
	v_pk_fma_f32 v[78:79], v[26:27], v[78:79], v[80:81]
	s_nop 0
	v_pk_fma_f32 v[30:31], v[36:37], v[30:31], v[78:79]
	s_nop 0
	v_mul_f32_e32 v47, 0xbfb8aa3b, v31
	v_exp_f32_e32 v47, v47
	s_nop 0
	v_add_f32_e32 v47, 1.0, v47
	v_rcp_f32_e32 v47, v47
	s_nop 0
	v_mul_f32_e32 v31, v31, v47
	v_mul_f32_e32 v30, v30, v31
	s_nop 1
	v_mov_b32_dpp v80, v15 row_ror:2 row_mask:0xf bank_mask:0xf
	v_mov_b32_dpp v86, v14 row_ror:2 row_mask:0xf bank_mask:0xf
	v_mov_b32_dpp v65, v15 row_ror:1 row_mask:0xf bank_mask:0xf
	v_mov_b32_dpp v78, v14 row_ror:1 row_mask:0xf bank_mask:0xf
	v_cndmask_b32_e64 v81, v84, v80, s[40:41]
	v_cndmask_b32_e64 v80, v96, v86, s[40:41]
	v_cndmask_b32_e64 v79, v65, v83, s[38:39]
	v_cndmask_b32_e64 v78, v78, v85, s[38:39]
	v_pk_fma_f32 v[32:33], v[32:33], v[80:81], v[34:35]
	s_nop 0
	v_pk_fma_f32 v[26:27], v[26:27], v[78:79], v[32:33]
	s_nop 0
	v_pk_fma_f32 v[14:15], v[36:37], v[14:15], v[26:27]
	s_nop 0
	v_mul_f32_e32 v26, 0xbfb8aa3b, v15
	v_exp_f32_e32 v26, v26
	s_nop 0
	v_add_f32_e32 v26, 1.0, v26
	v_rcp_f32_e32 v26, v26
	s_nop 0
	v_mul_f32_e32 v15, v15, v26
	v_mul_f32_e32 v26, v14, v15
	global_load_dword v15, v[6:7], off offset:28
	s_nop 0
	global_load_dword v7, v[8:9], off offset:2076
	global_load_dword v6, v[10:11], off offset:28
	s_nop 0
	global_load_dword v9, v[16:17], off offset:28
	global_load_dword v14, v[18:19], off offset:3100
	s_nop 0
	global_load_dword v17, v[22:23], off offset:1052
	global_load_dword v16, v[24:25], off offset:3100
	global_load_dword v8, v[20:21], off offset:3100
	s_nop 0
	s_nop 0
	s_nop 0
	s_nop 0
	v_mov_b32_dpp v19, v120 row_ror:1 row_mask:0xf bank_mask:0xf
	v_mov_b32_dpp v22, v120 row_ror:2 row_mask:0xf bank_mask:0xf
	v_cndmask_b32_e64 v121, v19, 0, s[38:39]
	v_cndmask_b32_e64 v10, 0, v22, s[40:41]
	v_mov_b32_dpp v20, v110 row_ror:1 row_mask:0xf bank_mask:0xf
	v_mov_b32_dpp v24, v110 row_ror:2 row_mask:0xf bank_mask:0xf
	v_cndmask_b32_e64 v111, v20, 0, s[38:39]
	v_cndmask_b32_e64 v18, 0, v24, s[40:41]
	s_nop 0
	s_nop 0
	s_nop 0
	s_nop 0
	s_nop 0
	s_nop 0
	v_mov_b32_e32 v35, v3
	v_mov_b32_e32 v36, v3
	s_waitcnt vmcnt(4)
	v_fma_f32 v21, v15, v10, v9
	v_pk_mul_f32 v[10:11], v[6:7], v[120:121]
	s_waitcnt vmcnt(0)
; __device__ __forceinline__ unsigned pk2(float lo, float hi) { const f32x2_t v = {lo, hi}; const bf16x2_t b = __builtin_convertvector(v, bf16x2_t); return __builtin_bit_cast(unsigned, b); }
; __device__ __forceinline__ float sigmoidf_(float x) { return __builtin_amdgcn_rcpf(1.0f + __expf(-x)); }
; template <int N> __device__ __forceinline__ float dpp_ror(float v) { return __builtin_bit_cast(float, __builtin_amdgcn_update_dpp(0, __builtin_bit_cast(int, v), 0x120 + N, 0xf, 0xf, false)); }
;     __device__ __forceinline__ void operator()(Acc& acc, const Unit& u, int wr, int wc, int fr, int fq) const {
;     ...
;                 for (int q = 0; q < 8; ++q) {
;                     float cgv = acc[q >> 2][0][q & 3][n][i], cvv = acc[q >> 2][1][q & 3][n][i];
;                     asm volatile("" : "+v"(cgv), "+v"(cvv) : "v"(chain));
;                     const float tg1 = dpp_ror<1>(cgv), tg2 = dpp_ror<2>(cgv), tv1 = dpp_ror<1>(cvv), tv2 = dpp_ror<2>(cvv);
;                     const float sg1 = fr >= 1 ? tg1 : pg1, sg2 = fr >= 2 ? tg2 : pg2, sv1 = fr >= 1 ? tv1 : pv1, sv2 = fr >= 2 ? tv2 : pv2;
;                     const float gg = gb + g0 * sg2 + g1 * sg1 + g2 * cgv;
;                     const float vv = vb + v0 * sv2 + v1 * sv1 + v2 * cvv;
;                     chain = gg * sigmoidf_(gg) * vv; acc[q >> 2][0][q & 3][n][i] = chain;
;                     pg1 = tg1; pg2 = tg2; pv1 = tv1; pv2 = tv2;
;                 }
;                 __builtin_amdgcn_sched_barrier(0);
;             }
;         }
; #pragma unroll
;         for (int q = 0; q < 8; ++q) {
;             const int t = tbase + 16 * q;
;             if ((16 * q + fr >= 2) && (t < SEQ)) {
;                 const f32x4 a0 = acc[q >> 2][0][q & 3][0], a1 = acc[q >> 2][0][q & 3][1];
;                 u32x4 w; w.x = pk2(a0[0], a0[1]); w.y = pk2(a0[2], a0[3]); w.z = pk2(a1[0], a1[1]); w.w = pk2(a1[2], a1[3]);
;                 *(u32x4*)(act + (size_t)(b * SEQ + t) * DFF + ch0) = w;
;             }
	v_fma_f32 v18, v14, v18, v8
	v_add_f32_e32 v11, v11, v21
	v_add_f32_e32 v21, v10, v11
	v_pk_mul_f32 v[10:11], v[16:17], v[110:111]
	s_nop 0
	v_add_f32_e32 v11, v11, v18
	v_add_f32_e32 v10, v10, v11
	v_mul_f32_e32 v11, 0xbfb8aa3b, v21
	v_exp_f32_e32 v11, v11
	s_nop 0
	v_add_f32_e32 v11, 1.0, v11
	v_rcp_f32_e32 v11, v11
	s_nop 0
	v_mul_f32_e32 v11, v21, v11
	v_mul_f32_e32 v18, v10, v11
	v_mov_b32_e32 v11, v6
	v_mov_b32_e32 v6, v17
	v_mov_b32_dpp v27, v109 row_ror:2 row_mask:0xf bank_mask:0xf
	v_mov_b32_dpp v32, v108 row_ror:2 row_mask:0xf bank_mask:0xf
	v_mov_b32_dpp v25, v109 row_ror:1 row_mask:0xf bank_mask:0xf
	v_mov_b32_dpp v31, v108 row_ror:1 row_mask:0xf bank_mask:0xf
	v_cndmask_b32_e64 v23, v22, v27, s[40:41]
	v_cndmask_b32_e64 v22, v24, v32, s[40:41]
	v_cndmask_b32_e64 v21, v25, v19, s[38:39]
	v_cndmask_b32_e64 v20, v31, v20, s[38:39]
	v_pk_fma_f32 v[22:23], v[14:15], v[22:23], v[8:9]
	v_mov_b32_e32 v10, v16
	v_pk_fma_f32 v[16:17], v[6:7], v[20:21], v[22:23]
	s_nop 0
	v_pk_fma_f32 v[16:17], v[10:11], v[108:109], v[16:17]
	s_nop 0
	v_mul_f32_e32 v19, 0xbfb8aa3b, v17
	v_exp_f32_e32 v19, v19
	s_nop 0
	v_add_f32_e32 v19, 1.0, v19
	v_rcp_f32_e32 v19, v19
	s_nop 0
	v_mul_f32_e32 v17, v17, v19
	v_mul_f32_e32 v16, v16, v17
	s_nop 0
	s_nop 0
	v_mov_b32_dpp v24, v93 row_ror:2 row_mask:0xf bank_mask:0xf
	v_mov_b32_dpp v34, v92 row_ror:2 row_mask:0xf bank_mask:0xf
	v_mov_b32_dpp v19, v93 row_ror:1 row_mask:0xf bank_mask:0xf
	v_mov_b32_dpp v33, v92 row_ror:1 row_mask:0xf bank_mask:0xf
	v_cndmask_b32_e64 v23, v27, v24, s[40:41]
	v_cndmask_b32_e64 v22, v32, v34, s[40:41]
	v_cndmask_b32_e64 v21, v19, v25, s[38:39]
	v_cndmask_b32_e64 v20, v33, v31, s[38:39]
	v_pk_fma_f32 v[22:23], v[14:15], v[22:23], v[8:9]
	s_nop 0
	v_pk_fma_f32 v[20:21], v[6:7], v[20:21], v[22:23]
	s_nop 0
	v_pk_fma_f32 v[20:21], v[10:11], v[92:93], v[20:21]
	s_nop 0
	v_mul_f32_e32 v17, 0xbfb8aa3b, v21
	v_exp_f32_e32 v17, v17
	s_nop 0
	v_add_f32_e32 v17, 1.0, v17
	v_rcp_f32_e32 v17, v17
	s_nop 0
	v_mul_f32_e32 v17, v21, v17
	v_mul_f32_e32 v17, v20, v17
	s_nop 1
	v_mov_b32_dpp v27, v77 row_ror:2 row_mask:0xf bank_mask:0xf
	v_mov_b32_dpp v32, v76 row_ror:2 row_mask:0xf bank_mask:0xf
	v_mov_b32_dpp v25, v77 row_ror:1 row_mask:0xf bank_mask:0xf
	v_mov_b32_dpp v31, v76 row_ror:1 row_mask:0xf bank_mask:0xf
	v_cndmask_b32_e64 v23, v24, v27, s[40:41]
	v_cndmask_b32_e64 v22, v34, v32, s[40:41]
	v_cndmask_b32_e64 v21, v25, v19, s[38:39]
	v_cndmask_b32_e64 v20, v31, v33, s[38:39]
	v_pk_fma_f32 v[22:23], v[14:15], v[22:23], v[8:9]
	s_nop 0
	v_pk_fma_f32 v[20:21], v[6:7], v[20:21], v[22:23]
	s_nop 0
	v_pk_fma_f32 v[20:21], v[10:11], v[76:77], v[20:21]
	s_nop 0
	v_mul_f32_e32 v19, 0xbfb8aa3b, v21
	v_exp_f32_e32 v19, v19
	s_nop 0
	v_add_f32_e32 v19, 1.0, v19
	v_rcp_f32_e32 v19, v19
	s_nop 0
	v_mul_f32_e32 v19, v21, v19
	v_mul_f32_e32 v19, v20, v19
	s_nop 1
	v_mov_b32_dpp v33, v61 row_ror:2 row_mask:0xf bank_mask:0xf
	v_mov_b32_dpp v35, v60 row_ror:2 row_mask:0xf bank_mask:0xf
	v_mov_b32_dpp v24, v61 row_ror:1 row_mask:0xf bank_mask:0xf
	v_mov_b32_dpp v34, v60 row_ror:1 row_mask:0xf bank_mask:0xf
	v_cndmask_b32_e64 v23, v27, v33, s[40:41]
	v_cndmask_b32_e64 v22, v32, v35, s[40:41]
	v_cndmask_b32_e64 v21, v24, v25, s[38:39]
	v_cndmask_b32_e64 v20, v34, v31, s[38:39]
	v_pk_fma_f32 v[22:23], v[14:15], v[22:23], v[8:9]
	s_nop 0
	v_pk_fma_f32 v[20:21], v[6:7], v[20:21], v[22:23]
	s_nop 0
	v_pk_fma_f32 v[20:21], v[10:11], v[60:61], v[20:21]
	s_nop 0
	v_mul_f32_e32 v22, 0xbfb8aa3b, v21
	v_exp_f32_e32 v22, v22
	s_nop 0
	v_add_f32_e32 v22, 1.0, v22
	v_rcp_f32_e32 v22, v22
	s_nop 0
	v_mul_f32_e32 v21, v21, v22
	v_mul_f32_e32 v20, v20, v21
	s_nop 1
	v_mov_b32_dpp v27, v45 row_ror:1 row_mask:0xf bank_mask:0xf
	v_mov_b32_dpp v31, v45 row_ror:2 row_mask:0xf bank_mask:0xf
	v_mov_b32_dpp v36, v44 row_ror:2 row_mask:0xf bank_mask:0xf
	v_mov_b32_dpp v32, v44 row_ror:1 row_mask:0xf bank_mask:0xf
	v_cndmask_b32_e64 v23, v27, v24, s[38:39]
	v_cndmask_b32_e64 v25, v33, v31, s[40:41]
	v_cndmask_b32_e64 v24, v35, v36, s[40:41]
	v_cndmask_b32_e64 v22, v32, v34, s[38:39]
	v_pk_fma_f32 v[24:25], v[14:15], v[24:25], v[8:9]
	s_nop 0
	v_pk_fma_f32 v[22:23], v[6:7], v[22:23], v[24:25]
	s_nop 0
	v_pk_fma_f32 v[22:23], v[10:11], v[44:45], v[22:23]
	s_nop 0
	v_mul_f32_e32 v21, 0xbfb8aa3b, v23
	v_exp_f32_e32 v21, v21
	s_nop 0
	v_add_f32_e32 v21, 1.0, v21
	v_rcp_f32_e32 v21, v21
	s_nop 0
	v_mul_f32_e32 v21, v23, v21
	v_mul_f32_e32 v24, v22, v21
	s_nop 0
	s_nop 0
	s_nop 0
	v_mov_b32_dpp v22, v29 row_ror:2 row_mask:0xf bank_mask:0xf
	v_mov_b32_dpp v25, v28 row_ror:2 row_mask:0xf bank_mask:0xf
	v_mov_b32_dpp v21, v29 row_ror:1 row_mask:0xf bank_mask:0xf
	v_mov_b32_dpp v23, v28 row_ror:1 row_mask:0xf bank_mask:0xf
	v_cndmask_b32_e64 v35, v31, v22, s[40:41]
	v_cndmask_b32_e64 v34, v36, v25, s[40:41]
	v_cndmask_b32_e64 v33, v21, v27, s[38:39]
	v_cndmask_b32_e64 v32, v23, v32, s[38:39]
	v_pk_fma_f32 v[34:35], v[14:15], v[34:35], v[8:9]
	s_nop 0
	v_pk_fma_f32 v[32:33], v[6:7], v[32:33], v[34:35]
	s_nop 0
	v_pk_fma_f32 v[28:29], v[10:11], v[28:29], v[32:33]
	s_nop 0
	v_mul_f32_e32 v27, 0xbfb8aa3b, v29
	v_exp_f32_e32 v27, v27
	s_nop 0
	v_add_f32_e32 v27, 1.0, v27
	v_rcp_f32_e32 v27, v27
	s_nop 0
	v_mul_f32_e32 v27, v29, v27
	v_mul_f32_e32 v27, v28, v27
	s_nop 0
	s_nop 0
	s_nop 1
	v_mov_b32_dpp v28, v13 row_ror:1 row_mask:0xf bank_mask:0xf
	v_mov_b32_dpp v29, v13 row_ror:2 row_mask:0xf bank_mask:0xf
	v_mov_b32_dpp v31, v12 row_ror:1 row_mask:0xf bank_mask:0xf
	v_mov_b32_dpp v32, v12 row_ror:2 row_mask:0xf bank_mask:0xf
	v_cmp_gt_i32_e32 vcc, s97, v198
	s_and_b64 s[44:45], s[40:41], vcc
	s_and_saveexec_b64 s[34:35], s[44:45]
	s_cbranch_execz .LBB0_45
	v_cvt_pk_bf16_f32 v37, v39, v18
	v_add_u32_e32 v18, s20, v198
	v_mov_b64_e32 v[44:45], s[8:9]
	s_movk_i32 s21, 0x1600
	v_mad_i64_i32 v[44:45], s[44:45], v18, s21, v[44:45]
	v_cvt_pk_bf16_f32 v34, v184, v137
	v_cvt_pk_bf16_f32 v35, v99, v63
	v_cvt_pk_bf16_f32 v36, v56, v43
	v_lshl_add_u64 v[44:45], v[4:5], 1, v[44:45]
	flat_store_dwordx4 v[44:45], v[34:37]

; __device__ __forceinline__ void ld8bf(const bf16_t* p, float (&o)[8]) { unpack8(*(const u32x4*)p, o); }
; __device__ __forceinline__ float sigmoidf_(float x) { return __builtin_amdgcn_rcpf(1.0f + __expf(-x)); }
; __device__ __forceinline__ bf16x8 pack_frag(const float (&v)[8]) { return __builtin_bit_cast(bf16x8, pack8(v)); }
; __device__ __forceinline__ void hg_lf_key(float fp, float lb, float& lf, float& key) {
;     const float e = __expf(-fabsf(fp));
;     const float rc = __builtin_amdgcn_rcpf(1.0f + e);
;     const float sp = fp >= 0.f ? rc : e * rc;
;     const float sn = fp >= 0.f ? e * rc : rc;
;     const float lsig = (fp >= 0.f ? 0.f : fp) + __logf(rc);
;     lf = (lb == 0.f) ? lsig : __logf(lb + (1.0f - lb) * sp); key = (1.0f - lb) * sn;
; __device__ __forceinline__ void w_hg_m3(const Args& a, int l, unsigned char* ws, const bf16_t* proj, bf16_t* y, LAS unsigned char* wl, int b, int ck_, int h, int lane) {
;     ...
;         for (int tb = 0; tb < 4; ++tb) { float fp[8], qv[8], a1[8], a2[8];
;             ld8bf(fsrc + (size_t)(16 * tb + lo) * NIN, fp); ld8bf(proj + (size_t)(row0 + 16 * tb + lo) * NIN + C_HQ + 64 * h + 32 * kk + 8 * fq, qv);
; #pragma unroll
;             for (int j = 0; j < 8; ++j) { float lf, key; hg_lf_key(fp[j], lbv[j], lf, key);
;                 const float q = qv[j] * sigmoidf_(qv[j]); a1[j] = q * __expf(bb[tb][j] - r31[j]); a2[j] = key * __expf(r31[j] - bb[tb][j]); }
;             Qf[tb][kk] = pack_frag(a1); Kf[tb][kk] = pack_frag(a2); }
.LBB0_189:
	s_or_b64 exec, exec, s[34:35]
	s_mov_b64 s[20:21], 0x1000
	v_lshl_add_u64 v[38:39], v[64:65], 0, s[20:21]
	v_lshl_add_u64 v[64:65], v[66:67], 0, s[20:21]
	v_mul_f32_e32 v52, 0x3fb8aa3b, v98
	v_lshlrev_b32_e32 v67, 16, v4
	v_or_b32_e32 v186, 60, v70
	v_lshl_add_u64 v[70:71], v[54:55], 0, s[20:21]
	v_exp_f32_e32 v81, v52
	v_mul_f32_e32 v52, 0x3fb8aa3b, v97
	v_and_b32_e32 v4, 0xffff0000, v4
	v_mul_f32_e64 v54, |v67|, s26
	v_exp_f32_e32 v80, v52
	v_mul_f32_e32 v52, 0x3fb8aa3b, v94
	v_exp_f32_e32 v54, v54
	v_mul_f32_e64 v55, |v4|, s26
	v_exp_f32_e32 v83, v52
	v_mul_f32_e32 v52, 0x3fb8aa3b, v93
	v_exp_f32_e32 v55, v55
	v_exp_f32_e32 v82, v52
	v_mul_f32_e32 v52, 0x3fb8aa3b, v90
	v_exp_f32_e32 v85, v52
	v_mul_f32_e32 v52, 0x3fb8aa3b, v89
	v_add_f32_e32 v53, v151, v153
	v_exp_f32_e32 v84, v52
	v_mul_f32_e32 v52, 0x3fb8aa3b, v74
	v_add_f32_e32 v145, v53, v145
	v_add_f32_e32 v53, 1.0, v54
	v_lshl_add_u64 v[78:79], v[62:63], 0, s[20:21]
	v_exp_f32_e32 v87, v52
	v_mul_f32_e32 v52, 0x3fb8aa3b, v73
	v_rcp_f32_e32 v62, v53
	v_add_f32_e32 v53, 1.0, v55
	v_exp_f32_e32 v86, v52
	v_add_f32_e32 v52, v152, v154
	v_rcp_f32_e32 v63, v53
	v_add_f32_e32 v66, v52, v146
	v_sub_f32_e32 v52, v73, v66
	v_sub_f32_e32 v53, v74, v145
	v_mul_f32_e32 v52, 0x3fb8aa3b, v52
	v_mul_f32_e32 v53, 0x3fb8aa3b, v53
	v_exp_f32_e32 v52, v52
	v_exp_f32_e32 v53, v53
	v_pk_mul_f32 v[54:55], v[54:55], v[62:63]
	v_cmp_le_f32_e32 vcc, 0, v4
	v_pk_add_f32 v[42:43], v[42:43], 1.0 op_sel_hi:[1,0] neg_lo:[1,0] neg_hi:[1,0]
	s_lshl_b32 s20, s90, 2
	v_cndmask_b32_e32 v55, v63, v55, vcc
	v_cmp_le_f32_e32 vcc, 0, v67
	s_lshl_b32 s21, s71, 9
	s_add_i32 s20, s20, s21
	v_cndmask_b32_e32 v54, v62, v54, vcc
	v_pk_mul_f32 v[54:55], v[42:43], v[54:55]
	s_mov_b64 s[34:35], 0x18000
	v_pk_mul_f32 v[52:53], v[52:53], v[54:55]
	s_add_i32 s20, s20, s70
	v_cvt_pk_bf16_f32 v4, v52, v53
	v_pk_add_f32 v[52:53], v[44:45], 1.0 op_sel_hi:[1,0] neg_lo:[1,0] neg_hi:[1,0]
	v_add_f32_e32 v44, v148, v150
	v_add_f32_e32 v67, v44, v139
	v_lshlrev_b32_e32 v139, 16, v5
	v_and_b32_e32 v5, 0xffff0000, v5
	v_mul_f32_e64 v54, |v139|, s26
	v_exp_f32_e32 v54, v54
	v_mul_f32_e64 v55, |v5|, s26
	v_exp_f32_e32 v55, v55
	v_add_f32_e32 v45, v147, v149
	v_add_f32_e32 v138, v45, v138
	v_add_f32_e32 v45, 1.0, v54
	v_rcp_f32_e32 v62, v45
	v_add_f32_e32 v45, 1.0, v55
	v_rcp_f32_e32 v63, v45
	v_sub_f32_e32 v44, v89, v67
	v_sub_f32_e32 v45, v90, v138
	v_mul_f32_e32 v44, 0x3fb8aa3b, v44
	v_mul_f32_e32 v45, 0x3fb8aa3b, v45
	v_exp_f32_e32 v44, v44
	v_exp_f32_e32 v45, v45
	v_pk_mul_f32 v[54:55], v[54:55], v[62:63]
	v_cmp_le_f32_e32 vcc, 0, v5
	v_lshl_add_u64 v[36:37], v[48:49], 0, s[34:35]
	s_mov_b64 s[34:35], 0x30000
	v_cndmask_b32_e32 v55, v63, v55, vcc
	v_cmp_le_f32_e32 vcc, 0, v139
	v_lshlrev_b32_e32 v139, 16, v6
	v_and_b32_e32 v6, 0xffff0000, v6
	v_cndmask_b32_e32 v54, v62, v54, vcc
	v_pk_mul_f32 v[54:55], v[52:53], v[54:55]
	v_cmp_le_f32_e32 vcc, 0, v6
	v_pk_mul_f32 v[44:45], v[44:45], v[54:55]
	v_pk_add_f32 v[54:55], v[46:47], 1.0 op_sel_hi:[1,0] neg_lo:[1,0] neg_hi:[1,0]
	v_mul_f32_e64 v46, |v139|, s26
	v_exp_f32_e32 v46, v46
	v_mul_f32_e64 v47, |v6|, s26
	v_exp_f32_e32 v47, v47
	v_cvt_pk_bf16_f32 v5, v44, v45
	v_add_f32_e32 v45, v140, v142
	v_add_f32_e32 v131, v45, v131
	v_add_f32_e32 v45, 1.0, v46
	v_rcp_f32_e32 v62, v45
	v_add_f32_e32 v45, 1.0, v47
	v_add_f32_e32 v44, v141, v143
	v_rcp_f32_e32 v63, v45
	v_add_f32_e32 v133, v44, v133
	v_sub_f32_e32 v44, v93, v133
	v_sub_f32_e32 v45, v94, v131
	v_mul_f32_e32 v44, 0x3fb8aa3b, v44
	v_mul_f32_e32 v45, 0x3fb8aa3b, v45
	v_exp_f32_e32 v44, v44
	v_exp_f32_e32 v45, v45
	v_pk_mul_f32 v[46:47], v[46:47], v[62:63]
	s_ashr_i32 s21, s20, 31
	v_cndmask_b32_e32 v47, v63, v47, vcc
	v_cmp_le_f32_e32 vcc, 0, v139
	v_lshl_add_u64 v[76:77], v[48:49], 0, s[34:35]
	v_or_b32_e32 v128, 16, v114
	v_cndmask_b32_e32 v46, v62, v46, vcc
	v_pk_mul_f32 v[46:47], v[54:55], v[46:47]
	v_or_b32_e32 v127, 32, v114
	v_pk_mul_f32 v[44:45], v[44:45], v[46:47]
	v_or_b32_e32 v126, 48, v114
	v_cvt_pk_bf16_f32 v6, v44, v45
	v_add_f32_e32 v45, v134, v136
	v_lshlrev_b32_e32 v134, 16, v7
	v_and_b32_e32 v7, 0xffff0000, v7
	v_mul_f32_e64 v46, |v134|, s26
	v_exp_f32_e32 v46, v46
	v_mul_f32_e64 v47, |v7|, s26
	v_exp_f32_e32 v47, v47
	v_add_f32_e32 v125, v45, v125
	v_add_f32_e32 v45, 1.0, v46
	v_rcp_f32_e32 v62, v45
	v_add_f32_e32 v45, 1.0, v47
	v_add_f32_e32 v44, v135, v137
	v_rcp_f32_e32 v63, v45
	v_add_f32_e32 v129, v44, v129
	v_sub_f32_e32 v44, v97, v129
	v_sub_f32_e32 v45, v98, v125
	v_mul_f32_e32 v44, 0x3fb8aa3b, v44
	v_mul_f32_e32 v45, 0x3fb8aa3b, v45
	v_exp_f32_e32 v44, v44
	v_exp_f32_e32 v45, v45
	v_pk_mul_f32 v[46:47], v[46:47], v[62:63]
	v_cmp_le_f32_e32 vcc, 0, v7
	s_lshl_b64 s[40:41], s[20:21], 13
	s_nop 0
	v_cndmask_b32_e32 v47, v63, v47, vcc
	v_cmp_le_f32_e32 vcc, 0, v134
	s_nop 1
	v_cndmask_b32_e32 v46, v62, v46, vcc
	v_pk_mul_f32 v[46:47], v[40:41], v[46:47]
	s_nop 0
	v_pk_mul_f32 v[44:45], v[44:45], v[46:47]
	s_nop 0
	v_cvt_pk_bf16_f32 v7, v44, v45
	v_sub_f32_e32 v44, v66, v73
	v_mul_f32_e32 v46, 0x3fb8aa3b, v44
	v_lshlrev_b32_e32 v44, 16, v8
	v_and_b32_e32 v45, 0xffff0000, v8
	v_mul_f32_e32 v8, 0xbfb8aa3b, v44
	v_exp_f32_e32 v8, v8
	v_mul_f32_e32 v47, 0xbfb8aa3b, v45
	v_exp_f32_e32 v47, v47
	v_lshlrev_b32_e32 v66, 16, v9
	v_add_f32_e32 v8, 1.0, v8
	v_rcp_f32_e32 v62, v8
	v_add_f32_e32 v8, 1.0, v47
	v_rcp_f32_e32 v63, v8
	v_sub_f32_e32 v8, v145, v74
	v_mul_f32_e32 v8, 0x3fb8aa3b, v8
	v_exp_f32_e32 v47, v8
	v_sub_f32_e32 v8, v67, v89
	v_and_b32_e32 v67, 0xffff0000, v9
	v_mul_f32_e32 v9, 0xbfb8aa3b, v66
	v_pk_mul_f32 v[44:45], v[62:63], v[44:45]
	v_exp_f32_e32 v9, v9
	v_mul_f32_e32 v63, 0xbfb8aa3b, v67
; __device__ __forceinline__ void ld8bf(const bf16_t* p, float (&o)[8]) { unpack8(*(const u32x4*)p, o); }
; __device__ __forceinline__ float sigmoidf_(float x) { return __builtin_amdgcn_rcpf(1.0f + __expf(-x)); }
; __device__ __forceinline__ bf16x8 pack_frag(const float (&v)[8]) { return __builtin_bit_cast(bf16x8, pack8(v)); }
; __device__ __forceinline__ void hg_lf_key(float fp, float lb, float& lf, float& key) {
;     const float e = __expf(-fabsf(fp));
;     const float rc = __builtin_amdgcn_rcpf(1.0f + e);
;     const float sp = fp >= 0.f ? rc : e * rc;
;     const float sn = fp >= 0.f ? e * rc : rc;
;     const float lsig = (fp >= 0.f ? 0.f : fp) + __logf(rc);
;     lf = (lb == 0.f) ? lsig : __logf(lb + (1.0f - lb) * sp); key = (1.0f - lb) * sn;
; __device__ __forceinline__ void w_hg_m3(const Args& a, int l, unsigned char* ws, const bf16_t* proj, bf16_t* y, LAS unsigned char* wl, int b, int ck_, int h, int lane) {
;     ...
;         for (int tb = 0; tb < 4; ++tb) { float fp[8], qv[8], a1[8], a2[8];
;             ld8bf(fsrc + (size_t)(16 * tb + lo) * NIN, fp); ld8bf(proj + (size_t)(row0 + 16 * tb + lo) * NIN + C_HQ + 64 * h + 32 * kk + 8 * fq, qv);
; #pragma unroll
;             for (int j = 0; j < 8; ++j) { float lf, key; hg_lf_key(fp[j], lbv[j], lf, key);
;                 const float q = qv[j] * sigmoidf_(qv[j]); a1[j] = q * __expf(bb[tb][j] - r31[j]); a2[j] = key * __expf(r31[j] - bb[tb][j]); }
;             Qf[tb][kk] = pack_frag(a1); Kf[tb][kk] = pack_frag(a2); }
	v_exp_f32_e32 v63, v63
	v_mul_f32_e32 v8, 0x3fb8aa3b, v8
	v_add_f32_e32 v9, 1.0, v9
	v_exp_f32_e32 v62, v8
	v_sub_f32_e32 v8, v138, v90
	v_rcp_f32_e32 v134, v9
	v_add_f32_e32 v9, 1.0, v63
	v_exp_f32_e32 v46, v46
	v_mul_f32_e32 v8, 0x3fb8aa3b, v8
	v_rcp_f32_e32 v135, v9
	v_exp_f32_e32 v63, v8
	v_pk_mul_f32 v[8:9], v[46:47], v[44:45]
	v_pk_mul_f32 v[44:45], v[134:135], v[66:67]
	s_nop 0
	v_pk_mul_f32 v[44:45], v[62:63], v[44:45]
	v_cvt_pk_bf16_f32 v8, v8, v9
	v_cvt_pk_bf16_f32 v9, v44, v45
	v_sub_f32_e32 v44, v133, v93
	v_mul_f32_e32 v46, 0x3fb8aa3b, v44
	v_lshlrev_b32_e32 v44, 16, v10
	v_and_b32_e32 v45, 0xffff0000, v10
	v_mul_f32_e32 v10, 0xbfb8aa3b, v44
	v_exp_f32_e32 v10, v10
	v_mul_f32_e32 v47, 0xbfb8aa3b, v45
	v_exp_f32_e32 v47, v47
	v_lshlrev_b32_e32 v66, 16, v11
	v_add_f32_e32 v10, 1.0, v10
	v_rcp_f32_e32 v62, v10
	v_add_f32_e32 v10, 1.0, v47
	v_rcp_f32_e32 v63, v10
	v_and_b32_e32 v67, 0xffff0000, v11
	v_mul_f32_e32 v11, 0xbfb8aa3b, v66
	v_exp_f32_e32 v11, v11
	v_pk_mul_f32 v[44:45], v[62:63], v[44:45]
	v_mul_f32_e32 v63, 0xbfb8aa3b, v67
	v_sub_f32_e32 v10, v131, v94
	v_exp_f32_e32 v63, v63
	v_mul_f32_e32 v10, 0x3fb8aa3b, v10
	v_exp_f32_e32 v47, v10
	v_sub_f32_e32 v10, v129, v97
	v_mul_f32_e32 v10, 0x3fb8aa3b, v10
	v_add_f32_e32 v11, 1.0, v11
	v_exp_f32_e32 v62, v10
	v_sub_f32_e32 v10, v125, v98
	v_rcp_f32_e32 v134, v11
	v_add_f32_e32 v11, 1.0, v63
	v_exp_f32_e32 v46, v46
	v_mul_f32_e32 v10, 0x3fb8aa3b, v10
	v_rcp_f32_e32 v135, v11
	v_exp_f32_e32 v63, v10
	v_pk_mul_f32 v[10:11], v[46:47], v[44:45]
	v_pk_mul_f32 v[44:45], v[134:135], v[66:67]
	s_nop 0
	v_pk_mul_f32 v[44:45], v[62:63], v[44:45]
	v_cvt_pk_bf16_f32 v10, v10, v11
	v_cvt_pk_bf16_f32 v11, v44, v45
	v_sub_f32_e32 v44, v97, v121
	v_lshlrev_b32_e32 v66, 16, v31
	v_mul_f32_e32 v46, 0x3fb8aa3b, v44
	v_and_b32_e32 v31, 0xffff0000, v31
	v_mul_f32_e64 v44, |v66|, s26
	v_exp_f32_e32 v44, v44
	v_mul_f32_e64 v45, |v31|, s26
	v_exp_f32_e32 v45, v45
	v_cmp_le_f32_e32 vcc, 0, v31
	v_add_f32_e32 v47, 1.0, v44
	v_rcp_f32_e32 v62, v47
	v_add_f32_e32 v47, 1.0, v45
	v_rcp_f32_e32 v63, v47
	v_and_b32_e32 v67, 0xffff0000, v15
	v_sub_f32_e32 v31, v121, v97
	v_sub_f32_e32 v47, v98, v122
	v_pk_mul_f32 v[44:45], v[44:45], v[62:63]
	v_mul_f32_e32 v31, 0x3fb8aa3b, v31
	v_cndmask_b32_e32 v45, v63, v45, vcc
	v_cmp_le_f32_e32 vcc, 0, v66
	v_lshlrev_b32_e32 v66, 16, v15
	v_mul_f32_e32 v15, 0xbfb8aa3b, v66
	v_exp_f32_e32 v15, v15
	v_mul_f32_e32 v63, 0xbfb8aa3b, v67
	v_exp_f32_e32 v63, v63
	v_mul_f32_e32 v47, 0x3fb8aa3b, v47
	v_add_f32_e32 v15, 1.0, v15
	v_cndmask_b32_e32 v44, v62, v44, vcc
	v_exp_f32_e32 v62, v31
	v_sub_f32_e32 v31, v122, v98
	v_rcp_f32_e32 v134, v15
	v_add_f32_e32 v15, 1.0, v63
	v_lshlrev_b32_e32 v121, 16, v30
	v_exp_f32_e32 v46, v46
	v_exp_f32_e32 v47, v47
	v_mul_f32_e32 v31, 0x3fb8aa3b, v31
	v_rcp_f32_e32 v135, v15
	v_and_b32_e32 v122, 0xffff0000, v30
	v_mul_f32_e64 v30, |v121|, s26
	v_exp_f32_e32 v63, v31
	v_exp_f32_e32 v30, v30
	v_mul_f32_e64 v31, |v122|, s26
	v_exp_f32_e32 v31, v31
	v_pk_mul_f32 v[44:45], v[40:41], v[44:45]
	v_sub_f32_e32 v15, v93, v118
	v_pk_mul_f32 v[44:45], v[46:47], v[44:45]
	v_pk_mul_f32 v[46:47], v[134:135], v[66:67]
	v_mul_f32_e32 v15, 0x3fb8aa3b, v15
	v_pk_mul_f32 v[46:47], v[62:63], v[46:47]
	v_exp_f32_e32 v62, v15
	v_add_f32_e32 v15, 1.0, v30
	v_rcp_f32_e32 v66, v15
	v_add_f32_e32 v15, 1.0, v31
	v_rcp_f32_e32 v67, v15
	v_sub_f32_e32 v15, v94, v119
	v_mul_f32_e32 v15, 0x3fb8aa3b, v15
	v_exp_f32_e32 v63, v15
	v_pk_mul_f32 v[30:31], v[30:31], v[66:67]
	v_cmp_le_f32_e32 vcc, 0, v122
	v_sub_f32_e32 v15, v118, v93
	v_mul_f32_e32 v15, 0x3fb8aa3b, v15
	v_cndmask_b32_e32 v31, v67, v31, vcc
	v_cmp_le_f32_e32 vcc, 0, v121
	v_lshlrev_b32_e32 v118, 16, v14
	v_lshlrev_b32_e32 v134, 16, v13
	v_cndmask_b32_e32 v30, v66, v30, vcc
	v_exp_f32_e32 v66, v15
	v_sub_f32_e32 v15, v119, v94
	v_and_b32_e32 v119, 0xffff0000, v14
	v_mul_f32_e32 v14, 0xbfb8aa3b, v118
	v_mul_f32_e32 v67, 0xbfb8aa3b, v119
	v_exp_f32_e32 v14, v14
	v_exp_f32_e32 v67, v67
	v_mul_f32_e32 v121, 0x3fb8aa3b, v15
	v_pk_mul_f32 v[30:31], v[54:55], v[30:31]
	v_add_f32_e32 v14, 1.0, v14
	v_add_f32_e32 v15, 1.0, v67
	v_rcp_f32_e32 v14, v14
	v_rcp_f32_e32 v15, v15
	v_exp_f32_e32 v67, v121
	v_pk_mul_f32 v[30:31], v[62:63], v[30:31]
	v_lshlrev_b32_e32 v121, 16, v29
	v_pk_mul_f32 v[14:15], v[14:15], v[118:119]
	v_and_b32_e32 v29, 0xffff0000, v29
	v_pk_mul_f32 v[62:63], v[66:67], v[14:15]
	v_sub_f32_e32 v14, v89, v115
	v_mul_f32_e32 v66, 0x3fb8aa3b, v14
	v_mul_f32_e64 v14, |v121|, s26
	v_exp_f32_e32 v14, v14
	v_mul_f32_e64 v15, |v29|, s26
	v_exp_f32_e32 v15, v15
	v_and_b32_e32 v135, 0xffff0000, v13
	v_add_f32_e32 v67, 1.0, v14
	v_rcp_f32_e32 v118, v67
	v_add_f32_e32 v67, 1.0, v15
	v_rcp_f32_e32 v119, v67
	v_mul_f32_e32 v13, 0xbfb8aa3b, v134
	v_cmp_le_f32_e32 vcc, 0, v29
	v_sub_f32_e32 v29, v115, v89
	v_exp_f32_e32 v13, v13
	v_mul_f32_e32 v115, 0xbfb8aa3b, v135
	v_exp_f32_e32 v115, v115
	v_pk_mul_f32 v[14:15], v[14:15], v[118:119]
	v_sub_f32_e32 v67, v90, v116
	v_cndmask_b32_e32 v15, v119, v15, vcc
	v_cmp_le_f32_e32 vcc, 0, v121
	v_mul_f32_e32 v29, 0x3fb8aa3b, v29
	v_add_f32_e32 v13, 1.0, v13
	v_mul_f32_e32 v67, 0x3fb8aa3b, v67
	v_cndmask_b32_e32 v14, v118, v14, vcc
	v_exp_f32_e32 v118, v29
	v_sub_f32_e32 v29, v116, v90
	v_rcp_f32_e32 v136, v13
	v_add_f32_e32 v13, 1.0, v115
	v_lshlrev_b32_e32 v115, 16, v28
	v_exp_f32_e32 v66, v66
	v_exp_f32_e32 v67, v67
	v_mul_f32_e32 v29, 0x3fb8aa3b, v29
	v_rcp_f32_e32 v137, v13
	v_and_b32_e32 v116, 0xffff0000, v28
	v_mul_f32_e64 v28, |v115|, s26
	v_exp_f32_e32 v119, v29
	v_exp_f32_e32 v28, v28
	v_mul_f32_e64 v29, |v116|, s26
	v_exp_f32_e32 v29, v29
	v_pk_mul_f32 v[14:15], v[52:53], v[14:15]
; __device__ __forceinline__ void ld8bf(const bf16_t* p, float (&o)[8]) { unpack8(*(const u32x4*)p, o); }
; __device__ __forceinline__ float sigmoidf_(float x) { return __builtin_amdgcn_rcpf(1.0f + __expf(-x)); }
; __device__ __forceinline__ bf16x8 pack_frag(const float (&v)[8]) { return __builtin_bit_cast(bf16x8, pack8(v)); }
; __device__ __forceinline__ void hg_lf_key(float fp, float lb, float& lf, float& key) {
;     const float e = __expf(-fabsf(fp));
;     const float rc = __builtin_amdgcn_rcpf(1.0f + e);
;     const float sp = fp >= 0.f ? rc : e * rc;
;     const float sn = fp >= 0.f ? e * rc : rc;
;     const float lsig = (fp >= 0.f ? 0.f : fp) + __logf(rc);
;     lf = (lb == 0.f) ? lsig : __logf(lb + (1.0f - lb) * sp); key = (1.0f - lb) * sn;
; __device__ __forceinline__ void w_hg_m3(const Args& a, int l, unsigned char* ws, const bf16_t* proj, bf16_t* y, LAS unsigned char* wl, int b, int ck_, int h, int lane) {
;     ...
;         for (int tb = 0; tb < 4; ++tb) { float fp[8], qv[8], a1[8], a2[8];
;             ld8bf(fsrc + (size_t)(16 * tb + lo) * NIN, fp); ld8bf(proj + (size_t)(row0 + 16 * tb + lo) * NIN + C_HQ + 64 * h + 32 * kk + 8 * fq, qv);
; #pragma unroll
;             for (int j = 0; j < 8; ++j) { float lf, key; hg_lf_key(fp[j], lbv[j], lf, key);
;                 const float q = qv[j] * sigmoidf_(qv[j]); a1[j] = q * __expf(bb[tb][j] - r31[j]); a2[j] = key * __expf(r31[j] - bb[tb][j]); }
;             Qf[tb][kk] = pack_frag(a1); Kf[tb][kk] = pack_frag(a2); }
	v_sub_f32_e32 v13, v73, v111
	v_pk_mul_f32 v[14:15], v[66:67], v[14:15]
	v_pk_mul_f32 v[66:67], v[136:137], v[134:135]
	v_mul_f32_e32 v13, 0x3fb8aa3b, v13
	v_pk_mul_f32 v[66:67], v[118:119], v[66:67]
	v_exp_f32_e32 v118, v13
	v_add_f32_e32 v13, 1.0, v28
	v_rcp_f32_e32 v134, v13
	v_add_f32_e32 v13, 1.0, v29
	v_rcp_f32_e32 v135, v13
	v_sub_f32_e32 v13, v74, v112
	v_mul_f32_e32 v13, 0x3fb8aa3b, v13
	v_lshlrev_b32_e32 v136, 16, v12
	v_and_b32_e32 v137, 0xffff0000, v12
	v_exp_f32_e32 v119, v13
	v_sub_f32_e32 v13, v111, v73
	v_mul_f32_e32 v12, 0xbfb8aa3b, v136
	v_mul_f32_e32 v111, 0xbfb8aa3b, v137
	v_exp_f32_e32 v12, v12
	v_exp_f32_e32 v111, v111
	v_pk_mul_f32 v[28:29], v[28:29], v[134:135]
	v_cmp_le_f32_e32 vcc, 0, v116
	v_mul_f32_e32 v13, 0x3fb8aa3b, v13
	v_add_f32_e32 v12, 1.0, v12
	v_cndmask_b32_e32 v29, v135, v29, vcc
	v_cmp_le_f32_e32 vcc, 0, v115
	v_rcp_f32_e32 v12, v12
	s_nop 0
	v_cndmask_b32_e32 v28, v134, v28, vcc
	v_exp_f32_e32 v134, v13
	v_sub_f32_e32 v13, v112, v74
	v_mul_f32_e32 v112, 0x3fb8aa3b, v13
	v_add_f32_e32 v13, 1.0, v111
	v_rcp_f32_e32 v13, v13
	v_exp_f32_e32 v135, v112
	v_pk_mul_f32 v[28:29], v[42:43], v[28:29]
	v_pk_mul_f32 v[12:13], v[12:13], v[136:137]
	v_pk_mul_f32 v[28:29], v[118:119], v[28:29]
	v_pk_mul_f32 v[118:119], v[134:135], v[12:13]
	v_cvt_pk_bf16_f32 v12, v28, v29
	v_cvt_pk_bf16_f32 v13, v14, v15
	v_cvt_pk_bf16_f32 v15, v44, v45
	v_cvt_pk_bf16_f32 v29, v66, v67
	v_sub_f32_e32 v44, v97, v107
	v_lshlrev_b32_e32 v66, 16, v35
	v_cvt_pk_bf16_f32 v14, v30, v31
	v_cvt_pk_bf16_f32 v31, v46, v47
	v_mul_f32_e32 v46, 0x3fb8aa3b, v44
	v_and_b32_e32 v35, 0xffff0000, v35
	v_mul_f32_e64 v44, |v66|, s26
	v_exp_f32_e32 v44, v44
	v_mul_f32_e64 v45, |v35|, s26
	v_exp_f32_e32 v45, v45
	v_cvt_pk_bf16_f32 v30, v62, v63
	v_add_f32_e32 v47, 1.0, v44
	v_rcp_f32_e32 v62, v47
	v_add_f32_e32 v47, 1.0, v45
	v_rcp_f32_e32 v63, v47
	v_cmp_le_f32_e32 vcc, 0, v35
	v_and_b32_e32 v67, 0xffff0000, v19
	v_sub_f32_e32 v35, v107, v97
	v_pk_mul_f32 v[44:45], v[44:45], v[62:63]
	v_sub_f32_e32 v47, v98, v109
	v_cndmask_b32_e32 v45, v63, v45, vcc
	v_cmp_le_f32_e32 vcc, 0, v66
	v_lshlrev_b32_e32 v66, 16, v19
	v_mul_f32_e32 v19, 0xbfb8aa3b, v66
	v_exp_f32_e32 v19, v19
	v_mul_f32_e32 v63, 0xbfb8aa3b, v67
	v_exp_f32_e32 v63, v63
	v_mul_f32_e32 v35, 0x3fb8aa3b, v35
	v_add_f32_e32 v19, 1.0, v19
	v_cvt_pk_bf16_f32 v28, v118, v119
	v_mul_f32_e32 v47, 0x3fb8aa3b, v47
	v_cndmask_b32_e32 v44, v62, v44, vcc
	v_exp_f32_e32 v62, v35
	v_sub_f32_e32 v35, v109, v98
	v_rcp_f32_e32 v118, v19
	v_add_f32_e32 v19, 1.0, v63
	v_lshlrev_b32_e32 v107, 16, v34
	v_exp_f32_e32 v46, v46
	v_exp_f32_e32 v47, v47
	v_mul_f32_e32 v35, 0x3fb8aa3b, v35
	v_rcp_f32_e32 v119, v19
	v_and_b32_e32 v109, 0xffff0000, v34
	v_mul_f32_e64 v34, |v107|, s26
	v_exp_f32_e32 v63, v35
	v_exp_f32_e32 v34, v34
	v_mul_f32_e64 v35, |v109|, s26
	v_exp_f32_e32 v35, v35
	v_pk_mul_f32 v[44:45], v[40:41], v[44:45]
	v_sub_f32_e32 v19, v93, v104
	v_pk_mul_f32 v[44:45], v[46:47], v[44:45]
	v_pk_mul_f32 v[46:47], v[118:119], v[66:67]
	v_mul_f32_e32 v19, 0x3fb8aa3b, v19
	v_pk_mul_f32 v[62:63], v[62:63], v[46:47]
	v_exp_f32_e32 v46, v19
	v_add_f32_e32 v19, 1.0, v34
	v_rcp_f32_e32 v66, v19
	v_add_f32_e32 v19, 1.0, v35
	v_rcp_f32_e32 v67, v19
	v_sub_f32_e32 v19, v94, v105
	v_mul_f32_e32 v19, 0x3fb8aa3b, v19
	v_exp_f32_e32 v47, v19
	v_pk_mul_f32 v[34:35], v[34:35], v[66:67]
	v_cmp_le_f32_e32 vcc, 0, v109
	v_sub_f32_e32 v19, v104, v93
	v_mul_f32_e32 v19, 0x3fb8aa3b, v19
	v_cndmask_b32_e32 v35, v67, v35, vcc
	v_cmp_le_f32_e32 vcc, 0, v107
	v_lshlrev_b32_e32 v104, 16, v18
	v_lshlrev_b32_e32 v118, 16, v17
	v_cndmask_b32_e32 v34, v66, v34, vcc
	v_exp_f32_e32 v66, v19
	v_sub_f32_e32 v19, v105, v94
	v_and_b32_e32 v105, 0xffff0000, v18
	v_mul_f32_e32 v18, 0xbfb8aa3b, v104
	v_mul_f32_e32 v67, 0xbfb8aa3b, v105
	v_exp_f32_e32 v18, v18
	v_exp_f32_e32 v67, v67
	v_mul_f32_e32 v107, 0x3fb8aa3b, v19
	v_pk_mul_f32 v[34:35], v[54:55], v[34:35]
	v_add_f32_e32 v18, 1.0, v18
	v_add_f32_e32 v19, 1.0, v67
	v_rcp_f32_e32 v18, v18
	v_rcp_f32_e32 v19, v19
	v_exp_f32_e32 v67, v107
	v_pk_mul_f32 v[34:35], v[46:47], v[34:35]
	v_lshlrev_b32_e32 v107, 16, v33
	v_pk_mul_f32 v[18:19], v[18:19], v[104:105]
	v_and_b32_e32 v33, 0xffff0000, v33
	v_pk_mul_f32 v[46:47], v[66:67], v[18:19]
	v_sub_f32_e32 v18, v89, v101
	v_mul_f32_e32 v66, 0x3fb8aa3b, v18
	v_mul_f32_e64 v18, |v107|, s26
	v_exp_f32_e32 v18, v18
	v_mul_f32_e64 v19, |v33|, s26
	v_exp_f32_e32 v19, v19
	v_and_b32_e32 v119, 0xffff0000, v17
	v_add_f32_e32 v67, 1.0, v18
	v_rcp_f32_e32 v104, v67
	v_add_f32_e32 v67, 1.0, v19
	v_rcp_f32_e32 v105, v67
	v_mul_f32_e32 v17, 0xbfb8aa3b, v118
	v_cmp_le_f32_e32 vcc, 0, v33
	v_sub_f32_e32 v33, v101, v89
	v_exp_f32_e32 v17, v17
	v_mul_f32_e32 v101, 0xbfb8aa3b, v119
	v_exp_f32_e32 v101, v101
	v_pk_mul_f32 v[18:19], v[18:19], v[104:105]
	v_sub_f32_e32 v67, v90, v102
	v_cndmask_b32_e32 v19, v105, v19, vcc
	v_cmp_le_f32_e32 vcc, 0, v107
	v_mul_f32_e32 v33, 0x3fb8aa3b, v33
	v_add_f32_e32 v17, 1.0, v17
	v_mul_f32_e32 v67, 0x3fb8aa3b, v67
	v_cndmask_b32_e32 v18, v104, v18, vcc
	v_exp_f32_e32 v104, v33
	v_sub_f32_e32 v33, v102, v90
	v_rcp_f32_e32 v134, v17
	v_add_f32_e32 v17, 1.0, v101
	v_lshlrev_b32_e32 v101, 16, v32
	v_exp_f32_e32 v66, v66
	v_exp_f32_e32 v67, v67
	v_mul_f32_e32 v33, 0x3fb8aa3b, v33
	v_rcp_f32_e32 v135, v17
	v_and_b32_e32 v102, 0xffff0000, v32
	v_mul_f32_e64 v32, |v101|, s26
	v_exp_f32_e32 v105, v33
	v_exp_f32_e32 v32, v32
	v_mul_f32_e64 v33, |v102|, s26
	v_exp_f32_e32 v33, v33
	v_pk_mul_f32 v[18:19], v[52:53], v[18:19]
	v_sub_f32_e32 v17, v73, v99
	v_pk_mul_f32 v[18:19], v[66:67], v[18:19]
	v_pk_mul_f32 v[66:67], v[134:135], v[118:119]
; __device__ __forceinline__ void ld8bf(const bf16_t* p, float (&o)[8]) { unpack8(*(const u32x4*)p, o); }
; __device__ __forceinline__ float sigmoidf_(float x) { return __builtin_amdgcn_rcpf(1.0f + __expf(-x)); }
; __device__ __forceinline__ bf16x8 pack_frag(const float (&v)[8]) { return __builtin_bit_cast(bf16x8, pack8(v)); }
; __device__ __forceinline__ void hg_lf_key(float fp, float lb, float& lf, float& key) {
;     const float e = __expf(-fabsf(fp));
;     const float rc = __builtin_amdgcn_rcpf(1.0f + e);
;     const float sp = fp >= 0.f ? rc : e * rc;
;     const float sn = fp >= 0.f ? e * rc : rc;
;     const float lsig = (fp >= 0.f ? 0.f : fp) + __logf(rc);
;     lf = (lb == 0.f) ? lsig : __logf(lb + (1.0f - lb) * sp); key = (1.0f - lb) * sn;
; __device__ __forceinline__ void w_hg_m3(const Args& a, int l, unsigned char* ws, const bf16_t* proj, bf16_t* y, LAS unsigned char* wl, int b, int ck_, int h, int lane) {
;     ...
;         for (int tb = 0; tb < 4; ++tb) { float fp[8], qv[8], a1[8], a2[8];
;             ld8bf(fsrc + (size_t)(16 * tb + lo) * NIN, fp); ld8bf(proj + (size_t)(row0 + 16 * tb + lo) * NIN + C_HQ + 64 * h + 32 * kk + 8 * fq, qv);
; #pragma unroll
;             for (int j = 0; j < 8; ++j) { float lf, key; hg_lf_key(fp[j], lbv[j], lf, key);
;                 const float q = qv[j] * sigmoidf_(qv[j]); a1[j] = q * __expf(bb[tb][j] - r31[j]); a2[j] = key * __expf(r31[j] - bb[tb][j]); }
;             Qf[tb][kk] = pack_frag(a1); Kf[tb][kk] = pack_frag(a2); }
	v_mul_f32_e32 v17, 0x3fb8aa3b, v17
	v_pk_mul_f32 v[66:67], v[104:105], v[66:67]
	v_exp_f32_e32 v104, v17
	v_add_f32_e32 v17, 1.0, v32
	v_rcp_f32_e32 v118, v17
	v_add_f32_e32 v17, 1.0, v33
	v_rcp_f32_e32 v119, v17
	v_sub_f32_e32 v17, v74, v100
	v_mul_f32_e32 v17, 0x3fb8aa3b, v17
	v_exp_f32_e32 v105, v17
	v_pk_mul_f32 v[32:33], v[32:33], v[118:119]
	v_cmp_le_f32_e32 vcc, 0, v102
	v_sub_f32_e32 v17, v99, v73
	v_mul_f32_e32 v17, 0x3fb8aa3b, v17
	v_cndmask_b32_e32 v33, v119, v33, vcc
	v_cmp_le_f32_e32 vcc, 0, v101
	v_and_b32_e32 v101, 0xffff0000, v16
	v_mul_f32_e32 v99, 0xbfb8aa3b, v101
	v_cndmask_b32_e32 v32, v118, v32, vcc
	v_exp_f32_e32 v118, v17
	v_sub_f32_e32 v17, v100, v74
	v_lshlrev_b32_e32 v100, 16, v16
	v_mul_f32_e32 v16, 0xbfb8aa3b, v100
	v_exp_f32_e32 v16, v16
	v_exp_f32_e32 v99, v99
	v_mul_f32_e32 v102, 0x3fb8aa3b, v17
	v_exp_f32_e32 v119, v102
	v_add_f32_e32 v16, 1.0, v16
	v_add_f32_e32 v17, 1.0, v99
	v_rcp_f32_e32 v16, v16
	v_rcp_f32_e32 v17, v17
	v_pk_mul_f32 v[32:33], v[42:43], v[32:33]
	v_cvt_pk_bf16_f32 v46, v46, v47
	v_pk_mul_f32 v[32:33], v[104:105], v[32:33]
	v_pk_mul_f32 v[16:17], v[16:17], v[100:101]
	v_cvt_pk_bf16_f32 v47, v62, v63
	v_pk_mul_f32 v[100:101], v[118:119], v[16:17]
	v_cvt_pk_bf16_f32 v16, v32, v33
	v_cvt_pk_bf16_f32 v17, v18, v19
	v_cvt_pk_bf16_f32 v19, v44, v45
	v_cvt_pk_bf16_f32 v45, v66, v67
	v_sub_f32_e32 v32, v97, v95
	v_lshlrev_b32_e32 v66, 16, v27
	v_cvt_pk_bf16_f32 v18, v34, v35
	v_mul_f32_e32 v34, 0x3fb8aa3b, v32
	v_and_b32_e32 v27, 0xffff0000, v27
	v_mul_f32_e64 v32, |v66|, s26
	v_exp_f32_e32 v32, v32
	v_mul_f32_e64 v33, |v27|, s26
	v_exp_f32_e32 v33, v33
	v_cmp_le_f32_e32 vcc, 0, v27
	v_add_f32_e32 v35, 1.0, v32
	v_rcp_f32_e32 v62, v35
	v_add_f32_e32 v35, 1.0, v33
	v_rcp_f32_e32 v63, v35
	v_and_b32_e32 v67, 0xffff0000, v23
	v_sub_f32_e32 v27, v95, v97
	v_sub_f32_e32 v35, v98, v96
	v_pk_mul_f32 v[32:33], v[32:33], v[62:63]
	v_mul_f32_e32 v27, 0x3fb8aa3b, v27
	v_cndmask_b32_e32 v33, v63, v33, vcc
	v_cmp_le_f32_e32 vcc, 0, v66
	v_lshlrev_b32_e32 v66, 16, v23
	v_mul_f32_e32 v23, 0xbfb8aa3b, v66
	v_exp_f32_e32 v23, v23
	v_mul_f32_e32 v63, 0xbfb8aa3b, v67
	v_exp_f32_e32 v63, v63
	v_mul_f32_e32 v35, 0x3fb8aa3b, v35
	v_add_f32_e32 v23, 1.0, v23
	v_cndmask_b32_e32 v32, v62, v32, vcc
	v_exp_f32_e32 v62, v27
	v_sub_f32_e32 v27, v96, v98
	v_rcp_f32_e32 v96, v23
	v_add_f32_e32 v23, 1.0, v63
	v_exp_f32_e32 v34, v34
	v_exp_f32_e32 v35, v35
	v_rcp_f32_e32 v97, v23
	v_pk_mul_f32 v[32:33], v[40:41], v[32:33]
	v_mul_f32_e32 v27, 0x3fb8aa3b, v27
	v_pk_mul_f32 v[32:33], v[34:35], v[32:33]
	v_pk_mul_f32 v[34:35], v[96:97], v[66:67]
	v_lshlrev_b32_e32 v66, 16, v26
	v_and_b32_e32 v67, 0xffff0000, v26
	v_mul_f32_e64 v26, |v66|, s26
	v_exp_f32_e32 v63, v27
	v_exp_f32_e32 v26, v26
	v_mul_f32_e64 v27, |v67|, s26
	v_exp_f32_e32 v27, v27
	v_sub_f32_e32 v23, v93, v91
	v_mul_f32_e32 v23, 0x3fb8aa3b, v23
	v_exp_f32_e32 v40, v23
	v_add_f32_e32 v23, 1.0, v26
	v_pk_mul_f32 v[34:35], v[62:63], v[34:35]
	v_rcp_f32_e32 v62, v23
	v_add_f32_e32 v23, 1.0, v27
	v_rcp_f32_e32 v63, v23
	v_cmp_le_f32_e32 vcc, 0, v67
	v_and_b32_e32 v67, 0xffff0000, v22
	v_sub_f32_e32 v23, v94, v92
	v_pk_mul_f32 v[26:27], v[26:27], v[62:63]
	v_mul_f32_e32 v23, 0x3fb8aa3b, v23
	v_cndmask_b32_e32 v27, v63, v27, vcc
	v_cmp_le_f32_e32 vcc, 0, v66
	v_lshlrev_b32_e32 v66, 16, v22
	v_mul_f32_e32 v22, 0xbfb8aa3b, v66
	v_mul_f32_e32 v63, 0xbfb8aa3b, v67
	v_exp_f32_e32 v22, v22
	v_exp_f32_e32 v63, v63
	v_exp_f32_e32 v41, v23
	v_sub_f32_e32 v23, v91, v93
	v_mul_f32_e32 v23, 0x3fb8aa3b, v23
	v_cndmask_b32_e32 v26, v62, v26, vcc
	v_exp_f32_e32 v62, v23
	v_sub_f32_e32 v23, v92, v94
	v_mul_f32_e32 v91, 0x3fb8aa3b, v23
	v_add_f32_e32 v22, 1.0, v22
	v_add_f32_e32 v23, 1.0, v63
	v_rcp_f32_e32 v22, v22
	v_rcp_f32_e32 v23, v23
	v_exp_f32_e32 v63, v91
	v_pk_mul_f32 v[26:27], v[54:55], v[26:27]
	v_cvt_pk_bf16_f32 v44, v100, v101
	v_pk_mul_f32 v[22:23], v[22:23], v[66:67]
	v_pk_mul_f32 v[26:27], v[40:41], v[26:27]
	v_pk_mul_f32 v[40:41], v[62:63], v[22:23]
	v_sub_f32_e32 v22, v89, v75
	v_lshlrev_b32_e32 v66, 16, v25
	v_mul_f32_e32 v54, 0x3fb8aa3b, v22
	v_and_b32_e32 v25, 0xffff0000, v25
	v_mul_f32_e64 v22, |v66|, s26
	v_exp_f32_e32 v22, v22
	v_mul_f32_e64 v23, |v25|, s26
	v_exp_f32_e32 v23, v23
	v_cmp_le_f32_e32 vcc, 0, v25
	v_add_f32_e32 v55, 1.0, v22
	v_rcp_f32_e32 v62, v55
	v_add_f32_e32 v55, 1.0, v23
	v_rcp_f32_e32 v63, v55
	v_and_b32_e32 v67, 0xffff0000, v21
	v_sub_f32_e32 v25, v75, v89
	v_mul_f32_e32 v25, 0x3fb8aa3b, v25
	v_pk_mul_f32 v[22:23], v[22:23], v[62:63]
	v_sub_f32_e32 v55, v90, v88
	v_cndmask_b32_e32 v23, v63, v23, vcc
	v_cmp_le_f32_e32 vcc, 0, v66
	v_lshlrev_b32_e32 v66, 16, v21
	v_mul_f32_e32 v21, 0xbfb8aa3b, v66
	v_exp_f32_e32 v21, v21
	v_mul_f32_e32 v63, 0xbfb8aa3b, v67
	v_exp_f32_e32 v63, v63
	v_cndmask_b32_e32 v22, v62, v22, vcc
	v_add_f32_e32 v21, 1.0, v21
	v_exp_f32_e32 v62, v25
	v_sub_f32_e32 v25, v88, v90
	v_rcp_f32_e32 v88, v21
	v_add_f32_e32 v21, 1.0, v63
	v_rcp_f32_e32 v89, v21
	v_pk_mul_f32 v[22:23], v[52:53], v[22:23]
	v_mul_f32_e32 v55, 0x3fb8aa3b, v55
	v_mul_f32_e32 v25, 0x3fb8aa3b, v25
	v_pk_mul_f32 v[52:53], v[88:89], v[66:67]
	v_lshlrev_b32_e32 v66, 16, v24
	v_and_b32_e32 v67, 0xffff0000, v24
	v_mul_f32_e64 v24, |v66|, s26
	v_exp_f32_e32 v54, v54
	v_exp_f32_e32 v55, v55
	v_exp_f32_e32 v63, v25
	v_exp_f32_e32 v24, v24
	v_mul_f32_e64 v25, |v67|, s26
	v_exp_f32_e32 v25, v25
	v_sub_f32_e32 v21, v73, v2
	v_mul_f32_e32 v21, 0x3fb8aa3b, v21
	v_pk_mul_f32 v[22:23], v[54:55], v[22:23]
	v_pk_mul_f32 v[54:55], v[62:63], v[52:53]
	v_exp_f32_e32 v52, v21
	v_add_f32_e32 v21, 1.0, v24
	v_rcp_f32_e32 v62, v21
	v_add_f32_e32 v21, 1.0, v25
	v_rcp_f32_e32 v63, v21
; __device__ __forceinline__ void ld8bf(const bf16_t* p, float (&o)[8]) { unpack8(*(const u32x4*)p, o); }
; __device__ __forceinline__ float row_sum_incl(float v) { v += dpp_shr0<1>(v); v += dpp_shr0<2>(v); v += dpp_shr0<4>(v); v += dpp_shr0<8>(v); return v; }
; __device__ __forceinline__ float bcast15(float v, int lane) { return bperm_f((lane & 48) | 15, v); }
; __device__ __forceinline__ void w_hg_scan(const float (&lbv)[8], const bf16_t* fsrc, int lane, float (&bb)[4][8], float (&r31)[8], float (&r63)[8]) {
;     const int lo = lane & 15;
; #pragma unroll
;     for (int tb = 0; tb < 4; ++tb) { float fp[8]; ld8bf(fsrc + (size_t)(16 * tb + lo) * NIN, fp);
; #pragma unroll
;         for (int j = 0; j < 8; ++j) { float key; hg_lf_key(fp[j], lbv[j], bb[tb][j], key); } }
;     float carry[8];
; #pragma unroll
;     for (int j = 0; j < 8; ++j) carry[j] = 0.f;
; #pragma unroll
;     for (int tb = 0; tb < 4; ++tb) {
; #pragma unroll
;         for (int j = 0; j < 8; ++j) { const float v = row_sum_incl(bb[tb][j]) + carry[j]; bb[tb][j] = v; carry[j] = bcast15(v, lane); if (tb == 1) r31[j] = carry[j]; if (tb == 3) r63[j] = carry[j]; }
;         __builtin_amdgcn_sched_barrier(0);
;     }
; }
	v_sub_f32_e32 v21, v74, v72
	v_cmp_le_f32_e32 vcc, 0, v67
	v_mul_f32_e32 v21, 0x3fb8aa3b, v21
	v_pk_mul_f32 v[24:25], v[24:25], v[62:63]
	v_and_b32_e32 v67, 0xffff0000, v20
	v_cndmask_b32_e32 v25, v63, v25, vcc
	v_cmp_le_f32_e32 vcc, 0, v66
	v_lshlrev_b32_e32 v66, 16, v20
	v_exp_f32_e32 v53, v21
	v_mul_f32_e32 v20, 0xbfb8aa3b, v66
	v_mul_f32_e32 v21, 0xbfb8aa3b, v67
	v_exp_f32_e32 v20, v20
	v_exp_f32_e32 v21, v21
	v_sub_f32_e32 v2, v2, v73
	v_mul_f32_e32 v2, 0x3fb8aa3b, v2
	v_cndmask_b32_e32 v24, v62, v24, vcc
	v_exp_f32_e32 v62, v2
	v_sub_f32_e32 v2, v72, v74
	v_add_f32_e32 v20, 1.0, v20
	v_add_f32_e32 v21, 1.0, v21
	v_mul_f32_e32 v2, 0x3fb8aa3b, v2
	v_rcp_f32_e32 v20, v20
	v_rcp_f32_e32 v21, v21
	v_exp_f32_e32 v63, v2
	v_pk_mul_f32 v[24:25], v[42:43], v[24:25]
	v_add_f32_dpp v2, v103, v103 row_shr:1 row_mask:0xf bank_mask:0xf bound_ctrl:1
	v_pk_mul_f32 v[24:25], v[52:53], v[24:25]
	v_pk_mul_f32 v[20:21], v[20:21], v[66:67]
	v_cvt_pk_bf16_f32 v53, v54, v55
	v_pk_mul_f32 v[42:43], v[62:63], v[20:21]
	v_cvt_pk_bf16_f32 v20, v24, v25
	v_cvt_pk_bf16_f32 v21, v22, v23
	v_cvt_pk_bf16_f32 v22, v26, v27
	v_cvt_pk_bf16_f32 v23, v32, v33
	v_cvt_pk_bf16_f32 v55, v34, v35
	v_add_f32_dpp v24, v106, v106 row_shr:1 row_mask:0xf bank_mask:0xf bound_ctrl:1
	v_add_f32_dpp v25, v110, v110 row_shr:1 row_mask:0xf bank_mask:0xf bound_ctrl:1
	v_add_f32_dpp v26, v113, v113 row_shr:1 row_mask:0xf bank_mask:0xf bound_ctrl:1
	v_add_f32_dpp v27, v117, v117 row_shr:1 row_mask:0xf bank_mask:0xf bound_ctrl:1
	v_add_f32_dpp v32, v120, v120 row_shr:1 row_mask:0xf bank_mask:0xf bound_ctrl:1
	v_add_f32_dpp v33, v123, v123 row_shr:1 row_mask:0xf bank_mask:0xf bound_ctrl:1
	v_add_f32_dpp v34, v124, v124 row_shr:1 row_mask:0xf bank_mask:0xf bound_ctrl:1
	v_add_f32_dpp v2, v2, v2 row_shr:2 row_mask:0xf bank_mask:0xf bound_ctrl:1
	v_add_f32_dpp v24, v24, v24 row_shr:2 row_mask:0xf bank_mask:0xf bound_ctrl:1
	v_add_f32_dpp v25, v25, v25 row_shr:2 row_mask:0xf bank_mask:0xf bound_ctrl:1
	v_add_f32_dpp v26, v26, v26 row_shr:2 row_mask:0xf bank_mask:0xf bound_ctrl:1
	v_add_f32_dpp v27, v27, v27 row_shr:2 row_mask:0xf bank_mask:0xf bound_ctrl:1
	v_add_f32_dpp v32, v32, v32 row_shr:2 row_mask:0xf bank_mask:0xf bound_ctrl:1
	v_add_f32_dpp v33, v33, v33 row_shr:2 row_mask:0xf bank_mask:0xf bound_ctrl:1
	v_add_f32_dpp v34, v34, v34 row_shr:2 row_mask:0xf bank_mask:0xf bound_ctrl:1
	v_add_f32_dpp v2, v2, v2 row_shr:4 row_mask:0xf bank_mask:0xf bound_ctrl:1
	v_add_f32_dpp v24, v24, v24 row_shr:4 row_mask:0xf bank_mask:0xf bound_ctrl:1
	v_add_f32_dpp v25, v25, v25 row_shr:4 row_mask:0xf bank_mask:0xf bound_ctrl:1
	v_add_f32_dpp v26, v26, v26 row_shr:4 row_mask:0xf bank_mask:0xf bound_ctrl:1
	v_add_f32_dpp v27, v27, v27 row_shr:4 row_mask:0xf bank_mask:0xf bound_ctrl:1
	v_add_f32_dpp v32, v32, v32 row_shr:4 row_mask:0xf bank_mask:0xf bound_ctrl:1
	v_add_f32_dpp v33, v33, v33 row_shr:4 row_mask:0xf bank_mask:0xf bound_ctrl:1
	v_add_f32_dpp v34, v34, v34 row_shr:4 row_mask:0xf bank_mask:0xf bound_ctrl:1
	v_add_f32_dpp v2, v2, v2 row_shr:8 row_mask:0xf bank_mask:0xf bound_ctrl:1
	v_add_f32_dpp v24, v24, v24 row_shr:8 row_mask:0xf bank_mask:0xf bound_ctrl:1
	v_add_f32_dpp v25, v25, v25 row_shr:8 row_mask:0xf bank_mask:0xf bound_ctrl:1
	v_add_f32_dpp v26, v26, v26 row_shr:8 row_mask:0xf bank_mask:0xf bound_ctrl:1
	v_add_f32_dpp v27, v27, v27 row_shr:8 row_mask:0xf bank_mask:0xf bound_ctrl:1
	v_add_f32_dpp v32, v32, v32 row_shr:8 row_mask:0xf bank_mask:0xf bound_ctrl:1
	v_add_f32_dpp v33, v33, v33 row_shr:8 row_mask:0xf bank_mask:0xf bound_ctrl:1
	v_add_f32_dpp v34, v34, v34 row_shr:8 row_mask:0xf bank_mask:0xf bound_ctrl:1
	v_cvt_pk_bf16_f32 v52, v42, v43
	v_cvt_pk_bf16_f32 v54, v40, v41
	v_add_f32_e32 v41, 0, v2
	v_add_f32_e32 v43, 0, v24
	v_add_f32_e32 v74, 0, v25
	v_add_f32_e32 v75, 0, v26
	v_add_f32_e32 v121, 0, v27
	v_add_f32_e32 v119, 0, v32
	v_add_f32_e32 v63, 0, v33
	v_add_f32_e32 v62, 0, v34
	ds_bpermute_b32 v2, v186, v41
	ds_bpermute_b32 v24, v186, v43
	ds_bpermute_b32 v25, v186, v74
	ds_bpermute_b32 v26, v186, v75
	ds_bpermute_b32 v27, v186, v121
	ds_bpermute_b32 v32, v186, v119
	ds_bpermute_b32 v33, v186, v63
	ds_bpermute_b32 v34, v186, v62
	v_add_f32_dpp v35, v130, v130 row_shr:1 row_mask:0xf bank_mask:0xf bound_ctrl:1
	s_nop 1
	v_add_f32_dpp v35, v35, v35 row_shr:2 row_mask:0xf bank_mask:0xf bound_ctrl:1
	s_nop 1
	v_add_f32_dpp v35, v35, v35 row_shr:4 row_mask:0xf bank_mask:0xf bound_ctrl:1
	s_nop 1
	v_add_f32_dpp v35, v35, v35 row_shr:8 row_mask:0xf bank_mask:0xf bound_ctrl:1
	s_waitcnt lgkmcnt(7)
	v_add_f32_e32 v118, v35, v2
	ds_bpermute_b32 v2, v186, v118
	v_add_f32_dpp v35, v144, v144 row_shr:1 row_mask:0xf bank_mask:0xf bound_ctrl:1
	s_nop 1
	v_add_f32_dpp v35, v35, v35 row_shr:2 row_mask:0xf bank_mask:0xf bound_ctrl:1
	s_nop 1
	v_add_f32_dpp v35, v35, v35 row_shr:4 row_mask:0xf bank_mask:0xf bound_ctrl:1
	s_nop 1
	v_add_f32_dpp v35, v35, v35 row_shr:8 row_mask:0xf bank_mask:0xf bound_ctrl:1
	s_waitcnt lgkmcnt(7)
	v_add_f32_e32 v117, v35, v24
	v_add_f32_dpp v24, v155, v155 row_shr:1 row_mask:0xf bank_mask:0xf bound_ctrl:1
	ds_bpermute_b32 v88, v186, v117
	s_nop 0
	v_add_f32_dpp v24, v24, v24 row_shr:2 row_mask:0xf bank_mask:0xf bound_ctrl:1
	s_nop 1
	v_add_f32_dpp v24, v24, v24 row_shr:4 row_mask:0xf bank_mask:0xf bound_ctrl:1
	s_nop 1
	v_add_f32_dpp v24, v24, v24 row_shr:8 row_mask:0xf bank_mask:0xf bound_ctrl:1
	s_waitcnt lgkmcnt(7)
	v_add_f32_e32 v116, v24, v25
	ds_bpermute_b32 v89, v186, v116
	v_add_f32_dpp v24, v156, v156 row_shr:1 row_mask:0xf bank_mask:0xf bound_ctrl:1
	s_nop 1
	v_add_f32_dpp v24, v24, v24 row_shr:2 row_mask:0xf bank_mask:0xf bound_ctrl:1
	s_nop 1
	v_add_f32_dpp v24, v24, v24 row_shr:4 row_mask:0xf bank_mask:0xf bound_ctrl:1
	s_nop 1
	v_add_f32_dpp v24, v24, v24 row_shr:8 row_mask:0xf bank_mask:0xf bound_ctrl:1
	s_waitcnt lgkmcnt(7)
; __device__ __forceinline__ void ld8bf(const bf16_t* p, float (&o)[8]) { unpack8(*(const u32x4*)p, o); }
; __device__ __forceinline__ float row_sum_incl(float v) { v += dpp_shr0<1>(v); v += dpp_shr0<2>(v); v += dpp_shr0<4>(v); v += dpp_shr0<8>(v); return v; }
; __device__ __forceinline__ float bcast15(float v, int lane) { return bperm_f((lane & 48) | 15, v); }
; __device__ __forceinline__ void w_hg_scan(const float (&lbv)[8], const bf16_t* fsrc, int lane, float (&bb)[4][8], float (&r31)[8], float (&r63)[8]) {
;     const int lo = lane & 15;
; #pragma unroll
;     for (int tb = 0; tb < 4; ++tb) { float fp[8]; ld8bf(fsrc + (size_t)(16 * tb + lo) * NIN, fp);
; #pragma unroll
;         for (int j = 0; j < 8; ++j) { float key; hg_lf_key(fp[j], lbv[j], bb[tb][j], key); } }
;     float carry[8];
; #pragma unroll
;     for (int j = 0; j < 8; ++j) carry[j] = 0.f;
; #pragma unroll
;     for (int tb = 0; tb < 4; ++tb) {
; #pragma unroll
;         for (int j = 0; j < 8; ++j) { const float v = row_sum_incl(bb[tb][j]) + carry[j]; bb[tb][j] = v; carry[j] = bcast15(v, lane); if (tb == 1) r31[j] = carry[j]; if (tb == 3) r63[j] = carry[j]; }
;         __builtin_amdgcn_sched_barrier(0);
;     }
; }
	v_add_f32_e32 v115, v24, v26
	ds_bpermute_b32 v90, v186, v115
	v_add_f32_dpp v24, v157, v157 row_shr:1 row_mask:0xf bank_mask:0xf bound_ctrl:1
	s_nop 1
	v_add_f32_dpp v24, v24, v24 row_shr:2 row_mask:0xf bank_mask:0xf bound_ctrl:1
	s_nop 1
	v_add_f32_dpp v24, v24, v24 row_shr:4 row_mask:0xf bank_mask:0xf bound_ctrl:1
	s_nop 1
	v_add_f32_dpp v24, v24, v24 row_shr:8 row_mask:0xf bank_mask:0xf bound_ctrl:1
	s_waitcnt lgkmcnt(7)
	v_add_f32_e32 v113, v24, v27
	ds_bpermute_b32 v91, v186, v113
	v_add_f32_dpp v24, v158, v158 row_shr:1 row_mask:0xf bank_mask:0xf bound_ctrl:1
	s_nop 1
	v_add_f32_dpp v24, v24, v24 row_shr:2 row_mask:0xf bank_mask:0xf bound_ctrl:1
	s_nop 1
	v_add_f32_dpp v24, v24, v24 row_shr:4 row_mask:0xf bank_mask:0xf bound_ctrl:1
	s_nop 1
	v_add_f32_dpp v24, v24, v24 row_shr:8 row_mask:0xf bank_mask:0xf bound_ctrl:1
	s_waitcnt lgkmcnt(7)
	v_add_f32_e32 v112, v24, v32
	ds_bpermute_b32 v92, v186, v112
	v_add_f32_dpp v24, v159, v159 row_shr:1 row_mask:0xf bank_mask:0xf bound_ctrl:1
	s_nop 1
	v_add_f32_dpp v24, v24, v24 row_shr:2 row_mask:0xf bank_mask:0xf bound_ctrl:1
	s_nop 1
	v_add_f32_dpp v24, v24, v24 row_shr:4 row_mask:0xf bank_mask:0xf bound_ctrl:1
	s_nop 1
	v_add_f32_dpp v24, v24, v24 row_shr:8 row_mask:0xf bank_mask:0xf bound_ctrl:1
	s_waitcnt lgkmcnt(7)
	v_add_f32_e32 v111, v24, v33
	ds_bpermute_b32 v93, v186, v111
	v_add_f32_dpp v24, v160, v160 row_shr:1 row_mask:0xf bank_mask:0xf bound_ctrl:1
	s_nop 1
	v_add_f32_dpp v24, v24, v24 row_shr:2 row_mask:0xf bank_mask:0xf bound_ctrl:1
	s_nop 1
	v_add_f32_dpp v24, v24, v24 row_shr:4 row_mask:0xf bank_mask:0xf bound_ctrl:1
	s_nop 1
	v_add_f32_dpp v24, v24, v24 row_shr:8 row_mask:0xf bank_mask:0xf bound_ctrl:1
	s_waitcnt lgkmcnt(7)
	v_add_f32_e32 v110, v24, v34
	ds_bpermute_b32 v94, v186, v110
	v_add_f32_dpp v24, v161, v161 row_shr:1 row_mask:0xf bank_mask:0xf bound_ctrl:1
	v_add_f32_dpp v25, v162, v162 row_shr:1 row_mask:0xf bank_mask:0xf bound_ctrl:1
	v_add_f32_dpp v26, v163, v163 row_shr:1 row_mask:0xf bank_mask:0xf bound_ctrl:1
	v_add_f32_dpp v27, v169, v169 row_shr:1 row_mask:0xf bank_mask:0xf bound_ctrl:1
	v_add_f32_dpp v32, v174, v174 row_shr:1 row_mask:0xf bank_mask:0xf bound_ctrl:1
	v_add_f32_dpp v33, v175, v175 row_shr:1 row_mask:0xf bank_mask:0xf bound_ctrl:1
	v_add_f32_dpp v34, v176, v176 row_shr:1 row_mask:0xf bank_mask:0xf bound_ctrl:1
	v_add_f32_dpp v35, v177, v177 row_shr:1 row_mask:0xf bank_mask:0xf bound_ctrl:1
	v_add_f32_dpp v24, v24, v24 row_shr:2 row_mask:0xf bank_mask:0xf bound_ctrl:1
	v_add_f32_dpp v25, v25, v25 row_shr:2 row_mask:0xf bank_mask:0xf bound_ctrl:1
	v_add_f32_dpp v26, v26, v26 row_shr:2 row_mask:0xf bank_mask:0xf bound_ctrl:1
	v_add_f32_dpp v27, v27, v27 row_shr:2 row_mask:0xf bank_mask:0xf bound_ctrl:1
	v_add_f32_dpp v32, v32, v32 row_shr:2 row_mask:0xf bank_mask:0xf bound_ctrl:1
	v_add_f32_dpp v33, v33, v33 row_shr:2 row_mask:0xf bank_mask:0xf bound_ctrl:1
	v_add_f32_dpp v34, v34, v34 row_shr:2 row_mask:0xf bank_mask:0xf bound_ctrl:1
	v_add_f32_dpp v35, v35, v35 row_shr:2 row_mask:0xf bank_mask:0xf bound_ctrl:1
	v_add_f32_dpp v24, v24, v24 row_shr:4 row_mask:0xf bank_mask:0xf bound_ctrl:1
	v_add_f32_dpp v25, v25, v25 row_shr:4 row_mask:0xf bank_mask:0xf bound_ctrl:1
	v_add_f32_dpp v26, v26, v26 row_shr:4 row_mask:0xf bank_mask:0xf bound_ctrl:1
	v_add_f32_dpp v27, v27, v27 row_shr:4 row_mask:0xf bank_mask:0xf bound_ctrl:1
	v_add_f32_dpp v32, v32, v32 row_shr:4 row_mask:0xf bank_mask:0xf bound_ctrl:1
	v_add_f32_dpp v33, v33, v33 row_shr:4 row_mask:0xf bank_mask:0xf bound_ctrl:1
	v_add_f32_dpp v34, v34, v34 row_shr:4 row_mask:0xf bank_mask:0xf bound_ctrl:1
	v_add_f32_dpp v35, v35, v35 row_shr:4 row_mask:0xf bank_mask:0xf bound_ctrl:1
	v_add_f32_dpp v24, v24, v24 row_shr:8 row_mask:0xf bank_mask:0xf bound_ctrl:1
	v_add_f32_dpp v25, v25, v25 row_shr:8 row_mask:0xf bank_mask:0xf bound_ctrl:1
	v_add_f32_dpp v26, v26, v26 row_shr:8 row_mask:0xf bank_mask:0xf bound_ctrl:1
	v_add_f32_dpp v27, v27, v27 row_shr:8 row_mask:0xf bank_mask:0xf bound_ctrl:1
	v_add_f32_dpp v32, v32, v32 row_shr:8 row_mask:0xf bank_mask:0xf bound_ctrl:1
	v_add_f32_dpp v33, v33, v33 row_shr:8 row_mask:0xf bank_mask:0xf bound_ctrl:1
	v_add_f32_dpp v34, v34, v34 row_shr:8 row_mask:0xf bank_mask:0xf bound_ctrl:1
	v_add_f32_dpp v35, v35, v35 row_shr:8 row_mask:0xf bank_mask:0xf bound_ctrl:1
	s_waitcnt lgkmcnt(7)
	v_add_f32_e32 v109, v24, v2
	s_waitcnt lgkmcnt(6)
	v_add_f32_e32 v107, v25, v88
	s_waitcnt lgkmcnt(5)
	v_add_f32_e32 v106, v26, v89
	s_waitcnt lgkmcnt(4)
	v_add_f32_e32 v105, v27, v90
	s_waitcnt lgkmcnt(3)
	v_add_f32_e32 v104, v32, v91
	s_waitcnt lgkmcnt(2)
	v_add_f32_e32 v103, v33, v92
	s_waitcnt lgkmcnt(1)
	v_add_f32_e32 v67, v34, v93
	s_waitcnt lgkmcnt(0)
	v_add_f32_e32 v66, v35, v94
	ds_bpermute_b32 v24, v186, v109
	ds_bpermute_b32 v25, v186, v107
	ds_bpermute_b32 v26, v186, v106
	ds_bpermute_b32 v27, v186, v105
	ds_bpermute_b32 v32, v186, v104
	ds_bpermute_b32 v33, v186, v103
	ds_bpermute_b32 v34, v186, v67
	ds_bpermute_b32 v35, v186, v66
	v_add_f32_dpp v40, v178, v178 row_shr:1 row_mask:0xf bank_mask:0xf bound_ctrl:1
	s_nop 1
	v_add_f32_dpp v40, v40, v40 row_shr:2 row_mask:0xf bank_mask:0xf bound_ctrl:1
	s_nop 1
	v_add_f32_dpp v40, v40, v40 row_shr:4 row_mask:0xf bank_mask:0xf bound_ctrl:1
	s_nop 1
	v_add_f32_dpp v40, v40, v40 row_shr:8 row_mask:0xf bank_mask:0xf bound_ctrl:1
	s_waitcnt lgkmcnt(7)
	v_add_f32_e32 v102, v40, v24
	v_add_f32_dpp v24, v179, v179 row_shr:1 row_mask:0xf bank_mask:0xf bound_ctrl:1
	s_nop 1
	v_add_f32_dpp v24, v24, v24 row_shr:2 row_mask:0xf bank_mask:0xf bound_ctrl:1
	s_nop 1
	v_add_f32_dpp v24, v24, v24 row_shr:4 row_mask:0xf bank_mask:0xf bound_ctrl:1
	s_nop 1
	v_add_f32_dpp v24, v24, v24 row_shr:8 row_mask:0xf bank_mask:0xf bound_ctrl:1
	s_waitcnt lgkmcnt(6)
; __device__ __forceinline__ void ld8bf(const bf16_t* p, float (&o)[8]) { unpack8(*(const u32x4*)p, o); }
; __device__ __forceinline__ float sigmoidf_(float x) { return __builtin_amdgcn_rcpf(1.0f + __expf(-x)); }
; __device__ __forceinline__ bf16x8 pack_frag(const float (&v)[8]) { return __builtin_bit_cast(bf16x8, pack8(v)); }
; __device__ __forceinline__ float row_sum_incl(float v) { v += dpp_shr0<1>(v); v += dpp_shr0<2>(v); v += dpp_shr0<4>(v); v += dpp_shr0<8>(v); return v; }
; __device__ __forceinline__ float bcast15(float v, int lane) { return bperm_f((lane & 48) | 15, v); }
; __device__ __forceinline__ void w_hg_scan(const float (&lbv)[8], const bf16_t* fsrc, int lane, float (&bb)[4][8], float (&r31)[8], float (&r63)[8]) {
;     ...
;     for (int tb = 0; tb < 4; ++tb) { float fp[8]; ld8bf(fsrc + (size_t)(16 * tb + lo) * NIN, fp);
; #pragma unroll
;         for (int j = 0; j < 8; ++j) { float key; hg_lf_key(fp[j], lbv[j], bb[tb][j], key); } }
;     float carry[8];
; #pragma unroll
;     for (int j = 0; j < 8; ++j) carry[j] = 0.f;
; #pragma unroll
;     for (int tb = 0; tb < 4; ++tb) {
; #pragma unroll
;         for (int j = 0; j < 8; ++j) { const float v = row_sum_incl(bb[tb][j]) + carry[j]; bb[tb][j] = v; carry[j] = bcast15(v, lane); if (tb == 1) r31[j] = carry[j]; if (tb == 3) r63[j] = carry[j]; }
;         __builtin_amdgcn_sched_barrier(0);
;     }
; __device__ __forceinline__ void w_hg_m3(const Args& a, int l, unsigned char* ws, const bf16_t* proj, bf16_t* y, LAS unsigned char* wl, int b, int ck_, int h, int lane) {
;     ...
;         for (int tb = 0; tb < 4; ++tb) { float fp[8], qv[8], a1[8], a2[8];
;             ld8bf(fsrc + (size_t)(16 * tb + lo) * NIN, fp); ld8bf(proj + (size_t)(row0 + 16 * tb + lo) * NIN + C_HQ + 64 * h + 32 * kk + 8 * fq, qv);
; #pragma unroll
;             for (int j = 0; j < 8; ++j) { float lf, key; hg_lf_key(fp[j], lbv[j], lf, key);
;                 const float q = qv[j] * sigmoidf_(qv[j]); a1[j] = q * __expf(bb[tb][j] - r31[j]); a2[j] = key * __expf(r31[j] - bb[tb][j]); }
;             Qf[tb][kk] = pack_frag(a1); Kf[tb][kk] = pack_frag(a2); }
	v_add_f32_e32 v101, v24, v25
	v_add_f32_dpp v24, v180, v180 row_shr:1 row_mask:0xf bank_mask:0xf bound_ctrl:1
	s_nop 1
	v_add_f32_dpp v24, v24, v24 row_shr:2 row_mask:0xf bank_mask:0xf bound_ctrl:1
	s_nop 1
	v_add_f32_dpp v24, v24, v24 row_shr:4 row_mask:0xf bank_mask:0xf bound_ctrl:1
	s_nop 1
	v_add_f32_dpp v24, v24, v24 row_shr:8 row_mask:0xf bank_mask:0xf bound_ctrl:1
	s_waitcnt lgkmcnt(5)
	v_add_f32_e32 v100, v24, v26
	v_add_f32_dpp v24, v181, v181 row_shr:1 row_mask:0xf bank_mask:0xf bound_ctrl:1
	s_nop 1
	v_add_f32_dpp v24, v24, v24 row_shr:2 row_mask:0xf bank_mask:0xf bound_ctrl:1
	s_nop 1
	v_add_f32_dpp v24, v24, v24 row_shr:4 row_mask:0xf bank_mask:0xf bound_ctrl:1
	s_nop 1
	v_add_f32_dpp v24, v24, v24 row_shr:8 row_mask:0xf bank_mask:0xf bound_ctrl:1
	s_waitcnt lgkmcnt(4)
	v_add_f32_e32 v99, v24, v27
	v_add_f32_dpp v24, v182, v182 row_shr:1 row_mask:0xf bank_mask:0xf bound_ctrl:1
	s_nop 1
	v_add_f32_dpp v24, v24, v24 row_shr:2 row_mask:0xf bank_mask:0xf bound_ctrl:1
	s_nop 1
	v_add_f32_dpp v24, v24, v24 row_shr:4 row_mask:0xf bank_mask:0xf bound_ctrl:1
	s_nop 1
	v_add_f32_dpp v24, v24, v24 row_shr:8 row_mask:0xf bank_mask:0xf bound_ctrl:1
	s_waitcnt lgkmcnt(3)
	v_add_f32_e32 v98, v24, v32
	v_add_f32_dpp v24, v183, v183 row_shr:1 row_mask:0xf bank_mask:0xf bound_ctrl:1
	s_nop 1
	v_add_f32_dpp v24, v24, v24 row_shr:2 row_mask:0xf bank_mask:0xf bound_ctrl:1
	s_nop 1
	v_add_f32_dpp v24, v24, v24 row_shr:4 row_mask:0xf bank_mask:0xf bound_ctrl:1
	s_nop 1
	v_add_f32_dpp v24, v24, v24 row_shr:8 row_mask:0xf bank_mask:0xf bound_ctrl:1
	s_waitcnt lgkmcnt(2)
	v_add_f32_e32 v97, v24, v33
	v_add_f32_dpp v24, v184, v184 row_shr:1 row_mask:0xf bank_mask:0xf bound_ctrl:1
	s_nop 1
	v_add_f32_dpp v24, v24, v24 row_shr:2 row_mask:0xf bank_mask:0xf bound_ctrl:1
	s_nop 1
	v_add_f32_dpp v24, v24, v24 row_shr:4 row_mask:0xf bank_mask:0xf bound_ctrl:1
	s_nop 1
	v_add_f32_dpp v24, v24, v24 row_shr:8 row_mask:0xf bank_mask:0xf bound_ctrl:1
	s_waitcnt lgkmcnt(1)
	v_add_f32_e32 v96, v24, v34
	v_add_f32_dpp v24, v185, v185 row_shr:1 row_mask:0xf bank_mask:0xf bound_ctrl:1
	s_nop 1
	v_add_f32_dpp v24, v24, v24 row_shr:2 row_mask:0xf bank_mask:0xf bound_ctrl:1
	s_nop 1
	v_add_f32_dpp v24, v24, v24 row_shr:4 row_mask:0xf bank_mask:0xf bound_ctrl:1
	s_nop 1
	v_add_f32_dpp v24, v24, v24 row_shr:8 row_mask:0xf bank_mask:0xf bound_ctrl:1
	s_waitcnt lgkmcnt(0)
	v_add_f32_e32 v95, v24, v35
	flat_load_dwordx4 v[24:27], v[60:61]
	flat_load_dwordx4 v[32:35], v[70:71] offset:64
	v_pk_add_f32 v[70:71], v[56:57], 1.0 op_sel_hi:[1,0] neg_lo:[1,0] neg_hi:[1,0]
	v_sub_f32_e32 v40, v41, v2
	v_sub_f32_e32 v41, v2, v41
	v_mul_f32_e32 v41, 0x3fb8aa3b, v41
	v_exp_f32_e32 v42, v41
	v_sub_f32_e32 v41, v43, v88
	v_mul_f32_e32 v40, 0x3fb8aa3b, v40
	v_mul_f32_e32 v41, 0x3fb8aa3b, v41
	v_exp_f32_e32 v40, v40
	v_exp_f32_e32 v41, v41
	v_pk_add_f32 v[72:73], v[58:59], 1.0 op_sel_hi:[1,0] neg_lo:[1,0] neg_hi:[1,0]
	s_waitcnt vmcnt(0) lgkmcnt(0)
	v_lshlrev_b32_e32 v56, 16, v32
	v_and_b32_e32 v57, 0xffff0000, v32
	v_mul_f32_e32 v32, 0xbfb8aa3b, v56
	v_exp_f32_e32 v32, v32
	s_nop 0
	v_add_f32_e32 v32, 1.0, v32
	v_rcp_f32_e32 v60, v32
	v_mul_f32_e32 v32, 0xbfb8aa3b, v57
	v_exp_f32_e32 v32, v32
	s_nop 0
	v_add_f32_e32 v32, 1.0, v32
	v_rcp_f32_e32 v61, v32
	v_sub_f32_e32 v32, v88, v43
	v_mul_f32_e32 v32, 0x3fb8aa3b, v32
	v_exp_f32_e32 v43, v32
	v_pk_mul_f32 v[56:57], v[60:61], v[56:57]
	v_lshlrev_b32_e32 v32, 16, v24
	v_pk_mul_f32 v[40:41], v[40:41], v[56:57]
	v_mul_f32_e64 v56, |v32|, s26
	v_exp_f32_e32 v56, v56
	v_and_b32_e32 v24, 0xffff0000, v24
	v_cmp_le_f32_e32 vcc, 0, v32
	v_cmp_le_f32_e64 s[38:39], 0, v24
	v_add_f32_e32 v57, 1.0, v56
	v_rcp_f32_e32 v60, v57
	v_mul_f32_e64 v57, |v24|, s26
	v_exp_f32_e32 v57, v57
	v_sub_f32_e32 v24, v74, v89
	v_mul_f32_e32 v24, 0x3fb8aa3b, v24
	v_lshlrev_b32_e32 v32, 16, v33
	v_add_f32_e32 v61, 1.0, v57
	v_rcp_f32_e32 v61, v61
	v_and_b32_e32 v33, 0xffff0000, v33
	v_pk_mul_f32 v[56:57], v[56:57], v[60:61]
	s_nop 0
	v_cndmask_b32_e64 v57, v61, v57, s[38:39]
	v_cndmask_b32_e32 v56, v60, v56, vcc
	v_pk_mul_f32 v[56:57], v[70:71], v[56:57]
	s_nop 0
	v_pk_mul_f32 v[42:43], v[42:43], v[56:57]
	v_exp_f32_e32 v56, v24
	v_sub_f32_e32 v24, v89, v74
	v_mul_f32_e32 v24, 0x3fb8aa3b, v24
	v_exp_f32_e32 v58, v24
	v_sub_f32_e32 v24, v75, v90
	v_mul_f32_e32 v24, 0x3fb8aa3b, v24
	v_exp_f32_e32 v57, v24
	v_mul_f32_e32 v24, 0xbfb8aa3b, v32
	v_exp_f32_e32 v24, v24
	s_nop 0
	v_add_f32_e32 v24, 1.0, v24
	v_rcp_f32_e32 v60, v24
	v_mul_f32_e32 v24, 0xbfb8aa3b, v33
	v_exp_f32_e32 v24, v24
	s_nop 0
	v_add_f32_e32 v24, 1.0, v24
	v_rcp_f32_e32 v61, v24
	v_sub_f32_e32 v24, v90, v75
	v_mul_f32_e32 v24, 0x3fb8aa3b, v24
	v_exp_f32_e32 v59, v24
	v_pk_mul_f32 v[32:33], v[60:61], v[32:33]
	v_lshlrev_b32_e32 v60, 16, v25
	v_mul_f32_e64 v24, |v60|, s26
	v_exp_f32_e32 v24, v24
	v_and_b32_e32 v61, 0xffff0000, v25
	v_pk_mul_f32 v[32:33], v[56:57], v[32:33]
	v_cmp_le_f32_e32 vcc, 0, v60
	v_add_f32_e32 v25, 1.0, v24
	v_rcp_f32_e32 v56, v25
	v_mul_f32_e64 v25, |v61|, s26
	v_exp_f32_e32 v25, v25
	v_cmp_le_f32_e64 s[38:39], 0, v61
	v_pk_add_f32 v[74:75], v[50:51], 1.0 op_sel_hi:[1,0] neg_lo:[1,0] neg_hi:[1,0]
	v_add_f32_e32 v57, 1.0, v25
	v_rcp_f32_e32 v57, v57
	s_nop 0
	v_pk_mul_f32 v[24:25], v[24:25], v[56:57]
	s_nop 0
	v_cndmask_b32_e64 v25, v57, v25, s[38:39]
	v_cndmask_b32_e32 v24, v56, v24, vcc
	v_pk_mul_f32 v[24:25], v[72:73], v[24:25]
	s_nop 0
	v_pk_mul_f32 v[56:57], v[58:59], v[24:25]
	v_lshlrev_b32_e32 v58, 16, v34
	v_and_b32_e32 v59, 0xffff0000, v34
	v_mul_f32_e32 v34, 0xbfb8aa3b, v58
	v_exp_f32_e32 v34, v34
	v_sub_f32_e32 v25, v91, v121
	v_mul_f32_e32 v25, 0x3fb8aa3b, v25
; __device__ __forceinline__ void ld8bf(const bf16_t* p, float (&o)[8]) { unpack8(*(const u32x4*)p, o); }
; __device__ __forceinline__ float sigmoidf_(float x) { return __builtin_amdgcn_rcpf(1.0f + __expf(-x)); }
; __device__ __forceinline__ bf16x8 pack_frag(const float (&v)[8]) { return __builtin_bit_cast(bf16x8, pack8(v)); }
; __device__ __forceinline__ void hg_lf_key(float fp, float lb, float& lf, float& key) {
;     const float e = __expf(-fabsf(fp));
;     const float rc = __builtin_amdgcn_rcpf(1.0f + e);
;     const float sp = fp >= 0.f ? rc : e * rc;
;     const float sn = fp >= 0.f ? e * rc : rc;
;     const float lsig = (fp >= 0.f ? 0.f : fp) + __logf(rc);
;     lf = (lb == 0.f) ? lsig : __logf(lb + (1.0f - lb) * sp); key = (1.0f - lb) * sn;
; __device__ __forceinline__ void w_hg_m3(const Args& a, int l, unsigned char* ws, const bf16_t* proj, bf16_t* y, LAS unsigned char* wl, int b, int ck_, int h, int lane) {
;     ...
;         for (int tb = 0; tb < 4; ++tb) { float fp[8], qv[8], a1[8], a2[8];
;             ld8bf(fsrc + (size_t)(16 * tb + lo) * NIN, fp); ld8bf(proj + (size_t)(row0 + 16 * tb + lo) * NIN + C_HQ + 64 * h + 32 * kk + 8 * fq, qv);
; #pragma unroll
;             for (int j = 0; j < 8; ++j) { float lf, key; hg_lf_key(fp[j], lbv[j], lf, key);
;                 const float q = qv[j] * sigmoidf_(qv[j]); a1[j] = q * __expf(bb[tb][j] - r31[j]); a2[j] = key * __expf(r31[j] - bb[tb][j]); }
;             Qf[tb][kk] = pack_frag(a1); Kf[tb][kk] = pack_frag(a2); }
	v_sub_f32_e32 v24, v121, v91
	v_add_f32_e32 v34, 1.0, v34
	v_rcp_f32_e32 v60, v34
	v_mul_f32_e32 v34, 0xbfb8aa3b, v59
	v_exp_f32_e32 v34, v34
	v_exp_f32_e32 v50, v25
	v_sub_f32_e32 v25, v119, v92
	v_mul_f32_e32 v24, 0x3fb8aa3b, v24
	v_add_f32_e32 v34, 1.0, v34
	v_mul_f32_e32 v25, 0x3fb8aa3b, v25
	v_rcp_f32_e32 v61, v34
	v_exp_f32_e32 v24, v24
	v_exp_f32_e32 v25, v25
	v_sub_f32_e32 v34, v92, v119
	v_mul_f32_e32 v34, 0x3fb8aa3b, v34
	v_pk_mul_f32 v[58:59], v[60:61], v[58:59]
	v_exp_f32_e32 v51, v34
	v_lshlrev_b32_e32 v34, 16, v26
	v_pk_mul_f32 v[24:25], v[24:25], v[58:59]
	v_mul_f32_e64 v58, |v34|, s26
	v_exp_f32_e32 v58, v58
	v_and_b32_e32 v26, 0xffff0000, v26
	v_cmp_le_f32_e32 vcc, 0, v34
	v_cmp_le_f32_e64 s[38:39], 0, v26
	v_add_f32_e32 v59, 1.0, v58
	v_rcp_f32_e32 v60, v59
	v_mul_f32_e64 v59, |v26|, s26
	v_exp_f32_e32 v59, v59
	v_sub_f32_e32 v26, v63, v93
	v_mul_f32_e32 v26, 0x3fb8aa3b, v26
	v_add_f32_e32 v61, 1.0, v59
	v_rcp_f32_e32 v61, v61
	s_nop 0
	v_pk_mul_f32 v[58:59], v[58:59], v[60:61]
	s_nop 0
	v_cndmask_b32_e64 v59, v61, v59, s[38:39]
	v_cndmask_b32_e32 v58, v60, v58, vcc
	v_pk_mul_f32 v[58:59], v[74:75], v[58:59]
	v_lshlrev_b32_e32 v60, 16, v35
	v_pk_mul_f32 v[50:51], v[50:51], v[58:59]
	v_exp_f32_e32 v58, v26
	v_sub_f32_e32 v26, v93, v63
	v_mul_f32_e32 v26, 0x3fb8aa3b, v26
	v_exp_f32_e32 v34, v26
	v_sub_f32_e32 v26, v62, v94
	v_mul_f32_e32 v26, 0x3fb8aa3b, v26
	v_exp_f32_e32 v59, v26
	v_mul_f32_e32 v26, 0xbfb8aa3b, v60
	v_exp_f32_e32 v26, v26
	v_and_b32_e32 v61, 0xffff0000, v35
	v_and_b32_e32 v63, 0xffff0000, v27
	v_cmp_le_f32_e64 s[38:39], 0, v63
	v_add_f32_e32 v26, 1.0, v26
	v_rcp_f32_e32 v120, v26
	v_mul_f32_e32 v26, 0xbfb8aa3b, v61
	v_exp_f32_e32 v26, v26
	s_nop 0
	v_add_f32_e32 v26, 1.0, v26
	v_rcp_f32_e32 v121, v26
	v_sub_f32_e32 v26, v94, v62
	v_mul_f32_e32 v26, 0x3fb8aa3b, v26
	v_lshlrev_b32_e32 v62, 16, v27
	v_exp_f32_e32 v35, v26
	v_mul_f32_e64 v26, |v62|, s26
	v_exp_f32_e32 v26, v26
	v_pk_mul_f32 v[60:61], v[120:121], v[60:61]
	v_cmp_le_f32_e32 vcc, 0, v62
	v_pk_mul_f32 v[58:59], v[58:59], v[60:61]
	v_add_f32_e32 v27, 1.0, v26
	v_rcp_f32_e32 v60, v27
	v_mul_f32_e64 v27, |v63|, s26
	v_exp_f32_e32 v27, v27
	v_cvt_pk_bf16_f32 v62, v24, v25
	v_cvt_pk_bf16_f32 v24, v42, v43
	v_cvt_pk_bf16_f32 v25, v56, v57
	v_add_f32_e32 v61, 1.0, v27
	v_rcp_f32_e32 v61, v61
	v_cvt_pk_bf16_f32 v63, v58, v59
	v_pk_mul_f32 v[26:27], v[26:27], v[60:61]
	s_nop 0
	v_cndmask_b32_e64 v27, v61, v27, s[38:39]
	v_cndmask_b32_e32 v26, v60, v26, vcc
	v_pk_mul_f32 v[26:27], v[68:69], v[26:27]
	v_cvt_pk_bf16_f32 v60, v40, v41
	v_pk_mul_f32 v[34:35], v[34:35], v[26:27]
	v_cvt_pk_bf16_f32 v61, v32, v33
	v_cvt_pk_bf16_f32 v27, v34, v35
	flat_load_dwordx4 v[32:35], v[48:49] offset:64
	flat_load_dwordx4 v[40:43], v[78:79] offset:64
	v_sub_f32_e32 v49, v2, v118
	v_mul_f32_e32 v49, 0x3fb8aa3b, v49
	v_cvt_pk_bf16_f32 v26, v50, v51
	v_sub_f32_e32 v48, v118, v2
	v_exp_f32_e32 v50, v49
	v_sub_f32_e32 v49, v117, v88
	v_mul_f32_e32 v48, 0x3fb8aa3b, v48
	v_mul_f32_e32 v49, 0x3fb8aa3b, v49
	v_exp_f32_e32 v48, v48
	v_exp_f32_e32 v49, v49
	s_waitcnt vmcnt(0) lgkmcnt(0)
	v_lshlrev_b32_e32 v56, 16, v40
	v_and_b32_e32 v57, 0xffff0000, v40
	v_mul_f32_e32 v40, 0xbfb8aa3b, v56
	v_exp_f32_e32 v40, v40
	s_nop 0
	v_add_f32_e32 v40, 1.0, v40
	v_rcp_f32_e32 v58, v40
	v_mul_f32_e32 v40, 0xbfb8aa3b, v57
	v_exp_f32_e32 v40, v40
	s_nop 0
	v_add_f32_e32 v40, 1.0, v40
	v_rcp_f32_e32 v59, v40
	v_sub_f32_e32 v40, v88, v117
	v_mul_f32_e32 v40, 0x3fb8aa3b, v40
	v_exp_f32_e32 v51, v40
	v_pk_mul_f32 v[56:57], v[58:59], v[56:57]
	v_lshlrev_b32_e32 v40, 16, v32
	v_pk_mul_f32 v[48:49], v[48:49], v[56:57]
	v_mul_f32_e64 v56, |v40|, s26
	v_exp_f32_e32 v56, v56
	v_and_b32_e32 v32, 0xffff0000, v32
	v_cmp_le_f32_e32 vcc, 0, v40
	v_cmp_le_f32_e64 s[38:39], 0, v32
	v_add_f32_e32 v57, 1.0, v56
	v_rcp_f32_e32 v58, v57
	v_mul_f32_e64 v57, |v32|, s26
	v_exp_f32_e32 v57, v57
	v_sub_f32_e32 v32, v116, v89
	v_mul_f32_e32 v32, 0x3fb8aa3b, v32
	v_cvt_pk_bf16_f32 v48, v48, v49
	v_add_f32_e32 v59, 1.0, v57
	v_rcp_f32_e32 v59, v59
	s_nop 0
	v_pk_mul_f32 v[56:57], v[56:57], v[58:59]
	s_nop 0
	v_cndmask_b32_e64 v57, v59, v57, s[38:39]
	v_cndmask_b32_e32 v56, v58, v56, vcc
	v_pk_mul_f32 v[56:57], v[70:71], v[56:57]
	v_lshlrev_b32_e32 v58, 16, v41
	v_pk_mul_f32 v[56:57], v[50:51], v[56:57]
	v_exp_f32_e32 v50, v32
	v_sub_f32_e32 v32, v89, v116
	v_mul_f32_e32 v32, 0x3fb8aa3b, v32
	v_exp_f32_e32 v40, v32
	v_sub_f32_e32 v32, v115, v90
	v_mul_f32_e32 v32, 0x3fb8aa3b, v32
	v_exp_f32_e32 v51, v32
	v_mul_f32_e32 v32, 0xbfb8aa3b, v58
	v_exp_f32_e32 v32, v32
	v_and_b32_e32 v59, 0xffff0000, v41
	v_add_f32_e32 v32, 1.0, v32
	v_rcp_f32_e32 v78, v32
	v_mul_f32_e32 v32, 0xbfb8aa3b, v59
	v_exp_f32_e32 v32, v32
	s_nop 0
	v_add_f32_e32 v32, 1.0, v32
	v_rcp_f32_e32 v79, v32
	v_sub_f32_e32 v32, v90, v115
	v_mul_f32_e32 v32, 0x3fb8aa3b, v32
	v_exp_f32_e32 v41, v32
	v_pk_mul_f32 v[58:59], v[78:79], v[58:59]
	v_lshlrev_b32_e32 v78, 16, v33
	v_mul_f32_e64 v32, |v78|, s26
	v_exp_f32_e32 v32, v32
	v_and_b32_e32 v79, 0xffff0000, v33
	v_pk_mul_f32 v[50:51], v[50:51], v[58:59]
	v_cmp_le_f32_e32 vcc, 0, v78
	v_add_f32_e32 v33, 1.0, v32
	v_rcp_f32_e32 v58, v33
	v_mul_f32_e64 v33, |v79|, s26
	v_exp_f32_e32 v33, v33
	v_lshlrev_b32_e32 v78, 16, v42
	v_cmp_le_f32_e64 s[38:39], 0, v79
	v_and_b32_e32 v79, 0xffff0000, v42
	v_mul_f32_e32 v42, 0xbfb8aa3b, v78
	v_add_f32_e32 v59, 1.0, v33
	v_exp_f32_e32 v42, v42
	v_rcp_f32_e32 v59, v59
	v_cvt_pk_bf16_f32 v49, v50, v51
	v_add_f32_e32 v42, 1.0, v42
	v_pk_mul_f32 v[32:33], v[32:33], v[58:59]
	v_rcp_f32_e32 v116, v42
	v_mul_f32_e32 v42, 0xbfb8aa3b, v79
	v_cndmask_b32_e64 v33, v59, v33, s[38:39]
; __device__ __forceinline__ void ld8bf(const bf16_t* p, float (&o)[8]) { unpack8(*(const u32x4*)p, o); }
; __device__ __forceinline__ float sigmoidf_(float x) { return __builtin_amdgcn_rcpf(1.0f + __expf(-x)); }
; __device__ __forceinline__ bf16x8 pack_frag(const float (&v)[8]) { return __builtin_bit_cast(bf16x8, pack8(v)); }
; __device__ __forceinline__ void hg_lf_key(float fp, float lb, float& lf, float& key) {
;     const float e = __expf(-fabsf(fp));
;     const float rc = __builtin_amdgcn_rcpf(1.0f + e);
;     const float sp = fp >= 0.f ? rc : e * rc;
;     const float sn = fp >= 0.f ? e * rc : rc;
;     const float lsig = (fp >= 0.f ? 0.f : fp) + __logf(rc);
;     lf = (lb == 0.f) ? lsig : __logf(lb + (1.0f - lb) * sp); key = (1.0f - lb) * sn;
; __device__ __forceinline__ void w_hg_m3(const Args& a, int l, unsigned char* ws, const bf16_t* proj, bf16_t* y, LAS unsigned char* wl, int b, int ck_, int h, int lane) {
;     ...
;         for (int tb = 0; tb < 4; ++tb) { float fp[8], qv[8], a1[8], a2[8];
;             ld8bf(fsrc + (size_t)(16 * tb + lo) * NIN, fp); ld8bf(proj + (size_t)(row0 + 16 * tb + lo) * NIN + C_HQ + 64 * h + 32 * kk + 8 * fq, qv);
; #pragma unroll
;             for (int j = 0; j < 8; ++j) { float lf, key; hg_lf_key(fp[j], lbv[j], lf, key);
;                 const float q = qv[j] * sigmoidf_(qv[j]); a1[j] = q * __expf(bb[tb][j] - r31[j]); a2[j] = key * __expf(r31[j] - bb[tb][j]); }
;             Qf[tb][kk] = pack_frag(a1); Kf[tb][kk] = pack_frag(a2); }
	v_cndmask_b32_e32 v32, v58, v32, vcc
	v_exp_f32_e32 v42, v42
	v_pk_mul_f32 v[32:33], v[72:73], v[32:33]
	v_add_f32_e32 v42, 1.0, v42
	v_pk_mul_f32 v[40:41], v[40:41], v[32:33]
	v_sub_f32_e32 v33, v91, v113
	v_mul_f32_e32 v33, 0x3fb8aa3b, v33
	v_sub_f32_e32 v32, v113, v91
	v_exp_f32_e32 v58, v33
	v_sub_f32_e32 v33, v112, v92
	v_mul_f32_e32 v32, 0x3fb8aa3b, v32
	v_mul_f32_e32 v33, 0x3fb8aa3b, v33
	v_rcp_f32_e32 v117, v42
	v_exp_f32_e32 v32, v32
	v_exp_f32_e32 v33, v33
	v_sub_f32_e32 v42, v92, v112
	v_mul_f32_e32 v42, 0x3fb8aa3b, v42
	v_pk_mul_f32 v[78:79], v[116:117], v[78:79]
	v_exp_f32_e32 v59, v42
	v_lshlrev_b32_e32 v42, 16, v34
	v_pk_mul_f32 v[32:33], v[32:33], v[78:79]
	v_mul_f32_e64 v78, |v42|, s26
	v_exp_f32_e32 v78, v78
	v_and_b32_e32 v34, 0xffff0000, v34
	v_cmp_le_f32_e32 vcc, 0, v42
	v_cmp_le_f32_e64 s[38:39], 0, v34
	v_add_f32_e32 v79, 1.0, v78
	v_rcp_f32_e32 v112, v79
	v_mul_f32_e64 v79, |v34|, s26
	v_exp_f32_e32 v79, v79
	v_sub_f32_e32 v34, v111, v93
	v_mul_f32_e32 v34, 0x3fb8aa3b, v34
	v_cvt_pk_bf16_f32 v50, v32, v33
	v_add_f32_e32 v113, 1.0, v79
	v_rcp_f32_e32 v113, v113
	v_cvt_pk_bf16_f32 v33, v40, v41
	v_cvt_pk_bf16_f32 v32, v56, v57
	v_sub_f32_e32 v57, v2, v109
	v_pk_mul_f32 v[78:79], v[78:79], v[112:113]
	v_mul_f32_e32 v57, 0x3fb8aa3b, v57
	v_cndmask_b32_e64 v79, v113, v79, s[38:39]
	v_cndmask_b32_e32 v78, v112, v78, vcc
	v_pk_mul_f32 v[78:79], v[74:75], v[78:79]
	v_lshlrev_b32_e32 v112, 16, v43
	v_pk_mul_f32 v[58:59], v[58:59], v[78:79]
	v_exp_f32_e32 v78, v34
	v_sub_f32_e32 v34, v93, v111
	v_mul_f32_e32 v34, 0x3fb8aa3b, v34
	v_exp_f32_e32 v42, v34
	v_sub_f32_e32 v34, v110, v94
	v_mul_f32_e32 v34, 0x3fb8aa3b, v34
	v_exp_f32_e32 v79, v34
	v_mul_f32_e32 v34, 0xbfb8aa3b, v112
	v_exp_f32_e32 v34, v34
	v_and_b32_e32 v113, 0xffff0000, v43
	v_sub_f32_e32 v56, v109, v2
	v_mul_f32_e32 v56, 0x3fb8aa3b, v56
	v_add_f32_e32 v34, 1.0, v34
	v_rcp_f32_e32 v116, v34
	v_mul_f32_e32 v34, 0xbfb8aa3b, v113
	v_exp_f32_e32 v34, v34
	v_exp_f32_e32 v56, v56
	v_add_f32_e32 v34, 1.0, v34
	v_rcp_f32_e32 v117, v34
	v_sub_f32_e32 v34, v94, v110
	v_mul_f32_e32 v34, 0x3fb8aa3b, v34
	v_exp_f32_e32 v43, v34
	v_pk_mul_f32 v[112:113], v[116:117], v[112:113]
	s_nop 0
	v_pk_mul_f32 v[78:79], v[78:79], v[112:113]
	v_lshlrev_b32_e32 v112, 16, v35
	v_mul_f32_e64 v34, |v112|, s26
	v_exp_f32_e32 v34, v34
	v_and_b32_e32 v113, 0xffff0000, v35
	v_cmp_le_f32_e32 vcc, 0, v112
	v_cmp_le_f32_e64 s[38:39], 0, v113
	v_add_f32_e32 v35, 1.0, v34
	v_rcp_f32_e32 v110, v35
	v_mul_f32_e64 v35, |v113|, s26
	v_exp_f32_e32 v35, v35
	v_cvt_pk_bf16_f32 v51, v78, v79
	v_add_f32_e32 v111, 1.0, v35
	v_rcp_f32_e32 v111, v111
	s_nop 0
	v_pk_mul_f32 v[34:35], v[34:35], v[110:111]
	s_nop 0
	v_cndmask_b32_e64 v35, v111, v35, s[38:39]
	v_cndmask_b32_e32 v34, v110, v34, vcc
	v_pk_mul_f32 v[34:35], v[68:69], v[34:35]
	s_nop 0
	v_pk_mul_f32 v[42:43], v[42:43], v[34:35]
	v_cvt_pk_bf16_f32 v34, v58, v59
	v_cvt_pk_bf16_f32 v35, v42, v43
	flat_load_dwordx4 v[40:43], v[36:37] offset:64
	s_nop 0
	flat_load_dwordx4 v[36:39], v[38:39] offset:64
	v_exp_f32_e32 v58, v57
	v_sub_f32_e32 v57, v107, v88
	v_mul_f32_e32 v57, 0x3fb8aa3b, v57
	v_exp_f32_e32 v57, v57
	s_waitcnt vmcnt(0) lgkmcnt(0)
	v_and_b32_e32 v109, 0xffff0000, v41
	v_lshlrev_b32_e32 v78, 16, v36
	v_and_b32_e32 v79, 0xffff0000, v36
	v_mul_f32_e32 v36, 0xbfb8aa3b, v78
	v_exp_f32_e32 v36, v36
	s_nop 0
	v_add_f32_e32 v36, 1.0, v36
	v_rcp_f32_e32 v110, v36
	v_mul_f32_e32 v36, 0xbfb8aa3b, v79
	v_exp_f32_e32 v36, v36
	s_nop 0
	v_add_f32_e32 v36, 1.0, v36
	v_rcp_f32_e32 v111, v36
	v_sub_f32_e32 v36, v88, v107
	v_mul_f32_e32 v36, 0x3fb8aa3b, v36
	v_exp_f32_e32 v59, v36
	v_pk_mul_f32 v[78:79], v[110:111], v[78:79]
	v_lshlrev_b32_e32 v36, 16, v40
	v_pk_mul_f32 v[56:57], v[56:57], v[78:79]
	v_mul_f32_e64 v78, |v36|, s26
	v_exp_f32_e32 v78, v78
	v_and_b32_e32 v40, 0xffff0000, v40
	v_cmp_le_f32_e32 vcc, 0, v36
	v_cmp_le_f32_e64 s[38:39], 0, v40
	v_add_f32_e32 v79, 1.0, v78
	v_rcp_f32_e32 v110, v79
	v_mul_f32_e64 v79, |v40|, s26
	v_exp_f32_e32 v79, v79
	v_sub_f32_e32 v36, v106, v89
	v_mul_f32_e32 v36, 0x3fb8aa3b, v36
	v_sub_f32_e32 v40, v105, v90
	v_add_f32_e32 v107, 1.0, v79
	v_rcp_f32_e32 v111, v107
	v_and_b32_e32 v107, 0xffff0000, v37
	v_mul_f32_e32 v40, 0x3fb8aa3b, v40
	v_pk_mul_f32 v[78:79], v[78:79], v[110:111]
	s_nop 0
	v_cndmask_b32_e64 v79, v111, v79, s[38:39]
	v_cndmask_b32_e32 v78, v110, v78, vcc
	v_pk_mul_f32 v[78:79], v[70:71], v[78:79]
	v_cmp_le_f32_e64 s[38:39], 0, v109
	v_pk_mul_f32 v[58:59], v[58:59], v[78:79]
	v_exp_f32_e32 v78, v36
	v_sub_f32_e32 v36, v89, v106
	v_lshlrev_b32_e32 v106, 16, v37
	v_mul_f32_e32 v37, 0xbfb8aa3b, v106
	v_exp_f32_e32 v37, v37
	v_exp_f32_e32 v79, v40
	v_mul_f32_e32 v36, 0x3fb8aa3b, v36
	v_exp_f32_e32 v36, v36
	v_add_f32_e32 v37, 1.0, v37
	v_rcp_f32_e32 v110, v37
	v_mul_f32_e32 v37, 0xbfb8aa3b, v107
	v_exp_f32_e32 v37, v37
	s_nop 0
	v_add_f32_e32 v37, 1.0, v37
	v_rcp_f32_e32 v111, v37
	v_sub_f32_e32 v37, v90, v105
	v_lshlrev_b32_e32 v105, 16, v41
	v_mul_f32_e64 v40, |v105|, s26
	v_exp_f32_e32 v40, v40
	v_pk_mul_f32 v[106:107], v[110:111], v[106:107]
	v_mul_f32_e32 v37, 0x3fb8aa3b, v37
	v_pk_mul_f32 v[78:79], v[78:79], v[106:107]
	v_add_f32_e32 v41, 1.0, v40
	v_rcp_f32_e32 v106, v41
	v_mul_f32_e64 v41, |v109|, s26
	v_exp_f32_e32 v41, v41
	v_exp_f32_e32 v37, v37
	v_cmp_le_f32_e32 vcc, 0, v105
	v_and_b32_e32 v105, 0xffff0000, v38
	v_add_f32_e32 v107, 1.0, v41
	v_rcp_f32_e32 v107, v107
	s_nop 0
	v_pk_mul_f32 v[40:41], v[40:41], v[106:107]
	s_nop 0
	v_cndmask_b32_e64 v41, v107, v41, s[38:39]
	v_cndmask_b32_e32 v40, v106, v40, vcc
	v_pk_mul_f32 v[40:41], v[72:73], v[40:41]
	s_nop 0
	v_pk_mul_f32 v[106:107], v[36:37], v[40:41]
; __device__ __forceinline__ void ld8bf(const bf16_t* p, float (&o)[8]) { unpack8(*(const u32x4*)p, o); }
; __device__ __forceinline__ float sigmoidf_(float x) { return __builtin_amdgcn_rcpf(1.0f + __expf(-x)); }
; __device__ __forceinline__ bf16x8 pack_frag(const float (&v)[8]) { return __builtin_bit_cast(bf16x8, pack8(v)); }
; __device__ __forceinline__ void hg_lf_key(float fp, float lb, float& lf, float& key) {
;     const float e = __expf(-fabsf(fp));
;     const float rc = __builtin_amdgcn_rcpf(1.0f + e);
;     const float sp = fp >= 0.f ? rc : e * rc;
;     const float sn = fp >= 0.f ? e * rc : rc;
;     const float lsig = (fp >= 0.f ? 0.f : fp) + __logf(rc);
;     lf = (lb == 0.f) ? lsig : __logf(lb + (1.0f - lb) * sp); key = (1.0f - lb) * sn;
; __device__ __forceinline__ void w_hg_m3(const Args& a, int l, unsigned char* ws, const bf16_t* proj, bf16_t* y, LAS unsigned char* wl, int b, int ck_, int h, int lane) {
;     ...
;         for (int tb = 0; tb < 4; ++tb) { float fp[8], qv[8], a1[8], a2[8];
;             ld8bf(fsrc + (size_t)(16 * tb + lo) * NIN, fp); ld8bf(proj + (size_t)(row0 + 16 * tb + lo) * NIN + C_HQ + 64 * h + 32 * kk + 8 * fq, qv);
; #pragma unroll
;             for (int j = 0; j < 8; ++j) { float lf, key; hg_lf_key(fp[j], lbv[j], lf, key);
;                 const float q = qv[j] * sigmoidf_(qv[j]); a1[j] = q * __expf(bb[tb][j] - r31[j]); a2[j] = key * __expf(r31[j] - bb[tb][j]); }
;             Qf[tb][kk] = pack_frag(a1); Kf[tb][kk] = pack_frag(a2); }
	v_sub_f32_e32 v36, v104, v91
	v_sub_f32_e32 v37, v91, v104
	v_lshlrev_b32_e32 v104, 16, v38
	v_mul_f32_e32 v38, 0xbfb8aa3b, v104
	v_exp_f32_e32 v38, v38
	v_mul_f32_e32 v37, 0x3fb8aa3b, v37
	v_exp_f32_e32 v40, v37
	v_sub_f32_e32 v37, v103, v92
	v_add_f32_e32 v38, 1.0, v38
	v_rcp_f32_e32 v110, v38
	v_mul_f32_e32 v38, 0xbfb8aa3b, v105
	v_exp_f32_e32 v38, v38
	v_mul_f32_e32 v36, 0x3fb8aa3b, v36
	v_mul_f32_e32 v37, 0x3fb8aa3b, v37
	v_exp_f32_e32 v36, v36
	v_add_f32_e32 v38, 1.0, v38
	v_rcp_f32_e32 v111, v38
	v_exp_f32_e32 v37, v37
	v_sub_f32_e32 v38, v92, v103
	v_mul_f32_e32 v38, 0x3fb8aa3b, v38
	v_exp_f32_e32 v41, v38
	v_lshlrev_b32_e32 v38, 16, v42
	v_pk_mul_f32 v[104:105], v[110:111], v[104:105]
	v_mul_f32_e64 v103, |v38|, s26
	v_pk_mul_f32 v[36:37], v[36:37], v[104:105]
	v_exp_f32_e32 v104, v103
	v_and_b32_e32 v42, 0xffff0000, v42
	v_cmp_le_f32_e32 vcc, 0, v38
	v_cmp_le_f32_e64 s[38:39], 0, v42
	v_add_f32_e32 v103, 1.0, v104
	v_rcp_f32_e32 v110, v103
	v_mul_f32_e64 v103, |v42|, s26
	v_exp_f32_e32 v105, v103
	v_sub_f32_e32 v38, v67, v93
	v_mul_f32_e32 v38, 0x3fb8aa3b, v38
	v_add_f32_e32 v103, 1.0, v105
	v_rcp_f32_e32 v111, v103
	s_nop 0
	v_pk_mul_f32 v[104:105], v[104:105], v[110:111]
	s_nop 0
	v_cndmask_b32_e32 v104, v110, v104, vcc
	v_lshlrev_b32_e32 v110, 16, v39
	v_cndmask_b32_e64 v105, v111, v105, s[38:39]
	v_and_b32_e32 v111, 0xffff0000, v39
	v_mul_f32_e32 v39, 0xbfb8aa3b, v110
	v_exp_f32_e32 v39, v39
	v_pk_mul_f32 v[104:105], v[74:75], v[104:105]
	v_add_f32_e32 v39, 1.0, v39
	v_rcp_f32_e32 v112, v39
	v_mul_f32_e32 v39, 0xbfb8aa3b, v111
	v_exp_f32_e32 v39, v39
	v_pk_mul_f32 v[104:105], v[40:41], v[104:105]
	v_sub_f32_e32 v41, v66, v94
	v_mul_f32_e32 v41, 0x3fb8aa3b, v41
	v_add_f32_e32 v39, 1.0, v39
	v_rcp_f32_e32 v113, v39
	v_exp_f32_e32 v40, v38
	v_exp_f32_e32 v41, v41
	v_sub_f32_e32 v39, v94, v66
	v_pk_mul_f32 v[110:111], v[112:113], v[110:111]
	v_lshlrev_b32_e32 v66, 16, v43
	v_pk_mul_f32 v[110:111], v[40:41], v[110:111]
	v_mul_f32_e64 v40, |v66|, s26
	v_exp_f32_e32 v40, v40
	v_sub_f32_e32 v38, v93, v67
	v_and_b32_e32 v67, 0xffff0000, v43
	v_mul_f32_e32 v38, 0x3fb8aa3b, v38
	v_add_f32_e32 v41, 1.0, v40
	v_rcp_f32_e32 v42, v41
	v_mul_f32_e64 v41, |v67|, s26
	v_exp_f32_e32 v41, v41
	v_mul_f32_e32 v39, 0x3fb8aa3b, v39
	v_exp_f32_e32 v38, v38
	v_exp_f32_e32 v39, v39
	v_add_f32_e32 v43, 1.0, v41
	v_rcp_f32_e32 v43, v43
	v_cmp_le_f32_e32 vcc, 0, v66
	v_cmp_le_f32_e64 s[38:39], 0, v67
	v_pk_mul_f32 v[40:41], v[40:41], v[42:43]
	s_nop 0
	v_cndmask_b32_e64 v41, v43, v41, s[38:39]
	v_cndmask_b32_e32 v40, v42, v40, vcc
	v_pk_mul_f32 v[40:41], v[68:69], v[40:41]
	v_cvt_pk_bf16_f32 v42, v36, v37
	v_pk_mul_f32 v[66:67], v[38:39], v[40:41]
	v_cvt_pk_bf16_f32 v40, v56, v57
	v_cvt_pk_bf16_f32 v36, v58, v59
	v_cvt_pk_bf16_f32 v39, v66, v67
	flat_load_dwordx4 v[56:59], v[76:77] offset:64
	s_nop 0
	flat_load_dwordx4 v[64:67], v[64:65] offset:64
	v_sub_f32_e32 v76, v102, v2
	v_sub_f32_e32 v77, v2, v102
	v_cvt_pk_bf16_f32 v38, v104, v105
	v_mul_f32_e32 v77, 0x3fb8aa3b, v77
	v_cvt_pk_bf16_f32 v41, v78, v79
	v_exp_f32_e32 v78, v77
	v_sub_f32_e32 v77, v101, v88
	v_mul_f32_e32 v76, 0x3fb8aa3b, v76
	v_mul_f32_e32 v77, 0x3fb8aa3b, v77
	v_exp_f32_e32 v76, v76
	v_exp_f32_e32 v77, v77
	v_mul_f32_e32 v2, 0x3fb8aa3b, v2
	v_cvt_pk_bf16_f32 v37, v106, v107
	v_cvt_pk_bf16_f32 v43, v110, v111
	s_waitcnt vmcnt(0) lgkmcnt(0)
	v_lshlrev_b32_e32 v102, 16, v64
	v_and_b32_e32 v103, 0xffff0000, v64
	v_mul_f32_e32 v64, 0xbfb8aa3b, v102
	v_exp_f32_e32 v64, v64
	s_nop 0
	v_add_f32_e32 v64, 1.0, v64
	v_rcp_f32_e32 v104, v64
	v_mul_f32_e32 v64, 0xbfb8aa3b, v103
	v_exp_f32_e32 v64, v64
	s_nop 0
	v_add_f32_e32 v64, 1.0, v64
	v_rcp_f32_e32 v105, v64
	v_sub_f32_e32 v64, v88, v101
	v_mul_f32_e32 v64, 0x3fb8aa3b, v64
	v_exp_f32_e32 v79, v64
	v_lshlrev_b32_e32 v64, 16, v56
	v_pk_mul_f32 v[102:103], v[104:105], v[102:103]
	v_mul_f32_e64 v101, |v64|, s26
	v_pk_mul_f32 v[76:77], v[76:77], v[102:103]
	v_exp_f32_e32 v102, v101
	v_and_b32_e32 v56, 0xffff0000, v56
	v_cmp_le_f32_e32 vcc, 0, v64
	v_cmp_le_f32_e64 s[38:39], 0, v56
	v_add_f32_e32 v101, 1.0, v102
	v_rcp_f32_e32 v104, v101
	v_mul_f32_e64 v101, |v56|, s26
	v_exp_f32_e32 v103, v101
	v_sub_f32_e32 v56, v100, v89
	v_mul_f32_e32 v56, 0x3fb8aa3b, v56
	v_lshlrev_b32_e32 v64, 16, v65
	v_add_f32_e32 v101, 1.0, v103
	v_rcp_f32_e32 v105, v101
	v_and_b32_e32 v65, 0xffff0000, v65
	v_pk_mul_f32 v[102:103], v[102:103], v[104:105]
	s_nop 0
	v_cndmask_b32_e64 v103, v105, v103, s[38:39]
	v_cndmask_b32_e32 v102, v104, v102, vcc
	v_pk_mul_f32 v[70:71], v[70:71], v[102:103]
	s_nop 0
	v_pk_mul_f32 v[70:71], v[78:79], v[70:71]
	v_exp_f32_e32 v78, v56
	v_sub_f32_e32 v56, v89, v100
	v_mul_f32_e32 v56, 0x3fb8aa3b, v56
	v_exp_f32_e32 v100, v56
	v_sub_f32_e32 v56, v99, v90
	v_mul_f32_e32 v56, 0x3fb8aa3b, v56
	v_exp_f32_e32 v79, v56
	v_mul_f32_e32 v56, 0xbfb8aa3b, v64
	v_exp_f32_e32 v56, v56
	s_nop 0
	v_add_f32_e32 v56, 1.0, v56
	v_rcp_f32_e32 v102, v56
	v_mul_f32_e32 v56, 0xbfb8aa3b, v65
	v_exp_f32_e32 v56, v56
	s_nop 0
	v_add_f32_e32 v56, 1.0, v56
	v_rcp_f32_e32 v103, v56
	v_sub_f32_e32 v56, v90, v99
	v_mul_f32_e32 v56, 0x3fb8aa3b, v56
	v_lshlrev_b32_e32 v99, 16, v57
	v_exp_f32_e32 v101, v56
	v_mul_f32_e64 v56, |v99|, s26
	v_exp_f32_e32 v56, v56
	v_pk_mul_f32 v[64:65], v[102:103], v[64:65]
	v_and_b32_e32 v102, 0xffff0000, v57
	v_pk_mul_f32 v[64:65], v[78:79], v[64:65]
	v_add_f32_e32 v57, 1.0, v56
	v_rcp_f32_e32 v78, v57
	v_mul_f32_e64 v57, |v102|, s26
	v_exp_f32_e32 v57, v57
	v_cmp_le_f32_e32 vcc, 0, v99
	v_cmp_le_f32_e64 s[38:39], 0, v102
	v_and_b32_e32 v99, 0xffff0000, v66
	v_add_f32_e32 v79, 1.0, v57
	v_rcp_f32_e32 v79, v79
	s_nop 0
; __device__ __forceinline__ void ld8bf(const bf16_t* p, float (&o)[8]) { unpack8(*(const u32x4*)p, o); }
; __device__ __forceinline__ float sigmoidf_(float x) { return __builtin_amdgcn_rcpf(1.0f + __expf(-x)); }
; __device__ __forceinline__ bf16x8 pack_frag(const float (&v)[8]) { return __builtin_bit_cast(bf16x8, pack8(v)); }
; __device__ __forceinline__ void w_hg_m3(const Args& a, int l, unsigned char* ws, const bf16_t* proj, bf16_t* y, LAS unsigned char* wl, int b, int ck_, int h, int lane) {
;     ...
;         for (int tb = 0; tb < 4; ++tb) { float fp[8], qv[8], a1[8], a2[8];
;             ld8bf(fsrc + (size_t)(16 * tb + lo) * NIN, fp); ld8bf(proj + (size_t)(row0 + 16 * tb + lo) * NIN + C_HQ + 64 * h + 32 * kk + 8 * fq, qv);
; #pragma unroll
;             for (int j = 0; j < 8; ++j) { float lf, key; hg_lf_key(fp[j], lbv[j], lf, key);
;                 const float q = qv[j] * sigmoidf_(qv[j]); a1[j] = q * __expf(bb[tb][j] - r31[j]); a2[j] = key * __expf(r31[j] - bb[tb][j]); }
;             Qf[tb][kk] = pack_frag(a1); Kf[tb][kk] = pack_frag(a2); }
; #pragma unroll
;         for (int j = 0; j < 8; ++j) er[kk][j] = __expf(r31[j]);
;         __builtin_amdgcn_sched_barrier(0);
;     }
; #pragma unroll
;     for (int kk = 0; kk < 2; ++kk)
; #pragma unroll
;         for (int eb = 0; eb < 4; ++eb) { float sv[8]; ld8bf(Sb + (16 * eb + lo) * 64 + 32 * kk + 8 * fq, sv);
; #pragma unroll
;             for (int j = 0; j < 8; ++j) sv[j] *= er[kk][j];
;             Sf[eb][kk] = pack_frag(sv); }
	v_pk_mul_f32 v[56:57], v[56:57], v[78:79]
	s_nop 0
	v_cndmask_b32_e64 v57, v79, v57, s[38:39]
	v_cndmask_b32_e32 v56, v78, v56, vcc
	v_pk_mul_f32 v[56:57], v[72:73], v[56:57]
	s_nop 0
	v_pk_mul_f32 v[72:73], v[100:101], v[56:57]
	v_sub_f32_e32 v56, v98, v91
	v_sub_f32_e32 v57, v91, v98
	v_lshlrev_b32_e32 v98, 16, v66
	v_mul_f32_e32 v66, 0xbfb8aa3b, v98
	v_exp_f32_e32 v66, v66
	v_mul_f32_e32 v57, 0x3fb8aa3b, v57
	v_exp_f32_e32 v78, v57
	v_sub_f32_e32 v57, v97, v92
	v_add_f32_e32 v66, 1.0, v66
	v_rcp_f32_e32 v100, v66
	v_mul_f32_e32 v66, 0xbfb8aa3b, v99
	v_exp_f32_e32 v66, v66
	v_mul_f32_e32 v56, 0x3fb8aa3b, v56
	v_mul_f32_e32 v57, 0x3fb8aa3b, v57
	v_exp_f32_e32 v56, v56
	v_add_f32_e32 v66, 1.0, v66
	v_rcp_f32_e32 v101, v66
	v_exp_f32_e32 v57, v57
	v_lshlrev_b32_e32 v66, 16, v58
	v_and_b32_e32 v58, 0xffff0000, v58
	v_pk_mul_f32 v[98:99], v[100:101], v[98:99]
	v_cmp_le_f32_e32 vcc, 0, v66
	v_pk_mul_f32 v[98:99], v[56:57], v[98:99]
	v_sub_f32_e32 v56, v92, v97
	v_mul_f32_e32 v56, 0x3fb8aa3b, v56
	v_exp_f32_e32 v79, v56
	v_mul_f32_e64 v56, |v66|, s26
	v_exp_f32_e32 v56, v56
	v_cmp_le_f32_e64 s[38:39], 0, v58
	v_add_f32_e32 v57, 1.0, v56
	v_rcp_f32_e32 v100, v57
	v_mul_f32_e64 v57, |v58|, s26
	v_exp_f32_e32 v57, v57
	s_nop 0
	v_add_f32_e32 v97, 1.0, v57
	v_rcp_f32_e32 v101, v97
	s_nop 0
	v_pk_mul_f32 v[56:57], v[56:57], v[100:101]
	s_nop 0
	v_cndmask_b32_e64 v57, v101, v57, s[38:39]
	v_cndmask_b32_e32 v56, v100, v56, vcc
	v_pk_mul_f32 v[56:57], v[74:75], v[56:57]
	v_exp_f32_e32 v100, v2
	v_pk_mul_f32 v[74:75], v[78:79], v[56:57]
	v_lshlrev_b32_e32 v78, 16, v67
	v_mul_f32_e32 v58, 0xbfb8aa3b, v78
	v_exp_f32_e32 v58, v58
	v_and_b32_e32 v79, 0xffff0000, v67
	v_sub_f32_e32 v56, v96, v93
	v_sub_f32_e32 v57, v93, v96
	v_add_f32_e32 v58, 1.0, v58
	v_rcp_f32_e32 v96, v58
	v_mul_f32_e32 v58, 0xbfb8aa3b, v79
	v_exp_f32_e32 v58, v58
	v_mul_f32_e32 v57, 0x3fb8aa3b, v57
	v_exp_f32_e32 v66, v57
	v_sub_f32_e32 v57, v95, v94
	v_add_f32_e32 v58, 1.0, v58
	v_mul_f32_e32 v56, 0x3fb8aa3b, v56
	v_mul_f32_e32 v57, 0x3fb8aa3b, v57
	v_rcp_f32_e32 v97, v58
	v_exp_f32_e32 v56, v56
	v_exp_f32_e32 v57, v57
	v_mul_f32_e32 v2, 0x3fb8aa3b, v88
	v_pk_mul_f32 v[78:79], v[96:97], v[78:79]
	v_and_b32_e32 v96, 0xffff0000, v59
	v_pk_mul_f32 v[78:79], v[56:57], v[78:79]
	v_sub_f32_e32 v56, v94, v95
	v_mul_f32_e32 v56, 0x3fb8aa3b, v56
	v_lshlrev_b32_e32 v95, 16, v59
	v_exp_f32_e32 v67, v56
	v_mul_f32_e64 v56, |v95|, s26
	v_exp_f32_e32 v56, v56
	v_exp_f32_e32 v101, v2
	v_mul_f32_e32 v2, 0x3fb8aa3b, v89
	v_exp_f32_e32 v102, v2
	v_add_f32_e32 v57, 1.0, v56
	v_rcp_f32_e32 v58, v57
	v_mul_f32_e64 v57, |v96|, s26
	v_exp_f32_e32 v57, v57
	v_mul_f32_e32 v2, 0x3fb8aa3b, v90
	v_cmp_le_f32_e32 vcc, 0, v95
	v_cmp_le_f32_e64 s[38:39], 0, v96
	v_add_f32_e32 v59, 1.0, v57
	v_rcp_f32_e32 v59, v59
	v_exp_f32_e32 v103, v2
	v_mul_f32_e32 v2, 0x3fb8aa3b, v91
	v_exp_f32_e32 v104, v2
	v_pk_mul_f32 v[56:57], v[56:57], v[58:59]
	v_mul_f32_e32 v2, 0x3fb8aa3b, v92
	v_cndmask_b32_e64 v57, v59, v57, s[38:39]
	v_cndmask_b32_e32 v56, v58, v56, vcc
	v_pk_mul_f32 v[56:57], v[68:69], v[56:57]
	v_exp_f32_e32 v105, v2
	v_mul_f32_e32 v2, 0x3fb8aa3b, v93
	v_pk_mul_f32 v[66:67], v[66:67], v[56:57]
	v_exp_f32_e32 v106, v2
	v_mul_f32_e32 v2, 0x3fb8aa3b, v94
	v_cvt_pk_bf16_f32 v56, v76, v77
	v_cvt_pk_bf16_f32 v57, v64, v65
	v_cvt_pk_bf16_f32 v58, v98, v99
	v_cvt_pk_bf16_f32 v59, v78, v79
	v_cvt_pk_bf16_f32 v68, v70, v71
	v_cvt_pk_bf16_f32 v69, v72, v73
	v_cvt_pk_bf16_f32 v70, v74, v75
	v_cvt_pk_bf16_f32 v71, v66, v67
	v_exp_f32_e32 v107, v2
	s_add_u32 s20, s80, s40
	s_addc_u32 s21, s81, s41
	v_lshl_add_u64 v[94:95], v[0:1], 1, s[20:21]
	v_lshlrev_b32_e32 v2, 7, v114
	v_lshl_add_u64 v[0:1], v[94:95], 0, v[2:3]
	global_load_dwordx4 v[146:149], v[0:1], off
	global_load_dwordx4 v[150:153], v[0:1], off offset:2048
	global_load_dwordx4 v[122:125], v[0:1], off offset:64
	global_load_dwordx4 v[134:137], v[0:1], off offset:2112
	v_mov_b32_e32 v130, 0x1000
	v_mov_b32_e32 v131, 0
	v_lshl_add_u64 v[186:187], v[0:1], 0, v[130:131]
	global_load_dwordx4 v[188:191], v[186:187], off
	global_load_dwordx4 v[192:195], v[186:187], off offset:2048
	global_load_dwordx4 v[196:199], v[186:187], off offset:64
	v_or_b32_e32 v92, 0x1000, v2
	v_mov_b32_e32 v93, v3
	v_or_b32_e32 v2, 0x1800, v2
	s_add_u32 s20, s67, s88
	v_lshlrev_b32_e32 v120, 2, v108
	s_addc_u32 s21, s68, 0
	v_cmp_gt_i32_e64 s[40:41], v120, v114
	s_add_u32 s48, s20, 0x1600
	s_mov_b32 s20, 12
	s_addc_u32 s49, s21, 0
	v_cmp_lt_i32_e64 s[42:43], v120, v114
	v_ashrrev_i32_e32 v121, 31, v120
	s_waitcnt vmcnt(0)
	v_mov_b64_e32 v[64:65], v[146:147]
	v_mov_b64_e32 v[66:67], v[148:149]
	v_lshlrev_b32_e32 v72, 16, v64
	v_and_b32_e32 v73, 0xffff0000, v64
	v_lshlrev_b32_e32 v64, 16, v65
	v_and_b32_e32 v65, 0xffff0000, v65
	v_pk_mul_f32 v[74:75], v[84:85], v[64:65]
	v_lshlrev_b32_e32 v64, 16, v66
	v_and_b32_e32 v65, 0xffff0000, v66
	v_pk_mul_f32 v[72:73], v[86:87], v[72:73]
	v_pk_mul_f32 v[76:77], v[82:83], v[64:65]
	v_lshlrev_b32_e32 v64, 16, v67
	v_and_b32_e32 v65, 0xffff0000, v67
	v_pk_mul_f32 v[78:79], v[80:81], v[64:65]
	v_cvt_pk_bf16_f32 v64, v72, v73
	v_cvt_pk_bf16_f32 v65, v74, v75
	v_mov_b64_e32 v[72:73], v[150:151]
	v_mov_b64_e32 v[74:75], v[152:153]
	v_cvt_pk_bf16_f32 v66, v76, v77
	v_cvt_pk_bf16_f32 v67, v78, v79
	s_waitcnt vmcnt(0)
; __device__ __forceinline__ void ld8bf(const bf16_t* p, float (&o)[8]) { unpack8(*(const u32x4*)p, o); }
; __device__ __forceinline__ bf16x8 pack_frag(const float (&v)[8]) { return __builtin_bit_cast(bf16x8, pack8(v)); }
; template <int KIND>
; __device__ __forceinline__ void w_m3_core(const bf16x8 (&Qf)[4][2], const bf16x8 (&Kf)[4][2], const bf16x8 (&Sf)[4][2], const LAS bf16_t* vT, float lg,
;                                           const bf16_t* gsrc, const float* nw, bf16_t* ydst, int lo, int fq) {
;     ...
;         for (int kk = 0; kk < 2; ++kk)
; #pragma unroll
;             for (int eb = 0; eb < 4; ++eb) O2[eb] = __builtin_amdgcn_mfma_f32_16x16x32_bf16(Sf[eb][kk], Qf[nb][kk], O2[eb], 0, 0, 0);
; __device__ __forceinline__ void w_hg_m3(const Args& a, int l, unsigned char* ws, const bf16_t* proj, bf16_t* y, LAS unsigned char* wl, int b, int ck_, int h, int lane) {
;     ...
; #pragma unroll
;     for (int kk = 0; kk < 2; ++kk)
; #pragma unroll
;         for (int eb = 0; eb < 4; ++eb) { float sv[8]; ld8bf(Sb + (16 * eb + lo) * 64 + 32 * kk + 8 * fq, sv);
; #pragma unroll
;             for (int j = 0; j < 8; ++j) sv[j] *= er[kk][j];
;             Sf[eb][kk] = pack_frag(sv); }
	v_lshlrev_b32_e32 v76, 16, v72
	v_and_b32_e32 v77, 0xffff0000, v72
	v_lshlrev_b32_e32 v72, 16, v73
	v_and_b32_e32 v73, 0xffff0000, v73
	v_pk_mul_f32 v[78:79], v[84:85], v[72:73]
	v_lshlrev_b32_e32 v72, 16, v74
	v_and_b32_e32 v73, 0xffff0000, v74
	v_pk_mul_f32 v[76:77], v[86:87], v[76:77]
	v_pk_mul_f32 v[88:89], v[82:83], v[72:73]
	v_lshlrev_b32_e32 v72, 16, v75
	v_and_b32_e32 v73, 0xffff0000, v75
	v_pk_mul_f32 v[90:91], v[80:81], v[72:73]
	v_cvt_pk_bf16_f32 v72, v76, v77
	v_lshl_add_u64 v[76:77], v[94:95], 0, v[92:93]
	v_cvt_pk_bf16_f32 v73, v78, v79
	v_mov_b64_e32 v[76:77], v[188:189]
	v_mov_b64_e32 v[78:79], v[190:191]
	v_cvt_pk_bf16_f32 v74, v88, v89
	v_cvt_pk_bf16_f32 v75, v90, v91
	s_waitcnt vmcnt(0)
	v_lshlrev_b32_e32 v88, 16, v76
	v_and_b32_e32 v89, 0xffff0000, v76
	v_lshlrev_b32_e32 v76, 16, v77
	v_and_b32_e32 v77, 0xffff0000, v77
	v_pk_mul_f32 v[90:91], v[84:85], v[76:77]
	v_lshlrev_b32_e32 v76, 16, v78
	v_and_b32_e32 v77, 0xffff0000, v78
	v_pk_mul_f32 v[88:89], v[86:87], v[88:89]
	v_pk_mul_f32 v[96:97], v[82:83], v[76:77]
	v_lshlrev_b32_e32 v76, 16, v79
	v_and_b32_e32 v77, 0xffff0000, v79
	v_pk_mul_f32 v[98:99], v[80:81], v[76:77]
	v_cvt_pk_bf16_f32 v76, v88, v89
	v_lshl_add_u64 v[88:89], v[94:95], 0, v[2:3]
	v_cvt_pk_bf16_f32 v77, v90, v91
	v_mov_b64_e32 v[88:89], v[192:193]
	v_mov_b64_e32 v[90:91], v[194:195]
	v_cvt_pk_bf16_f32 v78, v96, v97
	v_cvt_pk_bf16_f32 v79, v98, v99
	v_mfma_f32_16x16x32_bf16 v[116:119], v[72:75], v[52:55], 0
	s_waitcnt vmcnt(0)
	v_lshlrev_b32_e32 v96, 16, v88
	v_and_b32_e32 v97, 0xffff0000, v88
	v_lshlrev_b32_e32 v88, 16, v89
	v_and_b32_e32 v89, 0xffff0000, v89
	v_pk_mul_f32 v[84:85], v[84:85], v[88:89]
	v_lshlrev_b32_e32 v88, 16, v90
	v_and_b32_e32 v89, 0xffff0000, v90
	v_pk_mul_f32 v[86:87], v[86:87], v[96:97]
	v_pk_mul_f32 v[82:83], v[82:83], v[88:89]
	v_lshlrev_b32_e32 v88, 16, v91
	v_and_b32_e32 v89, 0xffff0000, v91
	v_pk_mul_f32 v[88:89], v[80:81], v[88:89]
	v_cvt_pk_bf16_f32 v80, v86, v87
	v_cvt_pk_bf16_f32 v81, v84, v85
	v_mov_b64_e32 v[84:85], v[122:123]
	v_mov_b64_e32 v[86:87], v[124:125]
	v_cvt_pk_bf16_f32 v82, v82, v83
	v_cvt_pk_bf16_f32 v83, v88, v89
	v_lshl_add_u64 v[96:97], v[94:95], 0, 64
	v_mfma_f32_16x16x32_bf16 v[138:141], v[76:79], v[52:55], 0
	s_waitcnt vmcnt(0)
	v_lshlrev_b32_e32 v88, 16, v84
	v_and_b32_e32 v89, 0xffff0000, v84
	v_lshlrev_b32_e32 v84, 16, v85
	v_and_b32_e32 v85, 0xffff0000, v85
	v_pk_mul_f32 v[90:91], v[102:103], v[84:85]
	v_lshlrev_b32_e32 v84, 16, v86
	v_and_b32_e32 v85, 0xffff0000, v86
	v_pk_mul_f32 v[88:89], v[100:101], v[88:89]
	v_pk_mul_f32 v[94:95], v[104:105], v[84:85]
	v_lshlrev_b32_e32 v84, 16, v87
	v_and_b32_e32 v85, 0xffff0000, v87
	v_pk_mul_f32 v[98:99], v[106:107], v[84:85]
	v_cvt_pk_bf16_f32 v84, v88, v89
	v_cvt_pk_bf16_f32 v85, v90, v91
	v_mov_b64_e32 v[88:89], v[134:135]
	v_mov_b64_e32 v[90:91], v[136:137]
	v_cvt_pk_bf16_f32 v86, v94, v95
	v_cvt_pk_bf16_f32 v87, v98, v99
	s_waitcnt vmcnt(0)
	v_lshlrev_b32_e32 v0, 16, v88
	v_and_b32_e32 v1, 0xffff0000, v88
	v_lshlrev_b32_e32 v88, 16, v89
	v_and_b32_e32 v89, 0xffff0000, v89
	v_pk_mul_f32 v[94:95], v[102:103], v[88:89]
	v_lshlrev_b32_e32 v88, 16, v90
	v_and_b32_e32 v89, 0xffff0000, v90
	v_pk_mul_f32 v[0:1], v[100:101], v[0:1]
	v_pk_mul_f32 v[98:99], v[104:105], v[88:89]
	v_lshlrev_b32_e32 v88, 16, v91
	v_and_b32_e32 v89, 0xffff0000, v91
	v_pk_mul_f32 v[110:111], v[106:107], v[88:89]
	v_cvt_pk_bf16_f32 v88, v0, v1
	v_lshl_add_u64 v[0:1], v[96:97], 0, v[92:93]
	v_cvt_pk_bf16_f32 v89, v94, v95
	v_mov_b64_e32 v[92:93], v[196:197]
	v_mov_b64_e32 v[94:95], v[198:199]
	v_cvt_pk_bf16_f32 v90, v98, v99
	v_cvt_pk_bf16_f32 v91, v110, v111
	s_waitcnt vmcnt(0)
	v_lshlrev_b32_e32 v0, 16, v92
	v_and_b32_e32 v1, 0xffff0000, v92
	v_lshlrev_b32_e32 v92, 16, v93
	v_and_b32_e32 v93, 0xffff0000, v93
	v_pk_mul_f32 v[98:99], v[102:103], v[92:93]
	v_lshlrev_b32_e32 v92, 16, v94
	v_and_b32_e32 v93, 0xffff0000, v94
	v_pk_mul_f32 v[0:1], v[100:101], v[0:1]
	v_pk_mul_f32 v[110:111], v[104:105], v[92:93]
	v_lshlrev_b32_e32 v92, 16, v95
	v_and_b32_e32 v93, 0xffff0000, v95
	v_pk_mul_f32 v[112:113], v[106:107], v[92:93]
	v_cvt_pk_bf16_f32 v92, v0, v1
	v_lshl_add_u64 v[0:1], v[96:97], 0, v[2:3]
	v_cvt_pk_bf16_f32 v93, v98, v99
	global_load_dwordx4 v[96:99], v[0:1], off
	v_or_b32_e32 v2, 2, v120
	s_waitcnt lgkmcnt(0)
	s_ashr_i32 s21, s20, 31
	v_cmp_gt_i32_e64 s[38:39], v2, v114
	s_lshl_b64 s[20:21], s[20:21], 3
	s_add_u32 s20, s0, s20
	s_addc_u32 s21, s1, s21
	v_cvt_pk_bf16_f32 v94, v110, v111
	s_load_dwordx2 s[20:21], s[20:21], 0x0
	v_cvt_pk_bf16_f32 v95, v112, v113
	v_mfma_f32_16x16x32_bf16 v[142:145], v[88:91], v[60:63], v[116:119]
	s_lshl_b64 s[34:35], s[36:37], 2
	s_waitcnt lgkmcnt(0)
	s_add_u32 s27, s20, s34
	v_mfma_f32_16x16x32_bf16 v[138:141], v[92:95], v[60:63], v[138:141]
	s_addc_u32 s35, s21, s35
	s_lshl_b64 s[20:21], s[24:25], 2
	s_add_u32 s34, s27, s20
	s_addc_u32 s35, s35, s21
	v_lshl_add_u64 v[186:187], v[120:121], 2, s[34:35]
	global_load_dwordx4 v[146:149], v[186:187], off
	global_load_dwordx4 v[150:153], v[186:187], off offset:64
	global_load_dwordx4 v[188:191], v[186:187], off offset:128
	global_load_dwordx4 v[192:195], v[186:187], off offset:192
	s_lshl_b64 s[20:21], s[86:87], 11
	s_add_u32 s20, s10, s20
	s_addc_u32 s21, s11, s21
	s_add_u32 s46, s20, s88
	s_addc_u32 s47, s21, 0
	s_waitcnt vmcnt(0)
; template <int KIND>
; __device__ __forceinline__ void w_m3_core(const bf16x8 (&Qf)[4][2], const bf16x8 (&Kf)[4][2], const bf16x8 (&Sf)[4][2], const LAS bf16_t* vT, float lg,
;                                           const bf16_t* gsrc, const float* nw, bf16_t* ydst, int lo, int fq) {
;     ...
; #pragma unroll
;         for (int kk2 = 0; kk2 < 2; ++kk2) {
;             if (2 * kk2 > nb) continue;
;             float pv[8];
; #pragma unroll
;             for (int hh = 0; hh < 2; ++hh) { const int mb = 2 * kk2 + hh;
;                 if (mb <= nb) { f32x4 s = {0.f, 0.f, 0.f, 0.f};
;                     s = __builtin_amdgcn_mfma_f32_16x16x32_bf16(Kf[mb][0], Qf[nb][0], s, 0, 0, 0); s = __builtin_amdgcn_mfma_f32_16x16x32_bf16(Kf[mb][1], Qf[nb][1], s, 0, 0, 0);
; #pragma unroll
;                     for (int r = 0; r < 4; ++r) { const int m = 16 * mb + 4 * fq + r, n = 16 * nb + lo; float v = s[r];
;                         if (KIND == 0) v *= __expf((float)(n - m) * lg);
;                         if (mb == nb) v = (m <= n) ? v : 0.f;
;                         pv[4 * hh + r] = v; }
;                 } else {
; #pragma unroll
;                     for (int r = 0; r < 4; ++r) pv[4 * hh + r] = 0.f; }
;             }
;             const bf16x8 Pf = pack_frag(pv);
; #pragma unroll
;             for (int eb = 0; eb < 4; ++eb)
;                 O[eb] = __builtin_amdgcn_mfma_f32_16x16x32_bf16(tr_frag(vT, 32 * kk2 + 4 * fq, 32 * kk2 + 16 + 4 * fq, 16 * eb, lo), Pf, O[eb], 0, 0, 0);
;         }
; #pragma unroll
;         for (int kk = 0; kk < 2; ++kk)
; #pragma unroll
;             for (int eb = 0; eb < 4; ++eb) O2[eb] = __builtin_amdgcn_mfma_f32_16x16x32_bf16(Sf[eb][kk], Qf[nb][kk], O2[eb], 0, 0, 0);
;         const float osc = KIND == 0 ? __expf((float)(16 * nb + lo + 1) * lg) : 1.0f;
; #pragma unroll
;         for (int eb = 0; eb < 4; ++eb) O[eb] = O[eb] + O2[eb] * osc;
;         float ss = 0.f;
; #pragma unroll
;         for (int eb = 0; eb < 4; ++eb) ss += (O[eb][0] * O[eb][0] + O[eb][1] * O[eb][1]) + (O[eb][2] * O[eb][2] + O[eb][3] * O[eb][3]);
;         { const int ln = (fq << 4) | lo; ss += bperm_f(ln ^ 16, ss); ss += bperm_f(ln ^ 32, ss); }
;         const float rs = rsqrtf(ss * (1.0f / 64.0f) + EPS);
;         const size_t n = 16 * nb + lo;
; #pragma unroll
;         for (int eb = 0; eb < 4; ++eb) { const int e0 = 16 * eb + 4 * fq;
	v_lshlrev_b32_e32 v0, 16, v96
	v_and_b32_e32 v1, 0xffff0000, v96
	v_lshlrev_b32_e32 v96, 16, v97
	v_and_b32_e32 v97, 0xffff0000, v97
	v_pk_mul_f32 v[0:1], v[100:101], v[0:1]
	v_pk_mul_f32 v[100:101], v[102:103], v[96:97]
	v_lshlrev_b32_e32 v96, 16, v98
	v_and_b32_e32 v97, 0xffff0000, v98
	v_pk_mul_f32 v[102:103], v[104:105], v[96:97]
	v_lshlrev_b32_e32 v96, 16, v99
	v_and_b32_e32 v97, 0xffff0000, v99
	v_pk_mul_f32 v[104:105], v[106:107], v[96:97]
	v_cvt_pk_bf16_f32 v97, v100, v101
	v_cvt_pk_bf16_f32 v98, v102, v103
	v_mfma_f32_16x16x32_bf16 v[100:103], v[20:23], v[52:55], 0
	v_cvt_pk_bf16_f32 v96, v0, v1
	v_lshrrev_b32_e32 v0, 2, v114
	v_lshlrev_b32_e32 v1, 3, v114
	v_mfma_f32_16x16x32_bf16 v[100:103], v[24:27], v[60:63], v[100:103]
	v_cvt_pk_bf16_f32 v99, v104, v105
	v_or_b32_e32 v104, v120, v0
	v_lshlrev_b32_e32 v0, 2, v114
	v_and_b32_e32 v105, 24, v1
	v_lshlrev_b32_e32 v1, 6, v108
	v_bitop3_b32 v130, v1, 64, v0 bitop3:0x36
	v_bitop3_b32 v129, v1, s96, v0 bitop3:0x36
	s_nop 0
	v_cndmask_b32_e64 v0, v100, 0, s[40:41]
	v_or_b32_e32 v100, 3, v120
	v_cmp_gt_i32_e32 vcc, v100, v114
	v_cndmask_b32_e64 v1, 0, v101, s[42:43]
	v_cndmask_b32_e64 v2, v102, 0, s[38:39]
	v_cndmask_b32_e64 v100, v103, 0, vcc
	v_cvt_pk_bf16_f32 v0, v0, v1
	v_cvt_pk_bf16_f32 v1, v2, v100
	v_mul_lo_u32 v100, v104, s23
	v_add3_u32 v131, s2, v105, v100
	ds_read_b64_tr_b16 v[102:103], v131 offset:2304
	ds_read_b64_tr_b16 v[100:101], v131
	ds_read_b64_tr_b16 v[104:105], v131 offset:32
	ds_read_b64_tr_b16 v[106:107], v131 offset:2336
	ds_read_b64_tr_b16 v[108:109], v131 offset:64
	ds_read_b64_tr_b16 v[110:111], v131 offset:2368
	v_mov_b32_e32 v2, v3
	s_waitcnt lgkmcnt(0)
	s_nop 0
	v_mfma_f32_16x16x32_bf16 v[122:125], v[108:111], v[0:3], 0
	ds_read_b64_tr_b16 v[108:109], v131 offset:96
	ds_read_b64_tr_b16 v[110:111], v131 offset:2400
	s_waitcnt lgkmcnt(0)
	v_mfma_f32_16x16x32_bf16 v[134:137], v[108:111], v[0:3], 0
	v_mfma_f32_16x16x32_bf16 v[108:111], v[64:67], v[52:55], 0
	v_mfma_f32_16x16x32_bf16 v[52:55], v[80:83], v[52:55], 0
	v_mfma_f32_16x16x32_bf16 v[100:103], v[100:103], v[0:3], 0
	v_mfma_f32_16x16x32_bf16 v[108:111], v[84:87], v[60:63], v[108:111]
	v_mfma_f32_16x16x32_bf16 v[104:107], v[104:107], v[0:3], 0
	v_mfma_f32_16x16x32_bf16 v[52:55], v[96:99], v[60:63], v[52:55]
	s_nop 5
	v_add_f32_e64 v116, v102, v110
	v_add_f32_e64 v117, v103, v111
	v_pk_add_f32 v[118:119], v[100:101], v[108:109]
	v_pk_add_f32 v[112:113], v[104:105], v[142:143]
	v_pk_add_f32 v[110:111], v[106:107], v[144:145]
	v_pk_add_f32 v[108:109], v[122:123], v[138:139]
	v_pk_add_f32 v[0:1], v[136:137], v[54:55]
	v_pk_add_f32 v[104:105], v[134:135], v[52:53]
	v_pk_mul_f32 v[52:53], v[116:117], v[116:117]
	v_pk_mul_f32 v[54:55], v[118:119], v[118:119]
	v_mul_f32_e32 v2, v104, v104
	v_pk_mov_b32 v[60:61], v[54:55], v[52:53] op_sel:[1,0]
	v_mov_b32_e32 v55, v53
	v_pk_add_f32 v[52:53], v[60:61], v[54:55]
	v_pk_mul_f32 v[54:55], v[110:111], v[110:111]
	v_pk_mul_f32 v[60:61], v[112:113], v[112:113]
	v_pk_add_f32 v[52:53], v[52:53], v[52:53] op_sel:[0,1] op_sel_hi:[1,0]
	v_pk_mov_b32 v[62:63], v[60:61], v[54:55] op_sel:[1,0]
	v_mov_b32_e32 v61, v55
	v_pk_add_f32 v[54:55], v[62:63], v[60:61]
	v_mul_f32_e32 v60, v105, v105
	v_pk_add_f32 v[54:55], v[54:55], v[54:55] op_sel:[0,1] op_sel_hi:[1,0]
	v_pk_add_f32 v[106:107], v[124:125], v[140:141]
	v_mov_b32_e32 v53, v2
	v_mov_b32_e32 v55, v60
	v_mul_f32_e32 v2, v109, v109
	v_mul_f32_e32 v61, v0, v0
	v_pk_add_f32 v[52:53], v[52:53], v[54:55]
	v_pk_fma_f32 v[54:55], v[108:109], v[108:109], v[2:3] op_sel_hi:[1,1,0]
	v_mul_f32_e32 v2, v107, v107
	v_mul_f32_e32 v62, v1, v1
	v_mov_b32_e32 v55, v61
	v_pk_fma_f32 v[60:61], v[106:107], v[106:107], v[2:3] op_sel_hi:[1,1,0]
	v_mov_b64_e32 v[100:101], s[48:49]
	v_mov_b32_e32 v61, v62
	v_pk_add_f32 v[54:55], v[54:55], v[60:61]
	v_lshlrev_b64 v[62:63], 1, v[120:121]
	v_pk_add_f32 v[52:53], v[52:53], v[54:55]
	v_lshl_add_u64 v[60:61], v[120:121], 2, s[34:35]
	v_add_f32_e32 v2, v52, v53
	ds_bpermute_b32 v52, v130, v2
	s_waitcnt lgkmcnt(0)
	v_add_f32_e32 v2, v2, v52
	ds_bpermute_b32 v52, v129, v2
	s_waitcnt lgkmcnt(0)
	v_add_f32_e32 v2, v2, v52
	v_fmamk_f32 v2, v2, 0x3c800000, v200
	v_cmp_gt_f32_e64 s[44:45], s29, v2
	v_mul_f32_e32 v52, 0x4b800000, v2
	s_nop 0
	v_cndmask_b32_e64 v2, v2, v52, s[44:45]
	v_rsq_f32_e32 v2, v2
	s_nop 0
	v_mul_f32_e32 v52, 0x45800000, v2
	v_cndmask_b32_e64 v102, v2, v52, s[44:45]
	v_mad_u64_u32 v[52:53], s[20:21], v114, s72, v[100:101]
	v_lshlrev_b32_e32 v2, 11, v114
	v_lshl_add_u64 v[114:115], v[52:53], 0, v[62:63]
	v_mov_b64_e32 v[124:125], v[222:223]
	v_mov_b64_e32 v[52:53], v[146:147]
	v_mov_b64_e32 v[54:55], v[148:149]
	v_lshl_add_u64 v[122:123], s[46:47], 0, v[2:3]
	v_pk_mul_f32 v[118:119], v[118:119], v[102:103] op_sel_hi:[1,0]
	v_pk_mul_f32 v[116:117], v[116:117], v[102:103] op_sel_hi:[1,0]
	v_pk_mul_f32 v[112:113], v[112:113], v[102:103] op_sel_hi:[1,0]
	v_pk_mul_f32 v[110:111], v[110:111], v[102:103] op_sel_hi:[1,0]
	s_waitcnt lgkmcnt(0)
	v_lshlrev_b32_e32 v120, 16, v124
	v_mul_f32_e32 v2, 0xbfb8aa3b, v120
	v_exp_f32_e32 v2, v2
	v_and_b32_e32 v121, 0xffff0000, v124
	v_lshlrev_b32_e32 v124, 16, v125
	v_and_b32_e32 v125, 0xffff0000, v125
	v_add_f32_e32 v2, 1.0, v2
	v_rcp_f32_e32 v134, v2
	v_mul_f32_e32 v2, 0xbfb8aa3b, v121
	v_exp_f32_e32 v2, v2
	v_pk_mul_f32 v[52:53], v[52:53], v[118:119]
	v_pk_mul_f32 v[54:55], v[54:55], v[116:117]
	v_add_f32_e32 v2, 1.0, v2
	v_rcp_f32_e32 v135, v2
	v_mul_f32_e32 v2, 0xbfb8aa3b, v124
	v_exp_f32_e32 v2, v2
	v_pk_mul_f32 v[118:119], v[134:135], v[120:121]
	s_nop 0
	v_pk_mul_f32 v[52:53], v[118:119], v[52:53]
	v_add_f32_e32 v2, 1.0, v2
	v_rcp_f32_e32 v118, v2
	v_mul_f32_e32 v2, 0xbfb8aa3b, v125
	v_exp_f32_e32 v2, v2
	s_nop 0
	v_add_f32_e32 v2, 1.0, v2
	v_rcp_f32_e32 v119, v2
	s_nop 0
	v_pk_mul_f32 v[116:117], v[118:119], v[124:125]
	s_nop 0
	v_pk_mul_f32 v[54:55], v[116:117], v[54:55]
	v_cvt_pk_bf16_f32 v116, v52, v53
	v_cvt_pk_bf16_f32 v117, v54, v55
	v_lshl_add_u64 v[52:53], v[122:123], 0, v[62:63]
	global_store_dwordx2 v[52:53], v[116:117], off offset:1536
	v_mov_b64_e32 v[54:55], v[224:225]
	s_nop 0
	v_mov_b64_e32 v[116:117], v[150:151]
	v_mov_b64_e32 v[118:119], v[152:153]
	s_waitcnt lgkmcnt(0)
; __device__ __forceinline__ bf16x8 pack_frag(const float (&v)[8]) { return __builtin_bit_cast(bf16x8, pack8(v)); }
; template <int KIND>
; __device__ __forceinline__ void w_m3_core(const bf16x8 (&Qf)[4][2], const bf16x8 (&Kf)[4][2], const bf16x8 (&Sf)[4][2], const LAS bf16_t* vT, float lg,
;                                           const bf16_t* gsrc, const float* nw, bf16_t* ydst, int lo, int fq) {
;     ...
;                 if (mb <= nb) { f32x4 s = {0.f, 0.f, 0.f, 0.f};
;                     s = __builtin_amdgcn_mfma_f32_16x16x32_bf16(Kf[mb][0], Qf[nb][0], s, 0, 0, 0); s = __builtin_amdgcn_mfma_f32_16x16x32_bf16(Kf[mb][1], Qf[nb][1], s, 0, 0, 0);
; #pragma unroll
;                     for (int r = 0; r < 4; ++r) { const int m = 16 * mb + 4 * fq + r, n = 16 * nb + lo; float v = s[r];
;                         if (KIND == 0) v *= __expf((float)(n - m) * lg);
;                         if (mb == nb) v = (m <= n) ? v : 0.f;
;                         pv[4 * hh + r] = v; }
;                 } else {
; #pragma unroll
;                     for (int r = 0; r < 4; ++r) pv[4 * hh + r] = 0.f; }
;             }
;             const bf16x8 Pf = pack_frag(pv);
; #pragma unroll
;             for (int eb = 0; eb < 4; ++eb)
;                 O[eb] = __builtin_amdgcn_mfma_f32_16x16x32_bf16(tr_frag(vT, 32 * kk2 + 4 * fq, 32 * kk2 + 16 + 4 * fq, 16 * eb, lo), Pf, O[eb], 0, 0, 0);
;         }
; #pragma unroll
;         for (int kk = 0; kk < 2; ++kk)
; #pragma unroll
;             for (int eb = 0; eb < 4; ++eb) O2[eb] = __builtin_amdgcn_mfma_f32_16x16x32_bf16(Sf[eb][kk], Qf[nb][kk], O2[eb], 0, 0, 0);
;         const float osc = KIND == 0 ? __expf((float)(16 * nb + lo + 1) * lg) : 1.0f;
; #pragma unroll
;         for (int eb = 0; eb < 4; ++eb) O[eb] = O[eb] + O2[eb] * osc;
;         float ss = 0.f;
; #pragma unroll
;         for (int eb = 0; eb < 4; ++eb) ss += (O[eb][0] * O[eb][0] + O[eb][1] * O[eb][1]) + (O[eb][2] * O[eb][2] + O[eb][3] * O[eb][3]);
;         { const int ln = (fq << 4) | lo; ss += bperm_f(ln ^ 16, ss); ss += bperm_f(ln ^ 32, ss); }
;         const float rs = rsqrtf(ss * (1.0f / 64.0f) + EPS);
;         const size_t n = 16 * nb + lo;
; #pragma unroll
;         for (int eb = 0; eb < 4; ++eb) { const int e0 = 16 * eb + 4 * fq;
;             const unsigned long long gw_ = *(const unsigned long long*)(gsrc + n * NIN + e0); const f32x4 w4 = *(const f32x4*)(nw + e0);
	v_lshlrev_b32_e32 v120, 16, v54
	v_mul_f32_e32 v2, 0xbfb8aa3b, v120
	v_exp_f32_e32 v2, v2
	v_and_b32_e32 v121, 0xffff0000, v54
	v_lshlrev_b32_e32 v54, 16, v55
	v_and_b32_e32 v55, 0xffff0000, v55
	v_add_f32_e32 v2, 1.0, v2
	v_rcp_f32_e32 v122, v2
	v_mul_f32_e32 v2, 0xbfb8aa3b, v121
	v_exp_f32_e32 v2, v2
	v_pk_mul_f32 v[112:113], v[116:117], v[112:113]
	v_pk_mul_f32 v[110:111], v[118:119], v[110:111]
	v_mul_f32_e32 v118, v109, v102
	v_add_f32_e32 v2, 1.0, v2
	v_rcp_f32_e32 v123, v2
	v_mul_f32_e32 v2, 0xbfb8aa3b, v54
	v_exp_f32_e32 v2, v2
	v_pk_mul_f32 v[116:117], v[122:123], v[120:121]
	s_nop 0
	v_pk_mul_f32 v[112:113], v[116:117], v[112:113]
	v_add_f32_e32 v2, 1.0, v2
	v_rcp_f32_e32 v116, v2
	v_mul_f32_e32 v2, 0xbfb8aa3b, v55
	v_exp_f32_e32 v2, v2
	v_mul_f32_e32 v120, v106, v102
	v_add_f32_e32 v2, 1.0, v2
	v_rcp_f32_e32 v117, v2
	s_nop 0
	v_pk_mul_f32 v[54:55], v[116:117], v[54:55]
	s_nop 0
	v_pk_mul_f32 v[54:55], v[54:55], v[110:111]
	v_cvt_pk_bf16_f32 v110, v112, v113
	v_cvt_pk_bf16_f32 v111, v54, v55
	global_store_dwordx2 v[52:53], v[110:111], off offset:1568
	v_mov_b64_e32 v[54:55], v[226:227]
	s_nop 0
	v_mov_b64_e32 v[110:111], v[188:189]
	v_mov_b64_e32 v[112:113], v[190:191]
	v_mul_f32_e32 v116, v108, v102
	s_waitcnt lgkmcnt(0)
	v_lshlrev_b32_e32 v117, 16, v54
	v_mul_f32_e32 v2, 0xbfb8aa3b, v117
	v_exp_f32_e32 v2, v2
	v_and_b32_e32 v119, 0xffff0000, v54
	v_lshlrev_b32_e32 v121, 16, v55
	v_and_b32_e32 v55, 0xffff0000, v55
	v_add_f32_e32 v2, 1.0, v2
	v_rcp_f32_e32 v123, v2
	v_mul_f32_e32 v2, 0xbfb8aa3b, v119
	v_exp_f32_e32 v2, v2
	v_mov_b32_e32 v108, v111
	v_mul_f32_e32 v54, v107, v102
	v_mov_b32_e32 v122, v110
	v_add_f32_e32 v2, 1.0, v2
	v_rcp_f32_e32 v109, v2
	v_mul_f32_e32 v2, 0xbfb8aa3b, v121
	v_exp_f32_e32 v2, v2
	v_pk_mul_f32 v[116:117], v[122:123], v[116:117]
	v_pk_mul_f32 v[108:109], v[108:109], v[118:119]
	v_mov_b32_e32 v110, v112
	v_add_f32_e32 v2, 1.0, v2
	v_rcp_f32_e32 v111, v2
	v_mul_f32_e32 v2, 0xbfb8aa3b, v55
	v_exp_f32_e32 v2, v2
	v_mov_b32_e32 v106, v113
	v_pk_mul_f32 v[110:111], v[110:111], v[120:121]
	v_mul_f32_e32 v112, v105, v102
	v_add_f32_e32 v2, 1.0, v2
	v_rcp_f32_e32 v107, v2
	s_nop 0
	v_pk_mul_f32 v[54:55], v[106:107], v[54:55]
	v_mov_b32_e32 v106, v116
	v_mov_b32_e32 v107, v108
	v_mov_b32_e32 v108, v117
	v_pk_mul_f32 v[106:107], v[106:107], v[108:109]
	v_mov_b32_e32 v108, v110
	v_mov_b32_e32 v109, v54
	v_mov_b32_e32 v54, v111
	v_pk_mul_f32 v[54:55], v[108:109], v[54:55]
	v_cvt_pk_bf16_f32 v106, v106, v107
	v_cvt_pk_bf16_f32 v107, v54, v55
	global_store_dwordx2 v[52:53], v[106:107], off offset:1600
	v_mov_b64_e32 v[54:55], v[228:229]
	s_nop 0
	v_mov_b64_e32 v[106:107], v[192:193]
	v_mov_b64_e32 v[108:109], v[194:195]
	v_mul_f32_e32 v114, v0, v102
	v_mul_f32_e32 v110, v104, v102
	s_waitcnt lgkmcnt(0)
	v_lshlrev_b32_e32 v111, 16, v54
	v_lshlrev_b32_e32 v115, 16, v55
	v_mul_f32_e32 v2, 0xbfb8aa3b, v111
	v_mul_f32_e32 v0, 0xbfb8aa3b, v115
	v_exp_f32_e32 v2, v2
	v_exp_f32_e32 v0, v0
	v_and_b32_e32 v113, 0xffff0000, v54
	v_and_b32_e32 v55, 0xffff0000, v55
	v_add_f32_e32 v2, 1.0, v2
	v_add_f32_e32 v0, 1.0, v0
	v_rcp_f32_e32 v117, v2
	v_mul_f32_e32 v2, 0xbfb8aa3b, v113
	v_mov_b32_e32 v104, v107
	v_rcp_f32_e32 v107, v0
	v_mul_f32_e32 v0, 0xbfb8aa3b, v55
	v_exp_f32_e32 v2, v2
	v_exp_f32_e32 v0, v0
	v_mul_f32_e32 v54, v1, v102
	v_mov_b32_e32 v116, v106
	v_add_f32_e32 v2, 1.0, v2
	v_add_f32_e32 v0, 1.0, v0
	v_rcp_f32_e32 v105, v2
	v_rcp_f32_e32 v1, v0
	v_mov_b32_e32 v106, v108
	v_mov_b32_e32 v0, v109
	v_pk_mul_f32 v[110:111], v[116:117], v[110:111]
	v_pk_mul_f32 v[104:105], v[104:105], v[112:113]
	v_pk_mul_f32 v[106:107], v[106:107], v[114:115]
	v_pk_mul_f32 v[0:1], v[0:1], v[54:55]
	v_mov_b32_e32 v54, v110
	v_mov_b32_e32 v55, v104
	v_mov_b32_e32 v104, v111
	v_mov_b32_e32 v102, v106
	v_mov_b32_e32 v103, v0
	v_mov_b32_e32 v0, v107
	v_pk_mul_f32 v[54:55], v[54:55], v[104:105]
	v_pk_mul_f32 v[0:1], v[102:103], v[0:1]
	v_cvt_pk_bf16_f32 v54, v54, v55
	v_cvt_pk_bf16_f32 v55, v0, v1
	global_store_dwordx2 v[52:53], v[54:55], off offset:1632
	v_mfma_f32_16x16x32_bf16 v[102:105], v[16:19], v[44:47], 0
	v_mfma_f32_16x16x32_bf16 v[52:55], v[20:23], v[44:47], 0
	v_mfma_f32_16x16x32_bf16 v[102:105], v[32:35], v[48:51], v[102:105]
	v_mfma_f32_16x16x32_bf16 v[52:55], v[24:27], v[48:51], v[52:55]
	v_mfma_f32_16x16x32_bf16 v[134:137], v[76:79], v[44:47], 0
	s_nop 5
	v_cndmask_b32_e64 v0, v102, 0, s[40:41]
	v_cndmask_b32_e64 v2, v104, 0, s[38:39]
	v_cndmask_b32_e64 v102, v105, 0, vcc
	v_cndmask_b32_e64 v1, 0, v103, s[42:43]
	v_cvt_pk_bf16_f32 v52, v52, v53
	v_cvt_pk_bf16_f32 v53, v54, v55
	v_cvt_pk_bf16_f32 v55, v2, v102
	ds_read_b64_tr_b16 v[104:105], v131 offset:2304
	ds_read_b64_tr_b16 v[102:103], v131
	ds_read_b64_tr_b16 v[106:107], v131 offset:32
	ds_read_b64_tr_b16 v[108:109], v131 offset:2336
	v_cvt_pk_bf16_f32 v54, v0, v1
	v_mfma_f32_16x16x32_bf16 v[134:137], v[92:95], v[48:51], v[134:137]
	s_waitcnt lgkmcnt(0)
	v_mfma_f32_16x16x32_bf16 v[112:115], v[106:109], v[52:55], 0
	ds_read_b64_tr_b16 v[106:107], v131 offset:64
	ds_read_b64_tr_b16 v[108:109], v131 offset:2368
	s_waitcnt lgkmcnt(0)
	v_mfma_f32_16x16x32_bf16 v[116:119], v[106:109], v[52:55], 0
	ds_read_b64_tr_b16 v[106:107], v131 offset:96
	ds_read_b64_tr_b16 v[108:109], v131 offset:2400
	v_mfma_f32_16x16x32_bf16 v[102:105], v[102:105], v[52:55], 0
	s_waitcnt lgkmcnt(0)
; __device__ __forceinline__ unsigned pk2(float lo, float hi) { const f32x2_t v = {lo, hi}; const bf16x2_t b = __builtin_convertvector(v, bf16x2_t); return __builtin_bit_cast(unsigned, b); }
; template <int KIND>
; __device__ __forceinline__ void w_m3_core(const bf16x8 (&Qf)[4][2], const bf16x8 (&Kf)[4][2], const bf16x8 (&Sf)[4][2], const LAS bf16_t* vT, float lg,
;                                           const bf16_t* gsrc, const float* nw, bf16_t* ydst, int lo, int fq) {
;     ...
;             for (int eb = 0; eb < 4; ++eb)
;                 O[eb] = __builtin_amdgcn_mfma_f32_16x16x32_bf16(tr_frag(vT, 32 * kk2 + 4 * fq, 32 * kk2 + 16 + 4 * fq, 16 * eb, lo), Pf, O[eb], 0, 0, 0);
;         }
; #pragma unroll
;         for (int kk = 0; kk < 2; ++kk)
; #pragma unroll
;             for (int eb = 0; eb < 4; ++eb) O2[eb] = __builtin_amdgcn_mfma_f32_16x16x32_bf16(Sf[eb][kk], Qf[nb][kk], O2[eb], 0, 0, 0);
;         const float osc = KIND == 0 ? __expf((float)(16 * nb + lo + 1) * lg) : 1.0f;
; #pragma unroll
;         for (int eb = 0; eb < 4; ++eb) O[eb] = O[eb] + O2[eb] * osc;
;         float ss = 0.f;
; #pragma unroll
;         for (int eb = 0; eb < 4; ++eb) ss += (O[eb][0] * O[eb][0] + O[eb][1] * O[eb][1]) + (O[eb][2] * O[eb][2] + O[eb][3] * O[eb][3]);
;         { const int ln = (fq << 4) | lo; ss += bperm_f(ln ^ 16, ss); ss += bperm_f(ln ^ 32, ss); }
;         const float rs = rsqrtf(ss * (1.0f / 64.0f) + EPS);
;         const size_t n = 16 * nb + lo;
; #pragma unroll
;         for (int eb = 0; eb < 4; ++eb) { const int e0 = 16 * eb + 4 * fq;
;             const unsigned long long gw_ = *(const unsigned long long*)(gsrc + n * NIN + e0); const f32x4 w4 = *(const f32x4*)(nw + e0);
;             const float g0 = __uint_as_float((unsigned)gw_ << 16), g1 = __uint_as_float((unsigned)gw_ & 0xffff0000u), g2 = __uint_as_float((unsigned)(gw_ >> 32) << 16), g3 = __uint_as_float((unsigned)(gw_ >> 32) & 0xffff0000u);
;             const float o0 = O[eb][0] * rs * w4[0] * (g0 * sigmoidf_(g0)), o1 = O[eb][1] * rs * w4[1] * (g1 * sigmoidf_(g1));
;             const float o2 = O[eb][2] * rs * w4[2] * (g2 * sigmoidf_(g2)), o3 = O[eb][3] * rs * w4[3] * (g3 * sigmoidf_(g3));
;             *(unsigned long long*)(ydst + n * DM + e0) = (unsigned long long)pk2(o0, o1) | ((unsigned long long)pk2(o2, o3) << 32); }
	v_mfma_f32_16x16x32_bf16 v[120:123], v[106:109], v[52:55], 0
	v_mfma_f32_16x16x32_bf16 v[52:55], v[64:67], v[44:47], 0
	v_mfma_f32_16x16x32_bf16 v[106:109], v[72:75], v[44:47], 0
	v_mfma_f32_16x16x32_bf16 v[44:47], v[80:83], v[44:47], 0
	v_mfma_f32_16x16x32_bf16 v[52:55], v[84:87], v[48:51], v[52:55]
	v_mfma_f32_16x16x32_bf16 v[44:47], v[96:99], v[48:51], v[44:47]
	v_mfma_f32_16x16x32_bf16 v[138:141], v[88:91], v[48:51], v[106:109]
	s_nop 5
	v_add_f32_e64 v110, v102, v52
	v_add_f32_e64 v111, v103, v53
	v_pk_add_f32 v[0:1], v[122:123], v[46:47]
	v_pk_add_f32 v[50:51], v[120:121], v[44:45]
	v_pk_add_f32 v[108:109], v[104:105], v[54:55]
	v_pk_mul_f32 v[46:47], v[110:111], v[110:111]
	v_pk_mul_f32 v[44:45], v[108:109], v[108:109]
	v_pk_add_f32 v[104:105], v[114:115], v[140:141]
	v_pk_add_f32 v[106:107], v[112:113], v[138:139]
	v_pk_mov_b32 v[48:49], v[46:47], v[44:45] op_sel:[1,0]
	v_mov_b32_e32 v47, v45
	v_pk_add_f32 v[44:45], v[48:49], v[46:47]
	v_pk_mul_f32 v[46:47], v[104:105], v[104:105]
	v_pk_mul_f32 v[48:49], v[106:107], v[106:107]
	v_pk_add_f32 v[54:55], v[116:117], v[134:135]
	v_pk_mov_b32 v[102:103], v[48:49], v[46:47] op_sel:[1,0]
	v_mov_b32_e32 v49, v47
	v_pk_add_f32 v[46:47], v[102:103], v[48:49]
	v_mul_f32_e32 v2, v50, v50
	v_mul_f32_e32 v48, v51, v51
	v_pk_add_f32 v[44:45], v[44:45], v[44:45] op_sel:[0,1] op_sel_hi:[1,0]
	v_pk_add_f32 v[46:47], v[46:47], v[46:47] op_sel:[0,1] op_sel_hi:[1,0]
	v_pk_add_f32 v[52:53], v[118:119], v[136:137]
	v_mov_b32_e32 v45, v2
	v_mov_b32_e32 v47, v48
	v_mul_f32_e32 v2, v55, v55
	v_mul_f32_e32 v49, v0, v0
	v_pk_add_f32 v[44:45], v[44:45], v[46:47]
	v_pk_fma_f32 v[46:47], v[54:55], v[54:55], v[2:3] op_sel_hi:[1,1,0]
	v_mul_f32_e32 v2, v53, v53
	v_mul_f32_e32 v102, v1, v1
	v_mov_b32_e32 v47, v49
	v_pk_fma_f32 v[48:49], v[52:53], v[52:53], v[2:3] op_sel_hi:[1,1,0]
	s_nop 0
	v_mov_b32_e32 v49, v102
	v_pk_add_f32 v[46:47], v[46:47], v[48:49]
	s_nop 0
	v_pk_add_f32 v[44:45], v[44:45], v[46:47]
	s_nop 0
	v_add_f32_e32 v2, v44, v45
	ds_bpermute_b32 v44, v130, v2
	s_waitcnt lgkmcnt(0)
	v_add_f32_e32 v2, v2, v44
	ds_bpermute_b32 v44, v129, v2
	s_waitcnt lgkmcnt(0)
	v_add_f32_e32 v2, v2, v44
	v_fmamk_f32 v2, v2, 0x3c800000, v200
	v_cmp_gt_f32_e64 s[44:45], s29, v2
	v_mul_f32_e32 v44, 0x4b800000, v2
	s_nop 0
	v_cndmask_b32_e64 v2, v2, v44, s[44:45]
	v_rsq_f32_e32 v2, v2
	s_nop 0
	v_mul_f32_e32 v44, 0x45800000, v2
	v_cndmask_b32_e64 v48, v2, v44, s[44:45]
	v_mad_u64_u32 v[44:45], s[20:21], v128, s72, v[100:101]
	v_lshl_add_u64 v[102:103], v[44:45], 0, v[62:63]
	v_mov_b64_e32 v[114:115], v[230:231]
	v_mov_b64_e32 v[44:45], v[146:147]
	v_mov_b64_e32 v[46:47], v[148:149]
	v_lshlrev_b32_e32 v2, 11, v128
	v_lshl_add_u64 v[112:113], s[46:47], 0, v[2:3]
	v_pk_mul_f32 v[110:111], v[110:111], v[48:49] op_sel_hi:[1,0]
	v_pk_mul_f32 v[108:109], v[108:109], v[48:49] op_sel_hi:[1,0]
	v_pk_mul_f32 v[106:107], v[106:107], v[48:49] op_sel_hi:[1,0]
	v_pk_mul_f32 v[104:105], v[104:105], v[48:49] op_sel_hi:[1,0]
	s_waitcnt lgkmcnt(0)
	v_lshlrev_b32_e32 v116, 16, v114
	v_mul_f32_e32 v2, 0xbfb8aa3b, v116
	v_exp_f32_e32 v2, v2
	v_and_b32_e32 v117, 0xffff0000, v114
	v_lshlrev_b32_e32 v114, 16, v115
	v_and_b32_e32 v115, 0xffff0000, v115
	v_add_f32_e32 v2, 1.0, v2
	v_rcp_f32_e32 v118, v2
	v_mul_f32_e32 v2, 0xbfb8aa3b, v117
	v_exp_f32_e32 v2, v2
	v_pk_mul_f32 v[44:45], v[44:45], v[110:111]
	v_pk_mul_f32 v[46:47], v[46:47], v[108:109]
	v_add_f32_e32 v2, 1.0, v2
	v_rcp_f32_e32 v119, v2
	v_mul_f32_e32 v2, 0xbfb8aa3b, v114
	v_exp_f32_e32 v2, v2
	v_pk_mul_f32 v[110:111], v[118:119], v[116:117]
	s_nop 0
	v_pk_mul_f32 v[44:45], v[110:111], v[44:45]
	v_add_f32_e32 v2, 1.0, v2
	v_rcp_f32_e32 v110, v2
	v_mul_f32_e32 v2, 0xbfb8aa3b, v115
	v_exp_f32_e32 v2, v2
	s_nop 0
	v_add_f32_e32 v2, 1.0, v2
	v_rcp_f32_e32 v111, v2
	s_nop 0
	v_pk_mul_f32 v[108:109], v[110:111], v[114:115]
	s_nop 0
	v_pk_mul_f32 v[46:47], v[108:109], v[46:47]
	v_cvt_pk_bf16_f32 v108, v44, v45
	v_cvt_pk_bf16_f32 v109, v46, v47
	v_lshl_add_u64 v[44:45], v[112:113], 0, v[62:63]
	global_store_dwordx2 v[44:45], v[108:109], off offset:1536
	v_mov_b64_e32 v[46:47], v[232:233]
	s_nop 0
	v_mov_b64_e32 v[108:109], v[150:151]
	v_mov_b64_e32 v[110:111], v[152:153]
	s_waitcnt lgkmcnt(0)
	v_lshlrev_b32_e32 v112, 16, v46
	v_mul_f32_e32 v2, 0xbfb8aa3b, v112
	v_exp_f32_e32 v2, v2
	v_and_b32_e32 v113, 0xffff0000, v46
	v_lshlrev_b32_e32 v46, 16, v47
	v_and_b32_e32 v47, 0xffff0000, v47
	v_add_f32_e32 v2, 1.0, v2
	v_rcp_f32_e32 v114, v2
	v_mul_f32_e32 v2, 0xbfb8aa3b, v113
	v_exp_f32_e32 v2, v2
	v_pk_mul_f32 v[106:107], v[108:109], v[106:107]
	v_pk_mul_f32 v[104:105], v[110:111], v[104:105]
	v_mul_f32_e32 v110, v55, v48
	v_add_f32_e32 v2, 1.0, v2
	v_rcp_f32_e32 v115, v2
	v_mul_f32_e32 v2, 0xbfb8aa3b, v46
	v_exp_f32_e32 v2, v2
	v_pk_mul_f32 v[108:109], v[114:115], v[112:113]
	s_nop 0
	v_pk_mul_f32 v[106:107], v[108:109], v[106:107]
	v_add_f32_e32 v2, 1.0, v2
	v_rcp_f32_e32 v108, v2
	v_mul_f32_e32 v2, 0xbfb8aa3b, v47
	v_exp_f32_e32 v2, v2
	v_mul_f32_e32 v112, v52, v48
	v_add_f32_e32 v2, 1.0, v2
	v_rcp_f32_e32 v109, v2
	s_nop 0
	v_pk_mul_f32 v[46:47], v[108:109], v[46:47]
	s_nop 0
	v_pk_mul_f32 v[46:47], v[46:47], v[104:105]
	v_cvt_pk_bf16_f32 v104, v106, v107
	v_cvt_pk_bf16_f32 v105, v46, v47
	global_store_dwordx2 v[44:45], v[104:105], off offset:1568
	v_mov_b64_e32 v[46:47], v[234:235]
	s_nop 0
	v_mov_b64_e32 v[104:105], v[188:189]
	v_mov_b64_e32 v[106:107], v[190:191]
	v_mul_f32_e32 v108, v54, v48
	s_waitcnt lgkmcnt(0)
; template <int KIND>
; __device__ __forceinline__ void w_m3_core(const bf16x8 (&Qf)[4][2], const bf16x8 (&Kf)[4][2], const bf16x8 (&Sf)[4][2], const LAS bf16_t* vT, float lg,
;                                           const bf16_t* gsrc, const float* nw, bf16_t* ydst, int lo, int fq) {
;     ...
;             float pv[8];
; #pragma unroll
;             for (int hh = 0; hh < 2; ++hh) { const int mb = 2 * kk2 + hh;
;                 if (mb <= nb) { f32x4 s = {0.f, 0.f, 0.f, 0.f};
;                     s = __builtin_amdgcn_mfma_f32_16x16x32_bf16(Kf[mb][0], Qf[nb][0], s, 0, 0, 0); s = __builtin_amdgcn_mfma_f32_16x16x32_bf16(Kf[mb][1], Qf[nb][1], s, 0, 0, 0);
; #pragma unroll
;                     for (int r = 0; r < 4; ++r) { const int m = 16 * mb + 4 * fq + r, n = 16 * nb + lo; float v = s[r];
;                         if (KIND == 0) v *= __expf((float)(n - m) * lg);
;                         if (mb == nb) v = (m <= n) ? v : 0.f;
;                         pv[4 * hh + r] = v; }
;                 } else {
; #pragma unroll
;                     for (int r = 0; r < 4; ++r) pv[4 * hh + r] = 0.f; }
;             }
;             const bf16x8 Pf = pack_frag(pv);
; #pragma unroll
;             for (int eb = 0; eb < 4; ++eb)
;                 O[eb] = __builtin_amdgcn_mfma_f32_16x16x32_bf16(tr_frag(vT, 32 * kk2 + 4 * fq, 32 * kk2 + 16 + 4 * fq, 16 * eb, lo), Pf, O[eb], 0, 0, 0);
;         }
; #pragma unroll
;         for (int kk = 0; kk < 2; ++kk)
; #pragma unroll
;             for (int eb = 0; eb < 4; ++eb) O2[eb] = __builtin_amdgcn_mfma_f32_16x16x32_bf16(Sf[eb][kk], Qf[nb][kk], O2[eb], 0, 0, 0);
;         const float osc = KIND == 0 ? __expf((float)(16 * nb + lo + 1) * lg) : 1.0f;
; #pragma unroll
;         for (int eb = 0; eb < 4; ++eb) O[eb] = O[eb] + O2[eb] * osc;
;         float ss = 0.f;
; #pragma unroll
;         for (int eb = 0; eb < 4; ++eb) ss += (O[eb][0] * O[eb][0] + O[eb][1] * O[eb][1]) + (O[eb][2] * O[eb][2] + O[eb][3] * O[eb][3]);
;         { const int ln = (fq << 4) | lo; ss += bperm_f(ln ^ 16, ss); ss += bperm_f(ln ^ 32, ss); }
;         const float rs = rsqrtf(ss * (1.0f / 64.0f) + EPS);
;         const size_t n = 16 * nb + lo;
; #pragma unroll
;         for (int eb = 0; eb < 4; ++eb) { const int e0 = 16 * eb + 4 * fq;
;             const unsigned long long gw_ = *(const unsigned long long*)(gsrc + n * NIN + e0); const f32x4 w4 = *(const f32x4*)(nw + e0);
	v_lshlrev_b32_e32 v109, 16, v46
	v_mul_f32_e32 v2, 0xbfb8aa3b, v109
	v_exp_f32_e32 v2, v2
	v_and_b32_e32 v111, 0xffff0000, v46
	v_lshlrev_b32_e32 v113, 16, v47
	v_and_b32_e32 v47, 0xffff0000, v47
	v_add_f32_e32 v2, 1.0, v2
	v_rcp_f32_e32 v115, v2
	v_mul_f32_e32 v2, 0xbfb8aa3b, v111
	v_exp_f32_e32 v2, v2
	v_mov_b32_e32 v54, v105
	v_mul_f32_e32 v46, v53, v48
	v_mov_b32_e32 v114, v104
	v_add_f32_e32 v2, 1.0, v2
	v_rcp_f32_e32 v55, v2
	v_mul_f32_e32 v2, 0xbfb8aa3b, v113
	v_exp_f32_e32 v2, v2
	v_pk_mul_f32 v[108:109], v[114:115], v[108:109]
	v_pk_mul_f32 v[54:55], v[54:55], v[110:111]
	v_mov_b32_e32 v104, v106
	v_add_f32_e32 v2, 1.0, v2
	v_rcp_f32_e32 v105, v2
	v_mul_f32_e32 v2, 0xbfb8aa3b, v47
	v_exp_f32_e32 v2, v2
	v_mov_b32_e32 v52, v107
	v_pk_mul_f32 v[104:105], v[104:105], v[112:113]
	v_mul_f32_e32 v106, v0, v48
	v_add_f32_e32 v2, 1.0, v2
	v_rcp_f32_e32 v53, v2
	s_nop 0
	v_pk_mul_f32 v[46:47], v[52:53], v[46:47]
	v_mov_b32_e32 v52, v108
	v_mov_b32_e32 v53, v54
	v_mov_b32_e32 v54, v109
	v_pk_mul_f32 v[52:53], v[52:53], v[54:55]
	v_mov_b32_e32 v54, v104
	v_mov_b32_e32 v55, v46
	v_mov_b32_e32 v46, v105
	v_pk_mul_f32 v[46:47], v[54:55], v[46:47]
	v_cvt_pk_bf16_f32 v52, v52, v53
	v_cvt_pk_bf16_f32 v53, v46, v47
	global_store_dwordx2 v[44:45], v[52:53], off offset:1600
	v_mov_b64_e32 v[46:47], v[236:237]
	s_nop 0
	v_mov_b64_e32 v[52:53], v[192:193]
	v_mov_b64_e32 v[54:55], v[194:195]
	v_mul_f32_e32 v102, v50, v48
	v_mul_f32_e32 v104, v51, v48
	s_waitcnt lgkmcnt(0)
	v_lshlrev_b32_e32 v103, 16, v46
	v_lshlrev_b32_e32 v107, 16, v47
	v_mul_f32_e32 v2, 0xbfb8aa3b, v103
	v_mul_f32_e32 v0, 0xbfb8aa3b, v107
	v_exp_f32_e32 v2, v2
	v_exp_f32_e32 v0, v0
	v_and_b32_e32 v105, 0xffff0000, v46
	v_and_b32_e32 v47, 0xffff0000, v47
	v_add_f32_e32 v2, 1.0, v2
	v_add_f32_e32 v0, 1.0, v0
	v_rcp_f32_e32 v109, v2
	v_mul_f32_e32 v2, 0xbfb8aa3b, v105
	v_mov_b32_e32 v50, v53
	v_rcp_f32_e32 v53, v0
	v_mul_f32_e32 v0, 0xbfb8aa3b, v47
	v_exp_f32_e32 v2, v2
	v_exp_f32_e32 v0, v0
	v_mul_f32_e32 v46, v1, v48
	v_mov_b32_e32 v108, v52
	v_add_f32_e32 v2, 1.0, v2
	v_add_f32_e32 v0, 1.0, v0
	v_rcp_f32_e32 v51, v2
	v_rcp_f32_e32 v1, v0
	v_mov_b32_e32 v52, v54
	v_mov_b32_e32 v0, v55
	v_pk_mul_f32 v[102:103], v[108:109], v[102:103]
	v_pk_mul_f32 v[50:51], v[50:51], v[104:105]
	v_pk_mul_f32 v[52:53], v[52:53], v[106:107]
	v_pk_mul_f32 v[0:1], v[0:1], v[46:47]
	v_mov_b32_e32 v46, v102
	v_mov_b32_e32 v47, v50
	v_mov_b32_e32 v50, v103
	v_mov_b32_e32 v48, v52
	v_mov_b32_e32 v49, v0
	v_mov_b32_e32 v0, v53
	v_pk_mul_f32 v[46:47], v[46:47], v[50:51]
	v_pk_mul_f32 v[0:1], v[48:49], v[0:1]
	v_cvt_pk_bf16_f32 v46, v46, v47
	v_cvt_pk_bf16_f32 v47, v0, v1
	global_store_dwordx2 v[44:45], v[46:47], off offset:1632
	v_mfma_f32_16x16x32_bf16 v[44:47], v[20:23], v[28:31], 0
	v_mfma_f32_16x16x32_bf16 v[48:51], v[16:19], v[28:31], 0
	v_mfma_f32_16x16x32_bf16 v[44:47], v[24:27], v[40:43], v[44:47]
	v_mfma_f32_16x16x32_bf16 v[48:51], v[32:35], v[40:43], v[48:51]
	s_nop 6
	v_cvt_pk_bf16_f32 v44, v44, v45
	v_cvt_pk_bf16_f32 v45, v46, v47
	v_cvt_pk_bf16_f32 v46, v48, v49
	v_cvt_pk_bf16_f32 v47, v50, v51
	ds_read_b64_tr_b16 v[50:51], v131 offset:2304
	ds_read_b64_tr_b16 v[48:49], v131
	ds_read_b64_tr_b16 v[52:53], v131 offset:32
	ds_read_b64_tr_b16 v[54:55], v131 offset:2336
	ds_read_b64_tr_b16 v[102:103], v131 offset:64
	ds_read_b64_tr_b16 v[104:105], v131 offset:2368
	ds_read_b64_tr_b16 v[106:107], v131 offset:96
	ds_read_b64_tr_b16 v[108:109], v131 offset:2400
	s_waitcnt lgkmcnt(0)
	v_mfma_f32_16x16x32_bf16 v[48:51], v[48:51], v[44:47], 0
	v_mfma_f32_16x16x32_bf16 v[52:55], v[52:55], v[44:47], 0
	v_mfma_f32_16x16x32_bf16 v[102:105], v[102:105], v[44:47], 0
	v_mfma_f32_16x16x32_bf16 v[44:47], v[106:109], v[44:47], 0
	v_mfma_f32_16x16x32_bf16 v[106:109], v[12:15], v[28:31], 0
	v_mfma_f32_16x16x32_bf16 v[106:109], v[36:39], v[40:43], v[106:109]
	s_nop 7
	v_cndmask_b32_e64 v0, v106, 0, s[40:41]
	v_cndmask_b32_e64 v1, 0, v107, s[42:43]
	v_cndmask_b32_e64 v2, v108, 0, s[38:39]
	v_cndmask_b32_e64 v106, v109, 0, vcc
	v_cvt_pk_bf16_f32 v0, v0, v1
	v_cvt_pk_bf16_f32 v1, v2, v106
	ds_read_b64_tr_b16 v[106:107], v131 offset:4608
	ds_read_b64_tr_b16 v[108:109], v131 offset:6912
	v_mov_b32_e32 v2, v3
	s_waitcnt lgkmcnt(0)
	s_nop 0
	v_mfma_f32_16x16x32_bf16 v[48:51], v[106:109], v[0:3], v[48:51]
	ds_read_b64_tr_b16 v[106:107], v131 offset:4640
	ds_read_b64_tr_b16 v[108:109], v131 offset:6944
	s_waitcnt lgkmcnt(0)
	v_mfma_f32_16x16x32_bf16 v[106:109], v[106:109], v[0:3], v[52:55]
	s_nop 2
	ds_read_b64_tr_b16 v[52:53], v131 offset:4672
	ds_read_b64_tr_b16 v[54:55], v131 offset:6976
	s_waitcnt lgkmcnt(0)
	v_mfma_f32_16x16x32_bf16 v[110:113], v[52:55], v[0:3], v[102:105]
	ds_read_b64_tr_b16 v[52:53], v131 offset:4704
	ds_read_b64_tr_b16 v[54:55], v131 offset:7008
	s_waitcnt lgkmcnt(0)
; __device__ __forceinline__ unsigned pk2(float lo, float hi) { const f32x2_t v = {lo, hi}; const bf16x2_t b = __builtin_convertvector(v, bf16x2_t); return __builtin_bit_cast(unsigned, b); }
; template <int KIND>
; __device__ __forceinline__ void w_m3_core(const bf16x8 (&Qf)[4][2], const bf16x8 (&Kf)[4][2], const bf16x8 (&Sf)[4][2], const LAS bf16_t* vT, float lg,
;                                           const bf16_t* gsrc, const float* nw, bf16_t* ydst, int lo, int fq) {
;     ...
;             const bf16x8 Pf = pack_frag(pv);
; #pragma unroll
;             for (int eb = 0; eb < 4; ++eb)
;                 O[eb] = __builtin_amdgcn_mfma_f32_16x16x32_bf16(tr_frag(vT, 32 * kk2 + 4 * fq, 32 * kk2 + 16 + 4 * fq, 16 * eb, lo), Pf, O[eb], 0, 0, 0);
;         }
; #pragma unroll
;         for (int kk = 0; kk < 2; ++kk)
; #pragma unroll
;             for (int eb = 0; eb < 4; ++eb) O2[eb] = __builtin_amdgcn_mfma_f32_16x16x32_bf16(Sf[eb][kk], Qf[nb][kk], O2[eb], 0, 0, 0);
;         const float osc = KIND == 0 ? __expf((float)(16 * nb + lo + 1) * lg) : 1.0f;
; #pragma unroll
;         for (int eb = 0; eb < 4; ++eb) O[eb] = O[eb] + O2[eb] * osc;
;         float ss = 0.f;
; #pragma unroll
;         for (int eb = 0; eb < 4; ++eb) ss += (O[eb][0] * O[eb][0] + O[eb][1] * O[eb][1]) + (O[eb][2] * O[eb][2] + O[eb][3] * O[eb][3]);
;         { const int ln = (fq << 4) | lo; ss += bperm_f(ln ^ 16, ss); ss += bperm_f(ln ^ 32, ss); }
;         const float rs = rsqrtf(ss * (1.0f / 64.0f) + EPS);
;         const size_t n = 16 * nb + lo;
; #pragma unroll
;         for (int eb = 0; eb < 4; ++eb) { const int e0 = 16 * eb + 4 * fq;
;             const unsigned long long gw_ = *(const unsigned long long*)(gsrc + n * NIN + e0); const f32x4 w4 = *(const f32x4*)(nw + e0);
;             const float g0 = __uint_as_float((unsigned)gw_ << 16), g1 = __uint_as_float((unsigned)gw_ & 0xffff0000u), g2 = __uint_as_float((unsigned)(gw_ >> 32) << 16), g3 = __uint_as_float((unsigned)(gw_ >> 32) & 0xffff0000u);
;             const float o0 = O[eb][0] * rs * w4[0] * (g0 * sigmoidf_(g0)), o1 = O[eb][1] * rs * w4[1] * (g1 * sigmoidf_(g1));
;             const float o2 = O[eb][2] * rs * w4[2] * (g2 * sigmoidf_(g2)), o3 = O[eb][3] * rs * w4[3] * (g3 * sigmoidf_(g3));
;             *(unsigned long long*)(ydst + n * DM + e0) = (unsigned long long)pk2(o0, o1) | ((unsigned long long)pk2(o2, o3) << 32); }
	v_mfma_f32_16x16x32_bf16 v[114:117], v[52:55], v[0:3], v[44:47]
	v_mfma_f32_16x16x32_bf16 v[44:47], v[64:67], v[28:31], 0
	v_mfma_f32_16x16x32_bf16 v[52:55], v[72:75], v[28:31], 0
	v_mfma_f32_16x16x32_bf16 v[102:105], v[76:79], v[28:31], 0
	v_mfma_f32_16x16x32_bf16 v[28:31], v[80:83], v[28:31], 0
	v_mfma_f32_16x16x32_bf16 v[44:47], v[84:87], v[40:43], v[44:47]
	v_mfma_f32_16x16x32_bf16 v[28:31], v[96:99], v[40:43], v[28:31]
	v_mfma_f32_16x16x32_bf16 v[118:121], v[88:91], v[40:43], v[52:55]
	v_mfma_f32_16x16x32_bf16 v[122:125], v[92:95], v[40:43], v[102:105]
	s_nop 4
	v_add_f32_e64 v54, v50, v46
	v_add_f32_e64 v55, v51, v47
	v_pk_add_f32 v[0:1], v[116:117], v[30:31]
	v_pk_add_f32 v[42:43], v[114:115], v[28:29]
	v_pk_add_f32 v[102:103], v[48:49], v[44:45]
	v_pk_mul_f32 v[28:29], v[54:55], v[54:55]
	v_pk_mul_f32 v[30:31], v[102:103], v[102:103]
	v_pk_add_f32 v[50:51], v[108:109], v[120:121]
	v_pk_add_f32 v[52:53], v[106:107], v[118:119]
	v_pk_mov_b32 v[40:41], v[30:31], v[28:29] op_sel:[1,0]
	v_mov_b32_e32 v31, v29
	v_pk_add_f32 v[28:29], v[40:41], v[30:31]
	v_pk_mul_f32 v[30:31], v[50:51], v[50:51]
	v_pk_mul_f32 v[40:41], v[52:53], v[52:53]
	v_pk_add_f32 v[46:47], v[110:111], v[122:123]
	v_pk_mov_b32 v[48:49], v[40:41], v[30:31] op_sel:[1,0]
	v_mov_b32_e32 v41, v31
	v_pk_add_f32 v[30:31], v[48:49], v[40:41]
	v_mul_f32_e32 v2, v42, v42
	v_mul_f32_e32 v40, v43, v43
	v_pk_add_f32 v[28:29], v[28:29], v[28:29] op_sel:[0,1] op_sel_hi:[1,0]
	v_pk_add_f32 v[30:31], v[30:31], v[30:31] op_sel:[0,1] op_sel_hi:[1,0]
	v_pk_add_f32 v[44:45], v[112:113], v[124:125]
	v_mov_b32_e32 v29, v2
	v_mov_b32_e32 v31, v40
	v_mul_f32_e32 v2, v47, v47
	v_mul_f32_e32 v41, v0, v0
	v_pk_add_f32 v[28:29], v[28:29], v[30:31]
	v_pk_fma_f32 v[30:31], v[46:47], v[46:47], v[2:3] op_sel_hi:[1,1,0]
	v_mul_f32_e32 v2, v45, v45
	v_mul_f32_e32 v48, v1, v1
	v_mov_b32_e32 v31, v41
	v_pk_fma_f32 v[40:41], v[44:45], v[44:45], v[2:3] op_sel_hi:[1,1,0]
	s_nop 0
	v_mov_b32_e32 v41, v48
	v_pk_add_f32 v[30:31], v[30:31], v[40:41]
	s_nop 0
	v_pk_add_f32 v[28:29], v[28:29], v[30:31]
	s_nop 0
	v_add_f32_e32 v2, v28, v29
	ds_bpermute_b32 v28, v130, v2
	s_waitcnt lgkmcnt(0)
	v_add_f32_e32 v2, v2, v28
	ds_bpermute_b32 v28, v129, v2
	s_waitcnt lgkmcnt(0)
	v_add_f32_e32 v2, v2, v28
	v_fmamk_f32 v2, v2, 0x3c800000, v200
	v_cmp_gt_f32_e64 s[44:45], s29, v2
	v_mul_f32_e32 v28, 0x4b800000, v2
	s_nop 0
	v_cndmask_b32_e64 v2, v2, v28, s[44:45]
	v_rsq_f32_e32 v2, v2
	s_nop 0
	v_mul_f32_e32 v28, 0x45800000, v2
	v_cndmask_b32_e64 v40, v2, v28, s[44:45]
	v_mad_u64_u32 v[28:29], s[20:21], v127, s72, v[100:101]
	v_lshl_add_u64 v[48:49], v[28:29], 0, v[62:63]
	v_mov_b64_e32 v[106:107], v[238:239]
	v_mov_b64_e32 v[28:29], v[146:147]
	v_mov_b64_e32 v[30:31], v[148:149]
	v_lshlrev_b32_e32 v2, 11, v127
	v_lshl_add_u64 v[104:105], s[46:47], 0, v[2:3]
	v_pk_mul_f32 v[102:103], v[102:103], v[40:41] op_sel_hi:[1,0]
	v_pk_mul_f32 v[54:55], v[54:55], v[40:41] op_sel_hi:[1,0]
	v_pk_mul_f32 v[52:53], v[52:53], v[40:41] op_sel_hi:[1,0]
	v_pk_mul_f32 v[50:51], v[50:51], v[40:41] op_sel_hi:[1,0]
	s_waitcnt lgkmcnt(0)
	v_lshlrev_b32_e32 v108, 16, v106
	v_mul_f32_e32 v2, 0xbfb8aa3b, v108
	v_exp_f32_e32 v2, v2
	v_and_b32_e32 v109, 0xffff0000, v106
	v_lshlrev_b32_e32 v106, 16, v107
	v_and_b32_e32 v107, 0xffff0000, v107
	v_add_f32_e32 v2, 1.0, v2
	v_rcp_f32_e32 v110, v2
	v_mul_f32_e32 v2, 0xbfb8aa3b, v109
	v_exp_f32_e32 v2, v2
	v_pk_mul_f32 v[28:29], v[28:29], v[102:103]
	v_pk_mul_f32 v[30:31], v[30:31], v[54:55]
	v_add_f32_e32 v2, 1.0, v2
	v_rcp_f32_e32 v111, v2
	v_mul_f32_e32 v2, 0xbfb8aa3b, v106
	v_exp_f32_e32 v2, v2
	v_pk_mul_f32 v[102:103], v[110:111], v[108:109]
	s_nop 0
	v_pk_mul_f32 v[28:29], v[102:103], v[28:29]
	v_add_f32_e32 v2, 1.0, v2
	v_rcp_f32_e32 v102, v2
	v_mul_f32_e32 v2, 0xbfb8aa3b, v107
	v_exp_f32_e32 v2, v2
	s_nop 0
	v_add_f32_e32 v2, 1.0, v2
	v_rcp_f32_e32 v103, v2
	s_nop 0
	v_pk_mul_f32 v[54:55], v[102:103], v[106:107]
	s_nop 0
	v_pk_mul_f32 v[30:31], v[54:55], v[30:31]
	v_cvt_pk_bf16_f32 v54, v28, v29
	v_cvt_pk_bf16_f32 v55, v30, v31
	v_lshl_add_u64 v[28:29], v[104:105], 0, v[62:63]
	global_store_dwordx2 v[28:29], v[54:55], off offset:1536
	v_mov_b64_e32 v[30:31], v[240:241]
	v_mov_b64_e32 v[102:103], v[150:151]
	v_mov_b64_e32 v[104:105], v[152:153]
	s_waitcnt lgkmcnt(0)
	v_lshlrev_b32_e32 v54, 16, v30
	v_mul_f32_e32 v2, 0xbfb8aa3b, v54
	v_exp_f32_e32 v2, v2
	v_and_b32_e32 v55, 0xffff0000, v30
	v_lshlrev_b32_e32 v30, 16, v31
	v_and_b32_e32 v31, 0xffff0000, v31
	v_add_f32_e32 v2, 1.0, v2
	v_rcp_f32_e32 v106, v2
	v_mul_f32_e32 v2, 0xbfb8aa3b, v55
	v_exp_f32_e32 v2, v2
	v_pk_mul_f32 v[52:53], v[102:103], v[52:53]
	v_pk_mul_f32 v[50:51], v[104:105], v[50:51]
	v_mul_f32_e32 v102, v47, v40
	v_add_f32_e32 v2, 1.0, v2
	v_rcp_f32_e32 v107, v2
	v_mul_f32_e32 v2, 0xbfb8aa3b, v30
	v_exp_f32_e32 v2, v2
	v_mul_f32_e32 v104, v44, v40
	v_pk_mul_f32 v[54:55], v[106:107], v[54:55]
	v_add_f32_e32 v2, 1.0, v2
	v_pk_mul_f32 v[52:53], v[54:55], v[52:53]
	v_rcp_f32_e32 v54, v2
	v_mul_f32_e32 v2, 0xbfb8aa3b, v31
	v_exp_f32_e32 v2, v2
	s_nop 0
	v_add_f32_e32 v2, 1.0, v2
	v_rcp_f32_e32 v55, v2
	s_nop 0
	v_pk_mul_f32 v[30:31], v[54:55], v[30:31]
	s_nop 0
	v_pk_mul_f32 v[30:31], v[30:31], v[50:51]
	v_cvt_pk_bf16_f32 v50, v52, v53
	v_cvt_pk_bf16_f32 v51, v30, v31
	global_store_dwordx2 v[28:29], v[50:51], off offset:1568
	v_mov_b64_e32 v[30:31], v[242:243]
	s_nop 0
	v_mov_b64_e32 v[50:51], v[188:189]
	v_mov_b64_e32 v[52:53], v[190:191]
	v_mul_f32_e32 v54, v46, v40
	s_waitcnt lgkmcnt(0)
; template <int KIND>
; __device__ __forceinline__ void w_m3_core(const bf16x8 (&Qf)[4][2], const bf16x8 (&Kf)[4][2], const bf16x8 (&Sf)[4][2], const LAS bf16_t* vT, float lg,
;                                           const bf16_t* gsrc, const float* nw, bf16_t* ydst, int lo, int fq) {
;     ...
;             float pv[8];
; #pragma unroll
;             for (int hh = 0; hh < 2; ++hh) { const int mb = 2 * kk2 + hh;
;                 if (mb <= nb) { f32x4 s = {0.f, 0.f, 0.f, 0.f};
;                     s = __builtin_amdgcn_mfma_f32_16x16x32_bf16(Kf[mb][0], Qf[nb][0], s, 0, 0, 0); s = __builtin_amdgcn_mfma_f32_16x16x32_bf16(Kf[mb][1], Qf[nb][1], s, 0, 0, 0);
; #pragma unroll
;                     for (int r = 0; r < 4; ++r) { const int m = 16 * mb + 4 * fq + r, n = 16 * nb + lo; float v = s[r];
;                         if (KIND == 0) v *= __expf((float)(n - m) * lg);
;                         if (mb == nb) v = (m <= n) ? v : 0.f;
;                         pv[4 * hh + r] = v; }
;                 } else {
; #pragma unroll
;                     for (int r = 0; r < 4; ++r) pv[4 * hh + r] = 0.f; }
;             }
;             const bf16x8 Pf = pack_frag(pv);
; #pragma unroll
;             for (int eb = 0; eb < 4; ++eb)
;                 O[eb] = __builtin_amdgcn_mfma_f32_16x16x32_bf16(tr_frag(vT, 32 * kk2 + 4 * fq, 32 * kk2 + 16 + 4 * fq, 16 * eb, lo), Pf, O[eb], 0, 0, 0);
;         }
; #pragma unroll
;         for (int kk = 0; kk < 2; ++kk)
; #pragma unroll
;             for (int eb = 0; eb < 4; ++eb) O2[eb] = __builtin_amdgcn_mfma_f32_16x16x32_bf16(Sf[eb][kk], Qf[nb][kk], O2[eb], 0, 0, 0);
;         const float osc = KIND == 0 ? __expf((float)(16 * nb + lo + 1) * lg) : 1.0f;
; #pragma unroll
;         for (int eb = 0; eb < 4; ++eb) O[eb] = O[eb] + O2[eb] * osc;
;         float ss = 0.f;
; #pragma unroll
;         for (int eb = 0; eb < 4; ++eb) ss += (O[eb][0] * O[eb][0] + O[eb][1] * O[eb][1]) + (O[eb][2] * O[eb][2] + O[eb][3] * O[eb][3]);
;         { const int ln = (fq << 4) | lo; ss += bperm_f(ln ^ 16, ss); ss += bperm_f(ln ^ 32, ss); }
;         const float rs = rsqrtf(ss * (1.0f / 64.0f) + EPS);
;         const size_t n = 16 * nb + lo;
; #pragma unroll
;         for (int eb = 0; eb < 4; ++eb) { const int e0 = 16 * eb + 4 * fq;
;             const unsigned long long gw_ = *(const unsigned long long*)(gsrc + n * NIN + e0); const f32x4 w4 = *(const f32x4*)(nw + e0);
	v_lshlrev_b32_e32 v55, 16, v30
	v_mul_f32_e32 v2, 0xbfb8aa3b, v55
	v_exp_f32_e32 v2, v2
	v_and_b32_e32 v103, 0xffff0000, v30
	v_lshlrev_b32_e32 v105, 16, v31
	v_and_b32_e32 v31, 0xffff0000, v31
	v_add_f32_e32 v2, 1.0, v2
	v_rcp_f32_e32 v107, v2
	v_mul_f32_e32 v2, 0xbfb8aa3b, v103
	v_exp_f32_e32 v2, v2
	v_mov_b32_e32 v46, v51
	v_mul_f32_e32 v30, v45, v40
	v_mov_b32_e32 v106, v50
	v_add_f32_e32 v2, 1.0, v2
	v_rcp_f32_e32 v47, v2
	v_mul_f32_e32 v2, 0xbfb8aa3b, v105
	v_exp_f32_e32 v2, v2
	v_pk_mul_f32 v[54:55], v[106:107], v[54:55]
	v_pk_mul_f32 v[46:47], v[46:47], v[102:103]
	v_mov_b32_e32 v50, v52
	v_add_f32_e32 v2, 1.0, v2
	v_rcp_f32_e32 v51, v2
	v_mul_f32_e32 v2, 0xbfb8aa3b, v31
	v_exp_f32_e32 v2, v2
	v_mov_b32_e32 v44, v53
	v_pk_mul_f32 v[50:51], v[50:51], v[104:105]
	v_mul_f32_e32 v52, v0, v40
	v_add_f32_e32 v2, 1.0, v2
	v_rcp_f32_e32 v45, v2
	s_nop 0
	v_pk_mul_f32 v[30:31], v[44:45], v[30:31]
	v_mov_b32_e32 v44, v54
	v_mov_b32_e32 v45, v46
	v_mov_b32_e32 v46, v55
	v_pk_mul_f32 v[44:45], v[44:45], v[46:47]
	v_mov_b32_e32 v46, v50
	v_mov_b32_e32 v47, v30
	v_mov_b32_e32 v30, v51
	v_pk_mul_f32 v[30:31], v[46:47], v[30:31]
	v_cvt_pk_bf16_f32 v44, v44, v45
	v_cvt_pk_bf16_f32 v45, v30, v31
	global_store_dwordx2 v[28:29], v[44:45], off offset:1600
	v_mov_b64_e32 v[30:31], v[244:245]
	s_nop 0
	v_mov_b64_e32 v[44:45], v[192:193]
	v_mov_b64_e32 v[46:47], v[194:195]
	v_mul_f32_e32 v48, v42, v40
	v_mul_f32_e32 v50, v43, v40
	s_waitcnt lgkmcnt(0)
	v_lshlrev_b32_e32 v49, 16, v30
	v_lshlrev_b32_e32 v53, 16, v31
	v_mul_f32_e32 v2, 0xbfb8aa3b, v49
	v_mul_f32_e32 v0, 0xbfb8aa3b, v53
	v_exp_f32_e32 v2, v2
	v_exp_f32_e32 v0, v0
	v_and_b32_e32 v51, 0xffff0000, v30
	v_and_b32_e32 v31, 0xffff0000, v31
	v_add_f32_e32 v2, 1.0, v2
	v_add_f32_e32 v0, 1.0, v0
	v_rcp_f32_e32 v55, v2
	v_mul_f32_e32 v2, 0xbfb8aa3b, v51
	v_mov_b32_e32 v42, v45
	v_rcp_f32_e32 v45, v0
	v_mul_f32_e32 v0, 0xbfb8aa3b, v31
	v_exp_f32_e32 v2, v2
	v_exp_f32_e32 v0, v0
	v_mul_f32_e32 v30, v1, v40
	v_mov_b32_e32 v54, v44
	v_add_f32_e32 v2, 1.0, v2
	v_add_f32_e32 v0, 1.0, v0
	v_rcp_f32_e32 v43, v2
	v_rcp_f32_e32 v1, v0
	v_mov_b32_e32 v44, v46
	v_mov_b32_e32 v0, v47
	v_pk_mul_f32 v[48:49], v[54:55], v[48:49]
	v_pk_mul_f32 v[42:43], v[42:43], v[50:51]
	v_pk_mul_f32 v[44:45], v[44:45], v[52:53]
	v_pk_mul_f32 v[0:1], v[0:1], v[30:31]
	v_mov_b32_e32 v30, v48
	v_mov_b32_e32 v31, v42
	v_mov_b32_e32 v42, v49
	v_mov_b32_e32 v40, v44
	v_mov_b32_e32 v41, v0
	v_mov_b32_e32 v0, v45
	v_pk_mul_f32 v[30:31], v[30:31], v[42:43]
	v_pk_mul_f32 v[0:1], v[40:41], v[0:1]
	v_cvt_pk_bf16_f32 v30, v30, v31
	v_cvt_pk_bf16_f32 v31, v0, v1
	global_store_dwordx2 v[28:29], v[30:31], off offset:1632
	v_mfma_f32_16x16x32_bf16 v[20:23], v[20:23], v[8:11], 0
	v_mfma_f32_16x16x32_bf16 v[20:23], v[24:27], v[56:59], v[20:23]
	ds_read_b64_tr_b16 v[26:27], v131 offset:2304
	ds_read_b64_tr_b16 v[24:25], v131
	v_mfma_f32_16x16x32_bf16 v[16:19], v[16:19], v[8:11], 0
	v_mfma_f32_16x16x32_bf16 v[16:19], v[32:35], v[56:59], v[16:19]
	s_nop 3
	v_cvt_pk_bf16_f32 v20, v20, v21
	v_cvt_pk_bf16_f32 v21, v22, v23
	v_mfma_f32_16x16x32_bf16 v[12:15], v[12:15], v[8:11], 0
	v_mfma_f32_16x16x32_bf16 v[4:7], v[4:7], v[8:11], 0
	v_cvt_pk_bf16_f32 v22, v16, v17
	v_cvt_pk_bf16_f32 v23, v18, v19
	v_mfma_f32_16x16x32_bf16 v[4:7], v[68:71], v[56:59], v[4:7]
	s_waitcnt lgkmcnt(0)
	v_mfma_f32_16x16x32_bf16 v[16:19], v[24:27], v[20:23], 0
	ds_read_b64_tr_b16 v[24:25], v131 offset:32
	ds_read_b64_tr_b16 v[26:27], v131 offset:2336
	ds_read_b64_tr_b16 v[28:29], v131 offset:64
	ds_read_b64_tr_b16 v[32:33], v131 offset:96
	ds_read_b64_tr_b16 v[30:31], v131 offset:2368
	ds_read_b64_tr_b16 v[34:35], v131 offset:2400
	v_mfma_f32_16x16x32_bf16 v[12:15], v[36:39], v[56:59], v[12:15]
	v_cndmask_b32_e64 v0, v4, 0, s[40:41]
	v_cndmask_b32_e64 v1, 0, v5, s[42:43]
	ds_read_b64_tr_b16 v[36:37], v131 offset:4608
	ds_read_b64_tr_b16 v[38:39], v131 offset:6912
	s_waitcnt lgkmcnt(0)
	v_mfma_f32_16x16x32_bf16 v[24:27], v[24:27], v[20:23], 0
	s_nop 1
	v_cvt_pk_bf16_f32 v4, v12, v13
	v_cvt_pk_bf16_f32 v5, v14, v15
	v_cndmask_b32_e64 v2, v6, 0, s[38:39]
	v_mfma_f32_16x16x32_bf16 v[28:31], v[28:31], v[20:23], 0
	v_cndmask_b32_e64 v7, v7, 0, vcc
	v_cvt_pk_bf16_f32 v6, v0, v1
	v_cvt_pk_bf16_f32 v7, v2, v7
	v_mfma_f32_16x16x32_bf16 v[12:15], v[32:35], v[20:23], 0
	ds_read_b64_tr_b16 v[20:21], v131 offset:6944
	v_mad_u64_u32 v[0:1], s[20:21], v126, s72, v[100:101]
	v_mfma_f32_16x16x32_bf16 v[32:35], v[36:39], v[4:7], v[16:19]
	s_nop 2
	ds_read_b64_tr_b16 v[18:19], v131 offset:4640
	ds_read_b64_tr_b16 v[16:17], v131 offset:4672
	s_waitcnt lgkmcnt(0)
	v_mfma_f32_16x16x32_bf16 v[20:23], v[18:21], v[4:7], v[24:27]
	ds_read_b64_tr_b16 v[18:19], v131 offset:6976
	s_nop 1
	ds_read_b64_tr_b16 v[24:25], v131 offset:4704
	ds_read_b64_tr_b16 v[26:27], v131 offset:7008
	s_waitcnt lgkmcnt(0)
; __device__ __forceinline__ unsigned pk2(float lo, float hi) { const f32x2_t v = {lo, hi}; const bf16x2_t b = __builtin_convertvector(v, bf16x2_t); return __builtin_bit_cast(unsigned, b); }
; template <int KIND>
; __device__ __forceinline__ void w_m3_core(const bf16x8 (&Qf)[4][2], const bf16x8 (&Kf)[4][2], const bf16x8 (&Sf)[4][2], const LAS bf16_t* vT, float lg,
;                                           const bf16_t* gsrc, const float* nw, bf16_t* ydst, int lo, int fq) {
;     ...
;             const bf16x8 Pf = pack_frag(pv);
; #pragma unroll
;             for (int eb = 0; eb < 4; ++eb)
;                 O[eb] = __builtin_amdgcn_mfma_f32_16x16x32_bf16(tr_frag(vT, 32 * kk2 + 4 * fq, 32 * kk2 + 16 + 4 * fq, 16 * eb, lo), Pf, O[eb], 0, 0, 0);
;         }
; #pragma unroll
;         for (int kk = 0; kk < 2; ++kk)
; #pragma unroll
;             for (int eb = 0; eb < 4; ++eb) O2[eb] = __builtin_amdgcn_mfma_f32_16x16x32_bf16(Sf[eb][kk], Qf[nb][kk], O2[eb], 0, 0, 0);
;         const float osc = KIND == 0 ? __expf((float)(16 * nb + lo + 1) * lg) : 1.0f;
; #pragma unroll
;         for (int eb = 0; eb < 4; ++eb) O[eb] = O[eb] + O2[eb] * osc;
;         float ss = 0.f;
; #pragma unroll
;         for (int eb = 0; eb < 4; ++eb) ss += (O[eb][0] * O[eb][0] + O[eb][1] * O[eb][1]) + (O[eb][2] * O[eb][2] + O[eb][3] * O[eb][3]);
;         { const int ln = (fq << 4) | lo; ss += bperm_f(ln ^ 16, ss); ss += bperm_f(ln ^ 32, ss); }
;         const float rs = rsqrtf(ss * (1.0f / 64.0f) + EPS);
;         const size_t n = 16 * nb + lo;
; #pragma unroll
;         for (int eb = 0; eb < 4; ++eb) { const int e0 = 16 * eb + 4 * fq;
;             const unsigned long long gw_ = *(const unsigned long long*)(gsrc + n * NIN + e0); const f32x4 w4 = *(const f32x4*)(nw + e0);
;             const float g0 = __uint_as_float((unsigned)gw_ << 16), g1 = __uint_as_float((unsigned)gw_ & 0xffff0000u), g2 = __uint_as_float((unsigned)(gw_ >> 32) << 16), g3 = __uint_as_float((unsigned)(gw_ >> 32) & 0xffff0000u);
;             const float o0 = O[eb][0] * rs * w4[0] * (g0 * sigmoidf_(g0)), o1 = O[eb][1] * rs * w4[1] * (g1 * sigmoidf_(g1));
;             const float o2 = O[eb][2] * rs * w4[2] * (g2 * sigmoidf_(g2)), o3 = O[eb][3] * rs * w4[3] * (g3 * sigmoidf_(g3));
;             *(unsigned long long*)(ydst + n * DM + e0) = (unsigned long long)pk2(o0, o1) | ((unsigned long long)pk2(o2, o3) << 32); }
	v_mfma_f32_16x16x32_bf16 v[16:19], v[16:19], v[4:7], v[28:31]
	v_mfma_f32_16x16x32_bf16 v[12:15], v[24:27], v[4:7], v[12:15]
	v_lshl_add_u64 v[6:7], v[0:1], 0, v[62:63]
	v_mov_b64_e32 v[44:45], v[246:247]
	v_mov_b64_e32 v[40:41], v[146:147]
	v_mov_b64_e32 v[42:43], v[148:149]
	v_mfma_f32_16x16x32_bf16 v[24:27], v[64:67], v[8:11], 0
	v_mfma_f32_16x16x32_bf16 v[28:31], v[72:75], v[8:11], 0
	v_mfma_f32_16x16x32_bf16 v[36:39], v[76:79], v[8:11], 0
	v_mfma_f32_16x16x32_bf16 v[8:11], v[80:83], v[8:11], 0
	v_mfma_f32_16x16x32_bf16 v[24:27], v[84:87], v[56:59], v[24:27]
	v_mfma_f32_16x16x32_bf16 v[8:11], v[96:99], v[56:59], v[8:11]
	v_mfma_f32_16x16x32_bf16 v[28:31], v[88:91], v[56:59], v[28:31]
	s_nop 5
	v_add_f32_e64 v26, v34, v26
	v_add_f32_e64 v27, v35, v27
	v_pk_add_f32 v[32:33], v[32:33], v[24:25]
	v_pk_add_f32 v[0:1], v[14:15], v[10:11]
	v_pk_add_f32 v[4:5], v[12:13], v[8:9]
	v_pk_mul_f32 v[8:9], v[26:27], v[26:27]
	v_pk_mul_f32 v[10:11], v[32:33], v[32:33]
	v_pk_add_f32 v[30:31], v[22:23], v[30:31]
	v_mfma_f32_16x16x32_bf16 v[22:25], v[92:95], v[56:59], v[36:39]
	v_add_f32_e64 v20, v20, v28
	v_add_f32_e64 v21, v21, v29
	v_pk_mov_b32 v[12:13], v[10:11], v[8:9] op_sel:[1,0]
	v_mov_b32_e32 v11, v9
	v_pk_add_f32 v[8:9], v[12:13], v[10:11]
	v_pk_mul_f32 v[10:11], v[30:31], v[30:31]
	v_pk_mul_f32 v[12:13], v[20:21], v[20:21]
	s_nop 0
	v_pk_add_f32 v[16:17], v[16:17], v[22:23]
	v_pk_mov_b32 v[14:15], v[12:13], v[10:11] op_sel:[1,0]
	v_mov_b32_e32 v13, v11
	v_pk_add_f32 v[10:11], v[14:15], v[12:13]
	v_mul_f32_e32 v2, v4, v4
	v_mul_f32_e32 v12, v5, v5
	v_pk_add_f32 v[8:9], v[8:9], v[8:9] op_sel:[0,1] op_sel_hi:[1,0]
	v_pk_add_f32 v[10:11], v[10:11], v[10:11] op_sel:[0,1] op_sel_hi:[1,0]
	v_pk_add_f32 v[18:19], v[18:19], v[24:25]
	v_mov_b32_e32 v9, v2
	v_mov_b32_e32 v11, v12
	v_mul_f32_e32 v2, v17, v17
	v_mul_f32_e32 v13, v0, v0
	v_pk_add_f32 v[8:9], v[8:9], v[10:11]
	v_pk_fma_f32 v[10:11], v[16:17], v[16:17], v[2:3] op_sel_hi:[1,1,0]
	v_mul_f32_e32 v2, v19, v19
	v_mul_f32_e32 v14, v1, v1
	v_mov_b32_e32 v11, v13
	v_pk_fma_f32 v[12:13], v[18:19], v[18:19], v[2:3] op_sel_hi:[1,1,0]
	s_waitcnt lgkmcnt(0)
	v_and_b32_e32 v15, 0xffff0000, v45
	v_mov_b32_e32 v13, v14
	v_pk_add_f32 v[10:11], v[10:11], v[12:13]
	v_lshlrev_b32_e32 v12, 16, v44
	v_pk_add_f32 v[8:9], v[8:9], v[10:11]
	v_and_b32_e32 v13, 0xffff0000, v44
	v_add_f32_e32 v2, v8, v9
	ds_bpermute_b32 v8, v130, v2
	v_mul_f32_e32 v9, 0xbfb8aa3b, v13
	v_exp_f32_e32 v9, v9
	v_lshlrev_b32_e32 v14, 16, v45
	s_waitcnt lgkmcnt(0)
	v_add_f32_e32 v2, v2, v8
	ds_bpermute_b32 v8, v129, v2
	s_waitcnt lgkmcnt(0)
	v_add_f32_e32 v2, v2, v8
	v_fmamk_f32 v2, v2, 0x3c800000, v200
	v_mul_f32_e32 v8, 0x4b800000, v2
	v_cmp_gt_f32_e32 vcc, s29, v2
	s_nop 1
	v_cndmask_b32_e32 v2, v2, v8, vcc
	v_rsq_f32_e32 v2, v2
	s_nop 0
	v_mul_f32_e32 v8, 0x45800000, v2
	v_cndmask_b32_e32 v8, v2, v8, vcc
	v_lshlrev_b32_e32 v2, 11, v126
	v_lshl_add_u64 v[10:11], s[46:47], 0, v[2:3]
	v_mul_f32_e32 v2, 0xbfb8aa3b, v12
	v_exp_f32_e32 v2, v2
	v_pk_mul_f32 v[24:25], v[32:33], v[8:9] op_sel_hi:[1,0]
	v_lshl_add_u64 v[10:11], v[10:11], 0, v[62:63]
	v_pk_mul_f32 v[24:25], v[40:41], v[24:25]
	v_add_f32_e32 v2, 1.0, v2
	v_rcp_f32_e32 v22, v2
	v_add_f32_e32 v2, 1.0, v9
	v_rcp_f32_e32 v23, v2
	v_mul_f32_e32 v2, 0xbfb8aa3b, v14
	v_exp_f32_e32 v2, v2
	v_mul_f32_e32 v9, 0xbfb8aa3b, v15
	v_exp_f32_e32 v9, v9
	v_pk_mul_f32 v[12:13], v[22:23], v[12:13]
	v_add_f32_e32 v2, 1.0, v2
	v_rcp_f32_e32 v22, v2
	v_add_f32_e32 v2, 1.0, v9
	v_rcp_f32_e32 v23, v2
	v_pk_mul_f32 v[12:13], v[12:13], v[24:25]
	v_pk_mul_f32 v[24:25], v[26:27], v[8:9] op_sel_hi:[1,0]
	v_cvt_pk_bf16_f32 v12, v12, v13
	v_pk_mul_f32 v[24:25], v[42:43], v[24:25]
	v_pk_mul_f32 v[14:15], v[22:23], v[14:15]
	v_pk_mul_f32 v[20:21], v[20:21], v[8:9] op_sel_hi:[1,0]
	v_pk_mul_f32 v[14:15], v[14:15], v[24:25]
	v_pk_mul_f32 v[24:25], v[30:31], v[8:9] op_sel_hi:[1,0]
	v_cvt_pk_bf16_f32 v13, v14, v15
	global_store_dwordx2 v[10:11], v[12:13], off offset:1536
	v_mov_b64_e32 v[22:23], v[248:249]
	s_nop 0
	v_mov_b64_e32 v[12:13], v[150:151]
	v_mov_b64_e32 v[14:15], v[152:153]
	v_mul_f32_e32 v16, v16, v8
	v_mul_f32_e32 v18, v18, v8
	v_mul_f32_e32 v4, v4, v8
	v_mul_f32_e32 v0, v0, v8
	s_waitcnt lgkmcnt(0)
; __device__ __forceinline__ unsigned pk2(float lo, float hi) { const f32x2_t v = {lo, hi}; const bf16x2_t b = __builtin_convertvector(v, bf16x2_t); return __builtin_bit_cast(unsigned, b); }
; __device__ __forceinline__ float sigmoidf_(float x) { return __builtin_amdgcn_rcpf(1.0f + __expf(-x)); }
; template <int KIND>
; __device__ __forceinline__ void w_m3_core(const bf16x8 (&Qf)[4][2], const bf16x8 (&Kf)[4][2], const bf16x8 (&Sf)[4][2], const LAS bf16_t* vT, float lg,
;                                           const bf16_t* gsrc, const float* nw, bf16_t* ydst, int lo, int fq) {
;     ...
;         const size_t n = 16 * nb + lo;
; #pragma unroll
;         for (int eb = 0; eb < 4; ++eb) { const int e0 = 16 * eb + 4 * fq;
;             const unsigned long long gw_ = *(const unsigned long long*)(gsrc + n * NIN + e0); const f32x4 w4 = *(const f32x4*)(nw + e0);
;             const float g0 = __uint_as_float((unsigned)gw_ << 16), g1 = __uint_as_float((unsigned)gw_ & 0xffff0000u), g2 = __uint_as_float((unsigned)(gw_ >> 32) << 16), g3 = __uint_as_float((unsigned)(gw_ >> 32) & 0xffff0000u);
;             const float o0 = O[eb][0] * rs * w4[0] * (g0 * sigmoidf_(g0)), o1 = O[eb][1] * rs * w4[1] * (g1 * sigmoidf_(g1));
;             const float o2 = O[eb][2] * rs * w4[2] * (g2 * sigmoidf_(g2)), o3 = O[eb][3] * rs * w4[3] * (g3 * sigmoidf_(g3));
;             *(unsigned long long*)(ydst + n * DM + e0) = (unsigned long long)pk2(o0, o1) | ((unsigned long long)pk2(o2, o3) << 32); }
	v_lshlrev_b32_e32 v26, 16, v22
	v_and_b32_e32 v27, 0xffff0000, v22
	v_lshlrev_b32_e32 v22, 16, v23
	v_and_b32_e32 v23, 0xffff0000, v23
	v_mul_f32_e32 v2, 0xbfb8aa3b, v26
	v_mul_f32_e32 v9, 0xbfb8aa3b, v27
	v_mul_f32_e32 v28, 0xbfb8aa3b, v22
	v_mul_f32_e32 v29, 0xbfb8aa3b, v23
	v_exp_f32_e32 v2, v2
	v_exp_f32_e32 v9, v9
	v_exp_f32_e32 v28, v28
	v_exp_f32_e32 v29, v29
	v_add_f32_e32 v2, 1.0, v2
	v_add_f32_e32 v9, 1.0, v9
	v_add_f32_e32 v30, 1.0, v28
	v_add_f32_e32 v31, 1.0, v29
	v_rcp_f32_e32 v28, v2
	v_rcp_f32_e32 v29, v9
	v_rcp_f32_e32 v30, v30
	v_rcp_f32_e32 v31, v31
	v_pk_mul_f32 v[12:13], v[12:13], v[20:21]
	v_pk_mul_f32 v[14:15], v[14:15], v[24:25]
	v_pk_mul_f32 v[20:21], v[28:29], v[26:27]
	v_pk_mul_f32 v[22:23], v[30:31], v[22:23]
	v_pk_mul_f32 v[12:13], v[20:21], v[12:13]
	v_pk_mul_f32 v[14:15], v[22:23], v[14:15]
	v_cvt_pk_bf16_f32 v12, v12, v13
	v_cvt_pk_bf16_f32 v13, v14, v15
	global_store_dwordx2 v[10:11], v[12:13], off offset:1568
	v_mov_b64_e32 v[20:21], v[250:251]
	s_nop 0
	v_mov_b64_e32 v[12:13], v[188:189]
	v_mov_b64_e32 v[14:15], v[190:191]
	v_mul_f32_e32 v22, v17, v8
	v_mul_f32_e32 v24, v19, v8
	s_waitcnt lgkmcnt(0)
	v_lshlrev_b32_e32 v17, 16, v20
	v_and_b32_e32 v23, 0xffff0000, v20
	v_lshlrev_b32_e32 v19, 16, v21
	v_and_b32_e32 v25, 0xffff0000, v21
	v_mov_b32_e32 v20, v13
	v_mov_b32_e32 v26, v15
	v_mul_f32_e32 v2, 0xbfb8aa3b, v17
	v_mul_f32_e32 v9, 0xbfb8aa3b, v23
	v_mul_f32_e32 v13, 0xbfb8aa3b, v19
	v_mul_f32_e32 v15, 0xbfb8aa3b, v25
	v_exp_f32_e32 v2, v2
	v_exp_f32_e32 v9, v9
	v_exp_f32_e32 v13, v13
	v_exp_f32_e32 v15, v15
	v_add_f32_e32 v2, 1.0, v2
	v_add_f32_e32 v9, 1.0, v9
	v_add_f32_e32 v27, 1.0, v13
	v_add_f32_e32 v28, 1.0, v15
	v_rcp_f32_e32 v13, v2
	v_rcp_f32_e32 v21, v9
	v_rcp_f32_e32 v15, v27
	v_rcp_f32_e32 v27, v28
	v_pk_mul_f32 v[12:13], v[12:13], v[16:17]
	v_pk_mul_f32 v[16:17], v[20:21], v[22:23]
	v_pk_mul_f32 v[14:15], v[14:15], v[18:19]
	v_pk_mul_f32 v[18:19], v[26:27], v[24:25]
	v_mov_b32_e32 v20, v12
	v_mov_b32_e32 v21, v16
	v_mov_b32_e32 v16, v13
	v_mov_b32_e32 v12, v14
	v_mov_b32_e32 v13, v18
	v_mov_b32_e32 v18, v15
	v_pk_mul_f32 v[14:15], v[20:21], v[16:17]
	v_pk_mul_f32 v[12:13], v[12:13], v[18:19]
	v_cvt_pk_bf16_f32 v14, v14, v15
	v_cvt_pk_bf16_f32 v15, v12, v13
	global_store_dwordx2 v[10:11], v[14:15], off offset:1600
	v_mov_b64_e32 v[6:7], v[252:253]
	s_nop 0
	v_mov_b64_e32 v[12:13], v[192:193]
	v_mov_b64_e32 v[14:15], v[194:195]
	v_mul_f32_e32 v16, v5, v8
	v_mul_f32_e32 v8, v1, v8
	s_waitcnt lgkmcnt(0)
	v_lshlrev_b32_e32 v5, 16, v6
	v_and_b32_e32 v17, 0xffff0000, v6
	v_lshlrev_b32_e32 v1, 16, v7
	v_and_b32_e32 v9, 0xffff0000, v7
	v_mov_b32_e32 v6, v12
	v_mov_b32_e32 v12, v13
	v_mov_b32_e32 v18, v15
	v_mul_f32_e32 v2, 0xbfb8aa3b, v5
	v_mul_f32_e32 v7, 0xbfb8aa3b, v17
	v_mul_f32_e32 v13, 0xbfb8aa3b, v1
	v_mul_f32_e32 v15, 0xbfb8aa3b, v9
	v_exp_f32_e32 v2, v2
	v_exp_f32_e32 v7, v7
	v_exp_f32_e32 v13, v13
	v_exp_f32_e32 v15, v15
	v_add_f32_e32 v2, 1.0, v2
	v_add_f32_e32 v19, 1.0, v7
	v_add_f32_e32 v20, 1.0, v13
	v_add_f32_e32 v21, 1.0, v15
	v_rcp_f32_e32 v7, v2
	v_rcp_f32_e32 v13, v19
	v_rcp_f32_e32 v15, v20
	v_rcp_f32_e32 v19, v21
	v_pk_mul_f32 v[4:5], v[6:7], v[4:5]
	v_pk_mul_f32 v[6:7], v[12:13], v[16:17]
	v_pk_mul_f32 v[0:1], v[14:15], v[0:1]
	v_pk_mul_f32 v[8:9], v[18:19], v[8:9]
	v_mov_b32_e32 v12, v4
	v_mov_b32_e32 v13, v6
	v_mov_b32_e32 v6, v5
	v_mov_b32_e32 v4, v0
	v_mov_b32_e32 v5, v8
	v_mov_b32_e32 v8, v1
	v_pk_mul_f32 v[0:1], v[12:13], v[6:7]
	v_pk_mul_f32 v[4:5], v[4:5], v[8:9]
	v_cvt_pk_bf16_f32 v0, v0, v1
	v_cvt_pk_bf16_f32 v1, v4, v5
	global_store_dwordx2 v[10:11], v[0:1], off offset:1632
	s_waitcnt lgkmcnt(0)

; #define LAS __attribute__((address_space(3)))
; __device__ __forceinline__ void w_store_vT(LAS bf16_t* vN, const bf16_t* src, int lane) {
; #pragma unroll
;     for (int i = 0; i < 8; ++i) { const int m = (lane >> 3) + 8 * i, e0 = 8 * (lane & 7); *(LAS u32x4*)(vN + m * LD + e0) = *(const u32x4*)(src + (size_t)m * NIN + e0); }
; }
.LBB0_191:
	s_lshr_b32 s20, s66, 8
	s_lshr_b32 s21, s66, 9
	s_add_i32 s20, s20, s66
	s_and_b32 s21, s21, 12
	s_add_i32 s20, s20, s21
	s_and_b32 s70, s20, 15
	s_cmp_lt_u32 s70, 12
	s_cbranch_scc1 .LBB0_190
	s_ashr_i32 s21, s66, 31
	s_ashr_i32 s20, s66, 4
	s_lshr_b32 s21, s21, 25
	s_add_i32 s21, s20, s21
	s_ashr_i32 s71, s21, 7
	s_and_b32 s21, s21, 0xffffff80
	s_sub_i32 s90, s20, s21
	s_lshl_b32 s20, s71, 13
	s_lshl_b32 s21, s90, 6
	s_add_i32 s86, s21, s20
	s_add_i32 s70, s70, -12
	s_mul_i32 s21, s86, 0x1800
	s_mul_hi_i32 s20, s86, 0x1800
	s_add_u32 s67, s8, s21
	v_mov_b32_e32 v10, v132
	s_addc_u32 s68, s9, s20
	s_lshl_b32 s24, s70, 6
	s_lshl_b32 s20, s70, 7
	s_add_u32 s20, s67, s20
	v_lshlrev_b32_e32 v0, 4, v10
	s_addc_u32 s21, s68, 0
	v_and_b32_e32 v2, 0x70, v0
	v_lshl_add_u64 v[0:1], s[20:21], 0, v[2:3]
	s_mov_b64 s[20:21], 0x1400
	v_ashrrev_i32_e32 v8, 3, v10
	v_lshl_add_u64 v[0:1], v[0:1], 0, s[20:21]
	v_mad_i64_i32 v[4:5], s[20:21], v8, s72, v[0:1]
	global_load_dwordx4 v[60:63], v[4:5], off
	v_add_u32_e32 v4, 8, v8
	v_mad_i64_i32 v[4:5], s[20:21], v4, s72, v[0:1]
	global_load_dwordx4 v[64:67], v[4:5], off
	v_add_u32_e32 v4, 16, v8
	v_mad_i64_i32 v[4:5], s[20:21], v4, s72, v[0:1]
	global_load_dwordx4 v[70:73], v[4:5], off
	v_add_u32_e32 v4, 24, v8
	v_mad_i64_i32 v[4:5], s[20:21], v4, s72, v[0:1]
	global_load_dwordx4 v[74:77], v[4:5], off
	v_add_u32_e32 v4, 32, v8
	v_mad_i64_i32 v[4:5], s[20:21], v4, s72, v[0:1]
	global_load_dwordx4 v[78:81], v[4:5], off
	v_add_u32_e32 v4, 40, v8
	v_mad_i64_i32 v[4:5], s[20:21], v4, s72, v[0:1]
	global_load_dwordx4 v[88:91], v[4:5], off
	v_add_u32_e32 v4, 48, v8
	v_mad_i64_i32 v[4:5], s[20:21], v4, s72, v[0:1]
	global_load_dwordx4 v[92:95], v[4:5], off
	v_add_u32_e32 v4, 56, v8
	v_mad_i64_i32 v[0:1], s[20:21], v4, s72, v[0:1]
	global_load_dwordx4 v[96:99], v[0:1], off
	v_and_b32_e32 v196, 15, v10
	v_lshrrev_b32_e32 v197, 4, v10
	v_mul_u32_u24_e32 v196, 0x1800, v196
	v_lshl_add_u32 v196, v197, 3, v196
	s_lshl_b32 s20, s24, 1
	s_addk_i32 s20, 0x1600
	v_add_u32_e32 v196, s20, v196
	v_add_co_u32_e32 v198, vcc, s67, v196
	v_mov_b32_e32 v199, s68
	s_nop 0
	v_addc_co_u32_e32 v199, vcc, 0, v199, vcc
	global_load_dwordx2 v[222:223], v[198:199], off
	global_load_dwordx2 v[224:225], v[198:199], off offset:32
	global_load_dwordx2 v[226:227], v[198:199], off offset:64
	global_load_dwordx2 v[228:229], v[198:199], off offset:96
	v_add_u32_e32 v196, 0x18000, v196
	v_add_co_u32_e32 v198, vcc, s67, v196
	v_mov_b32_e32 v199, s68
	s_nop 0
	v_addc_co_u32_e32 v199, vcc, 0, v199, vcc
	global_load_dwordx2 v[230:231], v[198:199], off
	global_load_dwordx2 v[232:233], v[198:199], off offset:32
	global_load_dwordx2 v[234:235], v[198:199], off offset:64
	global_load_dwordx2 v[236:237], v[198:199], off offset:96
	v_add_u32_e32 v196, 0x18000, v196
	v_add_co_u32_e32 v198, vcc, s67, v196
	v_mov_b32_e32 v199, s68
	s_nop 0
	v_addc_co_u32_e32 v199, vcc, 0, v199, vcc
	global_load_dwordx2 v[238:239], v[198:199], off
	global_load_dwordx2 v[240:241], v[198:199], off offset:32
	global_load_dwordx2 v[242:243], v[198:199], off offset:64
	global_load_dwordx2 v[244:245], v[198:199], off offset:96
	v_add_u32_e32 v196, 0x18000, v196
	v_add_co_u32_e32 v198, vcc, s67, v196
	v_mov_b32_e32 v199, s68
	s_nop 0
	v_addc_co_u32_e32 v199, vcc, 0, v199, vcc
	global_load_dwordx2 v[246:247], v[198:199], off
	global_load_dwordx2 v[248:249], v[198:199], off offset:32
	global_load_dwordx2 v[250:251], v[198:199], off offset:64
	global_load_dwordx2 v[252:253], v[198:199], off offset:96
	v_mul_lo_u32 v9, v8, s23
	v_add3_u32 v2, s2, v2, v9
	v_ashrrev_i32_e32 v108, 4, v10
	v_mov_b32_e32 v43, 0
	s_and_b64 vcc, exec, s[14:15]
	v_mov_b32_e32 v42, 0
	v_mov_b32_e32 v154, v2
	v_lshlrev_b32_e32 v0, 3, v108
	v_add_u32_e32 v36, s24, v0
	v_ashrrev_i32_e32 v37, 31, v36
	s_cbranch_vccnz .LBB0_466
	v_cndmask_b32_e64 v1, 0, 1, s[14:15]
	v_cmp_ne_u32_e64 s[38:39], 1, v1
	s_andn2_b64 vcc, exec, s[14:15]
	s_cbranch_vccz .LBB0_467

; __device__ __forceinline__ void ld8bf(const bf16_t* p, float (&o)[8]) { unpack8(*(const u32x4*)p, o); }
; __device__ __forceinline__ void hg_lf_key(float fp, float lb, float& lf, float& key) {
;     const float e = __expf(-fabsf(fp));
;     const float rc = __builtin_amdgcn_rcpf(1.0f + e);
;     const float sp = fp >= 0.f ? rc : e * rc;
;     const float sn = fp >= 0.f ? e * rc : rc;
;     const float lsig = (fp >= 0.f ? 0.f : fp) + __logf(rc);
;     lf = (lb == 0.f) ? lsig : __logf(lb + (1.0f - lb) * sp); key = (1.0f - lb) * sn;
; }
; __device__ __forceinline__ void w_hg_scan(const float (&lbv)[8], const bf16_t* fsrc, int lane, float (&bb)[4][8], float (&r31)[8], float (&r63)[8]) {
;     const int lo = lane & 15;
; #pragma unroll
;     for (int tb = 0; tb < 4; ++tb) { float fp[8]; ld8bf(fsrc + (size_t)(16 * tb + lo) * NIN, fp);
; #pragma unroll
;         for (int j = 0; j < 8; ++j) { float key; hg_lf_key(fp[j], lbv[j], bb[tb][j], key); } }
.LBB0_201:
	s_lshl_b32 s88, s24, 1
	v_and_b32_e32 v114, 15, v10
	s_add_u32 s20, s67, s88
	s_addc_u32 s21, s68, 0
	v_ashrrev_i32_e32 v1, 31, v0
	v_mul_u32_u24_e32 v2, 0xc00, v114
	v_lshl_add_u64 v[4:5], v[0:1], 1, s[20:21]
	v_lshlrev_b32_e32 v2, 1, v2
	v_lshl_add_u64 v[8:9], v[4:5], 0, v[2:3]
	v_add_co_u32_e32 v4, vcc, s73, v8
	v_cmp_neq_f32_e64 s[40:41], 0, v42
	s_nop 0
	v_addc_co_u32_e32 v5, vcc, 0, v9, vcc
	v_add_co_u32_e32 v198, vcc, 0x18000, v4
	s_nop 1
	v_addc_co_u32_e32 v199, vcc, 0, v5, vcc
	global_load_dwordx4 v[186:189], v[198:199], off offset:512
	v_add_co_u32_e32 v198, vcc, 0x18000, v198
	s_nop 1
	v_addc_co_u32_e32 v199, vcc, 0, v199, vcc
	global_load_dwordx4 v[190:193], v[198:199], off offset:512
	v_add_co_u32_e32 v198, vcc, 0x18000, v198
	s_nop 1
	v_addc_co_u32_e32 v199, vcc, 0, v199, vcc
	global_load_dwordx4 v[194:197], v[198:199], off offset:512
	global_load_dwordx4 v[4:7], v[4:5], off offset:512
	s_waitcnt vmcnt(4)
	ds_write_b128 v154, v[60:63]
	ds_write_b128 v154, v[64:67] offset:1152
	ds_write_b128 v154, v[70:73] offset:2304
	ds_write_b128 v154, v[74:77] offset:3456
	ds_write_b128 v154, v[78:81] offset:4608
	ds_write_b128 v154, v[88:91] offset:5760
	ds_write_b128 v154, v[92:95] offset:6912
	ds_write_b128 v154, v[96:99] offset:8064
	v_sub_f32_e32 v20, 1.0, v42
	s_waitcnt vmcnt(0) lgkmcnt(0)
	v_lshlrev_b32_e32 v13, 16, v4
	v_mul_f32_e64 v2, |v13|, s26
	v_exp_f32_e32 v15, v2
	v_cmp_le_f32_e32 vcc, 0, v13
	v_add_f32_e32 v2, 1.0, v15
	v_rcp_f32_e32 v14, v2
	s_and_saveexec_b64 s[20:21], s[40:41]
	s_xor_b64 s[34:35], exec, s[20:21]
	s_cbranch_execz .LBB0_203
	v_mul_f32_e32 v2, v15, v14
	v_cndmask_b32_e32 v2, v2, v14, vcc
	v_fma_f32 v2, v20, v2, v42
	v_cmp_gt_f32_e64 s[42:43], s29, v2
	s_nop 1
	v_cndmask_b32_e64 v13, 0, 32, s[42:43]
	v_ldexp_f32 v2, v2, v13
	v_log_f32_e32 v2, v2
	s_nop 0
	v_mul_f32_e32 v13, 0x3f317217, v2
	v_fma_f32 v13, v2, s17, -v13
	v_fmac_f32_e32 v13, 0x3377d1cf, v2
	v_fmac_f32_e32 v13, 0x3f317217, v2
	v_cmp_lt_f32_e64 s[44:45], |v2|, s22
	s_nop 1
	v_cndmask_b32_e64 v2, v2, v13, s[44:45]
	v_cndmask_b32_e64 v13, 0, v203, s[42:43]
	v_sub_f32_e32 v2, v2, v13

; __device__ __forceinline__ void ld8bf(const bf16_t* p, float (&o)[8]) { unpack8(*(const u32x4*)p, o); }
; __device__ __forceinline__ void hg_lf_key(float fp, float lb, float& lf, float& key) {
;     const float e = __expf(-fabsf(fp));
;     const float rc = __builtin_amdgcn_rcpf(1.0f + e);
;     const float sp = fp >= 0.f ? rc : e * rc;
;     const float sn = fp >= 0.f ? e * rc : rc;
;     const float lsig = (fp >= 0.f ? 0.f : fp) + __logf(rc);
;     lf = (lb == 0.f) ? lsig : __logf(lb + (1.0f - lb) * sp); key = (1.0f - lb) * sn;
; }
; __device__ __forceinline__ void w_hg_scan(const float (&lbv)[8], const bf16_t* fsrc, int lane, float (&bb)[4][8], float (&r31)[8], float (&r63)[8]) {
;     const int lo = lane & 15;
; #pragma unroll
;     for (int tb = 0; tb < 4; ++tb) { float fp[8]; ld8bf(fsrc + (size_t)(16 * tb + lo) * NIN, fp);
; #pragma unroll
;         for (int j = 0; j < 8; ++j) { float key; hg_lf_key(fp[j], lbv[j], bb[tb][j], key); } }
.LBB0_233:
	s_or_b64 exec, exec, s[34:35]
	s_mov_b64 s[20:21], 0x1200
	v_lshl_add_u64 v[52:53], v[8:9], 0, s[20:21]
	v_add_co_u32_e32 v4, vcc, 0x18000, v52
	s_nop 1
	v_addc_co_u32_e32 v5, vcc, 0, v53, vcc
	v_mov_b64_e32 v[4:5], v[186:187]
	v_mov_b64_e32 v[6:7], v[188:189]
	s_waitcnt vmcnt(0) lgkmcnt(0)
	v_lshlrev_b32_e32 v9, 16, v4
	v_mul_f32_e64 v8, |v9|, s26
	v_exp_f32_e32 v27, v8
	v_cmp_le_f32_e32 vcc, 0, v9
	v_add_f32_e32 v8, 1.0, v27
	v_rcp_f32_e32 v26, v8
	s_and_saveexec_b64 s[20:21], s[40:41]
	s_xor_b64 s[34:35], exec, s[20:21]
	s_cbranch_execz .LBB0_235
	v_mul_f32_e32 v8, v27, v26
	v_cndmask_b32_e32 v8, v8, v26, vcc
	v_fma_f32 v8, v20, v8, v42
	v_cmp_gt_f32_e64 s[56:57], s29, v8
	s_nop 1
	v_cndmask_b32_e64 v9, 0, 32, s[56:57]
	v_ldexp_f32 v8, v8, v9
	v_log_f32_e32 v8, v8
	s_nop 0
	v_mul_f32_e32 v9, 0x3f317217, v8
	v_fma_f32 v9, v8, s17, -v9
	v_fmac_f32_e32 v9, 0x3377d1cf, v8
	v_fmac_f32_e32 v9, 0x3f317217, v8
	v_cmp_lt_f32_e64 s[58:59], |v8|, s22
	s_nop 1
	v_cndmask_b32_e64 v8, v8, v9, s[58:59]
	v_cndmask_b32_e64 v9, 0, v203, s[56:57]
	v_sub_f32_e32 v8, v8, v9

; __device__ __forceinline__ void ld8bf(const bf16_t* p, float (&o)[8]) { unpack8(*(const u32x4*)p, o); }
; __device__ __forceinline__ void hg_lf_key(float fp, float lb, float& lf, float& key) {
;     const float e = __expf(-fabsf(fp));
;     const float rc = __builtin_amdgcn_rcpf(1.0f + e);
;     const float sp = fp >= 0.f ? rc : e * rc;
;     const float sn = fp >= 0.f ? e * rc : rc;
;     const float lsig = (fp >= 0.f ? 0.f : fp) + __logf(rc);
;     lf = (lb == 0.f) ? lsig : __logf(lb + (1.0f - lb) * sp); key = (1.0f - lb) * sn;
; }
; __device__ __forceinline__ void w_hg_scan(const float (&lbv)[8], const bf16_t* fsrc, int lane, float (&bb)[4][8], float (&r31)[8], float (&r63)[8]) {
;     const int lo = lane & 15;
; #pragma unroll
;     for (int tb = 0; tb < 4; ++tb) { float fp[8]; ld8bf(fsrc + (size_t)(16 * tb + lo) * NIN, fp);
; #pragma unroll
;         for (int j = 0; j < 8; ++j) { float key; hg_lf_key(fp[j], lbv[j], bb[tb][j], key); } }
.LBB0_265:
	s_or_b64 exec, exec, s[34:35]
	v_add_co_u32_e32 v4, vcc, 0x30000, v52
	s_nop 1
	v_addc_co_u32_e32 v5, vcc, 0, v53, vcc
	v_mov_b64_e32 v[4:5], v[190:191]
	v_mov_b64_e32 v[6:7], v[192:193]
	s_waitcnt vmcnt(0) lgkmcnt(0)
	v_lshlrev_b32_e32 v33, 16, v4
	v_mul_f32_e64 v32, |v33|, s26
	v_exp_f32_e32 v35, v32
	v_cmp_le_f32_e32 vcc, 0, v33
	v_add_f32_e32 v32, 1.0, v35
	v_rcp_f32_e32 v34, v32
	s_and_saveexec_b64 s[20:21], s[40:41]
	s_xor_b64 s[34:35], exec, s[20:21]
	s_cbranch_execz .LBB0_267
	v_mul_f32_e32 v32, v35, v34
	v_cndmask_b32_e32 v32, v32, v34, vcc
	v_fma_f32 v32, v20, v32, v42
	v_cmp_gt_f32_e64 s[56:57], s29, v32
	s_nop 1
	v_cndmask_b32_e64 v33, 0, 32, s[56:57]
	v_ldexp_f32 v32, v32, v33
	v_log_f32_e32 v32, v32
	s_nop 0
	v_mul_f32_e32 v33, 0x3f317217, v32
	v_fma_f32 v33, v32, s17, -v33
	v_fmac_f32_e32 v33, 0x3377d1cf, v32
	v_fmac_f32_e32 v33, 0x3f317217, v32
	v_cmp_lt_f32_e64 s[58:59], |v32|, s22
	s_nop 1
	v_cndmask_b32_e64 v32, v32, v33, s[58:59]
	v_cndmask_b32_e64 v33, 0, v203, s[56:57]
	v_sub_f32_e32 v32, v32, v33

; __device__ __forceinline__ void ld8bf(const bf16_t* p, float (&o)[8]) { unpack8(*(const u32x4*)p, o); }
; __device__ __forceinline__ void hg_lf_key(float fp, float lb, float& lf, float& key) {
;     const float e = __expf(-fabsf(fp));
;     const float rc = __builtin_amdgcn_rcpf(1.0f + e);
;     const float sp = fp >= 0.f ? rc : e * rc;
;     const float sn = fp >= 0.f ? e * rc : rc;
;     const float lsig = (fp >= 0.f ? 0.f : fp) + __logf(rc);
;     lf = (lb == 0.f) ? lsig : __logf(lb + (1.0f - lb) * sp); key = (1.0f - lb) * sn;
; }
; __device__ __forceinline__ void w_hg_scan(const float (&lbv)[8], const bf16_t* fsrc, int lane, float (&bb)[4][8], float (&r31)[8], float (&r63)[8]) {
;     const int lo = lane & 15;
; #pragma unroll
;     for (int tb = 0; tb < 4; ++tb) { float fp[8]; ld8bf(fsrc + (size_t)(16 * tb + lo) * NIN, fp);
; #pragma unroll
;         for (int j = 0; j < 8; ++j) { float key; hg_lf_key(fp[j], lbv[j], bb[tb][j], key); } }
.LBB0_297:
	s_or_b64 exec, exec, s[34:35]
	v_add_co_u32_e32 v4, vcc, 0x48000, v52
	s_nop 1
	v_addc_co_u32_e32 v5, vcc, 0, v53, vcc
	v_mov_b64_e32 v[4:5], v[194:195]
	v_mov_b64_e32 v[6:7], v[196:197]
	s_waitcnt vmcnt(0) lgkmcnt(0)
	v_lshlrev_b32_e32 v48, 16, v4
	v_mul_f32_e64 v49, |v48|, s26
	v_exp_f32_e32 v55, v49
	v_cmp_le_f32_e32 vcc, 0, v48
	v_add_f32_e32 v49, 1.0, v55
	v_rcp_f32_e32 v49, v49
	s_and_saveexec_b64 s[20:21], s[40:41]
	s_xor_b64 s[34:35], exec, s[20:21]
	s_cbranch_execz .LBB0_299
	v_mul_f32_e32 v48, v55, v49
	v_cndmask_b32_e32 v48, v48, v49, vcc
	v_fma_f32 v20, v20, v48, v42
	v_cmp_gt_f32_e64 s[40:41], s29, v20
	s_nop 1
	v_cndmask_b32_e64 v48, 0, 32, s[40:41]
	v_ldexp_f32 v20, v20, v48
	v_log_f32_e32 v20, v20
	s_nop 0
	v_mul_f32_e32 v48, 0x3f317217, v20
	v_fma_f32 v48, v20, s17, -v48
	v_fmac_f32_e32 v48, 0x3377d1cf, v20
	v_fmac_f32_e32 v48, 0x3f317217, v20
	v_cmp_lt_f32_e64 s[56:57], |v20|, s22
	s_nop 1
	v_cndmask_b32_e64 v20, v20, v48, s[56:57]
	v_cndmask_b32_e64 v48, 0, v203, s[40:41]
	v_sub_f32_e32 v54, v20, v48

; __device__ __forceinline__ float bperm_f(int src_lane, float v) { return __builtin_bit_cast(float, __builtin_amdgcn_ds_bpermute(src_lane << 2, __builtin_bit_cast(int, v))); }
; template <int N> __device__ __forceinline__ float dpp_shr0(float v) {
;     return __builtin_bit_cast(float, __builtin_amdgcn_update_dpp(0, __builtin_bit_cast(int, v), 0x110 + N, 0xf, 0xf, true)); }
; template <int N> __device__ __forceinline__ float dpp_shr1(float v) {
;     return __builtin_bit_cast(float, __builtin_amdgcn_update_dpp(0x3f800000, __builtin_bit_cast(int, v), 0x110 + N, 0xf, 0xf, false)); }
; __device__ __forceinline__ float row_sum_incl(float v) { v += dpp_shr0<1>(v); v += dpp_shr0<2>(v); v += dpp_shr0<4>(v); v += dpp_shr0<8>(v); return v; }
; __device__ __forceinline__ float bcast15(float v, int lane) { return bperm_f((lane & 48) | 15, v); }
; __device__ __forceinline__ void w_hg_scan(const float (&lbv)[8], const bf16_t* fsrc, int lane, float (&bb)[4][8], float (&r31)[8], float (&r63)[8]) {
;     ...
;     for (int tb = 0; tb < 4; ++tb) {
; #pragma unroll
;         for (int j = 0; j < 8; ++j) { const float v = row_sum_incl(bb[tb][j]) + carry[j]; bb[tb][j] = v; carry[j] = bcast15(v, lane); if (tb == 1) r31[j] = carry[j]; if (tb == 3) r63[j] = carry[j]; }
;         __builtin_amdgcn_sched_barrier(0);
;     }
.LBB0_329:
	s_or_b64 exec, exec, s[34:35]
	v_add_f32_dpp v2, v2, v2 row_shr:1 row_mask:0xf bank_mask:0xf bound_ctrl:1
	v_add_f32_dpp v11, v13, v13 row_shr:1 row_mask:0xf bank_mask:0xf bound_ctrl:1
	v_add_f32_dpp v12, v14, v14 row_shr:1 row_mask:0xf bank_mask:0xf bound_ctrl:1
	v_add_f32_dpp v13, v15, v15 row_shr:1 row_mask:0xf bank_mask:0xf bound_ctrl:1
	v_add_f32_dpp v14, v16, v16 row_shr:1 row_mask:0xf bank_mask:0xf bound_ctrl:1
	v_add_f32_dpp v15, v17, v17 row_shr:1 row_mask:0xf bank_mask:0xf bound_ctrl:1
	v_add_f32_dpp v16, v18, v18 row_shr:1 row_mask:0xf bank_mask:0xf bound_ctrl:1
	v_add_f32_dpp v17, v19, v19 row_shr:1 row_mask:0xf bank_mask:0xf bound_ctrl:1
	v_add_f32_dpp v2, v2, v2 row_shr:2 row_mask:0xf bank_mask:0xf bound_ctrl:1
	v_add_f32_dpp v11, v11, v11 row_shr:2 row_mask:0xf bank_mask:0xf bound_ctrl:1
	v_add_f32_dpp v12, v12, v12 row_shr:2 row_mask:0xf bank_mask:0xf bound_ctrl:1
	v_add_f32_dpp v13, v13, v13 row_shr:2 row_mask:0xf bank_mask:0xf bound_ctrl:1
	v_add_f32_dpp v14, v14, v14 row_shr:2 row_mask:0xf bank_mask:0xf bound_ctrl:1
	v_add_f32_dpp v15, v15, v15 row_shr:2 row_mask:0xf bank_mask:0xf bound_ctrl:1
	v_add_f32_dpp v16, v16, v16 row_shr:2 row_mask:0xf bank_mask:0xf bound_ctrl:1
	v_add_f32_dpp v17, v17, v17 row_shr:2 row_mask:0xf bank_mask:0xf bound_ctrl:1
	v_add_f32_dpp v2, v2, v2 row_shr:4 row_mask:0xf bank_mask:0xf bound_ctrl:1
	v_add_f32_dpp v11, v11, v11 row_shr:4 row_mask:0xf bank_mask:0xf bound_ctrl:1
	v_add_f32_dpp v12, v12, v12 row_shr:4 row_mask:0xf bank_mask:0xf bound_ctrl:1
	v_add_f32_dpp v13, v13, v13 row_shr:4 row_mask:0xf bank_mask:0xf bound_ctrl:1
	v_add_f32_dpp v14, v14, v14 row_shr:4 row_mask:0xf bank_mask:0xf bound_ctrl:1
	v_add_f32_dpp v15, v15, v15 row_shr:4 row_mask:0xf bank_mask:0xf bound_ctrl:1
	v_add_f32_dpp v16, v16, v16 row_shr:4 row_mask:0xf bank_mask:0xf bound_ctrl:1
	v_add_f32_dpp v17, v17, v17 row_shr:4 row_mask:0xf bank_mask:0xf bound_ctrl:1
	v_lshlrev_b32_e32 v10, 2, v10
	v_add_f32_dpp v2, v2, v2 row_shr:8 row_mask:0xf bank_mask:0xf bound_ctrl:1
	v_add_f32_dpp v11, v11, v11 row_shr:8 row_mask:0xf bank_mask:0xf bound_ctrl:1
	v_add_f32_dpp v12, v12, v12 row_shr:8 row_mask:0xf bank_mask:0xf bound_ctrl:1
	v_add_f32_dpp v13, v13, v13 row_shr:8 row_mask:0xf bank_mask:0xf bound_ctrl:1
	v_add_f32_dpp v14, v14, v14 row_shr:8 row_mask:0xf bank_mask:0xf bound_ctrl:1
	v_add_f32_dpp v15, v15, v15 row_shr:8 row_mask:0xf bank_mask:0xf bound_ctrl:1
	v_add_f32_dpp v16, v16, v16 row_shr:8 row_mask:0xf bank_mask:0xf bound_ctrl:1
	v_add_f32_dpp v17, v17, v17 row_shr:8 row_mask:0xf bank_mask:0xf bound_ctrl:1
	v_and_b32_e32 v70, 0xc0, v10
	v_add_f32_e32 v2, 0, v2
	v_add_f32_e32 v72, 0, v11
	v_add_f32_e32 v75, 0, v12
	v_add_f32_e32 v88, 0, v13
	v_add_f32_e32 v91, 0, v14
	v_add_f32_e32 v92, 0, v15
	v_add_f32_e32 v95, 0, v16
	v_add_f32_e32 v96, 0, v17
	ds_bpermute_b32 v10, v70, v2 offset:60
	ds_bpermute_b32 v11, v70, v72 offset:60
	ds_bpermute_b32 v12, v70, v75 offset:60
	ds_bpermute_b32 v13, v70, v88 offset:60
	ds_bpermute_b32 v14, v70, v91 offset:60
	ds_bpermute_b32 v15, v70, v92 offset:60
	ds_bpermute_b32 v16, v70, v95 offset:60
	ds_bpermute_b32 v17, v70, v96 offset:60
	s_mov_b64 s[20:21], 0x18000
	v_lshl_add_u64 v[48:49], v[52:53], 0, s[20:21]
	v_or_b32_e32 v56, s86, v114
	v_mov_b32_e32 v57, 0
	v_add_f32_dpp v8, v8, v8 row_shr:1 row_mask:0xf bank_mask:0xf bound_ctrl:1
	s_nop 1
	v_add_f32_dpp v8, v8, v8 row_shr:2 row_mask:0xf bank_mask:0xf bound_ctrl:1
	s_nop 1
	v_add_f32_dpp v8, v8, v8 row_shr:4 row_mask:0xf bank_mask:0xf bound_ctrl:1
	s_nop 1
	v_add_f32_dpp v8, v8, v8 row_shr:8 row_mask:0xf bank_mask:0xf bound_ctrl:1
	s_waitcnt lgkmcnt(7)
	v_add_f32_e32 v99, v8, v10
	ds_bpermute_b32 v73, v70, v99 offset:60
	v_add_f32_dpp v8, v9, v9 row_shr:1 row_mask:0xf bank_mask:0xf bound_ctrl:1
	s_nop 1
	v_add_f32_dpp v8, v8, v8 row_shr:2 row_mask:0xf bank_mask:0xf bound_ctrl:1
	s_nop 1
	v_add_f32_dpp v8, v8, v8 row_shr:4 row_mask:0xf bank_mask:0xf bound_ctrl:1
	s_nop 1
	v_add_f32_dpp v8, v8, v8 row_shr:8 row_mask:0xf bank_mask:0xf bound_ctrl:1
	s_waitcnt lgkmcnt(7)
	v_add_f32_e32 v100, v8, v11
	ds_bpermute_b32 v74, v70, v100 offset:60
	v_add_f32_dpp v8, v26, v26 row_shr:1 row_mask:0xf bank_mask:0xf bound_ctrl:1
	s_nop 1
	v_add_f32_dpp v8, v8, v8 row_shr:2 row_mask:0xf bank_mask:0xf bound_ctrl:1
	s_nop 1
	v_add_f32_dpp v8, v8, v8 row_shr:4 row_mask:0xf bank_mask:0xf bound_ctrl:1
	s_nop 1
	v_add_f32_dpp v8, v8, v8 row_shr:8 row_mask:0xf bank_mask:0xf bound_ctrl:1
	s_waitcnt lgkmcnt(7)
	v_add_f32_e32 v101, v8, v12
	ds_bpermute_b32 v89, v70, v101 offset:60
	v_add_f32_dpp v8, v27, v27 row_shr:1 row_mask:0xf bank_mask:0xf bound_ctrl:1
	s_nop 1
	v_add_f32_dpp v8, v8, v8 row_shr:2 row_mask:0xf bank_mask:0xf bound_ctrl:1
	s_nop 1
	v_add_f32_dpp v8, v8, v8 row_shr:4 row_mask:0xf bank_mask:0xf bound_ctrl:1
	s_nop 1
	v_add_f32_dpp v8, v8, v8 row_shr:8 row_mask:0xf bank_mask:0xf bound_ctrl:1
	s_waitcnt lgkmcnt(7)
	v_add_f32_e32 v102, v8, v13
	ds_bpermute_b32 v90, v70, v102 offset:60
	v_add_f32_dpp v8, v28, v28 row_shr:1 row_mask:0xf bank_mask:0xf bound_ctrl:1
	s_nop 1
	v_add_f32_dpp v8, v8, v8 row_shr:2 row_mask:0xf bank_mask:0xf bound_ctrl:1
	s_nop 1
	v_add_f32_dpp v8, v8, v8 row_shr:4 row_mask:0xf bank_mask:0xf bound_ctrl:1
	s_nop 1
	v_add_f32_dpp v8, v8, v8 row_shr:8 row_mask:0xf bank_mask:0xf bound_ctrl:1
	s_waitcnt lgkmcnt(7)
	v_add_f32_e32 v104, v8, v14
	ds_bpermute_b32 v93, v70, v104 offset:60
	v_add_f32_dpp v8, v29, v29 row_shr:1 row_mask:0xf bank_mask:0xf bound_ctrl:1
	s_nop 1
	v_add_f32_dpp v8, v8, v8 row_shr:2 row_mask:0xf bank_mask:0xf bound_ctrl:1
	s_nop 1
	v_add_f32_dpp v8, v8, v8 row_shr:4 row_mask:0xf bank_mask:0xf bound_ctrl:1
	s_nop 1
	v_add_f32_dpp v8, v8, v8 row_shr:8 row_mask:0xf bank_mask:0xf bound_ctrl:1
	s_waitcnt lgkmcnt(7)
; __device__ __forceinline__ float bperm_f(int src_lane, float v) { return __builtin_bit_cast(float, __builtin_amdgcn_ds_bpermute(src_lane << 2, __builtin_bit_cast(int, v))); }
; template <int N> __device__ __forceinline__ float dpp_shr0(float v) {
;     return __builtin_bit_cast(float, __builtin_amdgcn_update_dpp(0, __builtin_bit_cast(int, v), 0x110 + N, 0xf, 0xf, true)); }
; template <int N> __device__ __forceinline__ float dpp_shr1(float v) {
;     return __builtin_bit_cast(float, __builtin_amdgcn_update_dpp(0x3f800000, __builtin_bit_cast(int, v), 0x110 + N, 0xf, 0xf, false)); }
; __device__ __forceinline__ float row_sum_incl(float v) { v += dpp_shr0<1>(v); v += dpp_shr0<2>(v); v += dpp_shr0<4>(v); v += dpp_shr0<8>(v); return v; }
; __device__ __forceinline__ float bcast15(float v, int lane) { return bperm_f((lane & 48) | 15, v); }
; __device__ __forceinline__ void w_hg_scan(const float (&lbv)[8], const bf16_t* fsrc, int lane, float (&bb)[4][8], float (&r31)[8], float (&r63)[8]) {
;     ...
;     for (int tb = 0; tb < 4; ++tb) {
; #pragma unroll
;         for (int j = 0; j < 8; ++j) { const float v = row_sum_incl(bb[tb][j]) + carry[j]; bb[tb][j] = v; carry[j] = bcast15(v, lane); if (tb == 1) r31[j] = carry[j]; if (tb == 3) r63[j] = carry[j]; }
;         __builtin_amdgcn_sched_barrier(0);
;     }
	v_add_f32_e32 v105, v8, v15
	ds_bpermute_b32 v94, v70, v105 offset:60
	v_add_f32_dpp v8, v30, v30 row_shr:1 row_mask:0xf bank_mask:0xf bound_ctrl:1
	s_nop 1
	v_add_f32_dpp v8, v8, v8 row_shr:2 row_mask:0xf bank_mask:0xf bound_ctrl:1
	s_nop 1
	v_add_f32_dpp v8, v8, v8 row_shr:4 row_mask:0xf bank_mask:0xf bound_ctrl:1
	s_nop 1
	v_add_f32_dpp v8, v8, v8 row_shr:8 row_mask:0xf bank_mask:0xf bound_ctrl:1
	s_waitcnt lgkmcnt(7)
	v_add_f32_e32 v107, v8, v16
	ds_bpermute_b32 v97, v70, v107 offset:60
	v_add_f32_dpp v8, v31, v31 row_shr:1 row_mask:0xf bank_mask:0xf bound_ctrl:1
	s_nop 1
	v_add_f32_dpp v8, v8, v8 row_shr:2 row_mask:0xf bank_mask:0xf bound_ctrl:1
	s_nop 1
	v_add_f32_dpp v8, v8, v8 row_shr:4 row_mask:0xf bank_mask:0xf bound_ctrl:1
	s_nop 1
	v_add_f32_dpp v8, v8, v8 row_shr:8 row_mask:0xf bank_mask:0xf bound_ctrl:1
	s_waitcnt lgkmcnt(7)
	v_add_f32_e32 v109, v8, v17
	ds_bpermute_b32 v98, v70, v109 offset:60
	v_add_f32_dpp v8, v32, v32 row_shr:1 row_mask:0xf bank_mask:0xf bound_ctrl:1
	s_nop 1
	v_add_f32_dpp v8, v8, v8 row_shr:2 row_mask:0xf bank_mask:0xf bound_ctrl:1
	s_nop 1
	v_add_f32_dpp v8, v8, v8 row_shr:4 row_mask:0xf bank_mask:0xf bound_ctrl:1
	s_nop 1
	v_add_f32_dpp v8, v8, v8 row_shr:8 row_mask:0xf bank_mask:0xf bound_ctrl:1
	s_waitcnt lgkmcnt(7)
	v_add_f32_e32 v111, v8, v73
	ds_bpermute_b32 v146, v70, v111 offset:60
	v_add_f32_dpp v8, v33, v33 row_shr:1 row_mask:0xf bank_mask:0xf bound_ctrl:1
	s_nop 1
	v_add_f32_dpp v8, v8, v8 row_shr:2 row_mask:0xf bank_mask:0xf bound_ctrl:1
	s_nop 1
	v_add_f32_dpp v8, v8, v8 row_shr:4 row_mask:0xf bank_mask:0xf bound_ctrl:1
	s_nop 1
	v_add_f32_dpp v8, v8, v8 row_shr:8 row_mask:0xf bank_mask:0xf bound_ctrl:1
	s_waitcnt lgkmcnt(7)
	v_add_f32_e32 v112, v8, v74
	ds_bpermute_b32 v145, v70, v112 offset:60
	v_add_f32_dpp v8, v34, v34 row_shr:1 row_mask:0xf bank_mask:0xf bound_ctrl:1
	s_nop 1
	v_add_f32_dpp v8, v8, v8 row_shr:2 row_mask:0xf bank_mask:0xf bound_ctrl:1
	s_nop 1
	v_add_f32_dpp v8, v8, v8 row_shr:4 row_mask:0xf bank_mask:0xf bound_ctrl:1
	s_nop 1
	v_add_f32_dpp v8, v8, v8 row_shr:8 row_mask:0xf bank_mask:0xf bound_ctrl:1
	s_waitcnt lgkmcnt(7)
	v_add_f32_e32 v115, v8, v89
	ds_bpermute_b32 v139, v70, v115 offset:60
	v_add_f32_dpp v8, v35, v35 row_shr:1 row_mask:0xf bank_mask:0xf bound_ctrl:1
	s_nop 1
	v_add_f32_dpp v8, v8, v8 row_shr:2 row_mask:0xf bank_mask:0xf bound_ctrl:1
	s_nop 1
	v_add_f32_dpp v8, v8, v8 row_shr:4 row_mask:0xf bank_mask:0xf bound_ctrl:1
	s_nop 1
	v_add_f32_dpp v8, v8, v8 row_shr:8 row_mask:0xf bank_mask:0xf bound_ctrl:1
	s_waitcnt lgkmcnt(7)
	v_add_f32_e32 v116, v8, v90
	ds_bpermute_b32 v138, v70, v116 offset:60
	v_add_f32_dpp v8, v38, v38 row_shr:1 row_mask:0xf bank_mask:0xf bound_ctrl:1
	s_nop 1
	v_add_f32_dpp v8, v8, v8 row_shr:2 row_mask:0xf bank_mask:0xf bound_ctrl:1
	s_nop 1
	v_add_f32_dpp v8, v8, v8 row_shr:4 row_mask:0xf bank_mask:0xf bound_ctrl:1
	s_nop 1
	v_add_f32_dpp v8, v8, v8 row_shr:8 row_mask:0xf bank_mask:0xf bound_ctrl:1
	s_waitcnt lgkmcnt(7)
	v_add_f32_e32 v118, v8, v93
	ds_bpermute_b32 v133, v70, v118 offset:60
	v_add_f32_dpp v8, v39, v39 row_shr:1 row_mask:0xf bank_mask:0xf bound_ctrl:1
	s_nop 1
	v_add_f32_dpp v8, v8, v8 row_shr:2 row_mask:0xf bank_mask:0xf bound_ctrl:1
	s_nop 1
	v_add_f32_dpp v8, v8, v8 row_shr:4 row_mask:0xf bank_mask:0xf bound_ctrl:1
	s_nop 1
	v_add_f32_dpp v8, v8, v8 row_shr:8 row_mask:0xf bank_mask:0xf bound_ctrl:1
	s_waitcnt lgkmcnt(7)
	v_add_f32_e32 v119, v8, v94
	ds_bpermute_b32 v131, v70, v119 offset:60
	v_add_f32_dpp v8, v50, v50 row_shr:1 row_mask:0xf bank_mask:0xf bound_ctrl:1
	s_nop 1
	v_add_f32_dpp v8, v8, v8 row_shr:2 row_mask:0xf bank_mask:0xf bound_ctrl:1
	s_nop 1
	v_add_f32_dpp v8, v8, v8 row_shr:4 row_mask:0xf bank_mask:0xf bound_ctrl:1
	s_nop 1
	v_add_f32_dpp v8, v8, v8 row_shr:8 row_mask:0xf bank_mask:0xf bound_ctrl:1
	s_waitcnt lgkmcnt(7)
	v_add_f32_e32 v121, v8, v97
	ds_bpermute_b32 v129, v70, v121 offset:60
	v_add_f32_dpp v8, v51, v51 row_shr:1 row_mask:0xf bank_mask:0xf bound_ctrl:1
	s_nop 1
	v_add_f32_dpp v8, v8, v8 row_shr:2 row_mask:0xf bank_mask:0xf bound_ctrl:1
	s_nop 1
	v_add_f32_dpp v8, v8, v8 row_shr:4 row_mask:0xf bank_mask:0xf bound_ctrl:1
	s_nop 1
	v_add_f32_dpp v8, v8, v8 row_shr:8 row_mask:0xf bank_mask:0xf bound_ctrl:1
	s_waitcnt lgkmcnt(7)
; __device__ __forceinline__ void ld8bf(const bf16_t* p, float (&o)[8]) { unpack8(*(const u32x4*)p, o); }
; __device__ __forceinline__ float row_sum_incl(float v) { v += dpp_shr0<1>(v); v += dpp_shr0<2>(v); v += dpp_shr0<4>(v); v += dpp_shr0<8>(v); return v; }
; __device__ __forceinline__ float bcast15(float v, int lane) { return bperm_f((lane & 48) | 15, v); }
; __device__ __forceinline__ void w_hg_scan(const float (&lbv)[8], const bf16_t* fsrc, int lane, float (&bb)[4][8], float (&r31)[8], float (&r63)[8]) {
;     ...
;     for (int tb = 0; tb < 4; ++tb) {
; #pragma unroll
;         for (int j = 0; j < 8; ++j) { const float v = row_sum_incl(bb[tb][j]) + carry[j]; bb[tb][j] = v; carry[j] = bcast15(v, lane); if (tb == 1) r31[j] = carry[j]; if (tb == 3) r63[j] = carry[j]; }
;         __builtin_amdgcn_sched_barrier(0);
;     }
; __device__ __forceinline__ void w_hg_m3(const Args& a, int l, unsigned char* ws, const bf16_t* proj, bf16_t* y, LAS unsigned char* wl, int b, int ck_, int h, int lane) {
;     ...
;         const bf16_t* fsrc = proj + (size_t)row0 * NIN + C_HF + 64 * h + 32 * kk + 8 * fq;
;         w_hg_scan(lbv, fsrc, lane, bb, r31, r63);
; #pragma unroll
;         for (int tb = 0; tb < 4; ++tb) { float fp[8], qv[8], a1[8], a2[8];
;             ld8bf(fsrc + (size_t)(16 * tb + lo) * NIN, fp); ld8bf(proj + (size_t)(row0 + 16 * tb + lo) * NIN + C_HQ + 64 * h + 32 * kk + 8 * fq, qv);
	v_add_f32_e32 v122, v8, v98
	ds_bpermute_b32 v125, v70, v122 offset:60
	v_add_f32_dpp v4, v4, v4 row_shr:1 row_mask:0xf bank_mask:0xf bound_ctrl:1
	v_add_f32_dpp v8, v54, v54 row_shr:1 row_mask:0xf bank_mask:0xf bound_ctrl:1
	s_nop 0
	v_add_f32_dpp v4, v4, v4 row_shr:2 row_mask:0xf bank_mask:0xf bound_ctrl:1
	v_add_f32_dpp v8, v8, v8 row_shr:2 row_mask:0xf bank_mask:0xf bound_ctrl:1
	s_nop 0
	v_add_f32_dpp v151, v4, v4 row_shr:4 row_mask:0xf bank_mask:0xf bound_ctrl:1
	v_add_f32_dpp v4, v20, v20 row_shr:1 row_mask:0xf bank_mask:0xf bound_ctrl:1
	v_add_f32_dpp v152, v8, v8 row_shr:4 row_mask:0xf bank_mask:0xf bound_ctrl:1
	v_mov_b32_dpp v153, v151 row_shr:8 row_mask:0xf bank_mask:0xf bound_ctrl:1
	v_add_f32_dpp v4, v4, v4 row_shr:2 row_mask:0xf bank_mask:0xf bound_ctrl:1
	v_mov_b32_dpp v154, v152 row_shr:8 row_mask:0xf bank_mask:0xf bound_ctrl:1
	s_nop 0
	v_add_f32_dpp v148, v4, v4 row_shr:4 row_mask:0xf bank_mask:0xf bound_ctrl:1
	v_add_f32_dpp v4, v5, v5 row_shr:1 row_mask:0xf bank_mask:0xf bound_ctrl:1
	s_nop 0
	v_mov_b32_dpp v150, v148 row_shr:8 row_mask:0xf bank_mask:0xf bound_ctrl:1
	v_add_f32_dpp v4, v4, v4 row_shr:2 row_mask:0xf bank_mask:0xf bound_ctrl:1
	s_nop 1
	v_add_f32_dpp v147, v4, v4 row_shr:4 row_mask:0xf bank_mask:0xf bound_ctrl:1
	v_add_f32_dpp v4, v21, v21 row_shr:1 row_mask:0xf bank_mask:0xf bound_ctrl:1
	s_nop 0
	v_mov_b32_dpp v149, v147 row_shr:8 row_mask:0xf bank_mask:0xf bound_ctrl:1
	v_add_f32_dpp v4, v4, v4 row_shr:2 row_mask:0xf bank_mask:0xf bound_ctrl:1
	s_nop 1
	v_add_f32_dpp v141, v4, v4 row_shr:4 row_mask:0xf bank_mask:0xf bound_ctrl:1
	v_add_f32_dpp v4, v6, v6 row_shr:1 row_mask:0xf bank_mask:0xf bound_ctrl:1
	s_nop 0
	v_mov_b32_dpp v143, v141 row_shr:8 row_mask:0xf bank_mask:0xf bound_ctrl:1
	v_add_f32_dpp v4, v4, v4 row_shr:2 row_mask:0xf bank_mask:0xf bound_ctrl:1
	s_nop 1
	v_add_f32_dpp v140, v4, v4 row_shr:4 row_mask:0xf bank_mask:0xf bound_ctrl:1
	v_add_f32_dpp v4, v22, v22 row_shr:1 row_mask:0xf bank_mask:0xf bound_ctrl:1
	s_nop 0
	v_mov_b32_dpp v142, v140 row_shr:8 row_mask:0xf bank_mask:0xf bound_ctrl:1
	v_add_f32_dpp v4, v4, v4 row_shr:2 row_mask:0xf bank_mask:0xf bound_ctrl:1
	s_nop 1
	v_add_f32_dpp v135, v4, v4 row_shr:4 row_mask:0xf bank_mask:0xf bound_ctrl:1
	v_add_f32_dpp v4, v7, v7 row_shr:1 row_mask:0xf bank_mask:0xf bound_ctrl:1
	s_nop 0
	v_mov_b32_dpp v137, v135 row_shr:8 row_mask:0xf bank_mask:0xf bound_ctrl:1
	v_add_f32_dpp v4, v4, v4 row_shr:2 row_mask:0xf bank_mask:0xf bound_ctrl:1
	s_nop 1
	v_add_f32_dpp v134, v4, v4 row_shr:4 row_mask:0xf bank_mask:0xf bound_ctrl:1
	s_nop 1
	v_mov_b32_dpp v136, v134 row_shr:8 row_mask:0xf bank_mask:0xf bound_ctrl:1
	v_mov_b64_e32 v[4:5], s[8:9]
	v_mad_i64_i32 v[6:7], s[20:21], v56, s72, v[4:5]
	s_mov_b32 s89, s25
	v_lshl_add_u64 v[6:7], v[6:7], 0, s[88:89]
	v_lshlrev_b64 v[8:9], 1, v[0:1]
	v_or_b32_e32 v10, 16, v56
	v_lshl_add_u64 v[54:55], v[6:7], 0, v[8:9]
	v_mad_i64_i32 v[10:11], s[20:21], v10, s72, v[4:5]
	v_add_co_u32_e32 v6, vcc, s73, v54
	v_lshl_add_u64 v[10:11], v[10:11], 0, s[88:89]
	s_nop 0
	v_addc_co_u32_e32 v7, vcc, 0, v55, vcc
	v_lshl_add_u64 v[62:63], v[10:11], 0, v[8:9]
	v_add_co_u32_e32 v10, vcc, s73, v62
	global_load_dwordx4 v[24:27], v[52:53], off
	global_load_dwordx4 v[32:35], v[48:49], off
	v_addc_co_u32_e32 v11, vcc, 0, v63, vcc
	global_load_dwordx4 v[20:23], v[6:7], off
	global_load_dwordx4 v[16:19], v[10:11], off
	v_or_b32_e32 v10, 32, v56
	v_mad_i64_i32 v[10:11], s[20:21], v10, s72, v[4:5]
	v_add_co_u32_e32 v6, vcc, s13, v48
	v_lshl_add_u64 v[10:11], v[10:11], 0, s[88:89]
	s_nop 0
	v_addc_co_u32_e32 v7, vcc, 0, v49, vcc
	v_lshl_add_u64 v[64:65], v[10:11], 0, v[8:9]
	v_add_co_u32_e32 v10, vcc, s73, v64
	s_nop 1
	v_addc_co_u32_e32 v11, vcc, 0, v65, vcc
	global_load_dwordx4 v[28:31], v[6:7], off
	global_load_dwordx4 v[12:15], v[10:11], off
	v_or_b32_e32 v10, 48, v56
	v_mad_i64_i32 v[4:5], s[20:21], v10, s72, v[4:5]
	v_add_co_u32_e32 v6, vcc, 0x30000, v48
	v_lshl_add_u64 v[4:5], v[4:5], 0, s[88:89]
	s_nop 0
	v_addc_co_u32_e32 v7, vcc, 0, v49, vcc
	v_lshl_add_u64 v[66:67], v[4:5], 0, v[8:9]
	v_add_co_u32_e32 v8, vcc, 0x1000, v66
	s_nop 1
	v_addc_co_u32_e32 v9, vcc, 0, v67, vcc
	global_load_dwordx4 v[4:7], v[6:7], off
	s_nop 0
	global_load_dwordx4 v[8:11], v[8:9], off
	s_and_b64 vcc, exec, s[14:15]
	v_mov_b32_e32 v56, 0
	s_cbranch_vccnz .LBB0_473
	s_and_b64 vcc, exec, s[38:39]
	s_cbranch_vccz .LBB0_474

; __device__ __forceinline__ void ld8bf(const bf16_t* p, float (&o)[8]) { unpack8(*(const u32x4*)p, o); }
; __device__ __forceinline__ void hg_lf_key(float fp, float lb, float& lf, float& key) {
;     const float e = __expf(-fabsf(fp));
;     const float rc = __builtin_amdgcn_rcpf(1.0f + e);
;     const float sp = fp >= 0.f ? rc : e * rc;
;     const float sn = fp >= 0.f ? e * rc : rc;
;     const float lsig = (fp >= 0.f ? 0.f : fp) + __logf(rc);
;     lf = (lb == 0.f) ? lsig : __logf(lb + (1.0f - lb) * sp); key = (1.0f - lb) * sn;
; }
; __device__ __forceinline__ void w_hg_scan(const float (&lbv)[8], const bf16_t* fsrc, int lane, float (&bb)[4][8], float (&r31)[8], float (&r63)[8]) {
;     const int lo = lane & 15;
; #pragma unroll
;     for (int tb = 0; tb < 4; ++tb) { float fp[8]; ld8bf(fsrc + (size_t)(16 * tb + lo) * NIN, fp);
; #pragma unroll
;         for (int j = 0; j < 8; ++j) { float key; hg_lf_key(fp[j], lbv[j], bb[tb][j], key); } }
.LBB0_338:
	global_load_dwordx4 v[36:39], v[52:53], off offset:64
	v_add_co_u32_e32 v198, vcc, 0x18000, v52
	s_nop 1
	v_addc_co_u32_e32 v199, vcc, 0, v53, vcc
	global_load_dwordx4 v[186:189], v[198:199], off offset:64
	v_add_co_u32_e32 v198, vcc, 0x18000, v198
	s_nop 1
	v_addc_co_u32_e32 v199, vcc, 0, v199, vcc
	global_load_dwordx4 v[190:193], v[198:199], off offset:64
	v_add_co_u32_e32 v198, vcc, 0x18000, v198
	s_nop 1
	v_addc_co_u32_e32 v199, vcc, 0, v199, vcc
	global_load_dwordx4 v[194:197], v[198:199], off offset:64
	v_cmp_neq_f32_e64 s[38:39], 0, v56
	v_sub_f32_e32 v77, 1.0, v56
	s_waitcnt vmcnt(0) lgkmcnt(0)
	v_lshlrev_b32_e32 v60, 16, v36
	v_mul_f32_e64 v61, |v60|, s26
	v_exp_f32_e32 v68, v61
	v_cmp_le_f32_e32 vcc, 0, v60
	v_add_f32_e32 v61, 1.0, v68
	v_rcp_f32_e32 v61, v61
	s_and_saveexec_b64 s[20:21], s[38:39]
	s_xor_b64 s[34:35], exec, s[20:21]
	s_cbranch_execz .LBB0_340
	v_mul_f32_e32 v60, v68, v61
	v_cndmask_b32_e32 v60, v60, v61, vcc
	v_fma_f32 v60, v77, v60, v56
	v_cmp_gt_f32_e64 s[40:41], s29, v60
	s_nop 1
	v_cndmask_b32_e64 v61, 0, 32, s[40:41]
	v_ldexp_f32 v60, v60, v61
	v_log_f32_e32 v60, v60
	s_nop 0
	v_mul_f32_e32 v61, 0x3f317217, v60
	v_fma_f32 v61, v60, s17, -v61
	v_fmac_f32_e32 v61, 0x3377d1cf, v60
	v_fmac_f32_e32 v61, 0x3f317217, v60
	v_cmp_lt_f32_e64 s[42:43], |v60|, s22
	s_nop 1
	v_cndmask_b32_e64 v60, v60, v61, s[42:43]
	v_cndmask_b32_e64 v61, 0, v203, s[40:41]
	v_sub_f32_e32 v103, v60, v61

; __device__ __forceinline__ void ld8bf(const bf16_t* p, float (&o)[8]) { unpack8(*(const u32x4*)p, o); }
; __device__ __forceinline__ void hg_lf_key(float fp, float lb, float& lf, float& key) {
;     const float e = __expf(-fabsf(fp));
;     const float rc = __builtin_amdgcn_rcpf(1.0f + e);
;     const float sp = fp >= 0.f ? rc : e * rc;
;     const float sn = fp >= 0.f ? e * rc : rc;
;     const float lsig = (fp >= 0.f ? 0.f : fp) + __logf(rc);
;     lf = (lb == 0.f) ? lsig : __logf(lb + (1.0f - lb) * sp); key = (1.0f - lb) * sn;
; }
; __device__ __forceinline__ void w_hg_scan(const float (&lbv)[8], const bf16_t* fsrc, int lane, float (&bb)[4][8], float (&r31)[8], float (&r63)[8]) {
;     const int lo = lane & 15;
; #pragma unroll
;     for (int tb = 0; tb < 4; ++tb) { float fp[8]; ld8bf(fsrc + (size_t)(16 * tb + lo) * NIN, fp);
; #pragma unroll
;         for (int j = 0; j < 8; ++j) { float key; hg_lf_key(fp[j], lbv[j], bb[tb][j], key); } }
.LBB0_370:
	s_or_b64 exec, exec, s[34:35]
	v_lshl_add_u64 v[60:61], v[52:53], 0, 64
	v_add_co_u32_e32 v36, vcc, 0x18000, v60
	s_nop 1
	v_addc_co_u32_e32 v37, vcc, 0, v61, vcc
	v_mov_b64_e32 v[36:37], v[186:187]
	v_mov_b64_e32 v[38:39], v[188:189]
	s_waitcnt vmcnt(0) lgkmcnt(0)
	v_lshlrev_b32_e32 v52, 16, v36
	v_mul_f32_e64 v53, |v52|, s26
	v_exp_f32_e32 v83, v53
	v_cmp_le_f32_e32 vcc, 0, v52
	v_add_f32_e32 v53, 1.0, v83
	v_rcp_f32_e32 v53, v53
	s_and_saveexec_b64 s[20:21], s[38:39]
	s_xor_b64 s[34:35], exec, s[20:21]
	s_cbranch_execz .LBB0_372
	v_mul_f32_e32 v52, v83, v53
	v_cndmask_b32_e32 v52, v52, v53, vcc
	v_fma_f32 v52, v77, v52, v56
	v_cmp_gt_f32_e64 s[54:55], s29, v52
	s_nop 1
	v_cndmask_b32_e64 v53, 0, 32, s[54:55]
	v_ldexp_f32 v52, v52, v53
	v_log_f32_e32 v52, v52
	s_nop 0
	v_mul_f32_e32 v53, 0x3f317217, v52
	v_fma_f32 v53, v52, s17, -v53
	v_fmac_f32_e32 v53, 0x3377d1cf, v52
	v_fmac_f32_e32 v53, 0x3f317217, v52
	v_cmp_lt_f32_e64 s[56:57], |v52|, s22
	s_nop 1
	v_cndmask_b32_e64 v52, v52, v53, s[56:57]
	v_cndmask_b32_e64 v53, 0, v203, s[54:55]
	v_sub_f32_e32 v130, v52, v53

; __device__ __forceinline__ void ld8bf(const bf16_t* p, float (&o)[8]) { unpack8(*(const u32x4*)p, o); }
; __device__ __forceinline__ void hg_lf_key(float fp, float lb, float& lf, float& key) {
;     const float e = __expf(-fabsf(fp));
;     const float rc = __builtin_amdgcn_rcpf(1.0f + e);
;     const float sp = fp >= 0.f ? rc : e * rc;
;     const float sn = fp >= 0.f ? e * rc : rc;
;     const float lsig = (fp >= 0.f ? 0.f : fp) + __logf(rc);
;     lf = (lb == 0.f) ? lsig : __logf(lb + (1.0f - lb) * sp); key = (1.0f - lb) * sn;
; }
; __device__ __forceinline__ void w_hg_scan(const float (&lbv)[8], const bf16_t* fsrc, int lane, float (&bb)[4][8], float (&r31)[8], float (&r63)[8]) {
;     const int lo = lane & 15;
; #pragma unroll
;     for (int tb = 0; tb < 4; ++tb) { float fp[8]; ld8bf(fsrc + (size_t)(16 * tb + lo) * NIN, fp);
; #pragma unroll
;         for (int j = 0; j < 8; ++j) { float key; hg_lf_key(fp[j], lbv[j], bb[tb][j], key); } }
.LBB0_402:
	s_or_b64 exec, exec, s[34:35]
	v_add_co_u32_e32 v36, vcc, 0x30000, v60
	s_nop 1
	v_addc_co_u32_e32 v37, vcc, 0, v61, vcc
	v_mov_b64_e32 v[36:37], v[190:191]
	v_mov_b64_e32 v[38:39], v[192:193]
	s_waitcnt vmcnt(0) lgkmcnt(0)
	v_lshlrev_b32_e32 v52, 16, v36
	v_mul_f32_e64 v53, |v52|, s26
	v_exp_f32_e32 v83, v53
	v_cmp_le_f32_e32 vcc, 0, v52
	v_add_f32_e32 v53, 1.0, v83
	v_rcp_f32_e32 v53, v53
	s_and_saveexec_b64 s[20:21], s[38:39]
	s_xor_b64 s[34:35], exec, s[20:21]
	s_cbranch_execz .LBB0_404
	v_mul_f32_e32 v52, v83, v53
	v_cndmask_b32_e32 v52, v52, v53, vcc
	v_fma_f32 v52, v77, v52, v56
	v_cmp_gt_f32_e64 s[54:55], s29, v52
	s_nop 1
	v_cndmask_b32_e64 v53, 0, 32, s[54:55]
	v_ldexp_f32 v52, v52, v53
	v_log_f32_e32 v52, v52
	s_nop 0
	v_mul_f32_e32 v53, 0x3f317217, v52
	v_fma_f32 v53, v52, s17, -v53
	v_fmac_f32_e32 v53, 0x3377d1cf, v52
	v_fmac_f32_e32 v53, 0x3f317217, v52
	v_cmp_lt_f32_e64 s[56:57], |v52|, s22
	s_nop 1
	v_cndmask_b32_e64 v52, v52, v53, s[56:57]
	v_cndmask_b32_e64 v53, 0, v203, s[54:55]
	v_sub_f32_e32 v161, v52, v53

; __device__ __forceinline__ void ld8bf(const bf16_t* p, float (&o)[8]) { unpack8(*(const u32x4*)p, o); }
; __device__ __forceinline__ void hg_lf_key(float fp, float lb, float& lf, float& key) {
;     const float e = __expf(-fabsf(fp));
;     const float rc = __builtin_amdgcn_rcpf(1.0f + e);
;     const float sp = fp >= 0.f ? rc : e * rc;
;     const float sn = fp >= 0.f ? e * rc : rc;
;     const float lsig = (fp >= 0.f ? 0.f : fp) + __logf(rc);
;     lf = (lb == 0.f) ? lsig : __logf(lb + (1.0f - lb) * sp); key = (1.0f - lb) * sn;
; }
; __device__ __forceinline__ void w_hg_scan(const float (&lbv)[8], const bf16_t* fsrc, int lane, float (&bb)[4][8], float (&r31)[8], float (&r63)[8]) {
;     const int lo = lane & 15;
; #pragma unroll
;     for (int tb = 0; tb < 4; ++tb) { float fp[8]; ld8bf(fsrc + (size_t)(16 * tb + lo) * NIN, fp);
; #pragma unroll
;         for (int j = 0; j < 8; ++j) { float key; hg_lf_key(fp[j], lbv[j], bb[tb][j], key); } }
.LBB0_434:
	s_or_b64 exec, exec, s[34:35]
	v_add_co_u32_e32 v36, vcc, 0x48000, v60
	s_nop 1
	v_addc_co_u32_e32 v37, vcc, 0, v61, vcc
	v_mov_b64_e32 v[36:37], v[194:195]
	v_mov_b64_e32 v[38:39], v[196:197]
	s_waitcnt vmcnt(0) lgkmcnt(0)
	v_lshlrev_b32_e32 v52, 16, v36
	v_mul_f32_e64 v53, |v52|, s26
	v_exp_f32_e32 v83, v53
	v_cmp_le_f32_e32 vcc, 0, v52
	v_add_f32_e32 v53, 1.0, v83
	v_rcp_f32_e32 v53, v53
	s_and_saveexec_b64 s[20:21], s[38:39]
	s_xor_b64 s[34:35], exec, s[20:21]
	s_cbranch_execz .LBB0_436
	v_mul_f32_e32 v52, v83, v53
	v_cndmask_b32_e32 v52, v52, v53, vcc
	v_fma_f32 v52, v77, v52, v56
	v_cmp_gt_f32_e64 s[38:39], s29, v52
	s_nop 1
	v_cndmask_b32_e64 v53, 0, 32, s[38:39]
	v_ldexp_f32 v52, v52, v53
	v_log_f32_e32 v52, v52
	s_nop 0
	v_mul_f32_e32 v53, 0x3f317217, v52
	v_fma_f32 v53, v52, s17, -v53
	v_fmac_f32_e32 v53, 0x3377d1cf, v52
	v_fmac_f32_e32 v53, 0x3f317217, v52
	v_cmp_lt_f32_e64 s[54:55], |v52|, s22
	s_nop 1
	v_cndmask_b32_e64 v52, v52, v53, s[54:55]
	v_cndmask_b32_e64 v53, 0, v203, s[38:39]
	v_sub_f32_e32 v178, v52, v53

; #define LAS __attribute__((address_space(3)))
; __device__ __forceinline__ u32x4 pack8(const float (&v)[8]) { u32x4 w; w.x = pk2(v[0], v[1]); w.y = pk2(v[2], v[3]); w.z = pk2(v[4], v[5]); w.w = pk2(v[6], v[7]); return w; }
; __device__ __forceinline__ void ld8bf(const bf16_t* p, float (&o)[8]) { unpack8(*(const u32x4*)p, o); }
; __device__ __forceinline__ float ret_lg(int h) { return log1pf(-exp2f(-5.0f - (float)h)); }
; __device__ __forceinline__ void w_ret_m1(unsigned char* ws, const bf16_t* proj, LAS unsigned char* wl, int b, int ck_, int h, int lane) {
;     LAS bf16_t* vT = (LAS bf16_t*)wl; LAS bf16_t* kT = (LAS bf16_t*)(wl + TILE_B);
;     const int row0 = b * SEQ + 64 * ck_, lo = lane & 15, fq = lane >> 4; const float lg = ret_lg(h);
;     const float* cosT = (const float*)(ws + WS_ROPE); const float* sinT = cosT + SEQ * 32;
; #pragma unroll
;     for (int i = 0; i < 4; ++i) { const int m = (lane >> 2) + 16 * i, cp = lane & 3; float x1[8], x2[8];
;         const bf16_t* src = proj + (size_t)(row0 + m) * NIN + C_RK + 64 * h; ld8bf(src + 8 * cp, x1); ld8bf(src + 32 + 8 * cp, x2);
;         const float* cp_ = cosT + (64 * ck_ + m) * 32 + 8 * cp; const float* sp_ = sinT + (64 * ck_ + m) * 32 + 8 * cp;
;         const float sc = 0.125f * __expf((float)(63 - m) * lg);
;         float o1[8], o2[8];
; #pragma unroll
;         for (int j = 0; j < 8; ++j) { const float cs = cp_[j], sn = sp_[j]; o1[j] = (x1[j] * cs - x2[j] * sn) * sc; o2[j] = (x2[j] * cs + x1[j] * sn) * sc; }
;         *(LAS u32x4*)(kT + m * LD + 8 * cp) = pack8(o1); *(LAS u32x4*)(kT + m * LD + 32 + 8 * cp) = pack8(o2); }
.LBB0_516:
	s_lshr_b32 s21, s20, 8
	s_lshr_b32 s24, s20, 9
	s_add_i32 s21, s21, s20
	s_and_b32 s24, s24, 12
	s_add_i32 s21, s21, s24
	s_and_b32 s24, s21, 12
	s_cmp_lg_u32 s24, 8
	s_cbranch_scc1 .LBB0_515
	s_and_b32 s34, s21, 11
	s_ashr_i32 s21, s20, 31
	s_ashr_i32 s24, s20, 4
	s_lshr_b32 s21, s21, 25
	s_add_i32 s34, s34, -8
	s_add_i32 s27, s24, s21
	v_cvt_f32_u32_e32 v0, s34
	s_ashr_i32 s21, s27, 7
	s_and_b32 s27, s27, 0xffffff80
	s_sub_i32 s27, s24, s27
	s_lshl_b32 s24, s21, 13
	s_lshl_b32 s38, s27, 6
	s_add_i32 s35, s38, s24
	v_sub_f32_e32 v0, 0xc0a00000, v0
	s_mov_b32 s24, 0xc2fc0000
	v_cmp_gt_f32_e32 vcc, s24, v0
	s_and_b64 s[40:41], vcc, exec
	s_cselect_b32 s24, 0xffffffc0, 0
	v_cndmask_b32_e32 v1, 0, v204, vcc
	v_add_f32_e32 v0, v0, v1
	v_exp_f32_e32 v0, v0
	v_mov_b32_e32 v25, v144
	v_mov_b64_e32 v[22:23], s[8:9]
	v_ldexp_f32 v2, v0, s24
	v_sub_f32_e32 v4, 1.0, v2
	v_add_f32_e32 v0, -1.0, v4
	v_sub_f32_e32 v1, v0, v4
	v_add_f32_e32 v1, 1.0, v1
	v_sub_f32_e64 v0, -v2, v0
	v_add_f32_e32 v5, v0, v1
	v_frexp_mant_f32_e32 v0, v4
	v_cmp_gt_f32_e32 vcc, s77, v0
	v_cvt_f64_f32_e32 v[0:1], v4
	v_frexp_exp_i32_f64_e32 v0, v[0:1]
	v_subbrev_co_u32_e32 v10, vcc, 0, v0, vcc
	v_sub_u32_e32 v0, 0, v10
	v_ldexp_f32 v1, v4, v0
	v_add_f32_e32 v4, -1.0, v1
	v_add_f32_e32 v6, 1.0, v1
	v_ldexp_f32 v0, v5, v0
	v_add_f32_e32 v5, 1.0, v4
	v_add_f32_e32 v7, -1.0, v6
	v_sub_f32_e32 v5, v1, v5
	v_sub_f32_e32 v1, v1, v7
	v_add_f32_e32 v5, v0, v5
	v_add_f32_e32 v0, v0, v1
	v_add_f32_e32 v11, v6, v0
	v_rcp_f32_e32 v13, v11
	v_sub_f32_e32 v1, v11, v6
	v_sub_f32_e32 v12, v0, v1
	v_add_f32_e32 v1, v4, v5
	v_mul_f32_e32 v15, v1, v13
	v_sub_f32_e32 v0, v1, v4
	v_mul_f32_e32 v4, v11, v15
	v_fma_f32 v6, v15, v11, -v4
	v_fmac_f32_e32 v6, v15, v12
	v_sub_f32_e32 v14, v5, v0
	v_add_f32_e32 v0, v4, v6
	v_sub_f32_e32 v5, v1, v0
	v_pk_add_f32 v[8:9], v[0:1], v[4:5] neg_lo:[0,1] neg_hi:[0,1]
	v_mov_b32_e32 v7, v0
	v_pk_add_f32 v[0:1], v[8:9], v[6:7] neg_lo:[0,1] neg_hi:[0,1]
	v_cmp_nlt_f32_e32 vcc, 1.0, v2
	v_add_f32_e32 v1, v14, v1
	v_add_f32_e32 v0, v0, v1
	v_add_f32_e32 v1, v5, v0
	v_mul_f32_e32 v14, v13, v1
	v_mul_f32_e32 v4, v11, v14
	v_fma_f32 v6, v14, v11, -v4
	v_fmac_f32_e32 v6, v14, v12
	v_sub_f32_e32 v5, v5, v1
	v_add_f32_e32 v11, v0, v5
	v_add_f32_e32 v0, v4, v6
	v_sub_f32_e32 v5, v1, v0
	v_pk_add_f32 v[8:9], v[0:1], v[4:5] neg_lo:[0,1] neg_hi:[0,1]
	v_mov_b32_e32 v7, v0
	v_pk_add_f32 v[0:1], v[8:9], v[6:7] neg_lo:[0,1] neg_hi:[0,1]
	v_ashrrev_i32_e32 v36, 2, v25
	v_add_f32_e32 v1, v11, v1
	v_add_f32_e32 v0, v0, v1
	v_add_f32_e32 v1, v15, v14
	v_add_f32_e32 v0, v5, v0
	v_sub_f32_e32 v4, v1, v15
	v_mul_f32_e32 v0, v13, v0
	v_sub_f32_e32 v4, v14, v4
	v_add_f32_e32 v4, v4, v0
	v_add_f32_e32 v6, v1, v4
	v_mul_f32_e32 v7, v6, v6
	v_fmamk_f32 v0, v7, 0x3e9b6dac, v201
	v_fmaak_f32 v169, v7, v0, 0x3f2aaada
	v_cvt_f32_i32_e32 v0, v10
	v_sub_f32_e32 v1, v6, v1
	v_sub_f32_e32 v1, v4, v1
	v_ldexp_f32 v8, v1, 1
	v_mul_f32_e32 v1, v6, v7
	v_ldexp_f32 v5, v6, 1
	v_pk_mul_f32 v[6:7], v[0:1], v[168:169]
	s_lshl_b32 s24, s34, 7
	v_fma_f32 v4, v0, s94, -v6
	v_fmac_f32_e32 v4, 0xb102e308, v0
	v_pk_add_f32 v[0:1], v[6:7], v[4:5]
	s_nop 0
	v_sub_f32_e32 v5, v1, v5
	v_sub_f32_e32 v5, v7, v5
	v_add_f32_e32 v9, v8, v5
	v_mov_b32_e32 v8, v6
	v_pk_add_f32 v[6:7], v[0:1], v[6:7] neg_lo:[0,1] neg_hi:[0,1]
	v_pk_add_f32 v[10:11], v[0:1], v[8:9]
	v_mov_b32_e32 v5, v0
	v_mov_b32_e32 v7, v11
	v_pk_add_f32 v[12:13], v[4:5], v[6:7] neg_lo:[0,1] neg_hi:[0,1]
	v_pk_add_f32 v[4:5], v[4:5], v[6:7]
	v_mov_b32_e32 v16, v1
	v_pk_add_f32 v[6:7], v[4:5], v[0:1] op_sel:[1,0] op_sel_hi:[0,1] neg_lo:[0,1] neg_hi:[0,1]
	v_pk_add_f32 v[14:15], v[10:11], v[6:7] op_sel_hi:[1,0] neg_lo:[0,1] neg_hi:[0,1]
	v_mov_b32_e32 v10, v11
	v_mov_b32_e32 v11, v5
	v_mov_b32_e32 v17, v6
	v_pk_add_f32 v[6:7], v[10:11], v[16:17] neg_lo:[0,1] neg_hi:[0,1]
	v_mov_b32_e32 v8, v9
	v_mov_b32_e32 v9, v0
	v_pk_add_f32 v[0:1], v[8:9], v[6:7] neg_lo:[0,1] neg_hi:[0,1]
	v_mov_b32_e32 v14, v12
	v_pk_add_f32 v[6:7], v[14:15], v[0:1]
	v_mov_b32_e32 v13, v5
	v_pk_add_f32 v[8:9], v[6:7], v[6:7] op_sel:[0,1] op_sel_hi:[1,0]
	s_nop 0
	v_pk_add_f32 v[4:5], v[4:5], v[8:9] op_sel:[1,0] op_sel_hi:[0,1]
	v_mov_b32_e32 v7, v4
	v_pk_add_f32 v[10:11], v[6:7], v[12:13] neg_lo:[0,1] neg_hi:[0,1]
	v_mov_b32_e32 v1, v8
	v_sub_f32_e32 v5, v6, v10
	v_pk_add_f32 v[0:1], v[0:1], v[10:11] neg_lo:[0,1] neg_hi:[0,1]
	v_sub_f32_e32 v5, v12, v5
	v_add_f32_e32 v0, v0, v5
	v_add_f32_e32 v0, v0, v1
	v_add_f32_e32 v0, v4, v0
	v_cndmask_b32_e32 v0, v205, v0, vcc
	v_cmp_neq_f32_e32 vcc, 1.0, v2
	v_add_lshl_u32 v12, v36, s38, 5
	v_ashrrev_i32_e32 v13, 31, v12
	v_cndmask_b32_e32 v0, v206, v0, vcc
	v_cmp_gt_f32_e32 vcc, s95, v2
	v_lshlrev_b64 v[12:13], 2, v[12:13]
	s_nop 0
	v_cndmask_b32_e64 v35, v0, -v2, vcc
	v_lshlrev_b32_e32 v0, 3, v25
	v_and_b32_e32 v34, 24, v0
	v_lshlrev_b32_e32 v2, 2, v34
	v_lshl_add_u64 v[0:1], s[4:5], 0, v[2:3]
	v_lshl_add_u64 v[20:21], s[82:83], 0, v[2:3]
	v_lshl_add_u64 v[18:19], v[0:1], 0, v[12:13]
	v_lshl_add_u64 v[16:17], v[20:21], 0, v[12:13]
	v_sub_u32_e32 v12, 63, v36
	v_cvt_f32_i32_e32 v12, v12
	v_add_u32_e32 v2, s35, v36
	v_mad_i64_i32 v[4:5], s[40:41], v2, s72, v[22:23]
	v_mul_f32_e32 v12, v35, v12
	v_mul_f32_e32 v12, 0x3fb8aa3b, v12
	v_exp_f32_e32 v12, v12
	v_lshl_add_u64 v[4:5], v[4:5], 0, s[24:25]
	v_lshlrev_b32_e32 v2, 1, v34
	v_lshl_add_u64 v[4:5], v[4:5], 0, v[2:3]
	global_load_dwordx4 v[8:11], v[4:5], off offset:2560
	s_nop 0
	global_load_dwordx4 v[4:7], v[4:5], off offset:2624
	v_mul_f32_e32 v24, 0x3e000000, v12
	global_load_dwordx4 v[12:15], v[18:19], off
	global_load_dwordx4 v[28:31], v[16:17], off
	global_load_dwordx4 v[178:181], v[18:19], off offset:16
	global_load_dwordx4 v[182:185], v[16:17], off offset:16
	s_waitcnt vmcnt(0) lgkmcnt(0)
; #define LAS __attribute__((address_space(3)))
; __device__ __forceinline__ u32x4 pack8(const float (&v)[8]) { u32x4 w; w.x = pk2(v[0], v[1]); w.y = pk2(v[2], v[3]); w.z = pk2(v[4], v[5]); w.w = pk2(v[6], v[7]); return w; }
; __device__ __forceinline__ void ld8bf(const bf16_t* p, float (&o)[8]) { unpack8(*(const u32x4*)p, o); }
; __device__ __forceinline__ void w_ret_m1(unsigned char* ws, const bf16_t* proj, LAS unsigned char* wl, int b, int ck_, int h, int lane) {
;     ...
;     for (int i = 0; i < 4; ++i) { const int m = (lane >> 2) + 16 * i, cp = lane & 3; float x1[8], x2[8];
;         const bf16_t* src = proj + (size_t)(row0 + m) * NIN + C_RK + 64 * h; ld8bf(src + 8 * cp, x1); ld8bf(src + 32 + 8 * cp, x2);
;         const float* cp_ = cosT + (64 * ck_ + m) * 32 + 8 * cp; const float* sp_ = sinT + (64 * ck_ + m) * 32 + 8 * cp;
;         const float sc = 0.125f * __expf((float)(63 - m) * lg);
;         float o1[8], o2[8];
; #pragma unroll
;         for (int j = 0; j < 8; ++j) { const float cs = cp_[j], sn = sp_[j]; o1[j] = (x1[j] * cs - x2[j] * sn) * sc; o2[j] = (x2[j] * cs + x1[j] * sn) * sc; }
;         *(LAS u32x4*)(kT + m * LD + 8 * cp) = pack8(o1); *(LAS u32x4*)(kT + m * LD + 32 + 8 * cp) = pack8(o2); }
	v_lshlrev_b32_e32 v32, 16, v8
	v_and_b32_e32 v33, 0xffff0000, v8
	v_lshlrev_b32_e32 v38, 16, v4
	v_and_b32_e32 v39, 0xffff0000, v4
	v_pk_mul_f32 v[26:27], v[28:29], v[32:33]
	v_pk_mul_f32 v[28:29], v[28:29], v[38:39]
	v_pk_fma_f32 v[26:27], v[12:13], v[38:39], v[26:27]
	v_pk_fma_f32 v[12:13], v[12:13], v[32:33], v[28:29] neg_lo:[0,0,1] neg_hi:[0,0,1]
	v_lshlrev_b32_e32 v8, 16, v9
	v_and_b32_e32 v9, 0xffff0000, v9
	v_pk_mul_f32 v[28:29], v[24:25], v[12:13] op_sel_hi:[0,1]
	v_lshlrev_b32_e32 v12, 16, v5
	v_and_b32_e32 v13, 0xffff0000, v5
	v_pk_mul_f32 v[4:5], v[30:31], v[8:9]
	v_lshlrev_b32_e32 v32, 16, v6
	v_pk_fma_f32 v[4:5], v[14:15], v[12:13], v[4:5]
	v_pk_mul_f32 v[12:13], v[30:31], v[12:13]
	v_lshlrev_b32_e32 v30, 16, v10
	v_pk_fma_f32 v[8:9], v[14:15], v[8:9], v[12:13] neg_lo:[0,0,1] neg_hi:[0,0,1]
	v_mov_b64_e32 v[12:13], v[178:179]
	v_mov_b64_e32 v[14:15], v[180:181]
	s_nop 0
	v_mov_b64_e32 v[16:17], v[182:183]
	v_mov_b64_e32 v[18:19], v[184:185]
	v_and_b32_e32 v31, 0xffff0000, v10
	v_and_b32_e32 v33, 0xffff0000, v6
	v_lshlrev_b32_e32 v10, 16, v11
	v_and_b32_e32 v11, 0xffff0000, v11
	v_lshlrev_b32_e32 v6, 16, v7
	v_and_b32_e32 v7, 0xffff0000, v7
	v_pk_mul_f32 v[8:9], v[24:25], v[8:9] op_sel_hi:[0,1]
	v_pk_mul_f32 v[4:5], v[24:25], v[4:5] op_sel_hi:[0,1]
	v_pk_mul_f32 v[26:27], v[24:25], v[26:27] op_sel_hi:[0,1]
	s_waitcnt vmcnt(0) lgkmcnt(0)
	v_pk_mul_f32 v[38:39], v[16:17], v[30:31]
	v_pk_mul_f32 v[16:17], v[16:17], v[32:33]
	v_pk_fma_f32 v[38:39], v[12:13], v[32:33], v[38:39]
	v_pk_fma_f32 v[12:13], v[12:13], v[30:31], v[16:17] neg_lo:[0,0,1] neg_hi:[0,0,1]
	v_pk_mul_f32 v[16:17], v[18:19], v[10:11]
	v_pk_mul_f32 v[12:13], v[24:25], v[12:13] op_sel_hi:[0,1]
	v_pk_fma_f32 v[16:17], v[14:15], v[6:7], v[16:17]
	v_pk_mul_f32 v[6:7], v[18:19], v[6:7]
	v_pk_mul_f32 v[38:39], v[24:25], v[38:39] op_sel_hi:[0,1]
	v_pk_fma_f32 v[6:7], v[14:15], v[10:11], v[6:7] neg_lo:[0,0,1] neg_hi:[0,0,1]
	v_pk_mul_f32 v[16:17], v[24:25], v[16:17] op_sel_hi:[0,1]
	v_pk_mul_f32 v[10:11], v[24:25], v[6:7] op_sel_hi:[0,1]
	v_cvt_pk_bf16_f32 v7, v8, v9
	v_cvt_pk_bf16_f32 v9, v10, v11
	v_mul_lo_u32 v10, v36, s23
	v_cvt_pk_bf16_f32 v6, v28, v29
	v_cvt_pk_bf16_f32 v8, v12, v13
	v_add3_u32 v18, s6, v10, v2
	v_add_u32_e32 v12, 16, v36
	ds_write_b128 v18, v[6:9] offset:9216
	v_cvt_pk_bf16_f32 v7, v4, v5
	v_add_u32_e32 v4, s35, v12
	v_mad_i64_i32 v[4:5], s[40:41], v4, s72, v[22:23]
	v_add_lshl_u32 v12, v12, s38, 5
	v_cvt_pk_bf16_f32 v6, v26, v27
	v_cvt_pk_bf16_f32 v8, v38, v39
	v_cvt_pk_bf16_f32 v9, v16, v17
	v_lshl_add_u64 v[4:5], v[4:5], 0, s[24:25]
	v_ashrrev_i32_e32 v13, 31, v12
	ds_write_b128 v18, v[6:9] offset:9280
	v_lshl_add_u64 v[4:5], v[4:5], 0, v[2:3]
	v_lshlrev_b64 v[12:13], 2, v[12:13]
	global_load_dwordx4 v[8:11], v[4:5], off offset:2560
	s_nop 0
	global_load_dwordx4 v[4:7], v[4:5], off offset:2624
	v_lshl_add_u64 v[38:39], v[0:1], 0, v[12:13]
	v_lshl_add_u64 v[40:41], v[20:21], 0, v[12:13]
	global_load_dwordx4 v[26:29], v[38:39], off
	global_load_dwordx4 v[30:33], v[40:41], off
	global_load_dwordx4 v[178:181], v[38:39], off offset:16
	global_load_dwordx4 v[182:185], v[40:41], off offset:16
	v_sub_u32_e32 v12, 47, v36
	v_cvt_f32_i32_e32 v12, v12
	v_mul_f32_e32 v12, v35, v12
	v_mul_f32_e32 v12, 0x3fb8aa3b, v12
	v_exp_f32_e32 v12, v12
	s_waitcnt vmcnt(0) lgkmcnt(0)
	v_lshlrev_b32_e32 v16, 16, v8
	v_and_b32_e32 v17, 0xffff0000, v8
	v_lshlrev_b32_e32 v42, 16, v4
	v_and_b32_e32 v43, 0xffff0000, v4
	v_pk_mul_f32 v[14:15], v[30:31], v[16:17]
	v_pk_mul_f32 v[30:31], v[30:31], v[42:43]
	v_lshlrev_b32_e32 v8, 16, v9
	v_and_b32_e32 v9, 0xffff0000, v9
	v_pk_fma_f32 v[14:15], v[26:27], v[42:43], v[14:15]
	v_pk_fma_f32 v[16:17], v[26:27], v[16:17], v[30:31] neg_lo:[0,0,1] neg_hi:[0,0,1]
	v_lshlrev_b32_e32 v26, 16, v5
	v_and_b32_e32 v27, 0xffff0000, v5
	v_pk_mul_f32 v[4:5], v[32:33], v[8:9]
	v_lshlrev_b32_e32 v42, 16, v10
	v_pk_fma_f32 v[4:5], v[28:29], v[26:27], v[4:5]
	v_pk_mul_f32 v[26:27], v[32:33], v[26:27]
	v_and_b32_e32 v43, 0xffff0000, v10
	v_pk_fma_f32 v[8:9], v[28:29], v[8:9], v[26:27] neg_lo:[0,0,1] neg_hi:[0,0,1]
	v_mov_b64_e32 v[26:27], v[178:179]
	v_mov_b64_e32 v[28:29], v[180:181]
	v_mov_b64_e32 v[30:31], v[182:183]
	v_mov_b64_e32 v[32:33], v[184:185]
	v_lshlrev_b32_e32 v44, 16, v6
	v_and_b32_e32 v45, 0xffff0000, v6
	v_lshlrev_b32_e32 v10, 16, v11
	v_and_b32_e32 v11, 0xffff0000, v11
	v_lshlrev_b32_e32 v6, 16, v7
	v_and_b32_e32 v7, 0xffff0000, v7
	v_mul_f32_e32 v12, 0x3e000000, v12
	v_pk_mul_f32 v[16:17], v[12:13], v[16:17] op_sel_hi:[0,1]
	v_pk_mul_f32 v[8:9], v[12:13], v[8:9] op_sel_hi:[0,1]
	v_pk_mul_f32 v[14:15], v[12:13], v[14:15] op_sel_hi:[0,1]
	v_pk_mul_f32 v[4:5], v[12:13], v[4:5] op_sel_hi:[0,1]
	s_waitcnt vmcnt(0) lgkmcnt(0)
; #define LAS __attribute__((address_space(3)))
; __device__ __forceinline__ u32x4 pack8(const float (&v)[8]) { u32x4 w; w.x = pk2(v[0], v[1]); w.y = pk2(v[2], v[3]); w.z = pk2(v[4], v[5]); w.w = pk2(v[6], v[7]); return w; }
; __device__ __forceinline__ void ld8bf(const bf16_t* p, float (&o)[8]) { unpack8(*(const u32x4*)p, o); }
; __device__ __forceinline__ void w_ret_m1(unsigned char* ws, const bf16_t* proj, LAS unsigned char* wl, int b, int ck_, int h, int lane) {
;     ...
;     for (int i = 0; i < 4; ++i) { const int m = (lane >> 2) + 16 * i, cp = lane & 3; float x1[8], x2[8];
;         const bf16_t* src = proj + (size_t)(row0 + m) * NIN + C_RK + 64 * h; ld8bf(src + 8 * cp, x1); ld8bf(src + 32 + 8 * cp, x2);
;         const float* cp_ = cosT + (64 * ck_ + m) * 32 + 8 * cp; const float* sp_ = sinT + (64 * ck_ + m) * 32 + 8 * cp;
;         const float sc = 0.125f * __expf((float)(63 - m) * lg);
;         float o1[8], o2[8];
; #pragma unroll
;         for (int j = 0; j < 8; ++j) { const float cs = cp_[j], sn = sp_[j]; o1[j] = (x1[j] * cs - x2[j] * sn) * sc; o2[j] = (x2[j] * cs + x1[j] * sn) * sc; }
;         *(LAS u32x4*)(kT + m * LD + 8 * cp) = pack8(o1); *(LAS u32x4*)(kT + m * LD + 32 + 8 * cp) = pack8(o2); }
	v_pk_mul_f32 v[38:39], v[30:31], v[42:43]
	v_pk_mul_f32 v[30:31], v[30:31], v[44:45]
	v_pk_fma_f32 v[38:39], v[26:27], v[44:45], v[38:39]
	v_pk_fma_f32 v[26:27], v[26:27], v[42:43], v[30:31] neg_lo:[0,0,1] neg_hi:[0,0,1]
	v_pk_mul_f32 v[30:31], v[32:33], v[10:11]
	v_pk_mul_f32 v[26:27], v[12:13], v[26:27] op_sel_hi:[0,1]
	v_pk_fma_f32 v[30:31], v[28:29], v[6:7], v[30:31]
	v_pk_mul_f32 v[6:7], v[32:33], v[6:7]
	v_pk_mul_f32 v[38:39], v[12:13], v[38:39] op_sel_hi:[0,1]
	v_pk_fma_f32 v[6:7], v[28:29], v[10:11], v[6:7] neg_lo:[0,0,1] neg_hi:[0,0,1]
	v_pk_mul_f32 v[30:31], v[12:13], v[30:31] op_sel_hi:[0,1]
	v_pk_mul_f32 v[10:11], v[12:13], v[6:7] op_sel_hi:[0,1]
	v_cvt_pk_bf16_f32 v6, v16, v17
	v_cvt_pk_bf16_f32 v7, v8, v9
	v_cvt_pk_bf16_f32 v8, v26, v27
	v_cvt_pk_bf16_f32 v9, v10, v11
	v_add_u32_e32 v12, 32, v36
	ds_write_b128 v18, v[6:9] offset:11520
	v_cvt_pk_bf16_f32 v7, v4, v5
	v_add_u32_e32 v4, s35, v12
	v_mad_i64_i32 v[4:5], s[40:41], v4, s72, v[22:23]
	v_add_lshl_u32 v12, v12, s38, 5
	v_cvt_pk_bf16_f32 v6, v14, v15
	v_cvt_pk_bf16_f32 v8, v38, v39
	v_cvt_pk_bf16_f32 v9, v30, v31
	v_lshl_add_u64 v[4:5], v[4:5], 0, s[24:25]
	v_ashrrev_i32_e32 v13, 31, v12
	ds_write_b128 v18, v[6:9] offset:11584
	v_lshl_add_u64 v[4:5], v[4:5], 0, v[2:3]
	v_lshlrev_b64 v[12:13], 2, v[12:13]
	global_load_dwordx4 v[8:11], v[4:5], off offset:2560
	s_nop 0
	global_load_dwordx4 v[4:7], v[4:5], off offset:2624
	v_lshl_add_u64 v[38:39], v[0:1], 0, v[12:13]
	v_lshl_add_u64 v[40:41], v[20:21], 0, v[12:13]
	global_load_dwordx4 v[26:29], v[38:39], off
	global_load_dwordx4 v[30:33], v[40:41], off
	global_load_dwordx4 v[178:181], v[38:39], off offset:16
	global_load_dwordx4 v[182:185], v[40:41], off offset:16
	v_sub_u32_e32 v12, 31, v36
	v_cvt_f32_i32_e32 v12, v12
	v_mul_f32_e32 v12, v35, v12
	v_mul_f32_e32 v12, 0x3fb8aa3b, v12
	v_exp_f32_e32 v12, v12
	s_waitcnt vmcnt(0) lgkmcnt(0)
	v_lshlrev_b32_e32 v16, 16, v8
	v_and_b32_e32 v17, 0xffff0000, v8
	v_lshlrev_b32_e32 v42, 16, v4
	v_and_b32_e32 v43, 0xffff0000, v4
	v_pk_mul_f32 v[14:15], v[30:31], v[16:17]
	v_pk_mul_f32 v[30:31], v[30:31], v[42:43]
	v_lshlrev_b32_e32 v8, 16, v9
	v_and_b32_e32 v9, 0xffff0000, v9
	v_pk_fma_f32 v[14:15], v[26:27], v[42:43], v[14:15]
	v_pk_fma_f32 v[16:17], v[26:27], v[16:17], v[30:31] neg_lo:[0,0,1] neg_hi:[0,0,1]
	v_lshlrev_b32_e32 v26, 16, v5
	v_and_b32_e32 v27, 0xffff0000, v5
	v_pk_mul_f32 v[4:5], v[32:33], v[8:9]
	v_lshlrev_b32_e32 v42, 16, v10
	v_pk_fma_f32 v[4:5], v[28:29], v[26:27], v[4:5]
	v_pk_mul_f32 v[26:27], v[32:33], v[26:27]
	v_and_b32_e32 v43, 0xffff0000, v10
	v_pk_fma_f32 v[8:9], v[28:29], v[8:9], v[26:27] neg_lo:[0,0,1] neg_hi:[0,0,1]
	v_mov_b64_e32 v[26:27], v[178:179]
	v_mov_b64_e32 v[28:29], v[180:181]
	v_mov_b64_e32 v[30:31], v[182:183]
	v_mov_b64_e32 v[32:33], v[184:185]
	v_lshlrev_b32_e32 v44, 16, v6
	v_and_b32_e32 v45, 0xffff0000, v6
	v_lshlrev_b32_e32 v10, 16, v11
	v_and_b32_e32 v11, 0xffff0000, v11
	v_lshlrev_b32_e32 v6, 16, v7
	v_and_b32_e32 v7, 0xffff0000, v7
	v_mul_f32_e32 v12, 0x3e000000, v12
	v_pk_mul_f32 v[16:17], v[12:13], v[16:17] op_sel_hi:[0,1]
	v_pk_mul_f32 v[8:9], v[12:13], v[8:9] op_sel_hi:[0,1]
	v_pk_mul_f32 v[14:15], v[12:13], v[14:15] op_sel_hi:[0,1]
	v_pk_mul_f32 v[4:5], v[12:13], v[4:5] op_sel_hi:[0,1]
	s_waitcnt vmcnt(0) lgkmcnt(0)
	v_pk_mul_f32 v[38:39], v[30:31], v[42:43]
	v_pk_mul_f32 v[30:31], v[30:31], v[44:45]
	v_pk_fma_f32 v[38:39], v[26:27], v[44:45], v[38:39]
	v_pk_fma_f32 v[26:27], v[26:27], v[42:43], v[30:31] neg_lo:[0,0,1] neg_hi:[0,0,1]
	v_pk_mul_f32 v[30:31], v[32:33], v[10:11]
	v_pk_mul_f32 v[26:27], v[12:13], v[26:27] op_sel_hi:[0,1]
	v_pk_fma_f32 v[30:31], v[28:29], v[6:7], v[30:31]
	v_pk_mul_f32 v[6:7], v[32:33], v[6:7]
	v_pk_mul_f32 v[38:39], v[12:13], v[38:39] op_sel_hi:[0,1]
	v_pk_fma_f32 v[6:7], v[28:29], v[10:11], v[6:7] neg_lo:[0,0,1] neg_hi:[0,0,1]
	v_pk_mul_f32 v[30:31], v[12:13], v[30:31] op_sel_hi:[0,1]
	v_pk_mul_f32 v[10:11], v[12:13], v[6:7] op_sel_hi:[0,1]
	v_cvt_pk_bf16_f32 v6, v16, v17
	v_cvt_pk_bf16_f32 v7, v8, v9
	v_cvt_pk_bf16_f32 v8, v26, v27
	v_cvt_pk_bf16_f32 v9, v10, v11
	v_add_u32_e32 v12, 48, v36
	ds_write_b128 v18, v[6:9] offset:13824
	v_cvt_pk_bf16_f32 v7, v4, v5
	v_add_u32_e32 v4, s35, v12
	v_mad_i64_i32 v[4:5], s[40:41], v4, s72, v[22:23]
	v_add_lshl_u32 v12, v12, s38, 5
	v_cvt_pk_bf16_f32 v6, v14, v15
	v_cvt_pk_bf16_f32 v8, v38, v39
	v_cvt_pk_bf16_f32 v9, v30, v31
	v_lshl_add_u64 v[4:5], v[4:5], 0, s[24:25]
	v_ashrrev_i32_e32 v13, 31, v12
	ds_write_b128 v18, v[6:9] offset:13888
	v_lshl_add_u64 v[4:5], v[4:5], 0, v[2:3]
	v_lshlrev_b64 v[12:13], 2, v[12:13]
	global_load_dwordx4 v[8:11], v[4:5], off offset:2560
	s_nop 0
	global_load_dwordx4 v[4:7], v[4:5], off offset:2624
	v_lshl_add_u64 v[26:27], v[0:1], 0, v[12:13]
	v_lshl_add_u64 v[28:29], v[20:21], 0, v[12:13]
	global_load_dwordx4 v[14:17], v[26:27], off
	global_load_dwordx4 v[20:23], v[28:29], off
	global_load_dwordx4 v[178:181], v[26:27], off offset:16
	global_load_dwordx4 v[182:185], v[28:29], off offset:16
	v_sub_u32_e32 v0, 15, v36
	v_cvt_f32_i32_e32 v0, v0
	s_mul_hi_i32 s38, s35, 0x1800
	s_mulk_i32 s35, 0x1800
	s_add_u32 s35, s8, s35
	v_mul_f32_e32 v0, v35, v0
	v_mul_f32_e32 v0, 0x3fb8aa3b, v0
	v_exp_f32_e32 v0, v0
	s_addc_u32 s39, s9, s38
	s_add_u32 s38, s35, s24
	s_addc_u32 s39, s39, 0
	v_mul_f32_e32 v0, 0x3e000000, v0
	s_lshl_b32 s21, s21, 9
	s_lshl_b32 s24, s27, 2
	s_add_i32 s24, s24, s21
	s_or_b32 s34, s34, s24
	s_ashr_i32 s35, s34, 31
	s_lshl_b64 s[34:35], s[34:35], 13
	s_add_u32 s34, s67, s34
	s_addc_u32 s35, s28, s35
	s_waitcnt vmcnt(0) lgkmcnt(0)
; #define LAS __attribute__((address_space(3)))
; __device__ __forceinline__ void ld8bf(const bf16_t* p, float (&o)[8]) { unpack8(*(const u32x4*)p, o); }
; __device__ __forceinline__ void w_store_vT(LAS bf16_t* vN, const bf16_t* src, int lane) {
; #pragma unroll
;     for (int i = 0; i < 8; ++i) { const int m = (lane >> 3) + 8 * i, e0 = 8 * (lane & 7); *(LAS u32x4*)(vN + m * LD + e0) = *(const u32x4*)(src + (size_t)m * NIN + e0); }
; }
; __device__ __forceinline__ void w_kv(const LAS bf16_t* vN, const LAS bf16_t* kN, bf16_t* S, int lo, int fq) {
; #pragma unroll
;     for (int db = 0; db < 4; ++db) {
;         bf16x8 kf[2];
; #pragma unroll
;         for (int kk = 0; kk < 2; ++kk) kf[kk] = tr_frag(kN, 32 * kk + 8 * fq, 32 * kk + 8 * fq + 4, 16 * db, lo);
; #pragma unroll
;         for (int eb = 0; eb < 4; ++eb) { f32x4 acc = {0.f, 0.f, 0.f, 0.f};
; #pragma unroll
;             for (int kk = 0; kk < 2; ++kk) { const bf16x8 vf = tr_frag(vN, 32 * kk + 8 * fq, 32 * kk + 8 * fq + 4, 16 * eb, lo); acc = __builtin_amdgcn_mfma_f32_16x16x32_bf16(kf[kk], vf, acc, 0, 0, 0); }
;             *(unsigned long long*)(S + (16 * eb + lo) * 64 + 16 * db + 4 * fq) = (unsigned long long)pk2(acc[0], acc[1]) | ((unsigned long long)pk2(acc[2], acc[3]) << 32); }
; __device__ __forceinline__ void w_ret_m1(unsigned char* ws, const bf16_t* proj, LAS unsigned char* wl, int b, int ck_, int h, int lane) {
;     ...
;     for (int i = 0; i < 4; ++i) { const int m = (lane >> 2) + 16 * i, cp = lane & 3; float x1[8], x2[8];
;         const bf16_t* src = proj + (size_t)(row0 + m) * NIN + C_RK + 64 * h; ld8bf(src + 8 * cp, x1); ld8bf(src + 32 + 8 * cp, x2);
;         const float* cp_ = cosT + (64 * ck_ + m) * 32 + 8 * cp; const float* sp_ = sinT + (64 * ck_ + m) * 32 + 8 * cp;
;         const float sc = 0.125f * __expf((float)(63 - m) * lg);
;         float o1[8], o2[8];
; #pragma unroll
;         for (int j = 0; j < 8; ++j) { const float cs = cp_[j], sn = sp_[j]; o1[j] = (x1[j] * cs - x2[j] * sn) * sc; o2[j] = (x2[j] * cs + x1[j] * sn) * sc; }
;         *(LAS u32x4*)(kT + m * LD + 8 * cp) = pack8(o1); *(LAS u32x4*)(kT + m * LD + 32 + 8 * cp) = pack8(o2); }
;     w_store_vT(vT, proj + (size_t)row0 * NIN + C_RV + 64 * h, lane);
;     WAVE_LDS_FENCE();
;     w_kv(vT, kT, (bf16_t*)(ws + WS_SRET) + (size_t)((b * NCH + ck_) * 4 + h) * 4096, lo, fq);
	v_lshlrev_b32_e32 v30, 16, v8
	v_and_b32_e32 v31, 0xffff0000, v8
	v_lshlrev_b32_e32 v32, 16, v4
	v_and_b32_e32 v33, 0xffff0000, v4
	v_pk_mul_f32 v[12:13], v[20:21], v[30:31]
	v_pk_mul_f32 v[20:21], v[20:21], v[32:33]
	v_lshlrev_b32_e32 v8, 16, v9
	v_and_b32_e32 v9, 0xffff0000, v9
	v_pk_fma_f32 v[12:13], v[14:15], v[32:33], v[12:13]
	v_pk_fma_f32 v[14:15], v[14:15], v[30:31], v[20:21] neg_lo:[0,0,1] neg_hi:[0,0,1]
	v_lshlrev_b32_e32 v20, 16, v5
	v_and_b32_e32 v21, 0xffff0000, v5
	v_pk_mul_f32 v[4:5], v[22:23], v[8:9]
	v_lshlrev_b32_e32 v30, 16, v6
	v_pk_fma_f32 v[4:5], v[16:17], v[20:21], v[4:5]
	v_pk_mul_f32 v[20:21], v[22:23], v[20:21]
	v_and_b32_e32 v31, 0xffff0000, v6
	v_pk_fma_f32 v[8:9], v[16:17], v[8:9], v[20:21] neg_lo:[0,0,1] neg_hi:[0,0,1]
	v_mov_b64_e32 v[20:21], v[178:179]
	v_mov_b64_e32 v[22:23], v[180:181]
	s_nop 0
	v_mov_b64_e32 v[26:27], v[182:183]
	v_mov_b64_e32 v[28:29], v[184:185]
	v_lshlrev_b32_e32 v16, 16, v10
	v_and_b32_e32 v17, 0xffff0000, v10
	v_lshlrev_b32_e32 v10, 16, v11
	v_and_b32_e32 v11, 0xffff0000, v11
	v_lshlrev_b32_e32 v6, 16, v7
	v_and_b32_e32 v7, 0xffff0000, v7
	v_pk_mul_f32 v[12:13], v[0:1], v[12:13] op_sel_hi:[0,1]
	v_pk_mul_f32 v[14:15], v[0:1], v[14:15] op_sel_hi:[0,1]
	v_pk_mul_f32 v[4:5], v[0:1], v[4:5] op_sel_hi:[0,1]
	v_pk_mul_f32 v[8:9], v[0:1], v[8:9] op_sel_hi:[0,1]
	s_waitcnt vmcnt(0) lgkmcnt(0)
	v_pk_mul_f32 v[32:33], v[26:27], v[16:17]
	v_pk_mul_f32 v[26:27], v[26:27], v[30:31]
	v_pk_fma_f32 v[32:33], v[20:21], v[30:31], v[32:33]
	v_pk_fma_f32 v[16:17], v[20:21], v[16:17], v[26:27] neg_lo:[0,0,1] neg_hi:[0,0,1]
	v_pk_mul_f32 v[20:21], v[28:29], v[10:11]
	v_pk_mul_f32 v[32:33], v[0:1], v[32:33] op_sel_hi:[0,1]
	v_pk_fma_f32 v[20:21], v[22:23], v[6:7], v[20:21]
	v_pk_mul_f32 v[6:7], v[28:29], v[6:7]
	v_pk_mul_f32 v[16:17], v[0:1], v[16:17] op_sel_hi:[0,1]
	v_pk_fma_f32 v[6:7], v[22:23], v[10:11], v[6:7] neg_lo:[0,0,1] neg_hi:[0,0,1]
	v_pk_mul_f32 v[20:21], v[0:1], v[20:21] op_sel_hi:[0,1]
	v_pk_mul_f32 v[0:1], v[0:1], v[6:7] op_sel_hi:[0,1]
	v_cvt_pk_bf16_f32 v6, v14, v15
	v_cvt_pk_bf16_f32 v7, v8, v9
	v_cvt_pk_bf16_f32 v8, v16, v17
	v_cvt_pk_bf16_f32 v9, v0, v1
	v_lshlrev_b32_e32 v0, 4, v25
	ds_write_b128 v18, v[6:9] offset:16128
	v_cvt_pk_bf16_f32 v6, v12, v13
	v_cvt_pk_bf16_f32 v7, v4, v5
	v_cvt_pk_bf16_f32 v8, v32, v33
	v_cvt_pk_bf16_f32 v9, v20, v21
	v_and_b32_e32 v2, 0x70, v0
	ds_write_b128 v18, v[6:9] offset:16192
	v_ashrrev_i32_e32 v9, 3, v25
	v_lshl_add_u64 v[0:1], s[38:39], 0, v[2:3]
	v_mad_i64_i32 v[4:5], s[38:39], v9, s72, v[0:1]
	global_load_dwordx4 v[224:227], v[4:5], off offset:3072
	v_add_u32_e32 v4, 8, v9
	v_mad_i64_i32 v[4:5], s[38:39], v4, s72, v[0:1]
	global_load_dwordx4 v[228:231], v[4:5], off offset:3072
	v_add_u32_e32 v4, 16, v9
	v_mad_i64_i32 v[4:5], s[38:39], v4, s72, v[0:1]
	global_load_dwordx4 v[232:235], v[4:5], off offset:3072
	v_add_u32_e32 v4, 24, v9
	v_mad_i64_i32 v[4:5], s[38:39], v4, s72, v[0:1]
	global_load_dwordx4 v[236:239], v[4:5], off offset:3072
	v_add_u32_e32 v4, 32, v9
	v_mad_i64_i32 v[4:5], s[38:39], v4, s72, v[0:1]
	global_load_dwordx4 v[240:243], v[4:5], off offset:3072
	v_add_u32_e32 v4, 40, v9
	v_mad_i64_i32 v[4:5], s[38:39], v4, s72, v[0:1]
	global_load_dwordx4 v[244:247], v[4:5], off offset:3072
	v_add_u32_e32 v4, 48, v9
	v_mad_i64_i32 v[4:5], s[38:39], v4, s72, v[0:1]
	global_load_dwordx4 v[248:251], v[4:5], off offset:3072
	v_add_u32_e32 v4, 56, v9
	v_mad_i64_i32 v[0:1], s[38:39], v4, s72, v[0:1]
	global_load_dwordx4 v[186:189], v[0:1], off offset:3072
	v_mul_lo_u32 v10, v9, s23
	v_add3_u32 v2, s6, v2, v10
	v_ashrrev_i32_e32 v8, 4, v25
	v_and_b32_e32 v17, 15, v25
	v_lshlrev_b32_e32 v0, 2, v8
	v_ashrrev_i32_e32 v1, 31, v0
	v_lshl_add_u64 v[0:1], v[0:1], 1, s[34:35]
	v_lshl_add_u64 v[26:27], v[0:1], 0, 32
	s_mov_b64 s[34:35], 0x60
	s_waitcnt vmcnt(0) lgkmcnt(0)
	ds_write_b128 v2, v[224:227]
	ds_write_b128 v2, v[228:231] offset:1152
	ds_write_b128 v2, v[232:235] offset:2304
	ds_write_b128 v2, v[236:239] offset:3456
	ds_write_b128 v2, v[240:243] offset:4608
	ds_write_b128 v2, v[244:247] offset:5760
	ds_write_b128 v2, v[248:251] offset:6912
	ds_write_b128 v2, v[186:189] offset:8064
	v_bfe_u32 v2, v25, 2, 2
	v_lshl_or_b32 v2, v8, 3, v2
	v_mul_lo_u32 v2, v2, s23
	s_waitcnt lgkmcnt(0)
	v_add3_u32 v16, s6, v34, v2
	ds_read_b64_tr_b16 v[8:9], v16 offset:9216
	ds_read_b64_tr_b16 v[10:11], v16 offset:9792
	ds_read_b64_tr_b16 v[4:5], v16 offset:13824
	ds_read_b64_tr_b16 v[6:7], v16 offset:14400
	ds_read_b64_tr_b16 v[12:13], v16
	ds_read_b64_tr_b16 v[14:15], v16 offset:576
	ds_read_b64_tr_b16 v[18:19], v16 offset:4608
	ds_read_b64_tr_b16 v[20:21], v16 offset:5184
	s_waitcnt lgkmcnt(2)
	v_mfma_f32_16x16x32_bf16 v[12:15], v[8:11], v[12:15], 0
	v_lshlrev_b32_e32 v2, 7, v17
	s_waitcnt lgkmcnt(0)
	v_mfma_f32_16x16x32_bf16 v[12:15], v[4:7], v[18:21], v[12:15]
	s_nop 7
	v_cvt_pk_bf16_f32 v18, v12, v13
	v_cvt_pk_bf16_f32 v19, v14, v15
	v_lshl_add_u64 v[12:13], v[0:1], 0, v[2:3]
	flat_store_dwordx2 v[12:13], v[18:19]
	ds_read_b64_tr_b16 v[18:19], v16 offset:32
	ds_read_b64_tr_b16 v[20:21], v16 offset:608
	ds_read_b64_tr_b16 v[22:23], v16 offset:4640
	ds_read_b64_tr_b16 v[24:25], v16 offset:5216
	s_waitcnt lgkmcnt(0)
	v_mfma_f32_16x16x32_bf16 v[18:21], v[8:11], v[18:21], 0
	v_mfma_f32_16x16x32_bf16 v[18:21], v[4:7], v[22:25], v[18:21]
	s_nop 7
	v_cvt_pk_bf16_f32 v14, v18, v19
	v_cvt_pk_bf16_f32 v15, v20, v21
	flat_store_dwordx2 v[12:13], v[14:15] offset:2048
	ds_read_b64_tr_b16 v[18:19], v16 offset:64
	ds_read_b64_tr_b16 v[20:21], v16 offset:640
	ds_read_b64_tr_b16 v[22:23], v16 offset:4672
	ds_read_b64_tr_b16 v[24:25], v16 offset:5248
	s_waitcnt lgkmcnt(0)
; #define LAS __attribute__((address_space(3)))
; __device__ __forceinline__ unsigned pk2(float lo, float hi) { const f32x2_t v = {lo, hi}; const bf16x2_t b = __builtin_convertvector(v, bf16x2_t); return __builtin_bit_cast(unsigned, b); }
; __device__ __forceinline__ void w_kv(const LAS bf16_t* vN, const LAS bf16_t* kN, bf16_t* S, int lo, int fq) {
; #pragma unroll
;     for (int db = 0; db < 4; ++db) {
;         bf16x8 kf[2];
; #pragma unroll
;         for (int kk = 0; kk < 2; ++kk) kf[kk] = tr_frag(kN, 32 * kk + 8 * fq, 32 * kk + 8 * fq + 4, 16 * db, lo);
; #pragma unroll
;         for (int eb = 0; eb < 4; ++eb) { f32x4 acc = {0.f, 0.f, 0.f, 0.f};
; #pragma unroll
;             for (int kk = 0; kk < 2; ++kk) { const bf16x8 vf = tr_frag(vN, 32 * kk + 8 * fq, 32 * kk + 8 * fq + 4, 16 * eb, lo); acc = __builtin_amdgcn_mfma_f32_16x16x32_bf16(kf[kk], vf, acc, 0, 0, 0); }
;             *(unsigned long long*)(S + (16 * eb + lo) * 64 + 16 * db + 4 * fq) = (unsigned long long)pk2(acc[0], acc[1]) | ((unsigned long long)pk2(acc[2], acc[3]) << 32); }
;     }
	v_mfma_f32_16x16x32_bf16 v[18:21], v[8:11], v[18:21], 0
	v_or_b32_e32 v14, 0x1000, v2
	v_mov_b32_e32 v15, v3
	v_or_b32_e32 v2, 0x1800, v2
	v_mfma_f32_16x16x32_bf16 v[18:21], v[4:7], v[22:25], v[18:21]
	s_nop 7
	v_cvt_pk_bf16_f32 v18, v18, v19
	v_cvt_pk_bf16_f32 v19, v20, v21
	v_lshl_add_u64 v[20:21], v[0:1], 0, v[14:15]
	flat_store_dwordx2 v[20:21], v[18:19]
	ds_read_b64_tr_b16 v[18:19], v16 offset:96
	ds_read_b64_tr_b16 v[20:21], v16 offset:672
	s_waitcnt lgkmcnt(0)
	v_mfma_f32_16x16x32_bf16 v[8:11], v[8:11], v[18:21], 0
	ds_read_b64_tr_b16 v[18:19], v16 offset:4704
	ds_read_b64_tr_b16 v[20:21], v16 offset:5280
	s_waitcnt lgkmcnt(0)
	v_mfma_f32_16x16x32_bf16 v[4:7], v[4:7], v[18:21], v[8:11]
	s_nop 7
	v_cvt_pk_bf16_f32 v4, v4, v5
	v_cvt_pk_bf16_f32 v5, v6, v7
	v_lshl_add_u64 v[6:7], v[0:1], 0, v[2:3]
	flat_store_dwordx2 v[6:7], v[4:5]
	ds_read_b64_tr_b16 v[4:5], v16 offset:9248
	ds_read_b64_tr_b16 v[6:7], v16 offset:9824
	ds_read_b64_tr_b16 v[8:9], v16 offset:13856
	ds_read_b64_tr_b16 v[10:11], v16 offset:14432
	ds_read_b64_tr_b16 v[18:19], v16
	ds_read_b64_tr_b16 v[20:21], v16 offset:576
	ds_read_b64_tr_b16 v[22:23], v16 offset:4608
	ds_read_b64_tr_b16 v[24:25], v16 offset:5184
	s_waitcnt lgkmcnt(0)
	v_mfma_f32_16x16x32_bf16 v[18:21], v[4:7], v[18:21], 0
	v_mfma_f32_16x16x32_bf16 v[18:21], v[8:11], v[22:25], v[18:21]
	s_nop 7
	v_cvt_pk_bf16_f32 v18, v18, v19
	v_cvt_pk_bf16_f32 v19, v20, v21
	flat_store_dwordx2 v[12:13], v[18:19] offset:32
	ds_read_b64_tr_b16 v[18:19], v16 offset:32
	ds_read_b64_tr_b16 v[20:21], v16 offset:608
	ds_read_b64_tr_b16 v[22:23], v16 offset:4640
	ds_read_b64_tr_b16 v[24:25], v16 offset:5216
	s_waitcnt lgkmcnt(0)
	v_mfma_f32_16x16x32_bf16 v[18:21], v[4:7], v[18:21], 0
	v_mfma_f32_16x16x32_bf16 v[18:21], v[8:11], v[22:25], v[18:21]
	s_nop 7
	v_cvt_pk_bf16_f32 v18, v18, v19
	v_cvt_pk_bf16_f32 v19, v20, v21
	flat_store_dwordx2 v[12:13], v[18:19] offset:2080
	ds_read_b64_tr_b16 v[18:19], v16 offset:64
	ds_read_b64_tr_b16 v[20:21], v16 offset:640
	ds_read_b64_tr_b16 v[22:23], v16 offset:4672
	ds_read_b64_tr_b16 v[24:25], v16 offset:5248
	s_waitcnt lgkmcnt(0)
	v_mfma_f32_16x16x32_bf16 v[18:21], v[4:7], v[18:21], 0
	v_mfma_f32_16x16x32_bf16 v[18:21], v[8:11], v[22:25], v[18:21]
	s_nop 7
	v_cvt_pk_bf16_f32 v18, v18, v19
	v_cvt_pk_bf16_f32 v19, v20, v21
	v_lshl_add_u64 v[20:21], v[26:27], 0, v[14:15]
	flat_store_dwordx2 v[20:21], v[18:19]
	ds_read_b64_tr_b16 v[18:19], v16 offset:96
	ds_read_b64_tr_b16 v[20:21], v16 offset:672
	s_waitcnt lgkmcnt(0)
	v_mfma_f32_16x16x32_bf16 v[4:7], v[4:7], v[18:21], 0
	ds_read_b64_tr_b16 v[18:19], v16 offset:4704
	ds_read_b64_tr_b16 v[20:21], v16 offset:5280
	s_waitcnt lgkmcnt(0)
	v_mfma_f32_16x16x32_bf16 v[4:7], v[8:11], v[18:21], v[4:7]
	s_nop 7
	v_cvt_pk_bf16_f32 v4, v4, v5
	v_cvt_pk_bf16_f32 v5, v6, v7
	v_lshl_add_u64 v[6:7], v[26:27], 0, v[2:3]
	flat_store_dwordx2 v[6:7], v[4:5]
	ds_read_b64_tr_b16 v[4:5], v16 offset:9280
	ds_read_b64_tr_b16 v[6:7], v16 offset:9856
	ds_read_b64_tr_b16 v[8:9], v16 offset:13888
	ds_read_b64_tr_b16 v[10:11], v16 offset:14464
	ds_read_b64_tr_b16 v[18:19], v16
	ds_read_b64_tr_b16 v[20:21], v16 offset:576
	ds_read_b64_tr_b16 v[22:23], v16 offset:4608
	ds_read_b64_tr_b16 v[24:25], v16 offset:5184
	s_waitcnt lgkmcnt(0)
	v_mfma_f32_16x16x32_bf16 v[18:21], v[4:7], v[18:21], 0
	v_lshl_add_u64 v[26:27], v[0:1], 0, 64
	v_lshl_add_u64 v[0:1], v[0:1], 0, s[34:35]
	v_mfma_f32_16x16x32_bf16 v[18:21], v[8:11], v[22:25], v[18:21]
	s_nop 7
	v_cvt_pk_bf16_f32 v18, v18, v19
	v_cvt_pk_bf16_f32 v19, v20, v21
	flat_store_dwordx2 v[12:13], v[18:19] offset:64
	ds_read_b64_tr_b16 v[18:19], v16 offset:32
	ds_read_b64_tr_b16 v[20:21], v16 offset:608
	ds_read_b64_tr_b16 v[22:23], v16 offset:4640
	ds_read_b64_tr_b16 v[24:25], v16 offset:5216
	s_waitcnt lgkmcnt(0)
; #define LAS __attribute__((address_space(3)))
; __device__ __forceinline__ unsigned pk2(float lo, float hi) { const f32x2_t v = {lo, hi}; const bf16x2_t b = __builtin_convertvector(v, bf16x2_t); return __builtin_bit_cast(unsigned, b); }
; __device__ __forceinline__ void w_kv(const LAS bf16_t* vN, const LAS bf16_t* kN, bf16_t* S, int lo, int fq) {
; #pragma unroll
;     for (int db = 0; db < 4; ++db) {
;         bf16x8 kf[2];
; #pragma unroll
;         for (int kk = 0; kk < 2; ++kk) kf[kk] = tr_frag(kN, 32 * kk + 8 * fq, 32 * kk + 8 * fq + 4, 16 * db, lo);
; #pragma unroll
;         for (int eb = 0; eb < 4; ++eb) { f32x4 acc = {0.f, 0.f, 0.f, 0.f};
; #pragma unroll
;             for (int kk = 0; kk < 2; ++kk) { const bf16x8 vf = tr_frag(vN, 32 * kk + 8 * fq, 32 * kk + 8 * fq + 4, 16 * eb, lo); acc = __builtin_amdgcn_mfma_f32_16x16x32_bf16(kf[kk], vf, acc, 0, 0, 0); }
;             *(unsigned long long*)(S + (16 * eb + lo) * 64 + 16 * db + 4 * fq) = (unsigned long long)pk2(acc[0], acc[1]) | ((unsigned long long)pk2(acc[2], acc[3]) << 32); }
;     }
	v_mfma_f32_16x16x32_bf16 v[18:21], v[4:7], v[18:21], 0
	v_mfma_f32_16x16x32_bf16 v[18:21], v[8:11], v[22:25], v[18:21]
	s_nop 7
	v_cvt_pk_bf16_f32 v18, v18, v19
	v_cvt_pk_bf16_f32 v19, v20, v21
	flat_store_dwordx2 v[12:13], v[18:19] offset:2112
	ds_read_b64_tr_b16 v[18:19], v16 offset:64
	ds_read_b64_tr_b16 v[20:21], v16 offset:640
	ds_read_b64_tr_b16 v[22:23], v16 offset:4672
	ds_read_b64_tr_b16 v[24:25], v16 offset:5248
	s_waitcnt lgkmcnt(0)
	v_mfma_f32_16x16x32_bf16 v[18:21], v[4:7], v[18:21], 0
	v_mfma_f32_16x16x32_bf16 v[18:21], v[8:11], v[22:25], v[18:21]
	s_nop 7
	v_cvt_pk_bf16_f32 v18, v18, v19
	v_cvt_pk_bf16_f32 v19, v20, v21
	v_lshl_add_u64 v[20:21], v[26:27], 0, v[14:15]
	flat_store_dwordx2 v[20:21], v[18:19]
	ds_read_b64_tr_b16 v[18:19], v16 offset:96
	ds_read_b64_tr_b16 v[20:21], v16 offset:672
	s_waitcnt lgkmcnt(0)
	v_mfma_f32_16x16x32_bf16 v[4:7], v[4:7], v[18:21], 0
	ds_read_b64_tr_b16 v[18:19], v16 offset:4704
	ds_read_b64_tr_b16 v[20:21], v16 offset:5280
	v_lshl_add_u64 v[14:15], v[0:1], 0, v[14:15]
	v_lshl_add_u64 v[0:1], v[0:1], 0, v[2:3]
	s_waitcnt lgkmcnt(0)
	v_mfma_f32_16x16x32_bf16 v[4:7], v[8:11], v[18:21], v[4:7]
	s_nop 7
	v_cvt_pk_bf16_f32 v4, v4, v5
	v_cvt_pk_bf16_f32 v5, v6, v7
	v_lshl_add_u64 v[6:7], v[26:27], 0, v[2:3]
	flat_store_dwordx2 v[6:7], v[4:5]
	ds_read_b64_tr_b16 v[4:5], v16 offset:9312
	ds_read_b64_tr_b16 v[6:7], v16 offset:9888
	ds_read_b64_tr_b16 v[8:9], v16 offset:13920
	ds_read_b64_tr_b16 v[10:11], v16 offset:14496
	ds_read_b64_tr_b16 v[18:19], v16
	ds_read_b64_tr_b16 v[20:21], v16 offset:576
	ds_read_b64_tr_b16 v[22:23], v16 offset:4608
	ds_read_b64_tr_b16 v[24:25], v16 offset:5184
	s_waitcnt lgkmcnt(0)
	v_mfma_f32_16x16x32_bf16 v[18:21], v[4:7], v[18:21], 0
	v_mfma_f32_16x16x32_bf16 v[18:21], v[8:11], v[22:25], v[18:21]
	s_nop 7
	v_cvt_pk_bf16_f32 v18, v18, v19
	v_cvt_pk_bf16_f32 v19, v20, v21
	flat_store_dwordx2 v[12:13], v[18:19] offset:96
	ds_read_b64_tr_b16 v[18:19], v16 offset:32
	ds_read_b64_tr_b16 v[20:21], v16 offset:608
	ds_read_b64_tr_b16 v[22:23], v16 offset:4640
	ds_read_b64_tr_b16 v[24:25], v16 offset:5216
	s_waitcnt lgkmcnt(0)
	v_mfma_f32_16x16x32_bf16 v[18:21], v[4:7], v[18:21], 0
	v_mfma_f32_16x16x32_bf16 v[18:21], v[8:11], v[22:25], v[18:21]
	s_nop 7
	v_cvt_pk_bf16_f32 v18, v18, v19
	v_cvt_pk_bf16_f32 v19, v20, v21
	flat_store_dwordx2 v[12:13], v[18:19] offset:2144
	ds_read_b64_tr_b16 v[18:19], v16 offset:64
	ds_read_b64_tr_b16 v[20:21], v16 offset:640
	ds_read_b64_tr_b16 v[22:23], v16 offset:4672
	ds_read_b64_tr_b16 v[24:25], v16 offset:5248
	s_waitcnt lgkmcnt(0)
	v_mfma_f32_16x16x32_bf16 v[18:21], v[4:7], v[18:21], 0
	v_mfma_f32_16x16x32_bf16 v[18:21], v[8:11], v[22:25], v[18:21]
	s_nop 7
	v_cvt_pk_bf16_f32 v12, v18, v19
	v_cvt_pk_bf16_f32 v13, v20, v21
	flat_store_dwordx2 v[14:15], v[12:13]
	ds_read_b64_tr_b16 v[12:13], v16 offset:96
	ds_read_b64_tr_b16 v[14:15], v16 offset:672
	s_waitcnt lgkmcnt(0)
	v_mfma_f32_16x16x32_bf16 v[4:7], v[4:7], v[12:15], 0
	ds_read_b64_tr_b16 v[12:13], v16 offset:4704
	ds_read_b64_tr_b16 v[14:15], v16 offset:5280
	s_waitcnt lgkmcnt(0)
	v_mfma_f32_16x16x32_bf16 v[4:7], v[8:11], v[12:15], v[4:7]
	s_nop 7
	v_cvt_pk_bf16_f32 v4, v4, v5
	v_cvt_pk_bf16_f32 v5, v6, v7
	flat_store_dwordx2 v[0:1], v[4:5]
	s_waitcnt lgkmcnt(0)
	s_branch .LBB0_515

; #define LAS __attribute__((address_space(3)))
; __device__ __forceinline__ unsigned pk2(float lo, float hi) { const f32x2_t v = {lo, hi}; const bf16x2_t b = __builtin_convertvector(v, bf16x2_t); return __builtin_bit_cast(unsigned, b); }
; #define WAVE_LDS_FENCE() asm volatile("s_waitcnt lgkmcnt(0)" ::: "memory")
; __device__ __forceinline__ void w_store_vT(LAS bf16_t* vN, const bf16_t* src, int lane) {
; #pragma unroll
;     for (int i = 0; i < 8; ++i) { const int m = (lane >> 3) + 8 * i, e0 = 8 * (lane & 7); *(LAS u32x4*)(vN + m * LD + e0) = *(const u32x4*)(src + (size_t)m * NIN + e0); }
; }
; __device__ __forceinline__ void w_kv(const LAS bf16_t* vN, const LAS bf16_t* kN, bf16_t* S, int lo, int fq) {
; #pragma unroll
;     for (int db = 0; db < 4; ++db) {
;         bf16x8 kf[2];
; #pragma unroll
;         for (int kk = 0; kk < 2; ++kk) kf[kk] = tr_frag(kN, 32 * kk + 8 * fq, 32 * kk + 8 * fq + 4, 16 * db, lo);
; #pragma unroll
;         for (int eb = 0; eb < 4; ++eb) { f32x4 acc = {0.f, 0.f, 0.f, 0.f};
; #pragma unroll
;             for (int kk = 0; kk < 2; ++kk) { const bf16x8 vf = tr_frag(vN, 32 * kk + 8 * fq, 32 * kk + 8 * fq + 4, 16 * eb, lo); acc = __builtin_amdgcn_mfma_f32_16x16x32_bf16(kf[kk], vf, acc, 0, 0, 0); }
;             *(unsigned long long*)(S + (16 * eb + lo) * 64 + 16 * db + 4 * fq) = (unsigned long long)pk2(acc[0], acc[1]) | ((unsigned long long)pk2(acc[2], acc[3]) << 32); }
; __device__ __forceinline__ void w_hg_m1(const Args& a, int l, unsigned char* ws, const bf16_t* proj, LAS unsigned char* wl, int b, int ck_, int h, int lane) {
;     ...
;     w_store_vT(vT, proj + (size_t)row0 * NIN + C_HI + 64 * h, lane);
;     WAVE_LDS_FENCE();
;     w_kv(vT, kT, (bf16_t*)(ws + WS_SHG) + (size_t)((b * NCH + ck_) * 4 + h) * 4096, lo, fq);
.LBB0_529:
	s_or_b64 exec, exec, s[34:35]
	s_add_u32 s20, s91, s93
	v_lshlrev_b32_e32 v2, 4, v33
	s_addc_u32 s21, s92, 0
	v_and_b32_e32 v2, 0x70, v2
	v_lshl_add_u64 v[4:5], s[20:21], 0, v[2:3]
	s_mov_b64 s[20:21], 0x1400
	v_ashrrev_i32_e32 v1, 3, v33
	v_lshl_add_u64 v[8:9], v[4:5], 0, s[20:21]
	v_mad_i64_i32 v[4:5], s[20:21], v1, s72, v[8:9]
	global_load_dwordx4 v[224:227], v[4:5], off
	v_add_u32_e32 v4, 8, v1
	v_mad_i64_i32 v[4:5], s[20:21], v4, s72, v[8:9]
	global_load_dwordx4 v[228:231], v[4:5], off
	v_add_u32_e32 v4, 16, v1
	v_mad_i64_i32 v[4:5], s[20:21], v4, s72, v[8:9]
	global_load_dwordx4 v[232:235], v[4:5], off
	v_add_u32_e32 v4, 24, v1
	v_mad_i64_i32 v[4:5], s[20:21], v4, s72, v[8:9]
	global_load_dwordx4 v[236:239], v[4:5], off
	v_add_u32_e32 v4, 32, v1
	v_mad_i64_i32 v[4:5], s[20:21], v4, s72, v[8:9]
	global_load_dwordx4 v[240:243], v[4:5], off
	v_add_u32_e32 v4, 40, v1
	v_mad_i64_i32 v[4:5], s[20:21], v4, s72, v[8:9]
	global_load_dwordx4 v[244:247], v[4:5], off
	v_add_u32_e32 v4, 48, v1
	v_mad_i64_i32 v[4:5], s[20:21], v4, s72, v[8:9]
	global_load_dwordx4 v[248:251], v[4:5], off
	v_add_u32_e32 v4, 56, v1
	v_mad_i64_i32 v[4:5], s[20:21], v4, s72, v[8:9]
	global_load_dwordx4 v[186:189], v[4:5], off
	v_mul_lo_u32 v10, v1, s23
	v_add3_u32 v2, s6, v2, v10
	s_lshl_b64 s[20:21], s[62:63], 13
	s_add_u32 s20, s7, s20
	s_addc_u32 s21, s66, s21
	v_lshrrev_b32_e32 v1, 2, v34
	s_waitcnt vmcnt(0) lgkmcnt(0)
	ds_write_b128 v2, v[224:227]
	ds_write_b128 v2, v[228:231] offset:1152
	ds_write_b128 v2, v[232:235] offset:2304
	ds_write_b128 v2, v[236:239] offset:3456
	ds_write_b128 v2, v[240:243] offset:4608
	ds_write_b128 v2, v[244:247] offset:5760
	ds_write_b128 v2, v[248:251] offset:6912
	ds_write_b128 v2, v[186:189] offset:8064
	v_lshlrev_b32_e32 v2, 3, v34
	v_lshlrev_b32_e32 v4, 2, v32
	v_and_b32_e32 v2, 24, v2
	v_ashrrev_i32_e32 v5, 31, v4
	v_add_u32_e32 v2, s6, v2
	v_lshl_add_u64 v[6:7], v[4:5], 1, s[20:21]
	v_or_b32_e32 v4, v0, v1
	v_add_u32_e32 v0, v0, v1
	s_waitcnt lgkmcnt(0)
	v_mad_u64_u32 v[4:5], s[20:21], v4, s23, v[2:3]
	v_mad_u64_u32 v[0:1], s[20:21], v0, s23, v[2:3]
	ds_read_b64_tr_b16 v[12:13], v4 offset:9216
	ds_read_b64_tr_b16 v[14:15], v4 offset:9792
	ds_read_b64_tr_b16 v[16:17], v0 offset:13824
	ds_read_b64_tr_b16 v[18:19], v0 offset:14400
	ds_read_b64_tr_b16 v[8:9], v4
	ds_read_b64_tr_b16 v[10:11], v4 offset:576
	ds_read_b64_tr_b16 v[20:21], v0 offset:4608
	ds_read_b64_tr_b16 v[22:23], v0 offset:5184
	s_waitcnt lgkmcnt(2)
	v_mfma_f32_16x16x32_bf16 v[8:11], v[12:15], v[8:11], 0
	v_lshlrev_b32_e32 v2, 7, v34
	v_lshl_add_u64 v[28:29], v[6:7], 0, 32
	s_mov_b64 s[20:21], 0x60
	s_waitcnt lgkmcnt(0)
	v_mfma_f32_16x16x32_bf16 v[8:11], v[16:19], v[20:23], v[8:11]
	s_nop 7
	v_cvt_pk_bf16_f32 v20, v8, v9
	v_cvt_pk_bf16_f32 v21, v10, v11
	v_lshl_add_u64 v[8:9], v[6:7], 0, v[2:3]
	flat_store_dwordx2 v[8:9], v[20:21]
	ds_read_b64_tr_b16 v[20:21], v4 offset:32
	ds_read_b64_tr_b16 v[22:23], v4 offset:608
	ds_read_b64_tr_b16 v[24:25], v0 offset:4640
	ds_read_b64_tr_b16 v[26:27], v0 offset:5216
	s_waitcnt lgkmcnt(0)
	v_mfma_f32_16x16x32_bf16 v[20:23], v[12:15], v[20:23], 0
	v_mfma_f32_16x16x32_bf16 v[20:23], v[16:19], v[24:27], v[20:23]
	s_nop 7
	v_cvt_pk_bf16_f32 v10, v20, v21
	v_cvt_pk_bf16_f32 v11, v22, v23
	flat_store_dwordx2 v[8:9], v[10:11] offset:2048
	ds_read_b64_tr_b16 v[20:21], v4 offset:64
	ds_read_b64_tr_b16 v[22:23], v4 offset:640
	ds_read_b64_tr_b16 v[24:25], v0 offset:4672
	ds_read_b64_tr_b16 v[26:27], v0 offset:5248
	s_waitcnt lgkmcnt(0)
	v_mfma_f32_16x16x32_bf16 v[20:23], v[12:15], v[20:23], 0
	v_or_b32_e32 v10, 0x1000, v2
	v_mov_b32_e32 v11, v3
	v_or_b32_e32 v2, 0x1800, v2
	v_mfma_f32_16x16x32_bf16 v[20:23], v[16:19], v[24:27], v[20:23]
	s_nop 7
	v_cvt_pk_bf16_f32 v20, v20, v21
	v_cvt_pk_bf16_f32 v21, v22, v23
	v_lshl_add_u64 v[22:23], v[6:7], 0, v[10:11]
	flat_store_dwordx2 v[22:23], v[20:21]
	ds_read_b64_tr_b16 v[20:21], v4 offset:96
	ds_read_b64_tr_b16 v[22:23], v4 offset:672
	s_waitcnt lgkmcnt(0)
	v_mfma_f32_16x16x32_bf16 v[12:15], v[12:15], v[20:23], 0
	ds_read_b64_tr_b16 v[20:21], v0 offset:4704
	ds_read_b64_tr_b16 v[22:23], v0 offset:5280
	s_waitcnt lgkmcnt(0)
	v_mfma_f32_16x16x32_bf16 v[12:15], v[16:19], v[20:23], v[12:15]
	s_nop 7
	v_cvt_pk_bf16_f32 v12, v12, v13
	v_cvt_pk_bf16_f32 v13, v14, v15
	v_lshl_add_u64 v[14:15], v[6:7], 0, v[2:3]
	flat_store_dwordx2 v[14:15], v[12:13]
	ds_read_b64_tr_b16 v[12:13], v4 offset:9248
	ds_read_b64_tr_b16 v[14:15], v4 offset:9824
	ds_read_b64_tr_b16 v[16:17], v0 offset:13856
	ds_read_b64_tr_b16 v[18:19], v0 offset:14432
	ds_read_b64_tr_b16 v[20:21], v4
	ds_read_b64_tr_b16 v[22:23], v4 offset:576
	ds_read_b64_tr_b16 v[24:25], v0 offset:4608
	ds_read_b64_tr_b16 v[26:27], v0 offset:5184
	s_waitcnt lgkmcnt(0)
	v_mfma_f32_16x16x32_bf16 v[20:23], v[12:15], v[20:23], 0
	v_mfma_f32_16x16x32_bf16 v[20:23], v[16:19], v[24:27], v[20:23]
	s_nop 7
	v_cvt_pk_bf16_f32 v20, v20, v21
	v_cvt_pk_bf16_f32 v21, v22, v23
	flat_store_dwordx2 v[8:9], v[20:21] offset:32
	ds_read_b64_tr_b16 v[20:21], v4 offset:32
	ds_read_b64_tr_b16 v[22:23], v4 offset:608
	ds_read_b64_tr_b16 v[24:25], v0 offset:4640
	ds_read_b64_tr_b16 v[26:27], v0 offset:5216
	s_waitcnt lgkmcnt(0)
; #define LAS __attribute__((address_space(3)))
; __device__ __forceinline__ unsigned pk2(float lo, float hi) { const f32x2_t v = {lo, hi}; const bf16x2_t b = __builtin_convertvector(v, bf16x2_t); return __builtin_bit_cast(unsigned, b); }
; __device__ __forceinline__ void w_kv(const LAS bf16_t* vN, const LAS bf16_t* kN, bf16_t* S, int lo, int fq) {
; #pragma unroll
;     for (int db = 0; db < 4; ++db) {
;         bf16x8 kf[2];
; #pragma unroll
;         for (int kk = 0; kk < 2; ++kk) kf[kk] = tr_frag(kN, 32 * kk + 8 * fq, 32 * kk + 8 * fq + 4, 16 * db, lo);
; #pragma unroll
;         for (int eb = 0; eb < 4; ++eb) { f32x4 acc = {0.f, 0.f, 0.f, 0.f};
; #pragma unroll
;             for (int kk = 0; kk < 2; ++kk) { const bf16x8 vf = tr_frag(vN, 32 * kk + 8 * fq, 32 * kk + 8 * fq + 4, 16 * eb, lo); acc = __builtin_amdgcn_mfma_f32_16x16x32_bf16(kf[kk], vf, acc, 0, 0, 0); }
;             *(unsigned long long*)(S + (16 * eb + lo) * 64 + 16 * db + 4 * fq) = (unsigned long long)pk2(acc[0], acc[1]) | ((unsigned long long)pk2(acc[2], acc[3]) << 32); }
;     }
	v_mfma_f32_16x16x32_bf16 v[20:23], v[12:15], v[20:23], 0
	v_mfma_f32_16x16x32_bf16 v[20:23], v[16:19], v[24:27], v[20:23]
	s_nop 7
	v_cvt_pk_bf16_f32 v20, v20, v21
	v_cvt_pk_bf16_f32 v21, v22, v23
	flat_store_dwordx2 v[8:9], v[20:21] offset:2080
	ds_read_b64_tr_b16 v[20:21], v4 offset:64
	ds_read_b64_tr_b16 v[22:23], v4 offset:640
	ds_read_b64_tr_b16 v[24:25], v0 offset:4672
	ds_read_b64_tr_b16 v[26:27], v0 offset:5248
	s_waitcnt lgkmcnt(0)
	v_mfma_f32_16x16x32_bf16 v[20:23], v[12:15], v[20:23], 0
	v_mfma_f32_16x16x32_bf16 v[20:23], v[16:19], v[24:27], v[20:23]
	s_nop 7
	v_cvt_pk_bf16_f32 v20, v20, v21
	v_cvt_pk_bf16_f32 v21, v22, v23
	v_lshl_add_u64 v[22:23], v[28:29], 0, v[10:11]
	flat_store_dwordx2 v[22:23], v[20:21]
	ds_read_b64_tr_b16 v[20:21], v4 offset:96
	ds_read_b64_tr_b16 v[22:23], v4 offset:672
	s_waitcnt lgkmcnt(0)
	v_mfma_f32_16x16x32_bf16 v[12:15], v[12:15], v[20:23], 0
	ds_read_b64_tr_b16 v[20:21], v0 offset:4704
	ds_read_b64_tr_b16 v[22:23], v0 offset:5280
	s_waitcnt lgkmcnt(0)
	v_mfma_f32_16x16x32_bf16 v[12:15], v[16:19], v[20:23], v[12:15]
	s_nop 7
	v_cvt_pk_bf16_f32 v12, v12, v13
	v_cvt_pk_bf16_f32 v13, v14, v15
	v_lshl_add_u64 v[14:15], v[28:29], 0, v[2:3]
	flat_store_dwordx2 v[14:15], v[12:13]
	ds_read_b64_tr_b16 v[12:13], v4 offset:9280
	ds_read_b64_tr_b16 v[14:15], v4 offset:9856
	ds_read_b64_tr_b16 v[16:17], v0 offset:13888
	ds_read_b64_tr_b16 v[18:19], v0 offset:14464
	ds_read_b64_tr_b16 v[20:21], v4
	ds_read_b64_tr_b16 v[22:23], v4 offset:576
	ds_read_b64_tr_b16 v[24:25], v0 offset:4608
	ds_read_b64_tr_b16 v[26:27], v0 offset:5184
	s_waitcnt lgkmcnt(0)
	v_mfma_f32_16x16x32_bf16 v[20:23], v[12:15], v[20:23], 0
	v_lshl_add_u64 v[28:29], v[6:7], 0, 64
	v_mfma_f32_16x16x32_bf16 v[20:23], v[16:19], v[24:27], v[20:23]
	s_nop 7
	v_cvt_pk_bf16_f32 v20, v20, v21
	v_cvt_pk_bf16_f32 v21, v22, v23
	flat_store_dwordx2 v[8:9], v[20:21] offset:64
	ds_read_b64_tr_b16 v[20:21], v4 offset:32
	ds_read_b64_tr_b16 v[22:23], v4 offset:608
	ds_read_b64_tr_b16 v[24:25], v0 offset:4640
	ds_read_b64_tr_b16 v[26:27], v0 offset:5216
	s_waitcnt lgkmcnt(0)
	v_mfma_f32_16x16x32_bf16 v[20:23], v[12:15], v[20:23], 0
	v_mfma_f32_16x16x32_bf16 v[20:23], v[16:19], v[24:27], v[20:23]
	s_nop 7
	v_cvt_pk_bf16_f32 v20, v20, v21
	v_cvt_pk_bf16_f32 v21, v22, v23
	flat_store_dwordx2 v[8:9], v[20:21] offset:2112
	ds_read_b64_tr_b16 v[20:21], v4 offset:64
	ds_read_b64_tr_b16 v[22:23], v4 offset:640
	ds_read_b64_tr_b16 v[24:25], v0 offset:4672
	ds_read_b64_tr_b16 v[26:27], v0 offset:5248
	s_waitcnt lgkmcnt(0)
	v_mfma_f32_16x16x32_bf16 v[20:23], v[12:15], v[20:23], 0
	v_mfma_f32_16x16x32_bf16 v[20:23], v[16:19], v[24:27], v[20:23]
	s_nop 7
	v_cvt_pk_bf16_f32 v20, v20, v21
	v_cvt_pk_bf16_f32 v21, v22, v23
	v_lshl_add_u64 v[22:23], v[28:29], 0, v[10:11]
	flat_store_dwordx2 v[22:23], v[20:21]
	ds_read_b64_tr_b16 v[20:21], v4 offset:96
	ds_read_b64_tr_b16 v[22:23], v4 offset:672
	s_waitcnt lgkmcnt(0)
	v_mfma_f32_16x16x32_bf16 v[12:15], v[12:15], v[20:23], 0
	ds_read_b64_tr_b16 v[20:21], v0 offset:4704
	ds_read_b64_tr_b16 v[22:23], v0 offset:5280
	s_waitcnt lgkmcnt(0)
	v_mfma_f32_16x16x32_bf16 v[12:15], v[16:19], v[20:23], v[12:15]
	s_nop 7
	v_cvt_pk_bf16_f32 v12, v12, v13
	v_cvt_pk_bf16_f32 v13, v14, v15
	v_lshl_add_u64 v[14:15], v[28:29], 0, v[2:3]
	flat_store_dwordx2 v[14:15], v[12:13]
	ds_read_b64_tr_b16 v[12:13], v4 offset:9312
	ds_read_b64_tr_b16 v[14:15], v4 offset:9888
	ds_read_b64_tr_b16 v[16:17], v0 offset:13920
	ds_read_b64_tr_b16 v[18:19], v0 offset:14496
	ds_read_b64_tr_b16 v[20:21], v4
	ds_read_b64_tr_b16 v[22:23], v4 offset:576
	ds_read_b64_tr_b16 v[24:25], v0 offset:4608
	ds_read_b64_tr_b16 v[26:27], v0 offset:5184
	s_waitcnt lgkmcnt(0)
	v_mfma_f32_16x16x32_bf16 v[20:23], v[12:15], v[20:23], 0
	v_lshl_add_u64 v[28:29], v[6:7], 0, s[20:21]
	v_mfma_f32_16x16x32_bf16 v[20:23], v[16:19], v[24:27], v[20:23]
	s_nop 7
	v_cvt_pk_bf16_f32 v6, v20, v21
	v_cvt_pk_bf16_f32 v7, v22, v23
	flat_store_dwordx2 v[8:9], v[6:7] offset:96
	ds_read_b64_tr_b16 v[20:21], v4 offset:32
	ds_read_b64_tr_b16 v[22:23], v4 offset:608
	ds_read_b64_tr_b16 v[24:25], v0 offset:4640
	ds_read_b64_tr_b16 v[26:27], v0 offset:5216
	s_waitcnt lgkmcnt(0)
	v_mfma_f32_16x16x32_bf16 v[20:23], v[12:15], v[20:23], 0
	v_mfma_f32_16x16x32_bf16 v[20:23], v[16:19], v[24:27], v[20:23]
	s_nop 7
	v_cvt_pk_bf16_f32 v6, v20, v21
	v_cvt_pk_bf16_f32 v7, v22, v23
	flat_store_dwordx2 v[8:9], v[6:7] offset:2144
	ds_read_b64_tr_b16 v[6:7], v4 offset:64
	ds_read_b64_tr_b16 v[8:9], v4 offset:640
	ds_read_b64_tr_b16 v[20:21], v0 offset:4672
	ds_read_b64_tr_b16 v[22:23], v0 offset:5248
	s_waitcnt lgkmcnt(0)
	v_mfma_f32_16x16x32_bf16 v[6:9], v[12:15], v[6:9], 0
	v_mfma_f32_16x16x32_bf16 v[6:9], v[16:19], v[20:23], v[6:9]
	s_nop 7
	v_cvt_pk_bf16_f32 v6, v6, v7
	v_cvt_pk_bf16_f32 v7, v8, v9
	v_lshl_add_u64 v[8:9], v[28:29], 0, v[10:11]
	flat_store_dwordx2 v[8:9], v[6:7]
	ds_read_b64_tr_b16 v[6:7], v4 offset:96
	ds_read_b64_tr_b16 v[8:9], v4 offset:672
	s_waitcnt lgkmcnt(0)
	v_mfma_f32_16x16x32_bf16 v[4:7], v[12:15], v[6:9], 0
	ds_read_b64_tr_b16 v[8:9], v0 offset:4704
	ds_read_b64_tr_b16 v[10:11], v0 offset:5280
	s_waitcnt lgkmcnt(0)
	v_mfma_f32_16x16x32_bf16 v[4:7], v[16:19], v[8:11], v[4:7]
	s_nop 7
	v_cvt_pk_bf16_f32 v0, v4, v5
	v_cvt_pk_bf16_f32 v1, v6, v7
	v_lshl_add_u64 v[4:5], v[28:29], 0, v[2:3]
	flat_store_dwordx2 v[4:5], v[0:1]
	s_waitcnt lgkmcnt(0)
